# combo8: MFMA-LDS interleave - 4 of the 8 A-fragment reads of each 8-read slot issued in the second half of the preceding MFMA block; vmcnt(8) one slot earlier (on combo7)
# baseline (speedup 1.0000x reference)
; #define PG8_STAGE(bufoff, gbase, voff) do { _Pragma("unroll") for (int _i = 0; _i < 2; ++_i) \
;     __builtin_amdgcn_global_load_lds((const unsigned*)((const char*)(gbase) + (voff)[_i]), (LAS unsigned*)(lds + (bufoff) + ldsw + _i * 8192), 16, 0, 0); } while (0)
; #define PG8_LDA(dst, b, h) do { _Pragma("unroll") for (int m = 0; m < 4; ++m) _Pragma("unroll") for (int k = 0; k < 2; ++k) dst[m][k] = *(const LAS bf16x8*)(lds + PG8_SA(b, h) + aoff + m * 2048 + k * 1024); } while (0)
; #define PG8_LDB(dst, b, h) do { _Pragma("unroll") for (int n = 0; n < 2; ++n) _Pragma("unroll") for (int k = 0; k < 2; ++k) dst[n][k] = *(const LAS bf16x8*)(lds + PG8_SB(b, h) + boff + n * 2048 + k * 1024); } while (0)
; #define PG8_MMA(ai, bj, At, Bt) do { __builtin_amdgcn_s_setprio(1); _Pragma("unroll") for (int m = 0; m < 4; ++m) _Pragma("unroll") for (int n = 0; n < 2; ++n) _Pragma("unroll") for (int k = 0; k < 2; ++k) \
;     acc[ai][bj][m][n] = __builtin_amdgcn_mfma_f32_16x16x32_bf16(Bt[n][k], At[m][k], acc[ai][bj][m][n], 0, 0, 0); __builtin_amdgcn_s_setprio(0); } while (0)
; #define PG8_WAIT_L(n) asm volatile("s_waitcnt lgkmcnt(" #n ")" ::: "memory")
; #define PG8_BAR __builtin_amdgcn_s_barrier()
; template <class Epi, class Sched = StaticOrder>
; DI void gemm_phase(LAS unsigned char* lds, const Gemm g, const Sched& S, const Epi& E) {
;     ...
;     const bool has_next = S.next(ui + 1, nxt);
;     const char* nA = has_next ? (const char*)g.A + (size_t)nxt.pm * tstep : cA; const char* nB = has_next ? (const char*)g.Bt + (size_t)nxt.pn * tstep : cB;
;     for (int t = 0; t < nt; t += 2) {
;       const bool last = (t == nt - 2);
;       const char* a1 = cA + (size_t)(t + 1) * kstep;
;       const char* a2 = last ? nA : cA + (size_t)(t + 2) * kstep; const char* b2 = last ? nB : cB + (size_t)(t + 2) * kstep;
;       const char* a3 = a2 + kstep; const char* b3 = b2 + kstep;
;       PG8_LDB(B0, 0, 0); PG8_SCHED; PG8_LDA(At, 0, 0); PG8_STAGE(PG8_SA(1, 1), a1 + hstep, voffA);
;       PG8_WAIT_L(8); PG8_BAR; PG8_WAIT_L(0); PG8_MMA(0, 0, At, B0); PG8_BAR; PG8_SCHED;
;     ...
;     for (int a = 0; a < 2; ++a)
; #pragma unroll
;       for (int b = 0; b < 2; ++b)
; #pragma unroll
;         for (int m = 0; m < 4; ++m)
; #pragma unroll
;           for (int n = 0; n < 2; ++n) acc[a][b][m][n] = (f32x4){0.f, 0.f, 0.f, 0.f};
;     cur = nxt; cA = nA; cB = nB; ++ui;
.LBB0_345:
	s_ashr_i32 s31, s30, 31
	v_cmp_lt_i64_e32 vcc, s[10:11], v[150:151]
	s_lshl_b64 s[10:11], s[30:31], 20
	s_add_u32 s34, s33, s10
	s_addc_u32 s35, s38, s11
	s_and_b64 s[10:11], vcc, exec
	s_cselect_b32 s31, s35, s7
	s_cselect_b32 s42, s34, s6
	s_ashr_i32 s29, s28, 31
	s_lshl_b64 s[10:11], s[28:29], 20
	s_add_u32 s36, s39, s10
	s_addc_u32 s37, s40, s11
	s_and_b64 s[10:11], vcc, exec
	s_cselect_b32 s29, s37, s9
	s_cselect_b32 s43, s36, s8
	s_add_u32 s6, s6, 0x80080
	s_addc_u32 s7, s7, 0
	s_add_u32 s44, s8, 0x100
	v_mov_b32_e32 v0, 0
	s_addc_u32 s45, s9, 0
	s_mov_b32 s52, -2
	v_mov_b32_e32 v1, v0
	v_mov_b32_e32 v2, v0
	v_mov_b32_e32 v3, v0
	v_mov_b32_e32 v4, v0
	v_mov_b32_e32 v5, v0
	v_mov_b32_e32 v6, v0
	v_mov_b32_e32 v7, v0
	v_mov_b32_e32 v8, v0
	v_mov_b32_e32 v9, v0
	v_mov_b32_e32 v10, v0
	v_mov_b32_e32 v11, v0
	v_mov_b32_e32 v16, v0
	v_mov_b32_e32 v17, v0
	v_mov_b32_e32 v18, v0
	v_mov_b32_e32 v19, v0
	v_mov_b32_e32 v24, v0
	v_mov_b32_e32 v25, v0
	v_mov_b32_e32 v26, v0
	v_mov_b32_e32 v27, v0
	v_mov_b32_e32 v32, v0
	v_mov_b32_e32 v33, v0
	v_mov_b32_e32 v34, v0
	v_mov_b32_e32 v35, v0
	v_mov_b32_e32 v40, v0
	v_mov_b32_e32 v41, v0
	v_mov_b32_e32 v42, v0
	v_mov_b32_e32 v43, v0
	v_mov_b32_e32 v48, v0
	v_mov_b32_e32 v49, v0
	v_mov_b32_e32 v50, v0
	v_mov_b32_e32 v51, v0
	v_mov_b32_e32 v12, v0
	v_mov_b32_e32 v13, v0
	v_mov_b32_e32 v14, v0
	v_mov_b32_e32 v15, v0
	v_mov_b32_e32 v20, v0
	v_mov_b32_e32 v21, v0
	v_mov_b32_e32 v22, v0
	v_mov_b32_e32 v23, v0
	v_mov_b32_e32 v28, v0
	v_mov_b32_e32 v29, v0
	v_mov_b32_e32 v30, v0
	v_mov_b32_e32 v31, v0
	v_mov_b32_e32 v36, v0
	v_mov_b32_e32 v37, v0
	v_mov_b32_e32 v38, v0
	v_mov_b32_e32 v39, v0
	v_mov_b32_e32 v44, v0
	v_mov_b32_e32 v45, v0
	v_mov_b32_e32 v46, v0
	v_mov_b32_e32 v47, v0
	v_mov_b32_e32 v52, v0
	v_mov_b32_e32 v53, v0
	v_mov_b32_e32 v54, v0
	v_mov_b32_e32 v55, v0
	v_mov_b32_e32 v56, v0
	v_mov_b32_e32 v57, v0
	v_mov_b32_e32 v58, v0
	v_mov_b32_e32 v59, v0
	v_mov_b32_e32 v60, v0
	v_mov_b32_e32 v61, v0
	v_mov_b32_e32 v62, v0
	v_mov_b32_e32 v63, v0
	v_mov_b32_e32 v64, v0
	v_mov_b32_e32 v65, v0
	v_mov_b32_e32 v66, v0
	v_mov_b32_e32 v67, v0
	v_mov_b32_e32 v68, v0
	v_mov_b32_e32 v69, v0
	v_mov_b32_e32 v70, v0
	v_mov_b32_e32 v71, v0
	v_mov_b32_e32 v72, v0
	v_mov_b32_e32 v73, v0
	v_mov_b32_e32 v74, v0
	v_mov_b32_e32 v75, v0
	v_mov_b32_e32 v80, v0
	v_mov_b32_e32 v81, v0
	v_mov_b32_e32 v82, v0
	v_mov_b32_e32 v83, v0
	v_mov_b32_e32 v88, v0
	v_mov_b32_e32 v89, v0
	v_mov_b32_e32 v90, v0
	v_mov_b32_e32 v91, v0
	v_mov_b32_e32 v96, v0
	v_mov_b32_e32 v97, v0
	v_mov_b32_e32 v98, v0
	v_mov_b32_e32 v99, v0
	v_mov_b32_e32 v112, v0
	v_mov_b32_e32 v113, v0
	v_mov_b32_e32 v114, v0
	v_mov_b32_e32 v115, v0
	v_mov_b32_e32 v116, v0
	v_mov_b32_e32 v117, v0
	v_mov_b32_e32 v118, v0
	v_mov_b32_e32 v119, v0
	v_mov_b32_e32 v76, v0
	v_mov_b32_e32 v77, v0
	v_mov_b32_e32 v78, v0
	v_mov_b32_e32 v79, v0
	v_mov_b32_e32 v84, v0
	v_mov_b32_e32 v85, v0
	v_mov_b32_e32 v86, v0
	v_mov_b32_e32 v87, v0
	v_mov_b32_e32 v92, v0
	v_mov_b32_e32 v93, v0
	v_mov_b32_e32 v94, v0
	v_mov_b32_e32 v95, v0
	v_mov_b32_e32 v100, v0
	v_mov_b32_e32 v101, v0
	v_mov_b32_e32 v102, v0
	v_mov_b32_e32 v103, v0
	v_mov_b32_e32 v104, v0
	v_mov_b32_e32 v105, v0
	v_mov_b32_e32 v106, v0
	v_mov_b32_e32 v107, v0
	v_mov_b32_e32 v108, v0
	v_mov_b32_e32 v109, v0
	v_mov_b32_e32 v110, v0
	v_mov_b32_e32 v111, v0
	v_mov_b32_e32 v120, v0
	v_mov_b32_e32 v121, v0
	v_mov_b32_e32 v122, v0
	v_mov_b32_e32 v123, v0
	v_mov_b32_e32 v124, v0
	v_mov_b32_e32 v125, v0
	v_mov_b32_e32 v126, v0
	v_mov_b32_e32 v127, v0
	ds_read_b128 v[128:131], v173
	ds_read_b128 v[132:135], v173 offset:1024
	ds_read_b128 v[154:157], v173 offset:2048
	ds_read_b128 v[158:161], v173 offset:3072
	ds_read_b128 v[162:165], v174
	ds_read_b128 v[178:181], v174 offset:2048
	ds_read_b128 v[186:189], v174 offset:4096
	ds_read_b128 v[194:197], v174 offset:6144
.LBB0_346:
	s_add_u32 s8, s6, 0xfff80080
	s_addc_u32 s9, s7, -1
	s_cmp_eq_u32 s52, 28
	s_cselect_b32 s11, s31, s9
	s_cselect_b32 s10, s42, s8
	s_cselect_b32 s9, s29, s45
	s_cselect_b32 s8, s43, s44
	s_add_i32 m0, s48, 0xc000
	ds_read_b128 v[166:169], v174 offset:1024
	ds_read_b128 v[182:185], v174 offset:3072
	ds_read_b128 v[190:193], v174 offset:5120
	ds_read_b128 v[198:201], v174 offset:7168
	global_load_lds_dwordx4 v146, s[6:7]
	s_add_i32 m0, s48, 0xe000
	s_nop 0
	global_load_lds_dwordx4 v148, s[6:7]
	s_waitcnt lgkmcnt(0)
	s_waitcnt vmcnt(8)
	s_setprio 1
	s_barrier
	v_mfma_f32_16x16x32_bf16 v[124:127], v[128:131], v[162:165], v[124:127]
	v_mfma_f32_16x16x32_bf16 v[120:123], v[154:157], v[162:165], v[120:123]
	v_mfma_f32_16x16x32_bf16 v[108:111], v[128:131], v[178:181], v[108:111]
	v_mfma_f32_16x16x32_bf16 v[104:107], v[154:157], v[178:181], v[104:107]
	v_mfma_f32_16x16x32_bf16 v[100:103], v[128:131], v[186:189], v[100:103]
	v_mfma_f32_16x16x32_bf16 v[92:95], v[154:157], v[186:189], v[92:95]
	v_mfma_f32_16x16x32_bf16 v[84:87], v[128:131], v[194:197], v[84:87]
	v_mfma_f32_16x16x32_bf16 v[76:79], v[154:157], v[194:197], v[76:79]
	v_mfma_f32_16x16x32_bf16 v[124:127], v[132:135], v[166:169], v[124:127]
	v_mfma_f32_16x16x32_bf16 v[120:123], v[158:161], v[166:169], v[120:123]
	v_mfma_f32_16x16x32_bf16 v[108:111], v[132:135], v[182:185], v[108:111]
	v_mfma_f32_16x16x32_bf16 v[104:107], v[158:161], v[182:185], v[104:107]
	v_mfma_f32_16x16x32_bf16 v[100:103], v[132:135], v[190:193], v[100:103]
	v_mfma_f32_16x16x32_bf16 v[92:95], v[158:161], v[190:193], v[92:95]
	v_mfma_f32_16x16x32_bf16 v[84:87], v[132:135], v[198:201], v[84:87]
	v_mfma_f32_16x16x32_bf16 v[76:79], v[158:161], v[198:201], v[76:79]
	s_barrier
; #define PG8_STAGE(bufoff, gbase, voff) do { _Pragma("unroll") for (int _i = 0; _i < 2; ++_i) \
;     __builtin_amdgcn_global_load_lds((const unsigned*)((const char*)(gbase) + (voff)[_i]), (LAS unsigned*)(lds + (bufoff) + ldsw + _i * 8192), 16, 0, 0); } while (0)
; #define PG8_LDA(dst, b, h) do { _Pragma("unroll") for (int m = 0; m < 4; ++m) _Pragma("unroll") for (int k = 0; k < 2; ++k) dst[m][k] = *(const LAS bf16x8*)(lds + PG8_SA(b, h) + aoff + m * 2048 + k * 1024); } while (0)
; #define PG8_LDB(dst, b, h) do { _Pragma("unroll") for (int n = 0; n < 2; ++n) _Pragma("unroll") for (int k = 0; k < 2; ++k) dst[n][k] = *(const LAS bf16x8*)(lds + PG8_SB(b, h) + boff + n * 2048 + k * 1024); } while (0)
; #define PG8_MMA(ai, bj, At, Bt) do { __builtin_amdgcn_s_setprio(1); _Pragma("unroll") for (int m = 0; m < 4; ++m) _Pragma("unroll") for (int n = 0; n < 2; ++n) _Pragma("unroll") for (int k = 0; k < 2; ++k) \
;     acc[ai][bj][m][n] = __builtin_amdgcn_mfma_f32_16x16x32_bf16(Bt[n][k], At[m][k], acc[ai][bj][m][n], 0, 0, 0); __builtin_amdgcn_s_setprio(0); } while (0)
; #define PG8_WAIT_V(n) asm volatile("s_waitcnt vmcnt(" #n ")" ::: "memory")
; #define PG8_WAIT_L(n) asm volatile("s_waitcnt lgkmcnt(" #n ")" ::: "memory")
; #define PG8_BAR __builtin_amdgcn_s_barrier()
; #define PG8_SCHED __builtin_amdgcn_sched_barrier(0)
; template <class Epi, class Sched = StaticOrder>
; DI void gemm_phase(LAS unsigned char* lds, const Gemm g, const Sched& S, const Epi& E) {
;     ...
;       PG8_LDB(B1, 0, 1); PG8_STAGE(PG8_SB(0, 0), b2, voffB);
;       PG8_BAR; PG8_WAIT_L(0); PG8_MMA(0, 1, At, B1); PG8_BAR;
;       PG8_LDA(At, 0, 1); PG8_STAGE(PG8_SA(0, 0), a2, voffA);
;       PG8_BAR; PG8_WAIT_L(0); PG8_MMA(1, 0, At, B0); PG8_BAR; PG8_SCHED;
;       PG8_STAGE(PG8_SB(0, 1), b2 + hstep, voffB);
;       PG8_WAIT_V(6); PG8_BAR; PG8_MMA(1, 1, At, B1); PG8_BAR;
;       PG8_LDB(B0, 1, 0); PG8_SCHED; PG8_LDA(At, 1, 0); PG8_STAGE(PG8_SA(0, 1), a2 + hstep, voffA);
;       PG8_WAIT_L(8); PG8_BAR; PG8_WAIT_L(0); PG8_MMA(0, 0, At, B0); PG8_BAR; PG8_SCHED;
	s_setprio 0
	s_add_i32 s53, s65, s41
	s_add_u32 s98, s8, 0x80
	s_addc_u32 s99, s9, 0
	s_mov_b32 m0, s53
	ds_read_b128 v[202:205], v175
	ds_read_b128 v[206:209], v175 offset:1024
	ds_read_b128 v[212:215], v175 offset:2048
	ds_read_b128 v[216:219], v175 offset:3072
	global_load_lds_dwordx4 v140, s[8:9]
	s_add_i32 m0, s53, 0x2000
	s_nop 0
	global_load_lds_dwordx4 v136, s[8:9]
	s_waitcnt lgkmcnt(0)
	s_setprio 1
	s_barrier
	v_mfma_f32_16x16x32_bf16 v[116:119], v[202:205], v[162:165], v[116:119]
	v_mfma_f32_16x16x32_bf16 v[112:115], v[212:215], v[162:165], v[112:115]
	v_mfma_f32_16x16x32_bf16 v[96:99], v[202:205], v[178:181], v[96:99]
	v_mfma_f32_16x16x32_bf16 v[88:91], v[212:215], v[178:181], v[88:91]
	v_mfma_f32_16x16x32_bf16 v[80:83], v[202:205], v[186:189], v[80:83]
	v_mfma_f32_16x16x32_bf16 v[72:75], v[212:215], v[186:189], v[72:75]
	v_mfma_f32_16x16x32_bf16 v[68:71], v[202:205], v[194:197], v[68:71]
	v_mfma_f32_16x16x32_bf16 v[64:67], v[212:215], v[194:197], v[64:67]
	v_mfma_f32_16x16x32_bf16 v[116:119], v[206:209], v[166:169], v[116:119]
	ds_read_b128 v[162:165], v174 offset:16384
	v_mfma_f32_16x16x32_bf16 v[112:115], v[216:219], v[166:169], v[112:115]
	ds_read_b128 v[178:181], v174 offset:18432
	v_mfma_f32_16x16x32_bf16 v[96:99], v[206:209], v[182:185], v[96:99]
	ds_read_b128 v[186:189], v174 offset:20480
	v_mfma_f32_16x16x32_bf16 v[88:91], v[216:219], v[182:185], v[88:91]
	ds_read_b128 v[194:197], v174 offset:22528
	v_mfma_f32_16x16x32_bf16 v[80:83], v[206:209], v[190:193], v[80:83]
	v_mfma_f32_16x16x32_bf16 v[72:75], v[216:219], v[190:193], v[72:75]
	v_mfma_f32_16x16x32_bf16 v[68:71], v[206:209], v[198:201], v[68:71]
	v_mfma_f32_16x16x32_bf16 v[64:67], v[216:219], v[198:201], v[64:67]
	s_barrier
	s_setprio 0
	s_mov_b32 m0, s48
	s_add_u32 s100, s10, 0x80
	s_addc_u32 s101, s11, 0
	ds_read_b128 v[166:169], v174 offset:17408
	ds_read_b128 v[182:185], v174 offset:19456
	ds_read_b128 v[190:193], v174 offset:21504
	ds_read_b128 v[198:201], v174 offset:23552
	global_load_lds_dwordx4 v142, s[10:11]
	s_mov_b32 m0, s49
	s_nop 0
	global_load_lds_dwordx4 v138, s[10:11]
	s_waitcnt vmcnt(8)
	s_waitcnt lgkmcnt(0)
	s_setprio 1
	s_barrier
	v_mfma_f32_16x16x32_bf16 v[60:63], v[128:131], v[162:165], v[60:63]
	v_mfma_f32_16x16x32_bf16 v[56:59], v[154:157], v[162:165], v[56:59]
	v_mfma_f32_16x16x32_bf16 v[52:55], v[128:131], v[178:181], v[52:55]
	v_mfma_f32_16x16x32_bf16 v[44:47], v[154:157], v[178:181], v[44:47]
	v_mfma_f32_16x16x32_bf16 v[36:39], v[128:131], v[186:189], v[36:39]
	v_mfma_f32_16x16x32_bf16 v[28:31], v[154:157], v[186:189], v[28:31]
	v_mfma_f32_16x16x32_bf16 v[20:23], v[128:131], v[194:197], v[20:23]
	v_mfma_f32_16x16x32_bf16 v[12:15], v[154:157], v[194:197], v[12:15]
	v_mfma_f32_16x16x32_bf16 v[60:63], v[132:135], v[166:169], v[60:63]
	v_mfma_f32_16x16x32_bf16 v[56:59], v[158:161], v[166:169], v[56:59]
	v_mfma_f32_16x16x32_bf16 v[52:55], v[132:135], v[182:185], v[52:55]
	v_mfma_f32_16x16x32_bf16 v[44:47], v[158:161], v[182:185], v[44:47]
	v_mfma_f32_16x16x32_bf16 v[36:39], v[132:135], v[190:193], v[36:39]
	v_mfma_f32_16x16x32_bf16 v[28:31], v[158:161], v[190:193], v[28:31]
	v_mfma_f32_16x16x32_bf16 v[20:23], v[132:135], v[198:201], v[20:23]
	v_mfma_f32_16x16x32_bf16 v[12:15], v[158:161], v[198:201], v[12:15]
	s_barrier
	s_setprio 0
	s_add_u32 s54, s8, 0x80000
	s_addc_u32 s55, s9, 0
	s_add_i32 s53, s72, s41
	s_mov_b32 m0, s53
	s_nop 0
	global_load_lds_dwordx4 v140, s[54:55]
	s_add_i32 m0, s53, 0x2000
	s_nop 0
	global_load_lds_dwordx4 v136, s[54:55]
	s_add_i32 s53, 0, 0x18000
	v_add_u32_e32 v158, s53, v171
	ds_read_b128 v[128:131], v158
	ds_read_b128 v[132:135], v158 offset:1024
	ds_read_b128 v[154:157], v158 offset:2048
	ds_read_b128 v[158:161], v158 offset:3072
	s_waitcnt vmcnt(6)
	s_setprio 1
	s_barrier
	v_mfma_f32_16x16x32_bf16 v[48:51], v[202:205], v[162:165], v[48:51]
	v_mfma_f32_16x16x32_bf16 v[40:43], v[212:215], v[162:165], v[40:43]
	v_mfma_f32_16x16x32_bf16 v[32:35], v[202:205], v[178:181], v[32:35]
	v_mfma_f32_16x16x32_bf16 v[24:27], v[212:215], v[178:181], v[24:27]
	v_mfma_f32_16x16x32_bf16 v[16:19], v[202:205], v[186:189], v[16:19]
	v_mfma_f32_16x16x32_bf16 v[8:11], v[212:215], v[186:189], v[8:11]
	v_mfma_f32_16x16x32_bf16 v[4:7], v[202:205], v[194:197], v[4:7]
	v_mfma_f32_16x16x32_bf16 v[0:3], v[212:215], v[194:197], v[0:3]
	v_mfma_f32_16x16x32_bf16 v[48:51], v[206:209], v[166:169], v[48:51]
	ds_read_b128 v[162:165], v174 offset:32768
	v_mfma_f32_16x16x32_bf16 v[40:43], v[216:219], v[166:169], v[40:43]
	ds_read_b128 v[178:181], v174 offset:34816
	v_mfma_f32_16x16x32_bf16 v[32:35], v[206:209], v[182:185], v[32:35]
	ds_read_b128 v[186:189], v174 offset:36864
	v_mfma_f32_16x16x32_bf16 v[24:27], v[216:219], v[182:185], v[24:27]
	ds_read_b128 v[194:197], v174 offset:38912
	v_mfma_f32_16x16x32_bf16 v[16:19], v[206:209], v[190:193], v[16:19]
	v_mfma_f32_16x16x32_bf16 v[8:11], v[216:219], v[190:193], v[8:11]
	v_mfma_f32_16x16x32_bf16 v[4:7], v[206:209], v[198:201], v[4:7]
	v_mfma_f32_16x16x32_bf16 v[0:3], v[216:219], v[198:201], v[0:3]
	s_barrier
	s_setprio 0
	s_add_u32 s10, s10, 0x80000
	s_addc_u32 s11, s11, 0
	s_mov_b32 m0, s50
	ds_read_b128 v[166:169], v174 offset:33792
	ds_read_b128 v[182:185], v174 offset:35840
	ds_read_b128 v[190:193], v174 offset:37888
	ds_read_b128 v[198:201], v174 offset:39936
	global_load_lds_dwordx4 v142, s[10:11]
	s_mov_b32 m0, s51
	s_nop 0
	global_load_lds_dwordx4 v138, s[10:11]
	s_waitcnt lgkmcnt(0)
	s_waitcnt vmcnt(8)
	s_setprio 1
	s_barrier
; #define PG8_STAGE(bufoff, gbase, voff) do { _Pragma("unroll") for (int _i = 0; _i < 2; ++_i) \
;     __builtin_amdgcn_global_load_lds((const unsigned*)((const char*)(gbase) + (voff)[_i]), (LAS unsigned*)(lds + (bufoff) + ldsw + _i * 8192), 16, 0, 0); } while (0)
; #define PG8_LDA(dst, b, h) do { _Pragma("unroll") for (int m = 0; m < 4; ++m) _Pragma("unroll") for (int k = 0; k < 2; ++k) dst[m][k] = *(const LAS bf16x8*)(lds + PG8_SA(b, h) + aoff + m * 2048 + k * 1024); } while (0)
; #define PG8_LDB(dst, b, h) do { _Pragma("unroll") for (int n = 0; n < 2; ++n) _Pragma("unroll") for (int k = 0; k < 2; ++k) dst[n][k] = *(const LAS bf16x8*)(lds + PG8_SB(b, h) + boff + n * 2048 + k * 1024); } while (0)
; #define PG8_MMA(ai, bj, At, Bt) do { __builtin_amdgcn_s_setprio(1); _Pragma("unroll") for (int m = 0; m < 4; ++m) _Pragma("unroll") for (int n = 0; n < 2; ++n) _Pragma("unroll") for (int k = 0; k < 2; ++k) \
;     acc[ai][bj][m][n] = __builtin_amdgcn_mfma_f32_16x16x32_bf16(Bt[n][k], At[m][k], acc[ai][bj][m][n], 0, 0, 0); __builtin_amdgcn_s_setprio(0); } while (0)
; #define PG8_WAIT_V(n) asm volatile("s_waitcnt vmcnt(" #n ")" ::: "memory")
; #define PG8_WAIT_L(n) asm volatile("s_waitcnt lgkmcnt(" #n ")" ::: "memory")
; #define PG8_BAR __builtin_amdgcn_s_barrier()
; #define PG8_SCHED __builtin_amdgcn_sched_barrier(0)
; template <class Epi, class Sched = StaticOrder>
; DI void gemm_phase(LAS unsigned char* lds, const Gemm g, const Sched& S, const Epi& E) {
;     ...
;       PG8_WAIT_L(8); PG8_BAR; PG8_WAIT_L(0); PG8_MMA(0, 0, At, B0); PG8_BAR; PG8_SCHED;
;       PG8_LDB(B1, 1, 1); PG8_STAGE(PG8_SB(1, 0), b3, voffB);
;       PG8_BAR; PG8_WAIT_L(0); PG8_MMA(0, 1, At, B1); PG8_BAR;
;       PG8_LDA(At, 1, 1); PG8_STAGE(PG8_SA(1, 0), a3, voffA);
;       PG8_BAR; PG8_WAIT_L(0); PG8_MMA(1, 0, At, B0); PG8_BAR; PG8_SCHED;
;       PG8_STAGE(PG8_SB(1, 1), b3 + hstep, voffB);
;       PG8_WAIT_V(6); PG8_BAR; PG8_MMA(1, 1, At, B1); PG8_BAR;
	v_mfma_f32_16x16x32_bf16 v[124:127], v[128:131], v[162:165], v[124:127]
	v_mfma_f32_16x16x32_bf16 v[120:123], v[154:157], v[162:165], v[120:123]
	v_mfma_f32_16x16x32_bf16 v[108:111], v[128:131], v[178:181], v[108:111]
	v_mfma_f32_16x16x32_bf16 v[104:107], v[154:157], v[178:181], v[104:107]
	v_mfma_f32_16x16x32_bf16 v[100:103], v[128:131], v[186:189], v[100:103]
	v_mfma_f32_16x16x32_bf16 v[92:95], v[154:157], v[186:189], v[92:95]
	v_mfma_f32_16x16x32_bf16 v[84:87], v[128:131], v[194:197], v[84:87]
	v_mfma_f32_16x16x32_bf16 v[76:79], v[154:157], v[194:197], v[76:79]
	v_mfma_f32_16x16x32_bf16 v[124:127], v[132:135], v[166:169], v[124:127]
	v_mfma_f32_16x16x32_bf16 v[120:123], v[158:161], v[166:169], v[120:123]
	v_mfma_f32_16x16x32_bf16 v[108:111], v[132:135], v[182:185], v[108:111]
	v_mfma_f32_16x16x32_bf16 v[104:107], v[158:161], v[182:185], v[104:107]
	v_mfma_f32_16x16x32_bf16 v[100:103], v[132:135], v[190:193], v[100:103]
	v_mfma_f32_16x16x32_bf16 v[92:95], v[158:161], v[190:193], v[92:95]
	v_mfma_f32_16x16x32_bf16 v[84:87], v[132:135], v[198:201], v[84:87]
	v_mfma_f32_16x16x32_bf16 v[76:79], v[158:161], v[198:201], v[76:79]
	s_barrier
	s_setprio 0
	s_add_i32 s10, 0, 0x1c000
	s_add_i32 s11, s53, s41
	v_add_u32_e32 v177, s10, v171
	s_mov_b32 m0, s11
	ds_read_b128 v[202:205], v177
	ds_read_b128 v[206:209], v177 offset:1024
	ds_read_b128 v[212:215], v177 offset:2048
	ds_read_b128 v[216:219], v177 offset:3072
	global_load_lds_dwordx4 v140, s[98:99]
	s_add_i32 m0, s11, 0x2000
	s_nop 0
	global_load_lds_dwordx4 v136, s[98:99]
	s_waitcnt lgkmcnt(0)
	s_setprio 1
	s_barrier
	v_mfma_f32_16x16x32_bf16 v[116:119], v[202:205], v[162:165], v[116:119]
	v_mfma_f32_16x16x32_bf16 v[112:115], v[212:215], v[162:165], v[112:115]
	v_mfma_f32_16x16x32_bf16 v[96:99], v[202:205], v[178:181], v[96:99]
	v_mfma_f32_16x16x32_bf16 v[88:91], v[212:215], v[178:181], v[88:91]
	v_mfma_f32_16x16x32_bf16 v[80:83], v[202:205], v[186:189], v[80:83]
	v_mfma_f32_16x16x32_bf16 v[72:75], v[212:215], v[186:189], v[72:75]
	v_mfma_f32_16x16x32_bf16 v[68:71], v[202:205], v[194:197], v[68:71]
	v_mfma_f32_16x16x32_bf16 v[64:67], v[212:215], v[194:197], v[64:67]
	v_mfma_f32_16x16x32_bf16 v[116:119], v[206:209], v[166:169], v[116:119]
	ds_read_b128 v[162:165], v174 offset:49152
	v_mfma_f32_16x16x32_bf16 v[112:115], v[216:219], v[166:169], v[112:115]
	ds_read_b128 v[178:181], v174 offset:51200
	v_mfma_f32_16x16x32_bf16 v[96:99], v[206:209], v[182:185], v[96:99]
	ds_read_b128 v[186:189], v174 offset:53248
	v_mfma_f32_16x16x32_bf16 v[88:91], v[216:219], v[182:185], v[88:91]
	ds_read_b128 v[194:197], v174 offset:55296
	v_mfma_f32_16x16x32_bf16 v[80:83], v[206:209], v[190:193], v[80:83]
	v_mfma_f32_16x16x32_bf16 v[72:75], v[216:219], v[190:193], v[72:75]
	v_mfma_f32_16x16x32_bf16 v[68:71], v[206:209], v[198:201], v[68:71]
	v_mfma_f32_16x16x32_bf16 v[64:67], v[216:219], v[198:201], v[64:67]
	s_barrier
	s_setprio 0
	s_mov_b32 m0, s56
	ds_read_b128 v[166:169], v174 offset:50176
	ds_read_b128 v[182:185], v174 offset:52224
	ds_read_b128 v[190:193], v174 offset:54272
	ds_read_b128 v[198:201], v174 offset:56320
	global_load_lds_dwordx4 v142, s[100:101]
	s_mov_b32 m0, s57
	s_nop 0
	global_load_lds_dwordx4 v138, s[100:101]
	s_waitcnt vmcnt(8)
	s_waitcnt lgkmcnt(0)
	s_setprio 1
	s_barrier
	v_mfma_f32_16x16x32_bf16 v[60:63], v[128:131], v[162:165], v[60:63]
	v_mfma_f32_16x16x32_bf16 v[56:59], v[154:157], v[162:165], v[56:59]
	v_mfma_f32_16x16x32_bf16 v[52:55], v[128:131], v[178:181], v[52:55]
	v_mfma_f32_16x16x32_bf16 v[44:47], v[154:157], v[178:181], v[44:47]
	v_mfma_f32_16x16x32_bf16 v[36:39], v[128:131], v[186:189], v[36:39]
	v_mfma_f32_16x16x32_bf16 v[28:31], v[154:157], v[186:189], v[28:31]
	v_mfma_f32_16x16x32_bf16 v[20:23], v[128:131], v[194:197], v[20:23]
	v_mfma_f32_16x16x32_bf16 v[12:15], v[154:157], v[194:197], v[12:15]
	v_mfma_f32_16x16x32_bf16 v[60:63], v[132:135], v[166:169], v[60:63]
	v_mfma_f32_16x16x32_bf16 v[56:59], v[158:161], v[166:169], v[56:59]
	v_mfma_f32_16x16x32_bf16 v[52:55], v[132:135], v[182:185], v[52:55]
	v_mfma_f32_16x16x32_bf16 v[44:47], v[158:161], v[182:185], v[44:47]
	v_mfma_f32_16x16x32_bf16 v[36:39], v[132:135], v[190:193], v[36:39]
	v_mfma_f32_16x16x32_bf16 v[28:31], v[158:161], v[190:193], v[28:31]
	v_mfma_f32_16x16x32_bf16 v[20:23], v[132:135], v[198:201], v[20:23]
	v_mfma_f32_16x16x32_bf16 v[12:15], v[158:161], v[198:201], v[12:15]
	s_barrier
	s_setprio 0
	s_add_u32 s8, s8, 0x80080
	s_addc_u32 s9, s9, 0
	s_add_i32 s10, s10, s41
	s_mov_b32 m0, s10
	s_nop 0
	global_load_lds_dwordx4 v140, s[8:9]
	s_add_i32 m0, s10, 0x2000
	s_nop 0
	global_load_lds_dwordx4 v136, s[8:9]
	ds_read_b128 v[128:131], v173
	ds_read_b128 v[132:135], v173 offset:1024
	ds_read_b128 v[154:157], v173 offset:2048
	ds_read_b128 v[158:161], v173 offset:3072
	s_waitcnt vmcnt(6)
	s_add_i32 s52, s52, 2
	s_add_u32 s6, s6, 0x100
	s_addc_u32 s7, s7, 0
	s_add_u32 s44, s44, 0x100
	s_addc_u32 s45, s45, 0
	s_cmp_gt_u32 s52, 29
	s_setprio 1
	s_barrier
	v_mfma_f32_16x16x32_bf16 v[48:51], v[202:205], v[162:165], v[48:51]
	v_mfma_f32_16x16x32_bf16 v[40:43], v[212:215], v[162:165], v[40:43]
	v_mfma_f32_16x16x32_bf16 v[32:35], v[202:205], v[178:181], v[32:35]
	v_mfma_f32_16x16x32_bf16 v[24:27], v[212:215], v[178:181], v[24:27]
	v_mfma_f32_16x16x32_bf16 v[16:19], v[202:205], v[186:189], v[16:19]
	v_mfma_f32_16x16x32_bf16 v[8:11], v[212:215], v[186:189], v[8:11]
	v_mfma_f32_16x16x32_bf16 v[4:7], v[202:205], v[194:197], v[4:7]
	v_mfma_f32_16x16x32_bf16 v[0:3], v[212:215], v[194:197], v[0:3]
	v_mfma_f32_16x16x32_bf16 v[48:51], v[206:209], v[166:169], v[48:51]
	ds_read_b128 v[162:165], v174
	v_mfma_f32_16x16x32_bf16 v[40:43], v[216:219], v[166:169], v[40:43]
	ds_read_b128 v[178:181], v174 offset:2048
	v_mfma_f32_16x16x32_bf16 v[32:35], v[206:209], v[182:185], v[32:35]
	ds_read_b128 v[186:189], v174 offset:4096
	v_mfma_f32_16x16x32_bf16 v[24:27], v[216:219], v[182:185], v[24:27]
	ds_read_b128 v[194:197], v174 offset:6144
	v_mfma_f32_16x16x32_bf16 v[16:19], v[206:209], v[190:193], v[16:19]
	v_mfma_f32_16x16x32_bf16 v[8:11], v[216:219], v[190:193], v[8:11]
	v_mfma_f32_16x16x32_bf16 v[4:7], v[206:209], v[198:201], v[4:7]
	v_mfma_f32_16x16x32_bf16 v[0:3], v[216:219], v[198:201], v[0:3]
	s_barrier
; DI unsigned pack2(float lo, float hi) { f32x2 v = {lo, hi}; bf16v2 r = __builtin_convertvector(v, bf16v2); return __builtin_bit_cast(unsigned, r); }
; DI float row_rstd(const float* ssq, int row, int fq) {
;   const f32x4 a = *(const f32x4*)(ssq + (size_t)row * 32 + fq * 8), b = *(const f32x4*)(ssq + (size_t)row * 32 + fq * 8 + 4);
;   float sm = ((a[0] + a[1]) + (a[2] + a[3])) + ((b[0] + b[1]) + (b[2] + b[3]));
;   sm += __shfl_xor(sm, 16); sm += __shfl_xor(sm, 32);
;   return rsqrtf(sm * (1.0f / 2048.f) + 1e-6f);
; }
;   DI void operator()(const f32x4 (&acc)[2][2][4][2], const Unit& u, int wr, int wc, int fr, int fq) const {
;     const int row0 = u.pm * BM + wr * 64 + fr, col0 = u.pn * BM + wc * 32 + 8 * fq;
;     float rsv[2][4];
; #pragma unroll
;     for (int ai = 0; ai < 2; ++ai)
; #pragma unroll
;       for (int m = 0; m < 4; ++m) rsv[ai][m] = row_rstd(ssq, row0 + ai * HALF + m * 16, fq);
; #pragma unroll
;     for (int ai = 0; ai < 2; ++ai)
; #pragma unroll
;       for (int m = 0; m < 4; ++m) {
;         const int row = row0 + ai * HALF + m * 16;
;         const float rs = rsv[ai][m];
;         bf16_t* rowp = O + (size_t)row * ldc + col0;
; #pragma unroll
;         for (int bj = 0; bj < 2; ++bj) {
;           const f32x4 v0 = acc[ai][bj][m][0] * rs, v1 = acc[ai][bj][m][1] * rs;
;           u32x4 w; w.x = pack2(v0[0], v0[1]); w.y = pack2(v0[2], v0[3]); w.z = pack2(v1[0], v1[1]); w.w = pack2(v1[2], v1[3]);
;           *(u32x4*)(rowp + bj * HALF) = w;
;         }
;       }
;   }
	s_setprio 0
	s_cbranch_scc0 .LBB0_346
	s_waitcnt lgkmcnt(0)
	v_lshl_add_u32 v168, s4, 8, v170
	v_ashrrev_i32_e32 v169, 31, v168
	v_or_b32_e32 v154, 16, v168
	v_lshlrev_b64 v[128:129], 7, v[168:169]
	v_ashrrev_i32_e32 v155, 31, v154
	v_lshl_add_u64 v[128:129], v[144:145], 0, v[128:129]
	v_lshlrev_b64 v[156:157], 7, v[154:155]
	global_load_dwordx4 v[132:135], v[128:129], off
	s_nop 0
	global_load_dwordx4 v[128:131], v[128:129], off offset:16
	v_lshl_add_u64 v[156:157], v[144:145], 0, v[156:157]
	global_load_dwordx4 v[178:181], v[156:157], off
	global_load_dwordx4 v[182:185], v[156:157], off offset:16
	v_or_b32_e32 v160, 32, v168
	v_ashrrev_i32_e32 v161, 31, v160
	v_lshlrev_b64 v[156:157], 7, v[160:161]
	v_lshl_add_u64 v[156:157], v[144:145], 0, v[156:157]
	global_load_dwordx4 v[186:189], v[156:157], off
	global_load_dwordx4 v[190:193], v[156:157], off offset:16
	v_or_b32_e32 v156, 48, v168
	v_ashrrev_i32_e32 v157, 31, v156
	v_lshlrev_b64 v[158:159], 7, v[156:157]
	v_lshl_add_u64 v[158:159], v[144:145], 0, v[158:159]
	global_load_dwordx4 v[194:197], v[158:159], off
	global_load_dwordx4 v[198:201], v[158:159], off offset:16
	v_add_u32_e32 v164, 0x80, v168
	v_ashrrev_i32_e32 v165, 31, v164
	v_lshlrev_b64 v[158:159], 7, v[164:165]
	v_lshl_add_u64 v[158:159], v[144:145], 0, v[158:159]
	global_load_dwordx4 v[202:205], v[158:159], off
	global_load_dwordx4 v[206:209], v[158:159], off offset:16
	v_add_u32_e32 v158, 0x90, v168
	v_ashrrev_i32_e32 v159, 31, v158
	v_lshlrev_b64 v[162:163], 7, v[158:159]
	v_lshl_add_u64 v[162:163], v[144:145], 0, v[162:163]
	global_load_dwordx4 v[212:215], v[162:163], off
	global_load_dwordx4 v[216:219], v[162:163], off offset:16
	v_add_u32_e32 v166, 0xa0, v168
	v_ashrrev_i32_e32 v167, 31, v166
	v_lshlrev_b64 v[162:163], 7, v[166:167]
	v_lshl_add_u64 v[162:163], v[144:145], 0, v[162:163]
	global_load_dwordx4 v[220:223], v[162:163], off
	global_load_dwordx4 v[224:227], v[162:163], off offset:16
	v_add_u32_e32 v162, 0xb0, v168
	v_ashrrev_i32_e32 v163, 31, v162
	v_lshlrev_b64 v[228:229], 7, v[162:163]
	v_lshl_add_u64 v[232:233], v[144:145], 0, v[228:229]
	global_load_dwordx4 v[228:231], v[232:233], off
	s_nop 0
	global_load_dwordx4 v[232:235], v[232:233], off offset:16
	s_waitcnt vmcnt(0)
	v_mov_b32_e32 v236, v132
	v_mov_b32_e32 v237, v128
	v_mov_b32_e32 v128, v133
	v_mov_b32_e32 v132, v134
	v_mov_b32_e32 v133, v130
	v_mov_b32_e32 v130, v135
	v_pk_add_f32 v[130:131], v[132:133], v[130:131]
	v_mov_b32_e32 v132, v178
	v_mov_b32_e32 v133, v182
	v_mov_b32_e32 v182, v179
	v_mov_b32_e32 v134, v180
	v_mov_b32_e32 v135, v184
	v_mov_b32_e32 v184, v181
	v_pk_add_f32 v[128:129], v[236:237], v[128:129]
	v_pk_add_f32 v[132:133], v[132:133], v[182:183]
	v_pk_add_f32 v[134:135], v[134:135], v[184:185]
	v_pk_add_f32 v[128:129], v[128:129], v[130:131]
	v_pk_add_f32 v[130:131], v[132:133], v[134:135]
	v_mov_b32_e32 v133, v128
	v_mov_b32_e32 v132, v130
	v_and_b32_e32 v130, 64, v176
	v_add_u32_e32 v155, 64, v130
	v_xor_b32_e32 v130, 16, v176
	v_cmp_lt_i32_e32 vcc, v130, v155
	v_mov_b32_e32 v128, v131
	v_pk_add_f32 v[128:129], v[132:133], v[128:129]
	v_cndmask_b32_e32 v130, v176, v130, vcc
	v_lshlrev_b32_e32 v157, 2, v130
	ds_bpermute_b32 v131, v157, v129
	ds_bpermute_b32 v130, v157, v128
	v_mov_b32_e32 v178, v186
	v_mov_b32_e32 v179, v190
	v_mov_b32_e32 v190, v187
	v_mov_b32_e32 v186, v194
	s_waitcnt lgkmcnt(0)
	v_pk_add_f32 v[128:129], v[128:129], v[130:131]
	v_xor_b32_e32 v130, 32, v176
	v_cmp_lt_i32_e32 vcc, v130, v155
	v_mov_b32_e32 v187, v198
	v_mov_b32_e32 v198, v195
	v_cndmask_b32_e32 v130, v176, v130, vcc
	v_lshlrev_b32_e32 v155, 2, v130
	ds_bpermute_b32 v131, v155, v129
	ds_bpermute_b32 v130, v155, v128
	v_pk_add_f32 v[182:183], v[186:187], v[198:199]
	v_mov_b32_e32 v180, v188
	v_mov_b32_e32 v181, v192
	v_mov_b32_e32 v192, v189
	s_waitcnt lgkmcnt(0)
	v_pk_add_f32 v[128:129], v[128:129], v[130:131]
	v_mov_b64_e32 v[130:131], s[26:27]
	v_pk_fma_f32 v[128:129], v[128:129], s[24:25], v[130:131] op_sel_hi:[1,0,0]
	v_mov_b32_e32 v188, v196
	v_mul_f32_e32 v159, 0x4b800000, v129
	v_cmp_gt_f32_e32 vcc, s73, v129
	v_mov_b32_e32 v189, v200
	v_mov_b32_e32 v200, v197
	v_cndmask_b32_e32 v129, v129, v159, vcc
	v_rsq_f32_e32 v129, v129
	v_pk_add_f32 v[178:179], v[178:179], v[190:191]
	v_pk_add_f32 v[180:181], v[180:181], v[192:193]
	v_pk_add_f32 v[184:185], v[188:189], v[200:201]
	v_mul_f32_e32 v159, 0x45800000, v129
	v_cndmask_b32_e32 v198, v129, v159, vcc
	v_pk_mul_f32 v[126:127], v[126:127], v[198:199] op_sel_hi:[1,0]
	v_pk_mul_f32 v[124:125], v[124:125], v[198:199] op_sel_hi:[1,0]
	v_pk_mul_f32 v[122:123], v[122:123], v[198:199] op_sel_hi:[1,0]
	v_pk_mul_f32 v[120:121], v[120:121], v[198:199] op_sel_hi:[1,0]
	v_cvt_pk_bf16_f32 v124, v124, v125
	v_cvt_pk_bf16_f32 v125, v126, v127
	v_cvt_pk_bf16_f32 v127, v122, v123
	v_lshl_or_b32 v122, s5, 8, v172
	v_cvt_pk_bf16_f32 v126, v120, v121
	v_ashrrev_i32_e32 v123, 31, v122
	v_mov_b64_e32 v[120:121], s[2:3]
	v_mad_i64_i32 v[168:169], s[4:5], v168, s76, v[120:121]
	v_lshlrev_b64 v[122:123], 1, v[122:123]
	v_lshl_add_u64 v[168:169], v[168:169], 0, v[122:123]
	global_store_dwordx4 v[168:169], v[124:127], off
	v_mov_b32_e32 v194, v202
	v_mov_b32_e32 v195, v206
	v_pk_add_f32 v[124:125], v[178:179], v[180:181]
	v_pk_add_f32 v[126:127], v[182:183], v[184:185]
	v_mov_b32_e32 v179, v124
	v_mov_b32_e32 v178, v126
	v_mov_b32_e32 v124, v127
	v_pk_add_f32 v[124:125], v[178:179], v[124:125]
	ds_bpermute_b32 v127, v157, v125
	ds_bpermute_b32 v126, v157, v124
	v_mov_b32_e32 v206, v203
	v_mov_b32_e32 v196, v204
	v_mov_b32_e32 v197, v208
	v_mov_b32_e32 v208, v205
	v_mov_b32_e32 v202, v212
	v_mov_b32_e32 v203, v216
	v_mov_b32_e32 v216, v213
	v_mov_b32_e32 v204, v214
	v_mov_b32_e32 v205, v218
	v_mov_b32_e32 v218, v215
	v_pk_add_f32 v[186:187], v[194:195], v[206:207]
	v_pk_add_f32 v[188:189], v[196:197], v[208:209]
	v_pk_add_f32 v[190:191], v[202:203], v[216:217]
	v_pk_add_f32 v[192:193], v[204:205], v[218:219]
	v_pk_mul_f32 v[178:179], v[114:115], v[198:199] op_sel_hi:[1,0]
	s_waitcnt lgkmcnt(0)
; DI unsigned pack2(float lo, float hi) { f32x2 v = {lo, hi}; bf16v2 r = __builtin_convertvector(v, bf16v2); return __builtin_bit_cast(unsigned, r); }
; DI float row_rstd(const float* ssq, int row, int fq) {
;   const f32x4 a = *(const f32x4*)(ssq + (size_t)row * 32 + fq * 8), b = *(const f32x4*)(ssq + (size_t)row * 32 + fq * 8 + 4);
;   float sm = ((a[0] + a[1]) + (a[2] + a[3])) + ((b[0] + b[1]) + (b[2] + b[3]));
;   sm += __shfl_xor(sm, 16); sm += __shfl_xor(sm, 32);
;   return rsqrtf(sm * (1.0f / 2048.f) + 1e-6f);
; }
;   DI void operator()(const f32x4 (&acc)[2][2][4][2], const Unit& u, int wr, int wc, int fr, int fq) const {
;     const int row0 = u.pm * BM + wr * 64 + fr, col0 = u.pn * BM + wc * 32 + 8 * fq;
;     float rsv[2][4];
; #pragma unroll
;     for (int ai = 0; ai < 2; ++ai)
; #pragma unroll
;       for (int m = 0; m < 4; ++m) rsv[ai][m] = row_rstd(ssq, row0 + ai * HALF + m * 16, fq);
; #pragma unroll
;     for (int ai = 0; ai < 2; ++ai)
; #pragma unroll
;       for (int m = 0; m < 4; ++m) {
;         const int row = row0 + ai * HALF + m * 16;
;         const float rs = rsv[ai][m];
;         bf16_t* rowp = O + (size_t)row * ldc + col0;
; #pragma unroll
;         for (int bj = 0; bj < 2; ++bj) {
;           const f32x4 v0 = acc[ai][bj][m][0] * rs, v1 = acc[ai][bj][m][1] * rs;
;           u32x4 w; w.x = pack2(v0[0], v0[1]); w.y = pack2(v0[2], v0[3]); w.z = pack2(v1[0], v1[1]); w.w = pack2(v1[2], v1[3]);
;           *(u32x4*)(rowp + bj * HALF) = w;
;         }
;       }
	v_pk_add_f32 v[114:115], v[124:125], v[126:127]
	v_pk_add_f32 v[126:127], v[186:187], v[188:189]
	v_pk_add_f32 v[180:181], v[190:191], v[192:193]
	v_mov_b32_e32 v183, v126
	v_mov_b32_e32 v182, v180
	v_mov_b32_e32 v126, v181
	v_pk_add_f32 v[126:127], v[182:183], v[126:127]
	ds_bpermute_b32 v125, v155, v115
	ds_bpermute_b32 v124, v155, v114
	ds_bpermute_b32 v181, v157, v127
	ds_bpermute_b32 v180, v157, v126
	v_mul_f32_e32 v129, 0x4b800000, v128
	v_cmp_gt_f32_e32 vcc, s73, v128
	s_waitcnt lgkmcnt(2)
	v_pk_add_f32 v[114:115], v[114:115], v[124:125]
	v_mov_b32_e32 v194, v220
	s_waitcnt lgkmcnt(0)
	v_pk_add_f32 v[124:125], v[126:127], v[180:181]
	ds_bpermute_b32 v127, v155, v125
	ds_bpermute_b32 v126, v155, v124
	v_pk_fma_f32 v[114:115], v[114:115], s[24:25], v[130:131] op_sel_hi:[1,0,0]
	v_cndmask_b32_e32 v159, v128, v129, vcc
	v_mul_f32_e32 v128, 0x4b800000, v115
	v_cmp_gt_f32_e64 s[4:5], s73, v115
	v_cmp_gt_f32_e64 s[6:7], s73, v114
	v_mov_b32_e32 v195, v224
	v_cndmask_b32_e64 v161, v115, v128, s[4:5]
	v_mul_f32_e32 v115, 0x4b800000, v114
	v_mov_b32_e32 v224, v221
	v_mov_b32_e32 v196, v222
	v_mov_b32_e32 v197, v226
	v_mov_b32_e32 v226, v223
	v_cndmask_b32_e64 v163, v114, v115, s[6:7]
	s_waitcnt lgkmcnt(0)
	v_pk_add_f32 v[114:115], v[124:125], v[126:127]
	v_pk_add_f32 v[132:133], v[194:195], v[224:225]
	v_pk_add_f32 v[134:135], v[196:197], v[226:227]
	v_mov_b32_e32 v194, v228
	v_mov_b32_e32 v195, v232
	v_mov_b32_e32 v232, v229
	v_mov_b32_e32 v196, v230
	v_mov_b32_e32 v197, v234
	v_mov_b32_e32 v234, v231
	v_pk_fma_f32 v[114:115], v[114:115], s[24:25], v[130:131] op_sel_hi:[1,0,0]
	v_pk_add_f32 v[194:195], v[194:195], v[232:233]
	v_pk_add_f32 v[196:197], v[196:197], v[234:235]
	v_mul_f32_e32 v124, 0x4b800000, v115
	v_cmp_gt_f32_e64 s[8:9], s73, v115
	v_pk_add_f32 v[126:127], v[194:195], v[196:197]
	v_cmp_gt_f32_e64 s[10:11], s73, v114
	v_cndmask_b32_e64 v165, v115, v124, s[8:9]
	v_pk_add_f32 v[124:125], v[132:133], v[134:135]
	v_mov_b32_e32 v128, v126
	v_mov_b32_e32 v129, v124
	v_mov_b32_e32 v124, v127
	v_pk_add_f32 v[124:125], v[128:129], v[124:125]
	ds_bpermute_b32 v127, v157, v125
	ds_bpermute_b32 v126, v157, v124
	v_rsq_f32_e32 v128, v159
	v_mul_f32_e32 v115, 0x4b800000, v114
	v_cndmask_b32_e64 v129, v114, v115, s[10:11]
	v_pk_mul_f32 v[116:117], v[116:117], v[198:199] op_sel_hi:[1,0]
	s_waitcnt lgkmcnt(0)
	v_pk_add_f32 v[114:115], v[124:125], v[126:127]
	ds_bpermute_b32 v125, v155, v115
	ds_bpermute_b32 v124, v155, v114
	v_mul_f32_e32 v126, 0x45800000, v128
	v_rsq_f32_e32 v127, v161
	v_cndmask_b32_e32 v126, v128, v126, vcc
	v_rsq_f32_e32 v128, v163
	s_waitcnt lgkmcnt(0)
	v_pk_add_f32 v[114:115], v[114:115], v[124:125]
	v_mul_f32_e32 v124, 0x45800000, v127
	v_cndmask_b32_e64 v124, v127, v124, s[4:5]
	v_mul_f32_e32 v127, 0x45800000, v128
	v_pk_fma_f32 v[114:115], v[114:115], s[24:25], v[130:131] op_sel_hi:[1,0,0]
	v_rsq_f32_e32 v125, v165
	v_cndmask_b32_e64 v128, v128, v127, s[6:7]
	v_rsq_f32_e32 v127, v129
	v_mul_f32_e32 v129, 0x4b800000, v115
	v_cmp_gt_f32_e32 vcc, s73, v115
	v_cmp_gt_f32_e64 s[4:5], s73, v114
	v_pk_mul_f32 v[118:119], v[118:119], v[198:199] op_sel_hi:[1,0]
	v_cndmask_b32_e32 v129, v115, v129, vcc
	v_mul_f32_e32 v115, 0x4b800000, v114
	v_cndmask_b32_e64 v131, v114, v115, s[4:5]
	v_cvt_pk_bf16_f32 v114, v116, v117
	v_rsq_f32_e32 v117, v129
	v_cvt_pk_bf16_f32 v115, v118, v119
	v_rsq_f32_e32 v119, v131
	v_mul_f32_e32 v116, 0x45800000, v125
	v_pk_mul_f32 v[112:113], v[112:113], v[198:199] op_sel_hi:[1,0]
	v_cndmask_b32_e64 v118, v125, v116, s[8:9]
	v_mul_f32_e32 v116, 0x45800000, v127
	v_cndmask_b32_e64 v130, v127, v116, s[10:11]
	v_cvt_pk_bf16_f32 v116, v112, v113
	v_mul_f32_e32 v112, 0x45800000, v117
	v_cndmask_b32_e32 v132, v117, v112, vcc
	v_mul_f32_e32 v112, 0x45800000, v119
	v_cvt_pk_bf16_f32 v117, v178, v179
	v_cndmask_b32_e64 v112, v119, v112, s[4:5]
	global_store_dwordx4 v[168:169], v[114:117], off offset:256
	v_pk_mul_f32 v[110:111], v[110:111], v[126:127] op_sel_hi:[1,0]
	v_pk_mul_f32 v[108:109], v[108:109], v[126:127] op_sel_hi:[1,0]
	v_mad_i64_i32 v[114:115], s[4:5], v154, s76, v[120:121]
	v_pk_mul_f32 v[116:117], v[106:107], v[126:127] op_sel_hi:[1,0]
	v_pk_mul_f32 v[106:107], v[104:105], v[126:127] op_sel_hi:[1,0]
	v_lshl_add_u64 v[114:115], v[114:115], 0, v[122:123]
	v_cvt_pk_bf16_f32 v104, v108, v109
	v_cvt_pk_bf16_f32 v105, v110, v111
	v_cvt_pk_bf16_f32 v106, v106, v107
	v_cvt_pk_bf16_f32 v107, v116, v117
	global_store_dwordx4 v[114:115], v[104:107], off
	v_pk_mul_f32 v[98:99], v[98:99], v[126:127] op_sel_hi:[1,0]
	v_pk_mul_f32 v[96:97], v[96:97], v[126:127] op_sel_hi:[1,0]
	v_pk_mul_f32 v[104:105], v[90:91], v[126:127] op_sel_hi:[1,0]
	v_pk_mul_f32 v[90:91], v[88:89], v[126:127] op_sel_hi:[1,0]
	v_cvt_pk_bf16_f32 v88, v96, v97
	v_cvt_pk_bf16_f32 v89, v98, v99
	v_cvt_pk_bf16_f32 v90, v90, v91
	v_cvt_pk_bf16_f32 v91, v104, v105
	global_store_dwordx4 v[114:115], v[88:91], off offset:256
	v_pk_mul_f32 v[94:95], v[94:95], v[124:125] op_sel_hi:[1,0]
	v_pk_mul_f32 v[92:93], v[92:93], v[124:125] op_sel_hi:[1,0]
	v_mad_i64_i32 v[88:89], s[4:5], v160, s76, v[120:121]
	v_lshl_add_u64 v[96:97], v[88:89], 0, v[122:123]
	v_pk_mul_f32 v[90:91], v[102:103], v[124:125] op_sel_hi:[1,0]
	v_pk_mul_f32 v[88:89], v[100:101], v[124:125] op_sel_hi:[1,0]
	v_pk_mul_f32 v[82:83], v[82:83], v[124:125] op_sel_hi:[1,0]
	v_cvt_pk_bf16_f32 v88, v88, v89
	v_cvt_pk_bf16_f32 v89, v90, v91
	v_cvt_pk_bf16_f32 v90, v92, v93
; DI unsigned pack2(float lo, float hi) { f32x2 v = {lo, hi}; bf16v2 r = __builtin_convertvector(v, bf16v2); return __builtin_bit_cast(unsigned, r); }
; #define PG8_WAIT_V(n) asm volatile("s_waitcnt vmcnt(" #n ")" ::: "memory")
; #define PG8_BAR __builtin_amdgcn_s_barrier()
;   DI void operator()(const f32x4 (&acc)[2][2][4][2], const Unit& u, int wr, int wc, int fr, int fq) const {
;     ...
;     for (int ai = 0; ai < 2; ++ai)
; #pragma unroll
;       for (int m = 0; m < 4; ++m) {
;         const int row = row0 + ai * HALF + m * 16;
;         const float rs = rsv[ai][m];
;         bf16_t* rowp = O + (size_t)row * ldc + col0;
; #pragma unroll
;         for (int bj = 0; bj < 2; ++bj) {
;           const f32x4 v0 = acc[ai][bj][m][0] * rs, v1 = acc[ai][bj][m][1] * rs;
;           u32x4 w; w.x = pack2(v0[0], v0[1]); w.y = pack2(v0[2], v0[3]); w.z = pack2(v1[0], v1[1]); w.w = pack2(v1[2], v1[3]);
;           *(u32x4*)(rowp + bj * HALF) = w;
;         }
;       }
; template <class Epi, class Sched = StaticOrder>
; DI void gemm_phase(LAS unsigned char* lds, const Gemm g, const Sched& S, const Epi& E) {
;     ...
;   PG8_WAIT_V(0);
;   if (wr == 0) PG8_BAR;
;   PG8_BAR;
	v_cvt_pk_bf16_f32 v91, v94, v95
	global_store_dwordx4 v[96:97], v[88:91], off
	v_pk_mul_f32 v[80:81], v[80:81], v[124:125] op_sel_hi:[1,0]
	v_pk_mul_f32 v[78:79], v[78:79], v[128:129] op_sel_hi:[1,0]
	v_pk_mul_f32 v[88:89], v[74:75], v[124:125] op_sel_hi:[1,0]
	v_pk_mul_f32 v[74:75], v[72:73], v[124:125] op_sel_hi:[1,0]
	v_cvt_pk_bf16_f32 v72, v80, v81
	v_cvt_pk_bf16_f32 v73, v82, v83
	v_cvt_pk_bf16_f32 v74, v74, v75
	v_cvt_pk_bf16_f32 v75, v88, v89
	global_store_dwordx4 v[96:97], v[72:75], off offset:256
	v_pk_mul_f32 v[76:77], v[76:77], v[128:129] op_sel_hi:[1,0]
	v_pk_mul_f32 v[70:71], v[70:71], v[128:129] op_sel_hi:[1,0]
	v_mad_i64_i32 v[72:73], s[4:5], v156, s76, v[120:121]
	v_lshl_add_u64 v[80:81], v[72:73], 0, v[122:123]
	v_pk_mul_f32 v[74:75], v[86:87], v[128:129] op_sel_hi:[1,0]
	v_pk_mul_f32 v[72:73], v[84:85], v[128:129] op_sel_hi:[1,0]
	v_pk_mul_f32 v[68:69], v[68:69], v[128:129] op_sel_hi:[1,0]
	v_cvt_pk_bf16_f32 v72, v72, v73
	v_cvt_pk_bf16_f32 v73, v74, v75
	v_cvt_pk_bf16_f32 v74, v76, v77
	v_cvt_pk_bf16_f32 v75, v78, v79
	global_store_dwordx4 v[80:81], v[72:75], off
	v_pk_mul_f32 v[62:63], v[62:63], v[118:119] op_sel_hi:[1,0]
	v_pk_mul_f32 v[60:61], v[60:61], v[118:119] op_sel_hi:[1,0]
	v_pk_mul_f32 v[72:73], v[66:67], v[128:129] op_sel_hi:[1,0]
	v_pk_mul_f32 v[66:67], v[64:65], v[128:129] op_sel_hi:[1,0]
	v_cvt_pk_bf16_f32 v64, v68, v69
	v_cvt_pk_bf16_f32 v65, v70, v71
	v_cvt_pk_bf16_f32 v66, v66, v67
	v_cvt_pk_bf16_f32 v67, v72, v73
	global_store_dwordx4 v[80:81], v[64:67], off offset:256
	v_pk_mul_f32 v[50:51], v[50:51], v[118:119] op_sel_hi:[1,0]
	v_pk_mul_f32 v[48:49], v[48:49], v[118:119] op_sel_hi:[1,0]
	v_mad_i64_i32 v[64:65], s[4:5], v164, s76, v[120:121]
	v_pk_mul_f32 v[66:67], v[58:59], v[118:119] op_sel_hi:[1,0]
	v_pk_mul_f32 v[58:59], v[56:57], v[118:119] op_sel_hi:[1,0]
	v_lshl_add_u64 v[64:65], v[64:65], 0, v[122:123]
	v_cvt_pk_bf16_f32 v56, v60, v61
	v_cvt_pk_bf16_f32 v57, v62, v63
	v_cvt_pk_bf16_f32 v58, v58, v59
	v_cvt_pk_bf16_f32 v59, v66, v67
	global_store_dwordx4 v[64:65], v[56:59], off
	v_pk_mul_f32 v[46:47], v[46:47], v[130:131] op_sel_hi:[1,0]
	v_pk_mul_f32 v[44:45], v[44:45], v[130:131] op_sel_hi:[1,0]
	v_pk_mul_f32 v[56:57], v[42:43], v[118:119] op_sel_hi:[1,0]
	v_pk_mul_f32 v[42:43], v[40:41], v[118:119] op_sel_hi:[1,0]
	v_cvt_pk_bf16_f32 v40, v48, v49
	v_cvt_pk_bf16_f32 v41, v50, v51
	v_cvt_pk_bf16_f32 v42, v42, v43
	v_cvt_pk_bf16_f32 v43, v56, v57
	global_store_dwordx4 v[64:65], v[40:43], off offset:256
	v_pk_mul_f32 v[34:35], v[34:35], v[130:131] op_sel_hi:[1,0]
	v_pk_mul_f32 v[32:33], v[32:33], v[130:131] op_sel_hi:[1,0]
	v_mad_i64_i32 v[40:41], s[4:5], v158, s76, v[120:121]
	v_lshl_add_u64 v[48:49], v[40:41], 0, v[122:123]
	v_pk_mul_f32 v[42:43], v[54:55], v[130:131] op_sel_hi:[1,0]
	v_pk_mul_f32 v[40:41], v[52:53], v[130:131] op_sel_hi:[1,0]
	v_pk_mul_f32 v[30:31], v[30:31], v[132:133] op_sel_hi:[1,0]
	v_cvt_pk_bf16_f32 v40, v40, v41
	v_cvt_pk_bf16_f32 v41, v42, v43
	v_cvt_pk_bf16_f32 v42, v44, v45
	v_cvt_pk_bf16_f32 v43, v46, v47
	global_store_dwordx4 v[48:49], v[40:43], off
	v_pk_mul_f32 v[28:29], v[28:29], v[132:133] op_sel_hi:[1,0]
	v_pk_mul_f32 v[18:19], v[18:19], v[132:133] op_sel_hi:[1,0]
	v_pk_mul_f32 v[40:41], v[26:27], v[130:131] op_sel_hi:[1,0]
	v_pk_mul_f32 v[26:27], v[24:25], v[130:131] op_sel_hi:[1,0]
	v_cvt_pk_bf16_f32 v24, v32, v33
	v_cvt_pk_bf16_f32 v25, v34, v35
	v_cvt_pk_bf16_f32 v26, v26, v27
	v_cvt_pk_bf16_f32 v27, v40, v41
	global_store_dwordx4 v[48:49], v[24:27], off offset:256
	v_pk_mul_f32 v[16:17], v[16:17], v[132:133] op_sel_hi:[1,0]
	v_pk_mul_f32 v[14:15], v[14:15], v[112:113] op_sel_hi:[1,0]
	v_mad_i64_i32 v[24:25], s[4:5], v166, s76, v[120:121]
	v_lshl_add_u64 v[32:33], v[24:25], 0, v[122:123]
	v_pk_mul_f32 v[26:27], v[38:39], v[132:133] op_sel_hi:[1,0]
	v_pk_mul_f32 v[24:25], v[36:37], v[132:133] op_sel_hi:[1,0]
	v_pk_mul_f32 v[12:13], v[12:13], v[112:113] op_sel_hi:[1,0]
	v_cvt_pk_bf16_f32 v24, v24, v25
	v_cvt_pk_bf16_f32 v25, v26, v27
	v_cvt_pk_bf16_f32 v26, v28, v29
	v_cvt_pk_bf16_f32 v27, v30, v31
	global_store_dwordx4 v[32:33], v[24:27], off
	v_pk_mul_f32 v[6:7], v[6:7], v[112:113] op_sel_hi:[1,0]
	v_pk_mul_f32 v[4:5], v[4:5], v[112:113] op_sel_hi:[1,0]
	v_pk_mul_f32 v[24:25], v[10:11], v[132:133] op_sel_hi:[1,0]
	v_pk_mul_f32 v[10:11], v[8:9], v[132:133] op_sel_hi:[1,0]
	v_cvt_pk_bf16_f32 v8, v16, v17
	v_cvt_pk_bf16_f32 v9, v18, v19
	v_cvt_pk_bf16_f32 v10, v10, v11
	v_cvt_pk_bf16_f32 v11, v24, v25
	global_store_dwordx4 v[32:33], v[8:11], off offset:256
	s_and_b64 vcc, exec, s[0:1]
	s_mov_b64 s[8:9], s[36:37]
	v_mad_i64_i32 v[8:9], s[4:5], v162, s76, v[120:121]
	v_lshl_add_u64 v[16:17], v[8:9], 0, v[122:123]
	v_pk_mul_f32 v[10:11], v[22:23], v[112:113] op_sel_hi:[1,0]
	v_pk_mul_f32 v[8:9], v[20:21], v[112:113] op_sel_hi:[1,0]
	s_mov_b32 s5, s28
	v_cvt_pk_bf16_f32 v8, v8, v9
	v_cvt_pk_bf16_f32 v9, v10, v11
	v_cvt_pk_bf16_f32 v10, v12, v13
	v_cvt_pk_bf16_f32 v11, v14, v15
	global_store_dwordx4 v[16:17], v[8:11], off
	s_mov_b32 s4, s30
	s_mov_b64 s[6:7], s[34:35]
	v_pk_mul_f32 v[8:9], v[2:3], v[112:113] op_sel_hi:[1,0]
	v_pk_mul_f32 v[2:3], v[0:1], v[112:113] op_sel_hi:[1,0]
	v_cvt_pk_bf16_f32 v0, v4, v5
	v_cvt_pk_bf16_f32 v1, v6, v7
	v_cvt_pk_bf16_f32 v2, v2, v3
	v_cvt_pk_bf16_f32 v3, v8, v9
	global_store_dwordx4 v[16:17], v[0:3], off offset:256
	s_cbranch_vccz .LBB0_343
	s_waitcnt vmcnt(0)
	s_cmpk_gt_u32 s27, 0xff
	s_cbranch_scc1 .LBB0_350
	s_barrier

; #define PG8_STAGE(bufoff, gbase, voff) do { _Pragma("unroll") for (int _i = 0; _i < 2; ++_i) \
;     __builtin_amdgcn_global_load_lds((const unsigned*)((const char*)(gbase) + (voff)[_i]), (LAS unsigned*)(lds + (bufoff) + ldsw + _i * 8192), 16, 0, 0); } while (0)
; #define PG8_LDA(dst, b, h) do { _Pragma("unroll") for (int m = 0; m < 4; ++m) _Pragma("unroll") for (int k = 0; k < 2; ++k) dst[m][k] = *(const LAS bf16x8*)(lds + PG8_SA(b, h) + aoff + m * 2048 + k * 1024); } while (0)
; #define PG8_LDB(dst, b, h) do { _Pragma("unroll") for (int n = 0; n < 2; ++n) _Pragma("unroll") for (int k = 0; k < 2; ++k) dst[n][k] = *(const LAS bf16x8*)(lds + PG8_SB(b, h) + boff + n * 2048 + k * 1024); } while (0)
; #define PG8_MMA(ai, bj, At, Bt) do { __builtin_amdgcn_s_setprio(1); _Pragma("unroll") for (int m = 0; m < 4; ++m) _Pragma("unroll") for (int n = 0; n < 2; ++n) _Pragma("unroll") for (int k = 0; k < 2; ++k) \
;     acc[ai][bj][m][n] = __builtin_amdgcn_mfma_f32_16x16x32_bf16(Bt[n][k], At[m][k], acc[ai][bj][m][n], 0, 0, 0); __builtin_amdgcn_s_setprio(0); } while (0)
; #define PG8_WAIT_L(n) asm volatile("s_waitcnt lgkmcnt(" #n ")" ::: "memory")
; #define PG8_BAR __builtin_amdgcn_s_barrier()
; #define PG8_SCHED __builtin_amdgcn_sched_barrier(0)
; template <class Epi, class Sched = StaticOrder>
; DI void gemm_phase(LAS unsigned char* lds, const Gemm g, const Sched& S, const Epi& E) {
;     ...
;     const bool has_next = S.next(ui + 1, nxt);
;     const char* nA = has_next ? (const char*)g.A + (size_t)nxt.pm * tstep : cA; const char* nB = has_next ? (const char*)g.Bt + (size_t)nxt.pn * tstep : cB;
;     for (int t = 0; t < nt; t += 2) {
;       const bool last = (t == nt - 2);
;       const char* a1 = cA + (size_t)(t + 1) * kstep;
;       const char* a2 = last ? nA : cA + (size_t)(t + 2) * kstep; const char* b2 = last ? nB : cB + (size_t)(t + 2) * kstep;
;       const char* a3 = a2 + kstep; const char* b3 = b2 + kstep;
;       PG8_LDB(B0, 0, 0); PG8_SCHED; PG8_LDA(At, 0, 0); PG8_STAGE(PG8_SA(1, 1), a1 + hstep, voffA);
;       PG8_WAIT_L(8); PG8_BAR; PG8_WAIT_L(0); PG8_MMA(0, 0, At, B0); PG8_BAR; PG8_SCHED;
.LBB0_727:
	s_ashr_i32 s17, s16, 31
	v_cmp_lt_i64_e32 vcc, s[18:19], v[188:189]
	s_lshl_b64 s[18:19], s[16:17], 20
	s_add_u32 s18, s30, s18
	s_addc_u32 s19, s31, s19
	s_and_b64 s[20:21], vcc, exec
	s_cselect_b32 s17, s19, s23
	s_cselect_b32 s43, s18, s22
	s_ashr_i32 s15, s14, 31
	s_lshl_b64 s[20:21], s[14:15], 20
	s_add_u32 s20, s33, s20
	s_addc_u32 s21, s34, s21
	s_and_b64 s[26:27], vcc, exec
	s_cselect_b32 s15, s21, s25
	s_cselect_b32 s44, s20, s24
	s_add_u32 s22, s22, 0x80080
	s_addc_u32 s23, s23, 0
	s_add_u32 s45, s24, 0x100
	v_mov_b32_e32 v0, 0
	s_addc_u32 s52, s25, 0
	s_mov_b32 s53, -2
	s_waitcnt lgkmcnt(0)
	v_mov_b32_e32 v1, v0
	v_mov_b32_e32 v2, v0
	v_mov_b32_e32 v3, v0
	v_mov_b32_e32 v4, v0
	v_mov_b32_e32 v5, v0
	v_mov_b32_e32 v6, v0
	v_mov_b32_e32 v7, v0
	v_mov_b32_e32 v16, v0
	v_mov_b32_e32 v17, v0
	v_mov_b32_e32 v18, v0
	v_mov_b32_e32 v19, v0
	v_mov_b32_e32 v20, v0
	v_mov_b32_e32 v21, v0
	v_mov_b32_e32 v22, v0
	v_mov_b32_e32 v23, v0
	v_mov_b32_e32 v32, v0
	v_mov_b32_e32 v33, v0
	v_mov_b32_e32 v34, v0
	v_mov_b32_e32 v35, v0
	v_mov_b32_e32 v36, v0
	v_mov_b32_e32 v37, v0
	v_mov_b32_e32 v38, v0
	v_mov_b32_e32 v39, v0
	v_mov_b32_e32 v48, v0
	v_mov_b32_e32 v49, v0
	v_mov_b32_e32 v50, v0
	v_mov_b32_e32 v51, v0
	v_mov_b32_e32 v52, v0
	v_mov_b32_e32 v53, v0
	v_mov_b32_e32 v54, v0
	v_mov_b32_e32 v55, v0
	v_mov_b32_e32 v8, v0
	v_mov_b32_e32 v9, v0
	v_mov_b32_e32 v10, v0
	v_mov_b32_e32 v11, v0
	v_mov_b32_e32 v12, v0
	v_mov_b32_e32 v13, v0
	v_mov_b32_e32 v14, v0
	v_mov_b32_e32 v15, v0
	v_mov_b32_e32 v24, v0
	v_mov_b32_e32 v25, v0
	v_mov_b32_e32 v26, v0
	v_mov_b32_e32 v27, v0
	v_mov_b32_e32 v28, v0
	v_mov_b32_e32 v29, v0
	v_mov_b32_e32 v30, v0
	v_mov_b32_e32 v31, v0
	v_mov_b32_e32 v40, v0
	v_mov_b32_e32 v41, v0
	v_mov_b32_e32 v42, v0
	v_mov_b32_e32 v43, v0
	v_mov_b32_e32 v44, v0
	v_mov_b32_e32 v45, v0
	v_mov_b32_e32 v46, v0
	v_mov_b32_e32 v47, v0
	v_mov_b32_e32 v56, v0
	v_mov_b32_e32 v57, v0
	v_mov_b32_e32 v58, v0
	v_mov_b32_e32 v59, v0
	v_mov_b32_e32 v60, v0
	v_mov_b32_e32 v61, v0
	v_mov_b32_e32 v62, v0
	v_mov_b32_e32 v63, v0
	v_mov_b32_e32 v64, v0
	v_mov_b32_e32 v65, v0
	v_mov_b32_e32 v66, v0
	v_mov_b32_e32 v67, v0
	v_mov_b32_e32 v68, v0
	v_mov_b32_e32 v69, v0
	v_mov_b32_e32 v70, v0
	v_mov_b32_e32 v71, v0
	v_mov_b32_e32 v80, v0
	v_mov_b32_e32 v81, v0
	v_mov_b32_e32 v82, v0
	v_mov_b32_e32 v83, v0
	v_mov_b32_e32 v84, v0
	v_mov_b32_e32 v85, v0
	v_mov_b32_e32 v86, v0
	v_mov_b32_e32 v87, v0
	v_mov_b32_e32 v96, v0
	v_mov_b32_e32 v97, v0
	v_mov_b32_e32 v98, v0
	v_mov_b32_e32 v99, v0
	v_mov_b32_e32 v100, v0
	v_mov_b32_e32 v101, v0
	v_mov_b32_e32 v102, v0
	v_mov_b32_e32 v103, v0
	v_mov_b32_e32 v112, v0
	v_mov_b32_e32 v113, v0
	v_mov_b32_e32 v114, v0
	v_mov_b32_e32 v115, v0
	v_mov_b32_e32 v116, v0
	v_mov_b32_e32 v117, v0
	v_mov_b32_e32 v118, v0
	v_mov_b32_e32 v119, v0
	v_mov_b32_e32 v72, v0
	v_mov_b32_e32 v73, v0
	v_mov_b32_e32 v74, v0
	v_mov_b32_e32 v75, v0
	v_mov_b32_e32 v76, v0
	v_mov_b32_e32 v77, v0
	v_mov_b32_e32 v78, v0
	v_mov_b32_e32 v79, v0
	v_mov_b32_e32 v88, v0
	v_mov_b32_e32 v89, v0
	v_mov_b32_e32 v90, v0
	v_mov_b32_e32 v91, v0
	v_mov_b32_e32 v92, v0
	v_mov_b32_e32 v93, v0
	v_mov_b32_e32 v94, v0
	v_mov_b32_e32 v95, v0
	v_mov_b32_e32 v104, v0
	v_mov_b32_e32 v105, v0
	v_mov_b32_e32 v106, v0
	v_mov_b32_e32 v107, v0
	v_mov_b32_e32 v108, v0
	v_mov_b32_e32 v109, v0
	v_mov_b32_e32 v110, v0
	v_mov_b32_e32 v111, v0
	v_mov_b32_e32 v120, v0
	v_mov_b32_e32 v121, v0
	v_mov_b32_e32 v122, v0
	v_mov_b32_e32 v123, v0
	v_mov_b32_e32 v124, v0
	v_mov_b32_e32 v125, v0
	v_mov_b32_e32 v126, v0
	v_mov_b32_e32 v127, v0
	ds_read_b128 v[128:131], v207
	ds_read_b128 v[132:135], v207 offset:1024
	ds_read_b128 v[136:139], v207 offset:2048
	ds_read_b128 v[140:143], v207 offset:3072
	ds_read_b128 v[144:147], v208
	ds_read_b128 v[152:155], v208 offset:2048
	ds_read_b128 v[160:163], v208 offset:4096
	ds_read_b128 v[168:171], v208 offset:6144
.LBB0_728:
	s_add_u32 s24, s22, 0xfff80080
	s_addc_u32 s25, s23, -1
	s_cmp_eq_u32 s53, 28
	s_cselect_b32 s27, s17, s25
	s_cselect_b32 s26, s43, s24
	s_cselect_b32 s25, s15, s52
	s_cselect_b32 s24, s44, s45
	s_add_i32 m0, s37, 0xc000
	ds_read_b128 v[148:151], v208 offset:1024
	ds_read_b128 v[156:159], v208 offset:3072
	ds_read_b128 v[164:167], v208 offset:5120
	ds_read_b128 v[172:175], v208 offset:7168
	global_load_lds_dwordx4 v184, s[22:23]
	s_add_i32 m0, s37, 0xe000
	s_nop 0
	global_load_lds_dwordx4 v186, s[22:23]
	s_waitcnt lgkmcnt(0)
	s_waitcnt vmcnt(8)
	s_setprio 1
	s_barrier
	v_mfma_f32_16x16x32_bf16 v[124:127], v[128:131], v[144:147], v[124:127]
	v_mfma_f32_16x16x32_bf16 v[120:123], v[136:139], v[144:147], v[120:123]
	v_mfma_f32_16x16x32_bf16 v[108:111], v[128:131], v[152:155], v[108:111]
	v_mfma_f32_16x16x32_bf16 v[104:107], v[136:139], v[152:155], v[104:107]
	v_mfma_f32_16x16x32_bf16 v[92:95], v[128:131], v[160:163], v[92:95]
	v_mfma_f32_16x16x32_bf16 v[88:91], v[136:139], v[160:163], v[88:91]
	v_mfma_f32_16x16x32_bf16 v[76:79], v[128:131], v[168:171], v[76:79]
	v_mfma_f32_16x16x32_bf16 v[72:75], v[136:139], v[168:171], v[72:75]
	v_mfma_f32_16x16x32_bf16 v[124:127], v[132:135], v[148:151], v[124:127]
	v_mfma_f32_16x16x32_bf16 v[120:123], v[140:143], v[148:151], v[120:123]
	v_mfma_f32_16x16x32_bf16 v[108:111], v[132:135], v[156:159], v[108:111]
	v_mfma_f32_16x16x32_bf16 v[104:107], v[140:143], v[156:159], v[104:107]
	v_mfma_f32_16x16x32_bf16 v[92:95], v[132:135], v[164:167], v[92:95]
	v_mfma_f32_16x16x32_bf16 v[88:91], v[140:143], v[164:167], v[88:91]
	v_mfma_f32_16x16x32_bf16 v[76:79], v[132:135], v[172:175], v[76:79]
	v_mfma_f32_16x16x32_bf16 v[72:75], v[140:143], v[172:175], v[72:75]
	s_barrier
; #define PG8_STAGE(bufoff, gbase, voff) do { _Pragma("unroll") for (int _i = 0; _i < 2; ++_i) \
;     __builtin_amdgcn_global_load_lds((const unsigned*)((const char*)(gbase) + (voff)[_i]), (LAS unsigned*)(lds + (bufoff) + ldsw + _i * 8192), 16, 0, 0); } while (0)
; #define PG8_LDA(dst, b, h) do { _Pragma("unroll") for (int m = 0; m < 4; ++m) _Pragma("unroll") for (int k = 0; k < 2; ++k) dst[m][k] = *(const LAS bf16x8*)(lds + PG8_SA(b, h) + aoff + m * 2048 + k * 1024); } while (0)
; #define PG8_LDB(dst, b, h) do { _Pragma("unroll") for (int n = 0; n < 2; ++n) _Pragma("unroll") for (int k = 0; k < 2; ++k) dst[n][k] = *(const LAS bf16x8*)(lds + PG8_SB(b, h) + boff + n * 2048 + k * 1024); } while (0)
; #define PG8_MMA(ai, bj, At, Bt) do { __builtin_amdgcn_s_setprio(1); _Pragma("unroll") for (int m = 0; m < 4; ++m) _Pragma("unroll") for (int n = 0; n < 2; ++n) _Pragma("unroll") for (int k = 0; k < 2; ++k) \
;     acc[ai][bj][m][n] = __builtin_amdgcn_mfma_f32_16x16x32_bf16(Bt[n][k], At[m][k], acc[ai][bj][m][n], 0, 0, 0); __builtin_amdgcn_s_setprio(0); } while (0)
; #define PG8_WAIT_V(n) asm volatile("s_waitcnt vmcnt(" #n ")" ::: "memory")
; #define PG8_WAIT_L(n) asm volatile("s_waitcnt lgkmcnt(" #n ")" ::: "memory")
; #define PG8_BAR __builtin_amdgcn_s_barrier()
; #define PG8_SCHED __builtin_amdgcn_sched_barrier(0)
; template <class Epi, class Sched = StaticOrder>
; DI void gemm_phase(LAS unsigned char* lds, const Gemm g, const Sched& S, const Epi& E) {
;     ...
;       PG8_WAIT_L(8); PG8_BAR; PG8_WAIT_L(0); PG8_MMA(0, 0, At, B0); PG8_BAR; PG8_SCHED;
;       PG8_LDB(B1, 0, 1); PG8_STAGE(PG8_SB(0, 0), b2, voffB);
;       PG8_BAR; PG8_WAIT_L(0); PG8_MMA(0, 1, At, B1); PG8_BAR;
;       PG8_LDA(At, 0, 1); PG8_STAGE(PG8_SA(0, 0), a2, voffA);
;       PG8_BAR; PG8_WAIT_L(0); PG8_MMA(1, 0, At, B0); PG8_BAR; PG8_SCHED;
;       PG8_STAGE(PG8_SB(0, 1), b2 + hstep, voffB);
;       PG8_WAIT_V(6); PG8_BAR; PG8_MMA(1, 1, At, B1); PG8_BAR;
;       PG8_LDB(B0, 1, 0); PG8_SCHED; PG8_LDA(At, 1, 0); PG8_STAGE(PG8_SA(0, 1), a2 + hstep, voffA);
;       PG8_WAIT_L(8); PG8_BAR; PG8_WAIT_L(0); PG8_MMA(0, 0, At, B0); PG8_BAR; PG8_SCHED;
	s_setprio 0
	s_add_i32 s54, s50, s35
	s_add_u32 s98, s24, 0x80
	s_addc_u32 s99, s25, 0
	s_mov_b32 m0, s54
	ds_read_b128 v[192:195], v209
	ds_read_b128 v[196:199], v209 offset:1024
	ds_read_b128 v[200:203], v209 offset:2048
	ds_read_b128 v[212:215], v209 offset:3072
	global_load_lds_dwordx4 v180, s[24:25]
	s_add_i32 m0, s54, 0x2000
	s_nop 0
	global_load_lds_dwordx4 v176, s[24:25]
	s_waitcnt lgkmcnt(0)
	s_setprio 1
	s_barrier
	v_mfma_f32_16x16x32_bf16 v[116:119], v[192:195], v[144:147], v[116:119]
	v_mfma_f32_16x16x32_bf16 v[112:115], v[200:203], v[144:147], v[112:115]
	v_mfma_f32_16x16x32_bf16 v[100:103], v[192:195], v[152:155], v[100:103]
	v_mfma_f32_16x16x32_bf16 v[96:99], v[200:203], v[152:155], v[96:99]
	v_mfma_f32_16x16x32_bf16 v[84:87], v[192:195], v[160:163], v[84:87]
	v_mfma_f32_16x16x32_bf16 v[80:83], v[200:203], v[160:163], v[80:83]
	v_mfma_f32_16x16x32_bf16 v[68:71], v[192:195], v[168:171], v[68:71]
	v_mfma_f32_16x16x32_bf16 v[64:67], v[200:203], v[168:171], v[64:67]
	v_mfma_f32_16x16x32_bf16 v[116:119], v[196:199], v[148:151], v[116:119]
	ds_read_b128 v[144:147], v208 offset:16384
	v_mfma_f32_16x16x32_bf16 v[112:115], v[212:215], v[148:151], v[112:115]
	ds_read_b128 v[152:155], v208 offset:18432
	v_mfma_f32_16x16x32_bf16 v[100:103], v[196:199], v[156:159], v[100:103]
	ds_read_b128 v[160:163], v208 offset:20480
	v_mfma_f32_16x16x32_bf16 v[96:99], v[212:215], v[156:159], v[96:99]
	ds_read_b128 v[168:171], v208 offset:22528
	v_mfma_f32_16x16x32_bf16 v[84:87], v[196:199], v[164:167], v[84:87]
	v_mfma_f32_16x16x32_bf16 v[80:83], v[212:215], v[164:167], v[80:83]
	v_mfma_f32_16x16x32_bf16 v[68:71], v[196:199], v[172:175], v[68:71]
	v_mfma_f32_16x16x32_bf16 v[64:67], v[212:215], v[172:175], v[64:67]
	s_barrier
	s_setprio 0
	s_mov_b32 m0, s37
	s_add_u32 s100, s26, 0x80
	s_addc_u32 s101, s27, 0
	ds_read_b128 v[148:151], v208 offset:17408
	ds_read_b128 v[156:159], v208 offset:19456
	ds_read_b128 v[164:167], v208 offset:21504
	ds_read_b128 v[172:175], v208 offset:23552
	global_load_lds_dwordx4 v182, s[26:27]
	s_mov_b32 m0, s38
	s_nop 0
	global_load_lds_dwordx4 v178, s[26:27]
	s_waitcnt vmcnt(8)
	s_waitcnt lgkmcnt(0)
	s_setprio 1
	s_barrier
	v_mfma_f32_16x16x32_bf16 v[60:63], v[128:131], v[144:147], v[60:63]
	v_mfma_f32_16x16x32_bf16 v[56:59], v[136:139], v[144:147], v[56:59]
	v_mfma_f32_16x16x32_bf16 v[44:47], v[128:131], v[152:155], v[44:47]
	v_mfma_f32_16x16x32_bf16 v[40:43], v[136:139], v[152:155], v[40:43]
	v_mfma_f32_16x16x32_bf16 v[28:31], v[128:131], v[160:163], v[28:31]
	v_mfma_f32_16x16x32_bf16 v[24:27], v[136:139], v[160:163], v[24:27]
	v_mfma_f32_16x16x32_bf16 v[12:15], v[128:131], v[168:171], v[12:15]
	v_mfma_f32_16x16x32_bf16 v[8:11], v[136:139], v[168:171], v[8:11]
	v_mfma_f32_16x16x32_bf16 v[60:63], v[132:135], v[148:151], v[60:63]
	v_mfma_f32_16x16x32_bf16 v[56:59], v[140:143], v[148:151], v[56:59]
	v_mfma_f32_16x16x32_bf16 v[44:47], v[132:135], v[156:159], v[44:47]
	v_mfma_f32_16x16x32_bf16 v[40:43], v[140:143], v[156:159], v[40:43]
	v_mfma_f32_16x16x32_bf16 v[28:31], v[132:135], v[164:167], v[28:31]
	v_mfma_f32_16x16x32_bf16 v[24:27], v[140:143], v[164:167], v[24:27]
	v_mfma_f32_16x16x32_bf16 v[12:15], v[132:135], v[172:175], v[12:15]
	v_mfma_f32_16x16x32_bf16 v[8:11], v[140:143], v[172:175], v[8:11]
	s_barrier
	s_setprio 0
	s_add_u32 s54, s24, 0x80000
	s_addc_u32 s55, s25, 0
	s_add_i32 s57, s51, s35
	s_mov_b32 m0, s57
	s_nop 0
	global_load_lds_dwordx4 v180, s[54:55]
	s_add_i32 m0, s57, 0x2000
	s_nop 0
	global_load_lds_dwordx4 v176, s[54:55]
	s_add_i32 s54, 0, 0x18000
	v_add_u32_e32 v140, s54, v205
	ds_read_b128 v[128:131], v140
	ds_read_b128 v[132:135], v140 offset:1024
	ds_read_b128 v[136:139], v140 offset:2048
	ds_read_b128 v[140:143], v140 offset:3072
	s_waitcnt vmcnt(6)
	s_setprio 1
	s_barrier
	v_mfma_f32_16x16x32_bf16 v[52:55], v[192:195], v[144:147], v[52:55]
	v_mfma_f32_16x16x32_bf16 v[48:51], v[200:203], v[144:147], v[48:51]
	v_mfma_f32_16x16x32_bf16 v[36:39], v[192:195], v[152:155], v[36:39]
	v_mfma_f32_16x16x32_bf16 v[32:35], v[200:203], v[152:155], v[32:35]
	v_mfma_f32_16x16x32_bf16 v[20:23], v[192:195], v[160:163], v[20:23]
	v_mfma_f32_16x16x32_bf16 v[16:19], v[200:203], v[160:163], v[16:19]
	v_mfma_f32_16x16x32_bf16 v[4:7], v[192:195], v[168:171], v[4:7]
	v_mfma_f32_16x16x32_bf16 v[0:3], v[200:203], v[168:171], v[0:3]
	v_mfma_f32_16x16x32_bf16 v[52:55], v[196:199], v[148:151], v[52:55]
	ds_read_b128 v[144:147], v208 offset:32768
	v_mfma_f32_16x16x32_bf16 v[48:51], v[212:215], v[148:151], v[48:51]
	ds_read_b128 v[152:155], v208 offset:34816
	v_mfma_f32_16x16x32_bf16 v[36:39], v[196:199], v[156:159], v[36:39]
	ds_read_b128 v[160:163], v208 offset:36864
	v_mfma_f32_16x16x32_bf16 v[32:35], v[212:215], v[156:159], v[32:35]
	ds_read_b128 v[168:171], v208 offset:38912
	v_mfma_f32_16x16x32_bf16 v[20:23], v[196:199], v[164:167], v[20:23]
	v_mfma_f32_16x16x32_bf16 v[16:19], v[212:215], v[164:167], v[16:19]
	v_mfma_f32_16x16x32_bf16 v[4:7], v[196:199], v[172:175], v[4:7]
	v_mfma_f32_16x16x32_bf16 v[0:3], v[212:215], v[172:175], v[0:3]
	s_barrier
	s_setprio 0
	s_add_u32 s26, s26, 0x80000
	s_addc_u32 s27, s27, 0
	s_mov_b32 m0, s39
	ds_read_b128 v[148:151], v208 offset:33792
	ds_read_b128 v[156:159], v208 offset:35840
	ds_read_b128 v[164:167], v208 offset:37888
	ds_read_b128 v[172:175], v208 offset:39936
	global_load_lds_dwordx4 v182, s[26:27]
	s_mov_b32 m0, s40
	s_nop 0
	global_load_lds_dwordx4 v178, s[26:27]
	s_waitcnt lgkmcnt(0)
	s_waitcnt vmcnt(8)
	s_setprio 1
	s_barrier
; #define PG8_STAGE(bufoff, gbase, voff) do { _Pragma("unroll") for (int _i = 0; _i < 2; ++_i) \
;     __builtin_amdgcn_global_load_lds((const unsigned*)((const char*)(gbase) + (voff)[_i]), (LAS unsigned*)(lds + (bufoff) + ldsw + _i * 8192), 16, 0, 0); } while (0)
; #define PG8_LDA(dst, b, h) do { _Pragma("unroll") for (int m = 0; m < 4; ++m) _Pragma("unroll") for (int k = 0; k < 2; ++k) dst[m][k] = *(const LAS bf16x8*)(lds + PG8_SA(b, h) + aoff + m * 2048 + k * 1024); } while (0)
; #define PG8_LDB(dst, b, h) do { _Pragma("unroll") for (int n = 0; n < 2; ++n) _Pragma("unroll") for (int k = 0; k < 2; ++k) dst[n][k] = *(const LAS bf16x8*)(lds + PG8_SB(b, h) + boff + n * 2048 + k * 1024); } while (0)
; #define PG8_MMA(ai, bj, At, Bt) do { __builtin_amdgcn_s_setprio(1); _Pragma("unroll") for (int m = 0; m < 4; ++m) _Pragma("unroll") for (int n = 0; n < 2; ++n) _Pragma("unroll") for (int k = 0; k < 2; ++k) \
;     acc[ai][bj][m][n] = __builtin_amdgcn_mfma_f32_16x16x32_bf16(Bt[n][k], At[m][k], acc[ai][bj][m][n], 0, 0, 0); __builtin_amdgcn_s_setprio(0); } while (0)
; #define PG8_WAIT_V(n) asm volatile("s_waitcnt vmcnt(" #n ")" ::: "memory")
; #define PG8_WAIT_L(n) asm volatile("s_waitcnt lgkmcnt(" #n ")" ::: "memory")
; #define PG8_BAR __builtin_amdgcn_s_barrier()
; #define PG8_SCHED __builtin_amdgcn_sched_barrier(0)
; template <class Epi, class Sched = StaticOrder>
; DI void gemm_phase(LAS unsigned char* lds, const Gemm g, const Sched& S, const Epi& E) {
;     ...
;       PG8_WAIT_L(8); PG8_BAR; PG8_WAIT_L(0); PG8_MMA(0, 0, At, B0); PG8_BAR; PG8_SCHED;
;       PG8_LDB(B1, 1, 1); PG8_STAGE(PG8_SB(1, 0), b3, voffB);
;       PG8_BAR; PG8_WAIT_L(0); PG8_MMA(0, 1, At, B1); PG8_BAR;
;       PG8_LDA(At, 1, 1); PG8_STAGE(PG8_SA(1, 0), a3, voffA);
;       PG8_BAR; PG8_WAIT_L(0); PG8_MMA(1, 0, At, B0); PG8_BAR; PG8_SCHED;
;       PG8_STAGE(PG8_SB(1, 1), b3 + hstep, voffB);
;       PG8_WAIT_V(6); PG8_BAR; PG8_MMA(1, 1, At, B1); PG8_BAR;
	v_mfma_f32_16x16x32_bf16 v[124:127], v[128:131], v[144:147], v[124:127]
	v_mfma_f32_16x16x32_bf16 v[120:123], v[136:139], v[144:147], v[120:123]
	v_mfma_f32_16x16x32_bf16 v[108:111], v[128:131], v[152:155], v[108:111]
	v_mfma_f32_16x16x32_bf16 v[104:107], v[136:139], v[152:155], v[104:107]
	v_mfma_f32_16x16x32_bf16 v[92:95], v[128:131], v[160:163], v[92:95]
	v_mfma_f32_16x16x32_bf16 v[88:91], v[136:139], v[160:163], v[88:91]
	v_mfma_f32_16x16x32_bf16 v[76:79], v[128:131], v[168:171], v[76:79]
	v_mfma_f32_16x16x32_bf16 v[72:75], v[136:139], v[168:171], v[72:75]
	v_mfma_f32_16x16x32_bf16 v[124:127], v[132:135], v[148:151], v[124:127]
	v_mfma_f32_16x16x32_bf16 v[120:123], v[140:143], v[148:151], v[120:123]
	v_mfma_f32_16x16x32_bf16 v[108:111], v[132:135], v[156:159], v[108:111]
	v_mfma_f32_16x16x32_bf16 v[104:107], v[140:143], v[156:159], v[104:107]
	v_mfma_f32_16x16x32_bf16 v[92:95], v[132:135], v[164:167], v[92:95]
	v_mfma_f32_16x16x32_bf16 v[88:91], v[140:143], v[164:167], v[88:91]
	v_mfma_f32_16x16x32_bf16 v[76:79], v[132:135], v[172:175], v[76:79]
	v_mfma_f32_16x16x32_bf16 v[72:75], v[140:143], v[172:175], v[72:75]
	s_barrier
	s_setprio 0
	s_add_i32 s26, 0, 0x1c000
	s_add_i32 s27, s54, s35
	v_add_u32_e32 v212, s26, v205
	s_mov_b32 m0, s27
	ds_read_b128 v[192:195], v212
	ds_read_b128 v[196:199], v212 offset:1024
	ds_read_b128 v[200:203], v212 offset:2048
	ds_read_b128 v[212:215], v212 offset:3072
	global_load_lds_dwordx4 v180, s[98:99]
	s_add_i32 m0, s27, 0x2000
	s_nop 0
	global_load_lds_dwordx4 v176, s[98:99]
	s_waitcnt lgkmcnt(0)
	s_setprio 1
	s_barrier
	v_mfma_f32_16x16x32_bf16 v[116:119], v[192:195], v[144:147], v[116:119]
	v_mfma_f32_16x16x32_bf16 v[112:115], v[200:203], v[144:147], v[112:115]
	v_mfma_f32_16x16x32_bf16 v[100:103], v[192:195], v[152:155], v[100:103]
	v_mfma_f32_16x16x32_bf16 v[96:99], v[200:203], v[152:155], v[96:99]
	v_mfma_f32_16x16x32_bf16 v[84:87], v[192:195], v[160:163], v[84:87]
	v_mfma_f32_16x16x32_bf16 v[80:83], v[200:203], v[160:163], v[80:83]
	v_mfma_f32_16x16x32_bf16 v[68:71], v[192:195], v[168:171], v[68:71]
	v_mfma_f32_16x16x32_bf16 v[64:67], v[200:203], v[168:171], v[64:67]
	v_mfma_f32_16x16x32_bf16 v[116:119], v[196:199], v[148:151], v[116:119]
	ds_read_b128 v[144:147], v208 offset:49152
	v_mfma_f32_16x16x32_bf16 v[112:115], v[212:215], v[148:151], v[112:115]
	ds_read_b128 v[152:155], v208 offset:51200
	v_mfma_f32_16x16x32_bf16 v[100:103], v[196:199], v[156:159], v[100:103]
	ds_read_b128 v[160:163], v208 offset:53248
	v_mfma_f32_16x16x32_bf16 v[96:99], v[212:215], v[156:159], v[96:99]
	ds_read_b128 v[168:171], v208 offset:55296
	v_mfma_f32_16x16x32_bf16 v[84:87], v[196:199], v[164:167], v[84:87]
	v_mfma_f32_16x16x32_bf16 v[80:83], v[212:215], v[164:167], v[80:83]
	v_mfma_f32_16x16x32_bf16 v[68:71], v[196:199], v[172:175], v[68:71]
	v_mfma_f32_16x16x32_bf16 v[64:67], v[212:215], v[172:175], v[64:67]
	s_barrier
	s_setprio 0
	s_mov_b32 m0, s46
	ds_read_b128 v[148:151], v208 offset:50176
	ds_read_b128 v[156:159], v208 offset:52224
	ds_read_b128 v[164:167], v208 offset:54272
	ds_read_b128 v[172:175], v208 offset:56320
	global_load_lds_dwordx4 v182, s[100:101]
	s_mov_b32 m0, s47
	s_nop 0
	global_load_lds_dwordx4 v178, s[100:101]
	s_waitcnt vmcnt(8)
	s_waitcnt lgkmcnt(0)
	s_setprio 1
	s_barrier
	v_mfma_f32_16x16x32_bf16 v[60:63], v[128:131], v[144:147], v[60:63]
	v_mfma_f32_16x16x32_bf16 v[56:59], v[136:139], v[144:147], v[56:59]
	v_mfma_f32_16x16x32_bf16 v[44:47], v[128:131], v[152:155], v[44:47]
	v_mfma_f32_16x16x32_bf16 v[40:43], v[136:139], v[152:155], v[40:43]
	v_mfma_f32_16x16x32_bf16 v[28:31], v[128:131], v[160:163], v[28:31]
	v_mfma_f32_16x16x32_bf16 v[24:27], v[136:139], v[160:163], v[24:27]
	v_mfma_f32_16x16x32_bf16 v[12:15], v[128:131], v[168:171], v[12:15]
	v_mfma_f32_16x16x32_bf16 v[8:11], v[136:139], v[168:171], v[8:11]
	v_mfma_f32_16x16x32_bf16 v[60:63], v[132:135], v[148:151], v[60:63]
	v_mfma_f32_16x16x32_bf16 v[56:59], v[140:143], v[148:151], v[56:59]
	v_mfma_f32_16x16x32_bf16 v[44:47], v[132:135], v[156:159], v[44:47]
	v_mfma_f32_16x16x32_bf16 v[40:43], v[140:143], v[156:159], v[40:43]
	v_mfma_f32_16x16x32_bf16 v[28:31], v[132:135], v[164:167], v[28:31]
	v_mfma_f32_16x16x32_bf16 v[24:27], v[140:143], v[164:167], v[24:27]
	v_mfma_f32_16x16x32_bf16 v[12:15], v[132:135], v[172:175], v[12:15]
	v_mfma_f32_16x16x32_bf16 v[8:11], v[140:143], v[172:175], v[8:11]
	s_barrier
	s_setprio 0
	s_add_u32 s24, s24, 0x80080
	s_addc_u32 s25, s25, 0
	s_add_i32 s26, s26, s35
	s_mov_b32 m0, s26
	s_nop 0
	global_load_lds_dwordx4 v180, s[24:25]
	s_add_i32 m0, s26, 0x2000
	s_nop 0
	global_load_lds_dwordx4 v176, s[24:25]
	ds_read_b128 v[128:131], v207
	ds_read_b128 v[132:135], v207 offset:1024
	ds_read_b128 v[136:139], v207 offset:2048
	ds_read_b128 v[140:143], v207 offset:3072
	s_waitcnt vmcnt(6)
	s_add_i32 s53, s53, 2
	s_add_u32 s22, s22, 0x100
	s_addc_u32 s23, s23, 0
	s_add_u32 s45, s45, 0x100
	s_addc_u32 s52, s52, 0
	s_cmp_gt_u32 s53, 29
	s_setprio 1
	s_barrier
; DI unsigned pack2(float lo, float hi) { f32x2 v = {lo, hi}; bf16v2 r = __builtin_convertvector(v, bf16v2); return __builtin_bit_cast(unsigned, r); }
; #define PG8_MMA(ai, bj, At, Bt) do { __builtin_amdgcn_s_setprio(1); _Pragma("unroll") for (int m = 0; m < 4; ++m) _Pragma("unroll") for (int n = 0; n < 2; ++n) _Pragma("unroll") for (int k = 0; k < 2; ++k) \
;     acc[ai][bj][m][n] = __builtin_amdgcn_mfma_f32_16x16x32_bf16(Bt[n][k], At[m][k], acc[ai][bj][m][n], 0, 0, 0); __builtin_amdgcn_s_setprio(0); } while (0)
; #define PG8_BAR __builtin_amdgcn_s_barrier()
;   DI void operator()(const f32x4 (&acc)[2][2][4][2], const Unit& u, int wr, int wc, int fr, int fq) const {
;     const int row0 = u.pm * BM + wr * 64 + fr, col0 = u.pn * BM + wc * 32 + 8 * fq;
; #pragma unroll
;     for (int ai = 0; ai < 2; ++ai) {
;       f32x4 bv[4][2][2];
; #pragma unroll
;       for (int m = 0; m < 4; ++m)
; #pragma unroll
;         for (int bj = 0; bj < 2; ++bj) {
;           const float* bp = base + (size_t)(row0 + ai * HALF + m * 16) * 2048 + col0 + bj * HALF;
;           bv[m][bj][0] = *(const f32x4*)bp; bv[m][bj][1] = *(const f32x4*)(bp + 4);
;         }
; #pragma unroll
;       for (int m = 0; m < 4; ++m) {
;         const int row = row0 + ai * HALF + m * 16;
;         const size_t off = (size_t)row * 2048 + col0;
;         float ss = 0.f;
; #pragma unroll
;         for (int bj = 0; bj < 2; ++bj) {
;           const f32x4 v0 = acc[ai][bj][m][0] + bv[m][bj][0], v1 = acc[ai][bj][m][1] + bv[m][bj][1];
;           *(f32x4*)(C + off + bj * HALF) = v0; *(f32x4*)(C + off + bj * HALF + 4) = v1;
;           if (xb) {
;             u32x4 w; w.x = pack2(v0[0], v0[1]); w.y = pack2(v0[2], v0[3]); w.z = pack2(v1[0], v1[1]); w.w = pack2(v1[2], v1[3]);
;             *(u32x4*)(xb + off + bj * HALF) = w;
;             ss += v0[0] * v0[0] + v0[1] * v0[1] + v0[2] * v0[2] + v0[3] * v0[3] + v1[0] * v1[0] + v1[1] * v1[1] + v1[2] * v1[2] + v1[3] * v1[3];
;           }
;         }
;         if (xb) {
;           ss += __shfl_xor(ss, 16); ss += __shfl_xor(ss, 32);
;           if (fq == 0) ssq[(size_t)row * 32 + u.pn * 4 + wc] = ss;
;         }
; template <class Epi, class Sched = StaticOrder>
; DI void gemm_phase(LAS unsigned char* lds, const Gemm g, const Sched& S, const Epi& E) {
;     ...
;       PG8_WAIT_V(6); PG8_BAR; PG8_MMA(1, 1, At, B1); PG8_BAR;
;     }
;     E(acc, cur, wr, wc, fr, fq);
	v_mfma_f32_16x16x32_bf16 v[52:55], v[192:195], v[144:147], v[52:55]
	v_mfma_f32_16x16x32_bf16 v[48:51], v[200:203], v[144:147], v[48:51]
	v_mfma_f32_16x16x32_bf16 v[36:39], v[192:195], v[152:155], v[36:39]
	v_mfma_f32_16x16x32_bf16 v[32:35], v[200:203], v[152:155], v[32:35]
	v_mfma_f32_16x16x32_bf16 v[20:23], v[192:195], v[160:163], v[20:23]
	v_mfma_f32_16x16x32_bf16 v[16:19], v[200:203], v[160:163], v[16:19]
	v_mfma_f32_16x16x32_bf16 v[4:7], v[192:195], v[168:171], v[4:7]
	v_mfma_f32_16x16x32_bf16 v[0:3], v[200:203], v[168:171], v[0:3]
	v_mfma_f32_16x16x32_bf16 v[52:55], v[196:199], v[148:151], v[52:55]
	ds_read_b128 v[144:147], v208
	v_mfma_f32_16x16x32_bf16 v[48:51], v[212:215], v[148:151], v[48:51]
	ds_read_b128 v[152:155], v208 offset:2048
	v_mfma_f32_16x16x32_bf16 v[36:39], v[196:199], v[156:159], v[36:39]
	ds_read_b128 v[160:163], v208 offset:4096
	v_mfma_f32_16x16x32_bf16 v[32:35], v[212:215], v[156:159], v[32:35]
	ds_read_b128 v[168:171], v208 offset:6144
	v_mfma_f32_16x16x32_bf16 v[20:23], v[196:199], v[164:167], v[20:23]
	v_mfma_f32_16x16x32_bf16 v[16:19], v[212:215], v[164:167], v[16:19]
	v_mfma_f32_16x16x32_bf16 v[4:7], v[196:199], v[172:175], v[4:7]
	v_mfma_f32_16x16x32_bf16 v[0:3], v[212:215], v[172:175], v[0:3]
	s_barrier
	s_setprio 0
	s_cbranch_scc0 .LBB0_728
	s_waitcnt lgkmcnt(0)
	v_lshl_add_u32 v196, s12, 8, v204
	v_lshl_or_b32 v192, s42, 8, v206
	v_ashrrev_i32_e32 v193, 31, v192
	v_ashrrev_i32_e32 v197, 31, v196
	v_lshl_add_u64 v[194:195], v[192:193], 2, s[60:61]
	v_lshlrev_b64 v[128:129], 13, v[196:197]
	v_lshl_add_u64 v[128:129], v[194:195], 0, v[128:129]
	global_load_dwordx4 v[214:217], v[128:129], off
	global_load_dwordx4 v[218:221], v[128:129], off offset:16
	global_load_dwordx4 v[222:225], v[128:129], off offset:512
	global_load_dwordx4 v[226:229], v[128:129], off offset:528
	v_or_b32_e32 v202, 16, v196
	v_or_b32_e32 v200, 32, v196
	v_or_b32_e32 v198, 48, v196
	v_ashrrev_i32_e32 v203, 31, v202
	v_ashrrev_i32_e32 v201, 31, v200
	v_ashrrev_i32_e32 v199, 31, v198
	v_lshlrev_b64 v[128:129], 13, v[202:203]
	v_lshlrev_b64 v[130:131], 13, v[200:201]
	v_lshlrev_b64 v[132:133], 13, v[198:199]
	v_lshl_add_u64 v[128:129], v[194:195], 0, v[128:129]
	v_lshl_add_u64 v[130:131], v[194:195], 0, v[130:131]
	v_lshl_add_u64 v[132:133], v[194:195], 0, v[132:133]
	global_load_dwordx4 v[168:171], v[128:129], off offset:16
	global_load_dwordx4 v[172:175], v[128:129], off
	global_load_dwordx4 v[160:163], v[128:129], off offset:528
	global_load_dwordx4 v[164:167], v[128:129], off offset:512
	global_load_dwordx4 v[152:155], v[130:131], off offset:16
	global_load_dwordx4 v[156:159], v[130:131], off
	global_load_dwordx4 v[144:147], v[130:131], off offset:528
	global_load_dwordx4 v[148:151], v[130:131], off offset:512
	global_load_dwordx4 v[136:139], v[132:133], off offset:16
	global_load_dwordx4 v[140:143], v[132:133], off
	s_nop 0
	global_load_dwordx4 v[128:131], v[132:133], off offset:528
	s_nop 0
	global_load_dwordx4 v[132:135], v[132:133], off offset:512
	v_and_b32_e32 v212, 64, v211
	v_xor_b32_e32 v230, 16, v211
	v_add_u32_e32 v232, 64, v212
	v_xor_b32_e32 v231, 32, v211
	v_cmp_lt_i32_e32 vcc, v230, v232
	v_lshlrev_b64 v[212:213], 11, v[196:197]
	v_readlane_b32 s64, v243, 3
	v_cndmask_b32_e32 v233, v211, v230, vcc
	v_cmp_lt_i32_e32 vcc, v231, v232
	v_readlane_b32 s78, v243, 17
	v_readlane_b32 s79, v243, 18
	v_cndmask_b32_e32 v234, v211, v231, vcc
	v_lshl_add_u64 v[230:231], v[212:213], 0, v[192:193]
	v_lshlrev_b32_e32 v212, 2, v233
	v_lshl_add_u64 v[232:233], v[230:231], 2, s[78:79]
	v_lshl_add_u64 v[230:231], v[230:231], 1, s[2:3]
	s_lshl_b32 s22, s42, 2
	s_ashr_i32 s23, s22, 31
	v_readlane_b32 s65, v243, 4
	v_readlane_b32 s66, v243, 5
	v_readlane_b32 s67, v243, 6
	v_readlane_b32 s68, v243, 7
	v_readlane_b32 s69, v243, 8
	v_readlane_b32 s70, v243, 9
	v_readlane_b32 s71, v243, 10
	v_readlane_b32 s72, v243, 11
	v_readlane_b32 s73, v243, 12
	v_readlane_b32 s74, v243, 13
	v_readlane_b32 s75, v243, 14
	v_readlane_b32 s76, v243, 15
	v_readlane_b32 s77, v243, 16
	s_waitcnt vmcnt(0)
	v_pk_add_f32 v[126:127], v[126:127], v[216:217]
	v_pk_add_f32 v[124:125], v[124:125], v[214:215]
	v_pk_add_f32 v[116:117], v[116:117], v[222:223]
	v_pk_add_f32 v[122:123], v[122:123], v[220:221]
	v_pk_add_f32 v[120:121], v[120:121], v[218:219]
	v_pk_add_f32 v[214:215], v[112:113], v[226:227]
	global_store_dwordx4 v[232:233], v[124:127], off
	global_store_dwordx4 v[232:233], v[120:123], off offset:16
	v_cvt_pk_bf16_f32 v112, v124, v125
	v_mul_f32_e32 v125, v125, v125
	v_mul_f32_e32 v213, v117, v117
	v_pk_add_f32 v[118:119], v[118:119], v[224:225]
	v_fmac_f32_e32 v125, v124, v124
	v_fmac_f32_e32 v213, v116, v116
	v_fmac_f32_e32 v125, v126, v126
	v_fmac_f32_e32 v213, v118, v118
	v_fmac_f32_e32 v125, v127, v127
	v_fmac_f32_e32 v213, v119, v119
	v_fmac_f32_e32 v125, v120, v120
	v_fmac_f32_e32 v213, v214, v214
	v_pk_add_f32 v[216:217], v[114:115], v[228:229]
	v_fmac_f32_e32 v125, v121, v121
	v_fmac_f32_e32 v213, v215, v215
	v_fmac_f32_e32 v125, v122, v122
	v_fmac_f32_e32 v213, v216, v216
	v_fmac_f32_e32 v125, v123, v123
	v_fmac_f32_e32 v213, v217, v217
	v_cvt_pk_bf16_f32 v114, v120, v121
	v_add_f32_e32 v120, v125, v213
	ds_bpermute_b32 v121, v212, v120
	v_cvt_pk_bf16_f32 v113, v126, v127
	v_cvt_pk_bf16_f32 v115, v122, v123
	global_store_dwordx4 v[230:231], v[112:115], off
	global_store_dwordx4 v[232:233], v[116:119], off offset:512
	global_store_dwordx4 v[232:233], v[214:217], off offset:528
	v_cvt_pk_bf16_f32 v122, v116, v117
	s_waitcnt lgkmcnt(0)
	v_add_f32_e32 v112, v120, v121
	v_lshlrev_b32_e32 v120, 2, v234
	ds_bpermute_b32 v113, v120, v112
	v_cvt_pk_bf16_f32 v123, v118, v119
	v_cvt_pk_bf16_f32 v124, v214, v215
	v_cvt_pk_bf16_f32 v125, v216, v217
	global_store_dwordx4 v[230:231], v[122:125], off offset:256
	s_and_saveexec_b64 s[24:25], s[0:1]
	s_cbranch_execz .LBB0_731
	s_waitcnt lgkmcnt(0)
	v_add_f32_e32 v114, v112, v113
	v_lshlrev_b64 v[112:113], 7, v[196:197]
	v_lshl_add_u64 v[112:113], s[8:9], 0, v[112:113]
	v_lshl_add_u64 v[112:113], s[22:23], 2, v[112:113]
	s_lshl_b32 s12, s41, 2
	v_lshl_add_u64 v[112:113], v[112:113], 0, s[12:13]
	global_store_dword v[112:113], v114, off

; #define PG8_STAGE(bufoff, gbase, voff) do { _Pragma("unroll") for (int _i = 0; _i < 2; ++_i) \
;     __builtin_amdgcn_global_load_lds((const unsigned*)((const char*)(gbase) + (voff)[_i]), (LAS unsigned*)(lds + (bufoff) + ldsw + _i * 8192), 16, 0, 0); } while (0)
; #define PG8_LDA(dst, b, h) do { _Pragma("unroll") for (int m = 0; m < 4; ++m) _Pragma("unroll") for (int k = 0; k < 2; ++k) dst[m][k] = *(const LAS bf16x8*)(lds + PG8_SA(b, h) + aoff + m * 2048 + k * 1024); } while (0)
; #define PG8_LDB(dst, b, h) do { _Pragma("unroll") for (int n = 0; n < 2; ++n) _Pragma("unroll") for (int k = 0; k < 2; ++k) dst[n][k] = *(const LAS bf16x8*)(lds + PG8_SB(b, h) + boff + n * 2048 + k * 1024); } while (0)
; #define PG8_MMA(ai, bj, At, Bt) do { __builtin_amdgcn_s_setprio(1); _Pragma("unroll") for (int m = 0; m < 4; ++m) _Pragma("unroll") for (int n = 0; n < 2; ++n) _Pragma("unroll") for (int k = 0; k < 2; ++k) \
;     acc[ai][bj][m][n] = __builtin_amdgcn_mfma_f32_16x16x32_bf16(Bt[n][k], At[m][k], acc[ai][bj][m][n], 0, 0, 0); __builtin_amdgcn_s_setprio(0); } while (0)
; #define PG8_WAIT_L(n) asm volatile("s_waitcnt lgkmcnt(" #n ")" ::: "memory")
; #define PG8_BAR __builtin_amdgcn_s_barrier()
; #define PG8_SCHED __builtin_amdgcn_sched_barrier(0)
; template <class Epi, class Sched = StaticOrder>
; DI void gemm_phase(LAS unsigned char* lds, const Gemm g, const Sched& S, const Epi& E) {
;     ...
;     const bool has_next = S.next(ui + 1, nxt);
;     const char* nA = has_next ? (const char*)g.A + (size_t)nxt.pm * tstep : cA; const char* nB = has_next ? (const char*)g.Bt + (size_t)nxt.pn * tstep : cB;
;     for (int t = 0; t < nt; t += 2) {
;       const bool last = (t == nt - 2);
;       const char* a1 = cA + (size_t)(t + 1) * kstep;
;       const char* a2 = last ? nA : cA + (size_t)(t + 2) * kstep; const char* b2 = last ? nB : cB + (size_t)(t + 2) * kstep;
;       const char* a3 = a2 + kstep; const char* b3 = b2 + kstep;
;       PG8_LDB(B0, 0, 0); PG8_SCHED; PG8_LDA(At, 0, 0); PG8_STAGE(PG8_SA(1, 1), a1 + hstep, voffA);
;       PG8_WAIT_L(8); PG8_BAR; PG8_WAIT_L(0); PG8_MMA(0, 0, At, B0); PG8_BAR; PG8_SCHED;
.LBB0_810:
	s_ashr_i32 s37, s36, 31
	v_cmp_lt_i64_e32 vcc, s[38:39], v[174:175]
	s_lshl_b64 s[38:39], s[36:37], 20
	s_add_u32 s38, s77, s38
	s_addc_u32 s39, s78, s39
	s_and_b64 s[40:41], vcc, exec
	s_cselect_b32 s37, s39, s15
	s_cselect_b32 s42, s38, s14
	s_ashr_i32 s35, s34, 31
	s_lshl_b64 s[40:41], s[34:35], 20
	s_add_u32 s40, s79, s40
	s_addc_u32 s41, s80, s41
	s_and_b64 s[44:45], vcc, exec
	s_cselect_b32 s35, s41, s47
	s_cselect_b32 s43, s40, s46
	s_add_u32 s14, s14, 0x80080
	s_addc_u32 s15, s15, 0
	s_add_u32 s44, s46, 0x100
	v_mov_b32_e32 v0, 0
	s_addc_u32 s45, s47, 0
	s_mov_b32 s52, -2
	v_mov_b32_e32 v1, v0
	v_mov_b32_e32 v2, v0
	v_mov_b32_e32 v3, v0
	v_mov_b32_e32 v4, v0
	v_mov_b32_e32 v5, v0
	v_mov_b32_e32 v6, v0
	v_mov_b32_e32 v7, v0
	v_mov_b32_e32 v8, v0
	v_mov_b32_e32 v9, v0
	v_mov_b32_e32 v10, v0
	v_mov_b32_e32 v11, v0
	v_mov_b32_e32 v24, v0
	v_mov_b32_e32 v25, v0
	v_mov_b32_e32 v26, v0
	v_mov_b32_e32 v27, v0
	v_mov_b32_e32 v32, v0
	v_mov_b32_e32 v33, v0
	v_mov_b32_e32 v34, v0
	v_mov_b32_e32 v35, v0
	v_mov_b32_e32 v40, v0
	v_mov_b32_e32 v41, v0
	v_mov_b32_e32 v42, v0
	v_mov_b32_e32 v43, v0
	v_mov_b32_e32 v52, v0
	v_mov_b32_e32 v53, v0
	v_mov_b32_e32 v54, v0
	v_mov_b32_e32 v55, v0
	v_mov_b32_e32 v56, v0
	v_mov_b32_e32 v57, v0
	v_mov_b32_e32 v58, v0
	v_mov_b32_e32 v59, v0
	v_mov_b32_e32 v12, v0
	v_mov_b32_e32 v13, v0
	v_mov_b32_e32 v14, v0
	v_mov_b32_e32 v15, v0
	v_mov_b32_e32 v16, v0
	v_mov_b32_e32 v17, v0
	v_mov_b32_e32 v18, v0
	v_mov_b32_e32 v19, v0
	v_mov_b32_e32 v20, v0
	v_mov_b32_e32 v21, v0
	v_mov_b32_e32 v22, v0
	v_mov_b32_e32 v23, v0
	v_mov_b32_e32 v28, v0
	v_mov_b32_e32 v29, v0
	v_mov_b32_e32 v30, v0
	v_mov_b32_e32 v31, v0
	v_mov_b32_e32 v36, v0
	v_mov_b32_e32 v37, v0
	v_mov_b32_e32 v38, v0
	v_mov_b32_e32 v39, v0
	v_mov_b32_e32 v44, v0
	v_mov_b32_e32 v45, v0
	v_mov_b32_e32 v46, v0
	v_mov_b32_e32 v47, v0
	v_mov_b32_e32 v48, v0
	v_mov_b32_e32 v49, v0
	v_mov_b32_e32 v50, v0
	v_mov_b32_e32 v51, v0
	v_mov_b32_e32 v60, v0
	v_mov_b32_e32 v61, v0
	v_mov_b32_e32 v62, v0
	v_mov_b32_e32 v63, v0
	v_mov_b32_e32 v88, v0
	v_mov_b32_e32 v89, v0
	v_mov_b32_e32 v90, v0
	v_mov_b32_e32 v91, v0
	v_mov_b32_e32 v100, v0
	v_mov_b32_e32 v101, v0
	v_mov_b32_e32 v102, v0
	v_mov_b32_e32 v103, v0
	v_mov_b32_e32 v104, v0
	v_mov_b32_e32 v105, v0
	v_mov_b32_e32 v106, v0
	v_mov_b32_e32 v107, v0
	v_mov_b32_e32 v120, v0
	v_mov_b32_e32 v121, v0
	v_mov_b32_e32 v122, v0
	v_mov_b32_e32 v123, v0
	v_mov_b32_e32 v128, v0
	v_mov_b32_e32 v129, v0
	v_mov_b32_e32 v130, v0
	v_mov_b32_e32 v131, v0
	v_mov_b32_e32 v136, v0
	v_mov_b32_e32 v137, v0
	v_mov_b32_e32 v138, v0
	v_mov_b32_e32 v139, v0
	v_mov_b32_e32 v148, v0
	v_mov_b32_e32 v149, v0
	v_mov_b32_e32 v150, v0
	v_mov_b32_e32 v151, v0
	v_mov_b32_e32 v152, v0
	v_mov_b32_e32 v153, v0
	v_mov_b32_e32 v154, v0
	v_mov_b32_e32 v155, v0
	v_mov_b32_e32 v108, v0
	v_mov_b32_e32 v109, v0
	v_mov_b32_e32 v110, v0
	v_mov_b32_e32 v111, v0
	v_mov_b32_e32 v112, v0
	v_mov_b32_e32 v113, v0
	v_mov_b32_e32 v114, v0
	v_mov_b32_e32 v115, v0
	v_mov_b32_e32 v116, v0
	v_mov_b32_e32 v117, v0
	v_mov_b32_e32 v118, v0
	v_mov_b32_e32 v119, v0
	v_mov_b32_e32 v124, v0
	v_mov_b32_e32 v125, v0
	v_mov_b32_e32 v126, v0
	v_mov_b32_e32 v127, v0
	v_mov_b32_e32 v132, v0
	v_mov_b32_e32 v133, v0
	v_mov_b32_e32 v134, v0
	v_mov_b32_e32 v135, v0
	v_mov_b32_e32 v140, v0
	v_mov_b32_e32 v141, v0
	v_mov_b32_e32 v142, v0
	v_mov_b32_e32 v143, v0
	v_mov_b32_e32 v144, v0
	v_mov_b32_e32 v145, v0
	v_mov_b32_e32 v146, v0
	v_mov_b32_e32 v147, v0
	v_mov_b32_e32 v156, v0
	v_mov_b32_e32 v157, v0
	v_mov_b32_e32 v158, v0
	v_mov_b32_e32 v159, v0
	ds_read_b128 v[64:67], v201
	ds_read_b128 v[68:71], v201 offset:1024
	ds_read_b128 v[72:75], v201 offset:2048
	ds_read_b128 v[76:79], v201 offset:3072
	ds_read_b128 v[80:83], v202
	ds_read_b128 v[92:95], v202 offset:2048
	ds_read_b128 v[180:183], v202 offset:4096
	ds_read_b128 v[188:191], v202 offset:6144
.LBB0_811:
	s_add_u32 s46, s14, 0xfff80080
	s_addc_u32 s47, s15, -1
	s_cmp_eq_u32 s52, 28
	s_cselect_b32 s49, s37, s47
	s_cselect_b32 s48, s42, s46
	s_cselect_b32 s47, s35, s45
	s_cselect_b32 s46, s43, s44
	s_add_i32 m0, s62, 0xc000
	ds_read_b128 v[84:87], v202 offset:1024
	ds_read_b128 v[96:99], v202 offset:3072
	ds_read_b128 v[184:187], v202 offset:5120
	ds_read_b128 v[192:195], v202 offset:7168
	global_load_lds_dwordx4 v170, s[14:15]
	s_add_i32 m0, s62, 0xe000
	s_nop 0
	global_load_lds_dwordx4 v172, s[14:15]
	s_waitcnt lgkmcnt(0)
	s_waitcnt vmcnt(8)
	s_setprio 1
	s_barrier
	v_mfma_f32_16x16x32_bf16 v[156:159], v[64:67], v[80:83], v[156:159]
	v_mfma_f32_16x16x32_bf16 v[144:147], v[72:75], v[80:83], v[144:147]
	v_mfma_f32_16x16x32_bf16 v[140:143], v[64:67], v[92:95], v[140:143]
	v_mfma_f32_16x16x32_bf16 v[132:135], v[72:75], v[92:95], v[132:135]
	v_mfma_f32_16x16x32_bf16 v[124:127], v[64:67], v[180:183], v[124:127]
	v_mfma_f32_16x16x32_bf16 v[116:119], v[72:75], v[180:183], v[116:119]
	v_mfma_f32_16x16x32_bf16 v[112:115], v[64:67], v[188:191], v[112:115]
	v_mfma_f32_16x16x32_bf16 v[108:111], v[72:75], v[188:191], v[108:111]
	v_mfma_f32_16x16x32_bf16 v[156:159], v[68:71], v[84:87], v[156:159]
	v_mfma_f32_16x16x32_bf16 v[144:147], v[76:79], v[84:87], v[144:147]
	v_mfma_f32_16x16x32_bf16 v[140:143], v[68:71], v[96:99], v[140:143]
	v_mfma_f32_16x16x32_bf16 v[132:135], v[76:79], v[96:99], v[132:135]
	v_mfma_f32_16x16x32_bf16 v[124:127], v[68:71], v[184:187], v[124:127]
	v_mfma_f32_16x16x32_bf16 v[116:119], v[76:79], v[184:187], v[116:119]
	v_mfma_f32_16x16x32_bf16 v[112:115], v[68:71], v[192:195], v[112:115]
	v_mfma_f32_16x16x32_bf16 v[108:111], v[76:79], v[192:195], v[108:111]
	s_barrier
; #define PG8_STAGE(bufoff, gbase, voff) do { _Pragma("unroll") for (int _i = 0; _i < 2; ++_i) \
;     __builtin_amdgcn_global_load_lds((const unsigned*)((const char*)(gbase) + (voff)[_i]), (LAS unsigned*)(lds + (bufoff) + ldsw + _i * 8192), 16, 0, 0); } while (0)
; #define PG8_LDA(dst, b, h) do { _Pragma("unroll") for (int m = 0; m < 4; ++m) _Pragma("unroll") for (int k = 0; k < 2; ++k) dst[m][k] = *(const LAS bf16x8*)(lds + PG8_SA(b, h) + aoff + m * 2048 + k * 1024); } while (0)
; #define PG8_LDB(dst, b, h) do { _Pragma("unroll") for (int n = 0; n < 2; ++n) _Pragma("unroll") for (int k = 0; k < 2; ++k) dst[n][k] = *(const LAS bf16x8*)(lds + PG8_SB(b, h) + boff + n * 2048 + k * 1024); } while (0)
; #define PG8_MMA(ai, bj, At, Bt) do { __builtin_amdgcn_s_setprio(1); _Pragma("unroll") for (int m = 0; m < 4; ++m) _Pragma("unroll") for (int n = 0; n < 2; ++n) _Pragma("unroll") for (int k = 0; k < 2; ++k) \
;     acc[ai][bj][m][n] = __builtin_amdgcn_mfma_f32_16x16x32_bf16(Bt[n][k], At[m][k], acc[ai][bj][m][n], 0, 0, 0); __builtin_amdgcn_s_setprio(0); } while (0)
; #define PG8_WAIT_V(n) asm volatile("s_waitcnt vmcnt(" #n ")" ::: "memory")
; #define PG8_WAIT_L(n) asm volatile("s_waitcnt lgkmcnt(" #n ")" ::: "memory")
; #define PG8_BAR __builtin_amdgcn_s_barrier()
; #define PG8_SCHED __builtin_amdgcn_sched_barrier(0)
; template <class Epi, class Sched = StaticOrder>
; DI void gemm_phase(LAS unsigned char* lds, const Gemm g, const Sched& S, const Epi& E) {
;     ...
;       PG8_WAIT_L(8); PG8_BAR; PG8_WAIT_L(0); PG8_MMA(0, 0, At, B0); PG8_BAR; PG8_SCHED;
;       PG8_LDB(B1, 0, 1); PG8_STAGE(PG8_SB(0, 0), b2, voffB);
;       PG8_BAR; PG8_WAIT_L(0); PG8_MMA(0, 1, At, B1); PG8_BAR;
;       PG8_LDA(At, 0, 1); PG8_STAGE(PG8_SA(0, 0), a2, voffA);
;       PG8_BAR; PG8_WAIT_L(0); PG8_MMA(1, 0, At, B0); PG8_BAR; PG8_SCHED;
;       PG8_STAGE(PG8_SB(0, 1), b2 + hstep, voffB);
;       PG8_WAIT_V(6); PG8_BAR; PG8_MMA(1, 1, At, B1); PG8_BAR;
;       PG8_LDB(B0, 1, 0); PG8_SCHED; PG8_LDA(At, 1, 0); PG8_STAGE(PG8_SA(0, 1), a2 + hstep, voffA);
;       PG8_WAIT_L(8); PG8_BAR; PG8_WAIT_L(0); PG8_MMA(0, 0, At, B0); PG8_BAR; PG8_SCHED;
	s_setprio 0
	s_add_i32 s53, s72, s60
	s_add_u32 s98, s46, 0x80
	s_addc_u32 s99, s47, 0
	s_mov_b32 m0, s53
	ds_read_b128 v[206:209], v203
	ds_read_b128 v[212:215], v203 offset:1024
	ds_read_b128 v[216:219], v203 offset:2048
	ds_read_b128 v[220:223], v203 offset:3072
	global_load_lds_dwordx4 v164, s[46:47]
	s_add_i32 m0, s53, 0x2000
	s_nop 0
	global_load_lds_dwordx4 v160, s[46:47]
	s_waitcnt lgkmcnt(0)
	s_setprio 1
	s_barrier
	v_mfma_f32_16x16x32_bf16 v[152:155], v[206:209], v[80:83], v[152:155]
	v_mfma_f32_16x16x32_bf16 v[80:83], v[216:219], v[80:83], v[148:151]
	v_mfma_f32_16x16x32_bf16 v[152:155], v[212:215], v[84:87], v[152:155]
	v_mfma_f32_16x16x32_bf16 v[80:83], v[220:223], v[84:87], v[80:83]
	v_mfma_f32_16x16x32_bf16 v[84:87], v[206:209], v[92:95], v[136:139]
	v_mfma_f32_16x16x32_bf16 v[92:95], v[216:219], v[92:95], v[128:131]
	v_mfma_f32_16x16x32_bf16 v[104:107], v[216:219], v[180:183], v[104:107]
	v_mfma_f32_16x16x32_bf16 v[100:103], v[206:209], v[188:191], v[100:103]
	v_mfma_f32_16x16x32_bf16 v[88:91], v[216:219], v[188:191], v[88:91]
	ds_read_b128 v[128:131], v202 offset:17408
	v_mfma_f32_16x16x32_bf16 v[84:87], v[212:215], v[96:99], v[84:87]
	ds_read_b128 v[136:139], v202 offset:18432
	v_mfma_f32_16x16x32_bf16 v[92:95], v[220:223], v[96:99], v[92:95]
	ds_read_b128 v[148:151], v202 offset:19456
	v_mfma_f32_16x16x32_bf16 v[96:99], v[206:209], v[180:183], v[120:123]
	v_mfma_f32_16x16x32_bf16 v[104:107], v[220:223], v[184:187], v[104:107]
	v_mfma_f32_16x16x32_bf16 v[100:103], v[212:215], v[192:195], v[100:103]
	v_mfma_f32_16x16x32_bf16 v[88:91], v[220:223], v[192:195], v[88:91]
	v_mfma_f32_16x16x32_bf16 v[96:99], v[212:215], v[184:187], v[96:99]
	s_barrier
	s_setprio 0
	s_mov_b32 m0, s62
	s_add_u32 s100, s48, 0x80
	s_addc_u32 s101, s49, 0
	ds_read_b128 v[120:123], v202 offset:16384
	ds_read_b128 v[180:183], v202 offset:20480
	ds_read_b128 v[184:187], v202 offset:21504
	ds_read_b128 v[188:191], v202 offset:22528
	ds_read_b128 v[192:195], v202 offset:23552
	global_load_lds_dwordx4 v166, s[48:49]
	s_mov_b32 m0, s63
	s_nop 0
	global_load_lds_dwordx4 v162, s[48:49]
	s_waitcnt vmcnt(8)
	s_waitcnt lgkmcnt(0)
	s_setprio 1
	s_barrier
	v_mfma_f32_16x16x32_bf16 v[60:63], v[64:67], v[120:123], v[60:63]
	v_mfma_f32_16x16x32_bf16 v[48:51], v[72:75], v[120:123], v[48:51]
	v_mfma_f32_16x16x32_bf16 v[44:47], v[64:67], v[136:139], v[44:47]
	v_mfma_f32_16x16x32_bf16 v[36:39], v[72:75], v[136:139], v[36:39]
	v_mfma_f32_16x16x32_bf16 v[28:31], v[64:67], v[180:183], v[28:31]
	v_mfma_f32_16x16x32_bf16 v[20:23], v[72:75], v[180:183], v[20:23]
	v_mfma_f32_16x16x32_bf16 v[16:19], v[64:67], v[188:191], v[16:19]
	v_mfma_f32_16x16x32_bf16 v[12:15], v[72:75], v[188:191], v[12:15]
	v_mfma_f32_16x16x32_bf16 v[60:63], v[68:71], v[128:131], v[60:63]
	v_mfma_f32_16x16x32_bf16 v[48:51], v[76:79], v[128:131], v[48:51]
	v_mfma_f32_16x16x32_bf16 v[44:47], v[68:71], v[148:151], v[44:47]
	v_mfma_f32_16x16x32_bf16 v[36:39], v[76:79], v[148:151], v[36:39]
	v_mfma_f32_16x16x32_bf16 v[28:31], v[68:71], v[184:187], v[28:31]
	v_mfma_f32_16x16x32_bf16 v[20:23], v[76:79], v[184:187], v[20:23]
	v_mfma_f32_16x16x32_bf16 v[16:19], v[68:71], v[192:195], v[16:19]
	v_mfma_f32_16x16x32_bf16 v[12:15], v[76:79], v[192:195], v[12:15]
	s_barrier
	s_setprio 0
	s_add_u32 s54, s46, 0x80000
	s_addc_u32 s55, s47, 0
	s_add_i32 s53, s73, s60
	s_mov_b32 m0, s53
	s_nop 0
	global_load_lds_dwordx4 v164, s[54:55]
	s_add_i32 m0, s53, 0x2000
	s_nop 0
	global_load_lds_dwordx4 v160, s[54:55]
	s_add_i32 s53, 0, 0x18000
	v_add_u32_e32 v76, s53, v198
	ds_read_b128 v[64:67], v76
	ds_read_b128 v[68:71], v76 offset:1024
	ds_read_b128 v[72:75], v76 offset:2048
	ds_read_b128 v[76:79], v76 offset:3072
	s_waitcnt vmcnt(6)
	s_setprio 1
	s_barrier
	v_mfma_f32_16x16x32_bf16 v[56:59], v[206:209], v[120:123], v[56:59]
	v_mfma_f32_16x16x32_bf16 v[52:55], v[216:219], v[120:123], v[52:55]
	v_mfma_f32_16x16x32_bf16 v[40:43], v[206:209], v[136:139], v[40:43]
	v_mfma_f32_16x16x32_bf16 v[32:35], v[216:219], v[136:139], v[32:35]
	v_mfma_f32_16x16x32_bf16 v[24:27], v[206:209], v[180:183], v[24:27]
	v_mfma_f32_16x16x32_bf16 v[8:11], v[216:219], v[180:183], v[8:11]
	v_mfma_f32_16x16x32_bf16 v[4:7], v[206:209], v[188:191], v[4:7]
	v_mfma_f32_16x16x32_bf16 v[0:3], v[216:219], v[188:191], v[0:3]
	v_mfma_f32_16x16x32_bf16 v[56:59], v[212:215], v[128:131], v[56:59]
	ds_read_b128 v[120:123], v202 offset:32768
	v_mfma_f32_16x16x32_bf16 v[52:55], v[220:223], v[128:131], v[52:55]
	ds_read_b128 v[180:183], v202 offset:34816
	v_mfma_f32_16x16x32_bf16 v[40:43], v[212:215], v[148:151], v[40:43]
	ds_read_b128 v[188:191], v202 offset:36864
	v_mfma_f32_16x16x32_bf16 v[32:35], v[220:223], v[148:151], v[32:35]
	ds_read_b128 v[206:209], v202 offset:38912
	v_mfma_f32_16x16x32_bf16 v[24:27], v[212:215], v[184:187], v[24:27]
	v_mfma_f32_16x16x32_bf16 v[8:11], v[220:223], v[184:187], v[8:11]
	v_mfma_f32_16x16x32_bf16 v[4:7], v[212:215], v[192:195], v[4:7]
	v_mfma_f32_16x16x32_bf16 v[0:3], v[220:223], v[192:195], v[0:3]
	s_barrier
	s_setprio 0
	s_add_u32 s48, s48, 0x80000
	s_addc_u32 s49, s49, 0
	s_mov_b32 m0, s64
	ds_read_b128 v[128:131], v202 offset:33792
	ds_read_b128 v[184:187], v202 offset:35840
	ds_read_b128 v[192:195], v202 offset:37888
	ds_read_b128 v[212:215], v202 offset:39936
	global_load_lds_dwordx4 v166, s[48:49]
	s_mov_b32 m0, s65
	s_nop 0
	global_load_lds_dwordx4 v162, s[48:49]
	s_waitcnt lgkmcnt(0)
	s_waitcnt vmcnt(8)
	s_setprio 1
	s_barrier
; #define PG8_STAGE(bufoff, gbase, voff) do { _Pragma("unroll") for (int _i = 0; _i < 2; ++_i) \
;     __builtin_amdgcn_global_load_lds((const unsigned*)((const char*)(gbase) + (voff)[_i]), (LAS unsigned*)(lds + (bufoff) + ldsw + _i * 8192), 16, 0, 0); } while (0)
; #define PG8_LDA(dst, b, h) do { _Pragma("unroll") for (int m = 0; m < 4; ++m) _Pragma("unroll") for (int k = 0; k < 2; ++k) dst[m][k] = *(const LAS bf16x8*)(lds + PG8_SA(b, h) + aoff + m * 2048 + k * 1024); } while (0)
; #define PG8_LDB(dst, b, h) do { _Pragma("unroll") for (int n = 0; n < 2; ++n) _Pragma("unroll") for (int k = 0; k < 2; ++k) dst[n][k] = *(const LAS bf16x8*)(lds + PG8_SB(b, h) + boff + n * 2048 + k * 1024); } while (0)
; #define PG8_MMA(ai, bj, At, Bt) do { __builtin_amdgcn_s_setprio(1); _Pragma("unroll") for (int m = 0; m < 4; ++m) _Pragma("unroll") for (int n = 0; n < 2; ++n) _Pragma("unroll") for (int k = 0; k < 2; ++k) \
;     acc[ai][bj][m][n] = __builtin_amdgcn_mfma_f32_16x16x32_bf16(Bt[n][k], At[m][k], acc[ai][bj][m][n], 0, 0, 0); __builtin_amdgcn_s_setprio(0); } while (0)
; #define PG8_WAIT_V(n) asm volatile("s_waitcnt vmcnt(" #n ")" ::: "memory")
; #define PG8_WAIT_L(n) asm volatile("s_waitcnt lgkmcnt(" #n ")" ::: "memory")
; #define PG8_BAR __builtin_amdgcn_s_barrier()
; #define PG8_SCHED __builtin_amdgcn_sched_barrier(0)
; template <class Epi, class Sched = StaticOrder>
; DI void gemm_phase(LAS unsigned char* lds, const Gemm g, const Sched& S, const Epi& E) {
;     ...
;       PG8_WAIT_L(8); PG8_BAR; PG8_WAIT_L(0); PG8_MMA(0, 0, At, B0); PG8_BAR; PG8_SCHED;
;       PG8_LDB(B1, 1, 1); PG8_STAGE(PG8_SB(1, 0), b3, voffB);
;       PG8_BAR; PG8_WAIT_L(0); PG8_MMA(0, 1, At, B1); PG8_BAR;
;       PG8_LDA(At, 1, 1); PG8_STAGE(PG8_SA(1, 0), a3, voffA);
;       PG8_BAR; PG8_WAIT_L(0); PG8_MMA(1, 0, At, B0); PG8_BAR; PG8_SCHED;
;       PG8_STAGE(PG8_SB(1, 1), b3 + hstep, voffB);
;       PG8_WAIT_V(6); PG8_BAR; PG8_MMA(1, 1, At, B1); PG8_BAR;
	v_mfma_f32_16x16x32_bf16 v[136:139], v[64:67], v[120:123], v[156:159]
	v_mfma_f32_16x16x32_bf16 v[156:159], v[68:71], v[128:131], v[136:139]
	v_mfma_f32_16x16x32_bf16 v[136:139], v[72:75], v[120:123], v[144:147]
	v_mfma_f32_16x16x32_bf16 v[144:147], v[76:79], v[128:131], v[136:139]
	v_mfma_f32_16x16x32_bf16 v[136:139], v[64:67], v[180:183], v[140:143]
	v_mfma_f32_16x16x32_bf16 v[132:135], v[72:75], v[180:183], v[132:135]
	v_mfma_f32_16x16x32_bf16 v[124:127], v[64:67], v[188:191], v[124:127]
	v_mfma_f32_16x16x32_bf16 v[116:119], v[72:75], v[188:191], v[116:119]
	v_mfma_f32_16x16x32_bf16 v[112:115], v[64:67], v[206:209], v[112:115]
	v_mfma_f32_16x16x32_bf16 v[108:111], v[72:75], v[206:209], v[108:111]
	v_mfma_f32_16x16x32_bf16 v[140:143], v[68:71], v[184:187], v[136:139]
	v_mfma_f32_16x16x32_bf16 v[132:135], v[76:79], v[184:187], v[132:135]
	v_mfma_f32_16x16x32_bf16 v[124:127], v[68:71], v[192:195], v[124:127]
	v_mfma_f32_16x16x32_bf16 v[116:119], v[76:79], v[192:195], v[116:119]
	v_mfma_f32_16x16x32_bf16 v[112:115], v[68:71], v[212:215], v[112:115]
	v_mfma_f32_16x16x32_bf16 v[108:111], v[76:79], v[212:215], v[108:111]
	s_barrier
	s_setprio 0
	s_add_i32 s48, 0, 0x1c000
	v_add_u32_e32 v136, s48, v198
	s_add_i32 s49, s53, s60
	ds_read_b128 v[216:219], v136
	ds_read_b128 v[220:223], v136 offset:1024
	ds_read_b128 v[224:227], v136 offset:2048
	ds_read_b128 v[228:231], v136 offset:3072
	s_mov_b32 m0, s49
	s_nop 0
	global_load_lds_dwordx4 v164, s[98:99]
	s_add_i32 m0, s49, 0x2000
	s_nop 0
	global_load_lds_dwordx4 v160, s[98:99]
	s_waitcnt lgkmcnt(0)
	s_setprio 1
	s_barrier
	v_mfma_f32_16x16x32_bf16 v[80:83], v[224:227], v[120:123], v[80:83]
	v_mfma_f32_16x16x32_bf16 v[136:139], v[216:219], v[120:123], v[152:155]
	v_mfma_f32_16x16x32_bf16 v[148:151], v[228:231], v[128:131], v[80:83]
	v_mfma_f32_16x16x32_bf16 v[80:83], v[216:219], v[180:183], v[84:87]
	v_mfma_f32_16x16x32_bf16 v[152:155], v[220:223], v[128:131], v[136:139]
	v_mfma_f32_16x16x32_bf16 v[136:139], v[220:223], v[184:187], v[80:83]
	v_mfma_f32_16x16x32_bf16 v[80:83], v[224:227], v[180:183], v[92:95]
	v_mfma_f32_16x16x32_bf16 v[128:131], v[228:231], v[184:187], v[80:83]
	v_mfma_f32_16x16x32_bf16 v[80:83], v[216:219], v[188:191], v[96:99]
	ds_read_b128 v[84:87], v202 offset:50176
	v_mfma_f32_16x16x32_bf16 v[120:123], v[220:223], v[192:195], v[80:83]
	ds_read_b128 v[92:95], v202 offset:51200
	v_mfma_f32_16x16x32_bf16 v[80:83], v[224:227], v[188:191], v[104:107]
	ds_read_b128 v[180:183], v202 offset:53248
	v_mfma_f32_16x16x32_bf16 v[104:107], v[228:231], v[192:195], v[80:83]
	ds_read_b128 v[184:187], v202 offset:54272
	v_mfma_f32_16x16x32_bf16 v[80:83], v[216:219], v[206:209], v[100:103]
	v_mfma_f32_16x16x32_bf16 v[100:103], v[220:223], v[212:215], v[80:83]
	v_mfma_f32_16x16x32_bf16 v[80:83], v[224:227], v[206:209], v[88:91]
	v_mfma_f32_16x16x32_bf16 v[88:91], v[228:231], v[212:215], v[80:83]
	s_barrier
	s_setprio 0
	s_mov_b32 m0, s67
	s_nop 2
	ds_read_b128 v[80:83], v202 offset:49152
	ds_read_b128 v[96:99], v202 offset:52224
	ds_read_b128 v[188:191], v202 offset:55296
	ds_read_b128 v[192:195], v202 offset:56320
	global_load_lds_dwordx4 v166, s[100:101]
	s_mov_b32 m0, s68
	s_nop 0
	global_load_lds_dwordx4 v162, s[100:101]
	s_waitcnt vmcnt(8)
	s_waitcnt lgkmcnt(0)
	s_setprio 1
	s_barrier
	v_mfma_f32_16x16x32_bf16 v[60:63], v[64:67], v[80:83], v[60:63]
	v_mfma_f32_16x16x32_bf16 v[48:51], v[72:75], v[80:83], v[48:51]
	v_mfma_f32_16x16x32_bf16 v[44:47], v[64:67], v[92:95], v[44:47]
	v_mfma_f32_16x16x32_bf16 v[36:39], v[72:75], v[92:95], v[36:39]
	v_mfma_f32_16x16x32_bf16 v[28:31], v[64:67], v[180:183], v[28:31]
	v_mfma_f32_16x16x32_bf16 v[20:23], v[72:75], v[180:183], v[20:23]
	v_mfma_f32_16x16x32_bf16 v[16:19], v[64:67], v[188:191], v[16:19]
	v_mfma_f32_16x16x32_bf16 v[12:15], v[72:75], v[188:191], v[12:15]
	v_mfma_f32_16x16x32_bf16 v[60:63], v[68:71], v[84:87], v[60:63]
	v_mfma_f32_16x16x32_bf16 v[48:51], v[76:79], v[84:87], v[48:51]
	v_mfma_f32_16x16x32_bf16 v[44:47], v[68:71], v[96:99], v[44:47]
	v_mfma_f32_16x16x32_bf16 v[36:39], v[76:79], v[96:99], v[36:39]
	v_mfma_f32_16x16x32_bf16 v[28:31], v[68:71], v[184:187], v[28:31]
	v_mfma_f32_16x16x32_bf16 v[20:23], v[76:79], v[184:187], v[20:23]
	v_mfma_f32_16x16x32_bf16 v[16:19], v[68:71], v[192:195], v[16:19]
	v_mfma_f32_16x16x32_bf16 v[12:15], v[76:79], v[192:195], v[12:15]
	s_barrier
	s_setprio 0
	s_add_u32 s46, s46, 0x80080
	s_addc_u32 s47, s47, 0
	s_add_i32 s48, s48, s60
	s_mov_b32 m0, s48
	s_nop 0
	global_load_lds_dwordx4 v164, s[46:47]
	s_add_i32 m0, s48, 0x2000
	s_nop 0
	global_load_lds_dwordx4 v160, s[46:47]
	ds_read_b128 v[64:67], v201
	ds_read_b128 v[68:71], v201 offset:1024
	ds_read_b128 v[72:75], v201 offset:2048
	ds_read_b128 v[76:79], v201 offset:3072
	s_waitcnt vmcnt(6)
	s_add_i32 s52, s52, 2
	s_add_u32 s14, s14, 0x100
	s_addc_u32 s15, s15, 0
	s_add_u32 s44, s44, 0x100
	s_addc_u32 s45, s45, 0
	s_cmp_gt_u32 s52, 29
	s_setprio 1
	s_barrier
	v_mfma_f32_16x16x32_bf16 v[56:59], v[216:219], v[80:83], v[56:59]
	v_mfma_f32_16x16x32_bf16 v[52:55], v[224:227], v[80:83], v[52:55]
	v_mfma_f32_16x16x32_bf16 v[40:43], v[216:219], v[92:95], v[40:43]
	v_mfma_f32_16x16x32_bf16 v[32:35], v[224:227], v[92:95], v[32:35]
	v_mfma_f32_16x16x32_bf16 v[24:27], v[216:219], v[180:183], v[24:27]
	v_mfma_f32_16x16x32_bf16 v[8:11], v[224:227], v[180:183], v[8:11]
	v_mfma_f32_16x16x32_bf16 v[4:7], v[216:219], v[188:191], v[4:7]
	v_mfma_f32_16x16x32_bf16 v[0:3], v[224:227], v[188:191], v[0:3]
	v_mfma_f32_16x16x32_bf16 v[56:59], v[220:223], v[84:87], v[56:59]
	ds_read_b128 v[80:83], v202
	v_mfma_f32_16x16x32_bf16 v[52:55], v[228:231], v[84:87], v[52:55]
	ds_read_b128 v[92:95], v202 offset:2048
	v_mfma_f32_16x16x32_bf16 v[40:43], v[220:223], v[96:99], v[40:43]
	ds_read_b128 v[180:183], v202 offset:4096
	v_mfma_f32_16x16x32_bf16 v[32:35], v[228:231], v[96:99], v[32:35]
	ds_read_b128 v[188:191], v202 offset:6144
	v_mfma_f32_16x16x32_bf16 v[24:27], v[220:223], v[184:187], v[24:27]
	v_mfma_f32_16x16x32_bf16 v[8:11], v[228:231], v[184:187], v[8:11]
	v_mfma_f32_16x16x32_bf16 v[4:7], v[220:223], v[192:195], v[4:7]
	v_mfma_f32_16x16x32_bf16 v[0:3], v[228:231], v[192:195], v[0:3]
	s_barrier
;   DI void operator()(const f32x4 (&acc)[2][2][4][2], const Unit& u, int wr, int wc, int fr, int fq) const {
;     const int col = u.pn * 128 + wc * 32 + 8 * fq;
;     float w0[8], w1[8], w2[8], bb[8];
; #pragma unroll
;     for (int e = 0; e < 8; ++e) { w0[e] = cw[col + e]; w1[e] = cw[5632 + col + e]; w2[e] = cw[2 * 5632 + col + e]; bb[e] = cb[col + e]; }
; #pragma unroll
;     for (int ai = 0; ai < 2; ++ai) {
;       const int row0 = u.pm * BM + ai * HALF + wr * 64, span = row0 >> 6;
;       float rsv[4];
; #pragma unroll
;       for (int m = 0; m < 4; ++m) rsv[m] = row_rstd(ssq, row0 + 16 * m + fr, fq);
	s_setprio 0
	s_cbranch_scc0 .LBB0_811
	s_waitcnt lgkmcnt(0)
	s_lshl_b32 s35, s12, 8
	s_add_i32 s35, s35, s66
	v_or_b32_e32 v190, s35, v179
	v_ashrrev_i32_e32 v191, 31, v190
	v_lshlrev_b64 v[64:65], 7, v[190:191]
	v_or_b32_e32 v188, 16, v190
	v_lshl_add_u64 v[64:65], v[168:169], 0, v[64:65]
	v_ashrrev_i32_e32 v189, 31, v188
	global_load_dwordx4 v[192:195], v[64:65], off
	global_load_dwordx4 v[206:209], v[64:65], off offset:16
	v_lshlrev_b64 v[64:65], 7, v[188:189]
	v_lshl_add_u64 v[64:65], v[168:169], 0, v[64:65]
	global_load_dwordx4 v[212:215], v[64:65], off
	global_load_dwordx4 v[216:219], v[64:65], off offset:16
	v_or_b32_e32 v186, 32, v190
	v_ashrrev_i32_e32 v187, 31, v186
	v_lshlrev_b64 v[64:65], 7, v[186:187]
	v_or_b32_e32 v184, 48, v190
	v_lshl_add_u64 v[64:65], v[168:169], 0, v[64:65]
	v_ashrrev_i32_e32 v185, 31, v184
	global_load_dwordx4 v[220:223], v[64:65], off
	global_load_dwordx4 v[224:227], v[64:65], off offset:16
	v_lshlrev_b64 v[64:65], 7, v[184:185]
	v_lshl_add_u64 v[64:65], v[168:169], 0, v[64:65]
	global_load_dwordx4 v[228:231], v[64:65], off
	global_load_dwordx4 v[232:235], v[64:65], off offset:16
	v_lshl_or_b32 v180, s13, 7, v200
	v_and_b32_e32 v65, 64, v204
	v_xor_b32_e32 v64, 16, v204
	v_ashrrev_i32_e32 v181, 31, v180
	v_add_u32_e32 v65, 64, v65
	v_readlane_b32 s44, v243, 3
	v_xor_b32_e32 v66, 32, v204
	v_lshlrev_b64 v[182:183], 2, v[180:181]
	v_cmp_lt_i32_e32 vcc, v64, v65
	v_readlane_b32 s52, v243, 11
	v_readlane_b32 s53, v243, 12
	v_cndmask_b32_e32 v64, v204, v64, vcc
	v_cmp_lt_i32_e32 vcc, v66, v65
	v_lshl_add_u64 v[92:93], s[52:53], 0, v[182:183]
	v_readlane_b32 s54, v243, 13
	v_cndmask_b32_e32 v65, v204, v66, vcc
	v_add_co_u32_e32 v94, vcc, 0x5000, v92
	v_readlane_b32 s55, v243, 14
	s_nop 0
	v_addc_co_u32_e32 v95, vcc, 0, v93, vcc
	v_add_co_u32_e32 v96, vcc, 0xb000, v92
	v_lshl_add_u64 v[72:73], s[54:55], 0, v[182:183]
	v_lshl_add_u64 v[74:75], v[92:93], 0, s[26:27]
	v_lshl_add_u64 v[76:77], v[92:93], 0, s[28:29]
	v_addc_co_u32_e32 v97, vcc, 0, v93, vcc
	v_lshlrev_b32_e32 v187, 2, v64
	v_lshlrev_b32_e32 v185, 2, v65
	global_load_dwordx4 v[64:67], v[92:93], off offset:16
	global_load_dwordx4 v[80:83], v[92:93], off
	global_load_dwordx4 v[68:71], v[72:73], off offset:16
	global_load_dwordx4 v[84:87], v[72:73], off
	s_nop 0
	global_load_dwordx4 v[72:75], v[74:75], off offset:16
	s_nop 0
	global_load_dwordx4 v[76:79], v[76:77], off offset:16
	s_nop 0
	global_load_dwordx4 v[92:95], v[94:95], off offset:2048
	s_nop 0
	global_load_dwordx4 v[96:99], v[96:97], off
	v_mov_b32_e32 v211, 0
	v_mov_b32_e32 v205, 0
	v_readlane_b32 s45, v243, 4
	v_readlane_b32 s46, v243, 5
	v_readlane_b32 s47, v243, 6
	v_readlane_b32 s48, v243, 7
	v_readlane_b32 s49, v243, 8
	v_readlane_b32 s50, v243, 9
	v_readlane_b32 s51, v243, 10
	v_readlane_b32 s56, v243, 15
	v_readlane_b32 s57, v243, 16
	v_readlane_b32 s58, v243, 17
	v_readlane_b32 s59, v243, 18
	s_waitcnt vmcnt(0)
	v_mov_b32_e32 v196, v192
	v_mov_b32_e32 v197, v206
	v_mov_b32_e32 v206, v193
	v_mov_b32_e32 v192, v194
	v_mov_b32_e32 v193, v208
	v_mov_b32_e32 v208, v195
	v_pk_add_f32 v[194:195], v[196:197], v[206:207]
	v_pk_add_f32 v[192:193], v[192:193], v[208:209]
	v_mov_b32_e32 v196, v212
	v_mov_b32_e32 v197, v216
	v_mov_b32_e32 v216, v213
	v_mov_b32_e32 v206, v214
	v_mov_b32_e32 v207, v218
	v_mov_b32_e32 v218, v215
	v_pk_add_f32 v[192:193], v[194:195], v[192:193]
	v_pk_add_f32 v[194:195], v[196:197], v[216:217]
	v_pk_add_f32 v[196:197], v[206:207], v[218:219]
	v_mov_b32_e32 v208, v220
	v_pk_add_f32 v[194:195], v[194:195], v[196:197]
	v_mov_b32_e32 v197, v192
	v_mov_b32_e32 v196, v194
	v_mov_b32_e32 v192, v195
	v_pk_add_f32 v[192:193], v[196:197], v[192:193]
	ds_bpermute_b32 v195, v187, v193
	ds_bpermute_b32 v194, v187, v192
	v_mov_b32_e32 v209, v224
	v_mov_b32_e32 v224, v221
	v_mov_b32_e32 v212, v222
	v_mov_b32_e32 v213, v226
	s_waitcnt lgkmcnt(0)
	v_pk_add_f32 v[192:193], v[192:193], v[194:195]
	ds_bpermute_b32 v195, v185, v193
	ds_bpermute_b32 v194, v185, v192
	v_mov_b32_e32 v226, v223
	v_mov_b32_e32 v196, v228
	v_mov_b32_e32 v197, v232
	v_mov_b32_e32 v232, v229
	s_waitcnt lgkmcnt(0)
; DI unsigned pack2(float lo, float hi) { f32x2 v = {lo, hi}; bf16v2 r = __builtin_convertvector(v, bf16v2); return __builtin_bit_cast(unsigned, r); }
; DI float silu_f(float x) { return x * sigmoid_f(x); }
; DI float dpp_ror1(float v) { return __int_as_float(__builtin_amdgcn_update_dpp(0, __float_as_int(v), 0x121, 0xf, 0xf, false)); }
; DI float dpp_ror2(float v) { return __int_as_float(__builtin_amdgcn_update_dpp(0, __float_as_int(v), 0x122, 0xf, 0xf, false)); }
;   DI void operator()(const f32x4 (&acc)[2][2][4][2], const Unit& u, int wr, int wc, int fr, int fq) const {
;     ...
;       for (int m = 0; m < 4; ++m) rsv[m] = row_rstd(ssq, row0 + 16 * m + fr, fq);
;       float p1[8], p2[8];
; #pragma unroll
;       for (int e = 0; e < 8; ++e) { p1[e] = 0.f; p2[e] = 0.f; }
; #pragma unroll
;       for (int m = 0; m < 4; ++m) {
;         float g[8], uu[8], a[8];
;         const float rs = rsv[m];
; #pragma unroll
;         for (int e = 0; e < 4; ++e) { g[e] = acc[ai][0][m][0][e] * rs; g[4 + e] = acc[ai][0][m][1][e] * rs; uu[e] = acc[ai][1][m][0][e] * rs; uu[4 + e] = acc[ai][1][m][1][e] * rs; }
; #pragma unroll
;         for (int e = 0; e < 8; ++e) {
;           const float x1 = dpp_ror1(g[e]), x2 = dpp_ror2(g[e]);
;           const float pr1 = (fr == 0) ? p1[e] : x1, pr2 = (fr < 2) ? p2[e] : x2;
;           a[e] = w2[e] * g[e] + w1[e] * pr1 + w0[e] * pr2 + bb[e];
;           p1[e] = x1; p2[e] = x2;
;         }
;         if (m == 0 && fr < 2) {
;           float* ha = headA + (size_t)(span * 2 + fr) * 5632 + col; float* hu = headU + (size_t)(span * 2 + fr) * 5632 + col;
;           *(f32x4*)ha = (f32x4){a[0], a[1], a[2], a[3]}; *(f32x4*)(ha + 4) = (f32x4){a[4], a[5], a[6], a[7]};
;           *(f32x4*)hu = (f32x4){uu[0], uu[1], uu[2], uu[3]}; *(f32x4*)(hu + 4) = (f32x4){uu[4], uu[5], uu[6], uu[7]};
;         } else {
;           u32x4 w;
;           w.x = pack2(silu_f(a[0]) * uu[0], silu_f(a[1]) * uu[1]);
;           w.y = pack2(silu_f(a[2]) * uu[2], silu_f(a[3]) * uu[3]);
;           w.z = pack2(silu_f(a[4]) * uu[4], silu_f(a[5]) * uu[5]);
;           w.w = pack2(silu_f(a[6]) * uu[6], silu_f(a[7]) * uu[7]);
;           *(u32x4*)(H + (size_t)(row0 + 16 * m + fr) * 5632 + col) = w;
	v_pk_add_f32 v[192:193], v[192:193], v[194:195]
	v_mov_b32_e32 v206, v230
	v_pk_fma_f32 v[192:193], v[192:193], s[30:31], v[178:179] op_sel_hi:[1,0,0]
	v_mov_b32_e32 v207, v234
	v_mul_f32_e32 v189, 0x4b800000, v193
	v_cmp_gt_f32_e64 s[12:13], s74, v193
	v_mov_b32_e32 v234, v231
	v_pk_add_f32 v[208:209], v[208:209], v[224:225]
	v_cndmask_b32_e64 v189, v193, v189, s[12:13]
	v_rsq_f32_e32 v189, v189
	v_pk_add_f32 v[212:213], v[212:213], v[226:227]
	v_pk_add_f32 v[196:197], v[196:197], v[232:233]
	v_pk_add_f32 v[194:195], v[206:207], v[234:235]
	v_mul_f32_e32 v191, 0x45800000, v189
	v_cndmask_b32_e64 v220, v189, v191, s[12:13]
	v_pk_add_f32 v[208:209], v[208:209], v[212:213]
	v_pk_add_f32 v[194:195], v[196:197], v[194:195]
	v_pk_mul_f32 v[156:157], v[156:157], v[220:221] op_sel_hi:[1,0]
	v_mov_b32_e32 v216, 0
	v_mov_b32_e32 v218, 0
	v_mov_b32_e32 v196, v194
	v_mov_b32_e32 v197, v208
	v_mov_b32_e32 v208, v195
	v_mov_b32_dpp v216, v156 row_ror:1 row_mask:0xf bank_mask:0xf
	v_mov_b32_dpp v218, v157 row_ror:1 row_mask:0xf bank_mask:0xf
	v_pk_add_f32 v[194:195], v[196:197], v[208:209]
	v_cndmask_b32_e64 v207, v218, 0, s[0:1]
	v_cndmask_b32_e64 v206, v216, 0, s[0:1]
	v_pk_mul_f32 v[158:159], v[158:159], v[220:221] op_sel_hi:[1,0]
	v_mov_b32_e32 v212, 0
	v_mov_b32_e32 v214, 0
	ds_bpermute_b32 v197, v187, v195
	ds_bpermute_b32 v196, v187, v194
	v_mov_b32_e32 v215, 0
	v_mov_b32_e32 v217, 0
	v_pk_mul_f32 v[206:207], v[92:93], v[206:207]
	v_mov_b32_dpp v212, v158 row_ror:1 row_mask:0xf bank_mask:0xf
	v_mov_b32_dpp v214, v159 row_ror:1 row_mask:0xf bank_mask:0xf
	v_mov_b32_dpp v215, v156 row_ror:2 row_mask:0xf bank_mask:0xf
	v_mov_b32_dpp v217, v157 row_ror:2 row_mask:0xf bank_mask:0xf
	v_pk_fma_f32 v[156:157], v[96:97], v[156:157], v[206:207]
	v_mov_b32_e32 v213, 0
	v_cndmask_b32_e64 v207, v214, 0, s[0:1]
	v_cndmask_b32_e64 v206, v212, 0, s[0:1]
	v_cndmask_b32_e64 v209, v217, 0, s[4:5]
	v_cndmask_b32_e64 v208, v215, 0, s[4:5]
	v_mov_b32_dpp v211, v158 row_ror:2 row_mask:0xf bank_mask:0xf
	v_mov_b32_dpp v213, v159 row_ror:2 row_mask:0xf bank_mask:0xf
	v_pk_mul_f32 v[206:207], v[94:95], v[206:207]
	v_pk_fma_f32 v[156:157], v[80:81], v[208:209], v[156:157]
	v_cndmask_b32_e64 v209, v213, 0, s[4:5]
	v_cndmask_b32_e64 v208, v211, 0, s[4:5]
	v_pk_fma_f32 v[158:159], v[98:99], v[158:159], v[206:207]
	v_pk_mul_f32 v[144:145], v[144:145], v[220:221] op_sel_hi:[1,0]
	v_pk_fma_f32 v[158:159], v[82:83], v[208:209], v[158:159]
	v_mov_b32_e32 v207, 0
	v_mov_b32_e32 v209, 0
	v_pk_mul_f32 v[146:147], v[146:147], v[220:221] op_sel_hi:[1,0]
	v_mov_b32_e32 v191, 0
	s_waitcnt lgkmcnt(0)
	v_pk_add_f32 v[194:195], v[194:195], v[196:197]
	v_mov_b32_dpp v207, v144 row_ror:1 row_mask:0xf bank_mask:0xf
	v_mov_b32_dpp v209, v145 row_ror:1 row_mask:0xf bank_mask:0xf
	v_mov_b32_dpp v191, v146 row_ror:1 row_mask:0xf bank_mask:0xf
	v_mov_b32_dpp v205, v147 row_ror:1 row_mask:0xf bank_mask:0xf
	ds_bpermute_b32 v197, v185, v195
	ds_bpermute_b32 v196, v185, v194
	v_pk_mul_f32 v[152:153], v[152:153], v[220:221] op_sel_hi:[1,0]
	v_pk_mul_f32 v[148:149], v[148:149], v[220:221] op_sel_hi:[1,0]
	v_pk_mul_f32 v[154:155], v[154:155], v[220:221] op_sel_hi:[1,0]
	v_pk_mul_f32 v[150:151], v[150:151], v[220:221] op_sel_hi:[1,0]
	v_mov_b32_e32 v206, 0
	v_mov_b32_e32 v208, 0
	v_cndmask_b32_e64 v223, v209, 0, s[0:1]
	v_cndmask_b32_e64 v222, v207, 0, s[0:1]
	v_mov_b32_e32 v189, 0
	v_mov_b32_e32 v193, 0
	v_cndmask_b32_e64 v221, v205, 0, s[0:1]
	v_cndmask_b32_e64 v220, v191, 0, s[0:1]
	v_mov_b32_dpp v206, v144 row_ror:2 row_mask:0xf bank_mask:0xf
	v_mov_b32_dpp v208, v145 row_ror:2 row_mask:0xf bank_mask:0xf
	v_pk_mul_f32 v[222:223], v[72:73], v[222:223]
	v_mov_b32_dpp v189, v146 row_ror:2 row_mask:0xf bank_mask:0xf
	v_mov_b32_dpp v193, v147 row_ror:2 row_mask:0xf bank_mask:0xf
	v_pk_mul_f32 v[220:221], v[74:75], v[220:221]
	v_cndmask_b32_e64 v225, v208, 0, s[4:5]
	v_cndmask_b32_e64 v224, v206, 0, s[4:5]
	v_pk_fma_f32 v[144:145], v[76:77], v[144:145], v[222:223]
	v_cndmask_b32_e64 v223, v193, 0, s[4:5]
	v_cndmask_b32_e64 v222, v189, 0, s[4:5]
	v_pk_fma_f32 v[146:147], v[78:79], v[146:147], v[220:221]
	v_pk_fma_f32 v[144:145], v[64:65], v[224:225], v[144:145]
	v_pk_fma_f32 v[146:147], v[66:67], v[222:223], v[146:147]
	v_cmp_gt_f32_e32 vcc, s74, v192
	v_pk_add_f32 v[156:157], v[84:85], v[156:157]
	v_pk_add_f32 v[158:159], v[86:87], v[158:159]
	v_pk_add_f32 v[144:145], v[68:69], v[144:145]
	v_pk_add_f32 v[146:147], v[70:71], v[146:147]
	s_and_saveexec_b64 s[12:13], s[10:11]
	s_xor_b64 s[12:13], exec, s[12:13]
	s_cbranch_execz .LBB0_814
	v_mul_f32_e32 v219, 0xbfb8aa3b, v156
	v_exp_f32_e32 v219, v219
	v_mul_f32_e32 v220, 0xbfb8aa3b, v157
	v_exp_f32_e32 v220, v220
	v_mul_f32_e32 v222, 0xbfb8aa3b, v159
	v_add_f32_e32 v219, 1.0, v219
	v_exp_f32_e32 v223, v222
	v_add_f32_e32 v221, 1.0, v220
	v_rcp_f32_e32 v220, v219
	v_mul_f32_e32 v219, 0xbfb8aa3b, v158
	v_exp_f32_e32 v219, v219
	v_rcp_f32_e32 v221, v221
	v_add_f32_e32 v219, 1.0, v219
	v_rcp_f32_e32 v222, v219
	v_add_f32_e32 v219, 1.0, v223
	v_rcp_f32_e32 v223, v219
	v_pk_mul_f32 v[156:157], v[156:157], v[220:221]
	s_nop 0
	v_pk_mul_f32 v[152:153], v[152:153], v[156:157]
	v_pk_mul_f32 v[156:157], v[158:159], v[222:223]
	v_cvt_pk_bf16_f32 v152, v152, v153
	v_mul_f32_e32 v153, 0xbfb8aa3b, v144
	v_pk_mul_f32 v[154:155], v[154:155], v[156:157]
	v_exp_f32_e32 v156, v153
	v_mul_f32_e32 v153, 0xbfb8aa3b, v145
	v_exp_f32_e32 v157, v153
	v_cvt_pk_bf16_f32 v153, v154, v155
	v_add_f32_e32 v154, 1.0, v156
	v_mul_f32_e32 v156, 0xbfb8aa3b, v146
	v_add_f32_e32 v155, 1.0, v157
	v_mul_f32_e32 v157, 0xbfb8aa3b, v147
	v_exp_f32_e32 v156, v156
	v_exp_f32_e32 v157, v157
	v_rcp_f32_e32 v154, v154
	v_rcp_f32_e32 v155, v155
	v_add_f32_e32 v156, 1.0, v156
	v_add_f32_e32 v157, 1.0, v157
	v_rcp_f32_e32 v156, v156
	v_rcp_f32_e32 v157, v157
	v_pk_mul_f32 v[144:145], v[144:145], v[154:155]
	s_nop 0
	v_pk_mul_f32 v[144:145], v[148:149], v[144:145]
	s_nop 0
	v_cvt_pk_bf16_f32 v154, v144, v145
	v_pk_mul_f32 v[144:145], v[146:147], v[156:157]
	s_nop 0
	v_pk_mul_f32 v[144:145], v[150:151], v[144:145]
	s_nop 0
	v_cvt_pk_bf16_f32 v155, v144, v145
	v_mov_b64_e32 v[144:145], s[16:17]
	v_mad_i64_i32 v[144:145], s[14:15], v190, s75, v[144:145]
	v_lshl_add_u64 v[144:145], v[180:181], 1, v[144:145]
	global_store_dwordx4 v[144:145], v[152:155], off

; #define PG8_STAGE(bufoff, gbase, voff) do { _Pragma("unroll") for (int _i = 0; _i < 2; ++_i) \
;     __builtin_amdgcn_global_load_lds((const unsigned*)((const char*)(gbase) + (voff)[_i]), (LAS unsigned*)(lds + (bufoff) + ldsw + _i * 8192), 16, 0, 0); } while (0)
; #define PG8_LDA(dst, b, h) do { _Pragma("unroll") for (int m = 0; m < 4; ++m) _Pragma("unroll") for (int k = 0; k < 2; ++k) dst[m][k] = *(const LAS bf16x8*)(lds + PG8_SA(b, h) + aoff + m * 2048 + k * 1024); } while (0)
; #define PG8_LDB(dst, b, h) do { _Pragma("unroll") for (int n = 0; n < 2; ++n) _Pragma("unroll") for (int k = 0; k < 2; ++k) dst[n][k] = *(const LAS bf16x8*)(lds + PG8_SB(b, h) + boff + n * 2048 + k * 1024); } while (0)
; #define PG8_MMA(ai, bj, At, Bt) do { __builtin_amdgcn_s_setprio(1); _Pragma("unroll") for (int m = 0; m < 4; ++m) _Pragma("unroll") for (int n = 0; n < 2; ++n) _Pragma("unroll") for (int k = 0; k < 2; ++k) \
;     acc[ai][bj][m][n] = __builtin_amdgcn_mfma_f32_16x16x32_bf16(Bt[n][k], At[m][k], acc[ai][bj][m][n], 0, 0, 0); __builtin_amdgcn_s_setprio(0); } while (0)
; #define PG8_WAIT_L(n) asm volatile("s_waitcnt lgkmcnt(" #n ")" ::: "memory")
; #define PG8_BAR __builtin_amdgcn_s_barrier()
; #define PG8_SCHED __builtin_amdgcn_sched_barrier(0)
; template <class Epi, class Sched = StaticOrder>
; DI void gemm_phase(LAS unsigned char* lds, const Gemm g, const Sched& S, const Epi& E) {
;     ...
;     const bool has_next = S.next(ui + 1, nxt);
;     const char* nA = has_next ? (const char*)g.A + (size_t)nxt.pm * tstep : cA; const char* nB = has_next ? (const char*)g.Bt + (size_t)nxt.pn * tstep : cB;
;     for (int t = 0; t < nt; t += 2) {
;       const bool last = (t == nt - 2);
;       const char* a1 = cA + (size_t)(t + 1) * kstep;
;       const char* a2 = last ? nA : cA + (size_t)(t + 2) * kstep; const char* b2 = last ? nB : cB + (size_t)(t + 2) * kstep;
;       const char* a3 = a2 + kstep; const char* b3 = b2 + kstep;
;       PG8_LDB(B0, 0, 0); PG8_SCHED; PG8_LDA(At, 0, 0); PG8_STAGE(PG8_SA(1, 1), a1 + hstep, voffA);
;       PG8_WAIT_L(8); PG8_BAR; PG8_WAIT_L(0); PG8_MMA(0, 0, At, B0); PG8_BAR; PG8_SCHED;
;       PG8_LDB(B1, 0, 1); PG8_STAGE(PG8_SB(0, 0), b2, voffB);
;       PG8_BAR; PG8_WAIT_L(0); PG8_MMA(0, 1, At, B1); PG8_BAR;
.LBB0_960:
	s_add_u32 s18, s18, 0x160080
	s_addc_u32 s19, s19, 0
	s_add_u32 s42, s20, 0x100
	v_mov_b32_e32 v0, 0
	s_addc_u32 s43, s21, 0
	s_mov_b32 s44, -2
	s_waitcnt lgkmcnt(0)
	v_mov_b32_e32 v1, v0
	v_mov_b32_e32 v2, v0
	v_mov_b32_e32 v3, v0
	v_mov_b32_e32 v4, v0
	v_mov_b32_e32 v5, v0
	v_mov_b32_e32 v6, v0
	v_mov_b32_e32 v7, v0
	v_mov_b32_e32 v16, v0
	v_mov_b32_e32 v17, v0
	v_mov_b32_e32 v18, v0
	v_mov_b32_e32 v19, v0
	v_mov_b32_e32 v20, v0
	v_mov_b32_e32 v21, v0
	v_mov_b32_e32 v22, v0
	v_mov_b32_e32 v23, v0
	v_mov_b32_e32 v32, v0
	v_mov_b32_e32 v33, v0
	v_mov_b32_e32 v34, v0
	v_mov_b32_e32 v35, v0
	v_mov_b32_e32 v36, v0
	v_mov_b32_e32 v37, v0
	v_mov_b32_e32 v38, v0
	v_mov_b32_e32 v39, v0
	v_mov_b32_e32 v48, v0
	v_mov_b32_e32 v49, v0
	v_mov_b32_e32 v50, v0
	v_mov_b32_e32 v51, v0
	v_mov_b32_e32 v52, v0
	v_mov_b32_e32 v53, v0
	v_mov_b32_e32 v54, v0
	v_mov_b32_e32 v55, v0
	v_mov_b32_e32 v8, v0
	v_mov_b32_e32 v9, v0
	v_mov_b32_e32 v10, v0
	v_mov_b32_e32 v11, v0
	v_mov_b32_e32 v12, v0
	v_mov_b32_e32 v13, v0
	v_mov_b32_e32 v14, v0
	v_mov_b32_e32 v15, v0
	v_mov_b32_e32 v24, v0
	v_mov_b32_e32 v25, v0
	v_mov_b32_e32 v26, v0
	v_mov_b32_e32 v27, v0
	v_mov_b32_e32 v28, v0
	v_mov_b32_e32 v29, v0
	v_mov_b32_e32 v30, v0
	v_mov_b32_e32 v31, v0
	v_mov_b32_e32 v40, v0
	v_mov_b32_e32 v41, v0
	v_mov_b32_e32 v42, v0
	v_mov_b32_e32 v43, v0
	v_mov_b32_e32 v44, v0
	v_mov_b32_e32 v45, v0
	v_mov_b32_e32 v46, v0
	v_mov_b32_e32 v47, v0
	v_mov_b32_e32 v56, v0
	v_mov_b32_e32 v57, v0
	v_mov_b32_e32 v58, v0
	v_mov_b32_e32 v59, v0
	v_mov_b32_e32 v60, v0
	v_mov_b32_e32 v61, v0
	v_mov_b32_e32 v62, v0
	v_mov_b32_e32 v63, v0
	v_mov_b32_e32 v64, v0
	v_mov_b32_e32 v65, v0
	v_mov_b32_e32 v66, v0
	v_mov_b32_e32 v67, v0
	v_mov_b32_e32 v68, v0
	v_mov_b32_e32 v69, v0
	v_mov_b32_e32 v70, v0
	v_mov_b32_e32 v71, v0
	v_mov_b32_e32 v80, v0
	v_mov_b32_e32 v81, v0
	v_mov_b32_e32 v82, v0
	v_mov_b32_e32 v83, v0
	v_mov_b32_e32 v84, v0
	v_mov_b32_e32 v85, v0
	v_mov_b32_e32 v86, v0
	v_mov_b32_e32 v87, v0
	v_mov_b32_e32 v96, v0
	v_mov_b32_e32 v97, v0
	v_mov_b32_e32 v98, v0
	v_mov_b32_e32 v99, v0
	v_mov_b32_e32 v100, v0
	v_mov_b32_e32 v101, v0
	v_mov_b32_e32 v102, v0
	v_mov_b32_e32 v103, v0
	v_mov_b32_e32 v112, v0
	v_mov_b32_e32 v113, v0
	v_mov_b32_e32 v114, v0
	v_mov_b32_e32 v115, v0
	v_mov_b32_e32 v116, v0
	v_mov_b32_e32 v117, v0
	v_mov_b32_e32 v118, v0
	v_mov_b32_e32 v119, v0
	v_mov_b32_e32 v72, v0
	v_mov_b32_e32 v73, v0
	v_mov_b32_e32 v74, v0
	v_mov_b32_e32 v75, v0
	v_mov_b32_e32 v76, v0
	v_mov_b32_e32 v77, v0
	v_mov_b32_e32 v78, v0
	v_mov_b32_e32 v79, v0
	v_mov_b32_e32 v88, v0
	v_mov_b32_e32 v89, v0
	v_mov_b32_e32 v90, v0
	v_mov_b32_e32 v91, v0
	v_mov_b32_e32 v92, v0
	v_mov_b32_e32 v93, v0
	v_mov_b32_e32 v94, v0
	v_mov_b32_e32 v95, v0
	v_mov_b32_e32 v104, v0
	v_mov_b32_e32 v105, v0
	v_mov_b32_e32 v106, v0
	v_mov_b32_e32 v107, v0
	v_mov_b32_e32 v108, v0
	v_mov_b32_e32 v109, v0
	v_mov_b32_e32 v110, v0
	v_mov_b32_e32 v111, v0
	v_mov_b32_e32 v120, v0
	v_mov_b32_e32 v121, v0
	v_mov_b32_e32 v122, v0
	v_mov_b32_e32 v123, v0
	v_mov_b32_e32 v124, v0
	v_mov_b32_e32 v125, v0
	v_mov_b32_e32 v126, v0
	v_mov_b32_e32 v127, v0
	ds_read_b128 v[128:131], v214
	ds_read_b128 v[132:135], v214 offset:1024
	ds_read_b128 v[136:139], v214 offset:2048
	ds_read_b128 v[140:143], v214 offset:3072
	ds_read_b128 v[144:147], v215
	ds_read_b128 v[152:155], v215 offset:2048
	ds_read_b128 v[160:163], v215 offset:4096
	ds_read_b128 v[168:171], v215 offset:6144
.LBB0_961:
	s_add_u32 s20, s18, 0xffea0080
	s_addc_u32 s21, s19, -1
	s_cmpk_eq_i32 s44, 0x54
	s_cselect_b32 s23, s5, s21
	s_cselect_b32 s22, s4, s20
	s_cselect_b32 s21, s7, s43
	s_cselect_b32 s20, s6, s42
	s_add_i32 m0, s31, 0xc000
	ds_read_b128 v[148:151], v215 offset:1024
	ds_read_b128 v[156:159], v215 offset:3072
	ds_read_b128 v[164:167], v215 offset:5120
	ds_read_b128 v[172:175], v215 offset:7168
	global_load_lds_dwordx4 v184, s[18:19]
	s_add_i32 m0, s31, 0xe000
	s_nop 0
	global_load_lds_dwordx4 v186, s[18:19]
	s_waitcnt lgkmcnt(0)
	s_waitcnt vmcnt(8)
	s_setprio 1
	s_barrier
	v_mfma_f32_16x16x32_bf16 v[124:127], v[128:131], v[144:147], v[124:127]
	v_mfma_f32_16x16x32_bf16 v[120:123], v[136:139], v[144:147], v[120:123]
	v_mfma_f32_16x16x32_bf16 v[108:111], v[128:131], v[152:155], v[108:111]
	v_mfma_f32_16x16x32_bf16 v[104:107], v[136:139], v[152:155], v[104:107]
	v_mfma_f32_16x16x32_bf16 v[92:95], v[128:131], v[160:163], v[92:95]
	v_mfma_f32_16x16x32_bf16 v[88:91], v[136:139], v[160:163], v[88:91]
	v_mfma_f32_16x16x32_bf16 v[76:79], v[128:131], v[168:171], v[76:79]
	v_mfma_f32_16x16x32_bf16 v[72:75], v[136:139], v[168:171], v[72:75]
	v_mfma_f32_16x16x32_bf16 v[124:127], v[132:135], v[148:151], v[124:127]
	v_mfma_f32_16x16x32_bf16 v[120:123], v[140:143], v[148:151], v[120:123]
	v_mfma_f32_16x16x32_bf16 v[108:111], v[132:135], v[156:159], v[108:111]
	v_mfma_f32_16x16x32_bf16 v[104:107], v[140:143], v[156:159], v[104:107]
	v_mfma_f32_16x16x32_bf16 v[92:95], v[132:135], v[164:167], v[92:95]
	v_mfma_f32_16x16x32_bf16 v[88:91], v[140:143], v[164:167], v[88:91]
	v_mfma_f32_16x16x32_bf16 v[76:79], v[132:135], v[172:175], v[76:79]
	v_mfma_f32_16x16x32_bf16 v[72:75], v[140:143], v[172:175], v[72:75]
	s_barrier
	s_setprio 0
	s_add_i32 s45, s46, s30
	s_add_u32 s98, s20, 0x80
	s_addc_u32 s99, s21, 0
	s_mov_b32 m0, s45
	ds_read_b128 v[192:195], v216
	ds_read_b128 v[196:199], v216 offset:1024
	ds_read_b128 v[200:203], v216 offset:2048
	ds_read_b128 v[204:207], v216 offset:3072
	global_load_lds_dwordx4 v178, s[20:21]
	s_add_i32 m0, s45, 0x2000
	s_nop 0
	global_load_lds_dwordx4 v182, s[20:21]
	s_waitcnt lgkmcnt(0)
	s_setprio 1
	s_barrier
; #define PG8_STAGE(bufoff, gbase, voff) do { _Pragma("unroll") for (int _i = 0; _i < 2; ++_i) \
;     __builtin_amdgcn_global_load_lds((const unsigned*)((const char*)(gbase) + (voff)[_i]), (LAS unsigned*)(lds + (bufoff) + ldsw + _i * 8192), 16, 0, 0); } while (0)
; #define PG8_LDA(dst, b, h) do { _Pragma("unroll") for (int m = 0; m < 4; ++m) _Pragma("unroll") for (int k = 0; k < 2; ++k) dst[m][k] = *(const LAS bf16x8*)(lds + PG8_SA(b, h) + aoff + m * 2048 + k * 1024); } while (0)
; #define PG8_LDB(dst, b, h) do { _Pragma("unroll") for (int n = 0; n < 2; ++n) _Pragma("unroll") for (int k = 0; k < 2; ++k) dst[n][k] = *(const LAS bf16x8*)(lds + PG8_SB(b, h) + boff + n * 2048 + k * 1024); } while (0)
; #define PG8_MMA(ai, bj, At, Bt) do { __builtin_amdgcn_s_setprio(1); _Pragma("unroll") for (int m = 0; m < 4; ++m) _Pragma("unroll") for (int n = 0; n < 2; ++n) _Pragma("unroll") for (int k = 0; k < 2; ++k) \
;     acc[ai][bj][m][n] = __builtin_amdgcn_mfma_f32_16x16x32_bf16(Bt[n][k], At[m][k], acc[ai][bj][m][n], 0, 0, 0); __builtin_amdgcn_s_setprio(0); } while (0)
; #define PG8_WAIT_V(n) asm volatile("s_waitcnt vmcnt(" #n ")" ::: "memory")
; #define PG8_WAIT_L(n) asm volatile("s_waitcnt lgkmcnt(" #n ")" ::: "memory")
; #define PG8_BAR __builtin_amdgcn_s_barrier()
; #define PG8_SCHED __builtin_amdgcn_sched_barrier(0)
; template <class Epi, class Sched = StaticOrder>
; DI void gemm_phase(LAS unsigned char* lds, const Gemm g, const Sched& S, const Epi& E) {
;     ...
;       PG8_BAR; PG8_WAIT_L(0); PG8_MMA(0, 1, At, B1); PG8_BAR;
;       PG8_LDA(At, 0, 1); PG8_STAGE(PG8_SA(0, 0), a2, voffA);
;       PG8_BAR; PG8_WAIT_L(0); PG8_MMA(1, 0, At, B0); PG8_BAR; PG8_SCHED;
;       PG8_STAGE(PG8_SB(0, 1), b2 + hstep, voffB);
;       PG8_WAIT_V(6); PG8_BAR; PG8_MMA(1, 1, At, B1); PG8_BAR;
;       PG8_LDB(B0, 1, 0); PG8_SCHED; PG8_LDA(At, 1, 0); PG8_STAGE(PG8_SA(0, 1), a2 + hstep, voffA);
;       PG8_WAIT_L(8); PG8_BAR; PG8_WAIT_L(0); PG8_MMA(0, 0, At, B0); PG8_BAR; PG8_SCHED;
;       PG8_LDB(B1, 1, 1); PG8_STAGE(PG8_SB(1, 0), b3, voffB);
;       PG8_BAR; PG8_WAIT_L(0); PG8_MMA(0, 1, At, B1); PG8_BAR;
	v_mfma_f32_16x16x32_bf16 v[116:119], v[192:195], v[144:147], v[116:119]
	v_mfma_f32_16x16x32_bf16 v[112:115], v[200:203], v[144:147], v[112:115]
	v_mfma_f32_16x16x32_bf16 v[100:103], v[192:195], v[152:155], v[100:103]
	v_mfma_f32_16x16x32_bf16 v[96:99], v[200:203], v[152:155], v[96:99]
	v_mfma_f32_16x16x32_bf16 v[84:87], v[192:195], v[160:163], v[84:87]
	v_mfma_f32_16x16x32_bf16 v[80:83], v[200:203], v[160:163], v[80:83]
	v_mfma_f32_16x16x32_bf16 v[68:71], v[192:195], v[168:171], v[68:71]
	v_mfma_f32_16x16x32_bf16 v[64:67], v[200:203], v[168:171], v[64:67]
	v_mfma_f32_16x16x32_bf16 v[116:119], v[196:199], v[148:151], v[116:119]
	ds_read_b128 v[144:147], v215 offset:16384
	v_mfma_f32_16x16x32_bf16 v[112:115], v[204:207], v[148:151], v[112:115]
	ds_read_b128 v[152:155], v215 offset:18432
	v_mfma_f32_16x16x32_bf16 v[100:103], v[196:199], v[156:159], v[100:103]
	ds_read_b128 v[160:163], v215 offset:20480
	v_mfma_f32_16x16x32_bf16 v[96:99], v[204:207], v[156:159], v[96:99]
	ds_read_b128 v[168:171], v215 offset:22528
	v_mfma_f32_16x16x32_bf16 v[84:87], v[196:199], v[164:167], v[84:87]
	v_mfma_f32_16x16x32_bf16 v[80:83], v[204:207], v[164:167], v[80:83]
	v_mfma_f32_16x16x32_bf16 v[68:71], v[196:199], v[172:175], v[68:71]
	v_mfma_f32_16x16x32_bf16 v[64:67], v[204:207], v[172:175], v[64:67]
	s_barrier
	s_setprio 0
	s_mov_b32 m0, s31
	s_add_u32 s100, s22, 0x80
	s_addc_u32 s101, s23, 0
	ds_read_b128 v[148:151], v215 offset:17408
	ds_read_b128 v[156:159], v215 offset:19456
	ds_read_b128 v[164:167], v215 offset:21504
	ds_read_b128 v[172:175], v215 offset:23552
	global_load_lds_dwordx4 v176, s[22:23]
	s_mov_b32 m0, s33
	s_nop 0
	global_load_lds_dwordx4 v180, s[22:23]
	s_waitcnt vmcnt(8)
	s_waitcnt lgkmcnt(0)
	s_setprio 1
	s_barrier
	v_mfma_f32_16x16x32_bf16 v[60:63], v[128:131], v[144:147], v[60:63]
	v_mfma_f32_16x16x32_bf16 v[56:59], v[136:139], v[144:147], v[56:59]
	v_mfma_f32_16x16x32_bf16 v[44:47], v[128:131], v[152:155], v[44:47]
	v_mfma_f32_16x16x32_bf16 v[40:43], v[136:139], v[152:155], v[40:43]
	v_mfma_f32_16x16x32_bf16 v[28:31], v[128:131], v[160:163], v[28:31]
	v_mfma_f32_16x16x32_bf16 v[24:27], v[136:139], v[160:163], v[24:27]
	v_mfma_f32_16x16x32_bf16 v[12:15], v[128:131], v[168:171], v[12:15]
	v_mfma_f32_16x16x32_bf16 v[8:11], v[136:139], v[168:171], v[8:11]
	v_mfma_f32_16x16x32_bf16 v[60:63], v[132:135], v[148:151], v[60:63]
	v_mfma_f32_16x16x32_bf16 v[56:59], v[140:143], v[148:151], v[56:59]
	v_mfma_f32_16x16x32_bf16 v[44:47], v[132:135], v[156:159], v[44:47]
	v_mfma_f32_16x16x32_bf16 v[40:43], v[140:143], v[156:159], v[40:43]
	v_mfma_f32_16x16x32_bf16 v[28:31], v[132:135], v[164:167], v[28:31]
	v_mfma_f32_16x16x32_bf16 v[24:27], v[140:143], v[164:167], v[24:27]
	v_mfma_f32_16x16x32_bf16 v[12:15], v[132:135], v[172:175], v[12:15]
	v_mfma_f32_16x16x32_bf16 v[8:11], v[140:143], v[172:175], v[8:11]
	s_barrier
	s_setprio 0
	s_add_u32 s52, s20, 0x160000
	s_addc_u32 s53, s21, 0
	s_add_i32 s45, s47, s30
	s_mov_b32 m0, s45
	s_nop 0
	global_load_lds_dwordx4 v178, s[52:53]
	s_add_i32 m0, s45, 0x2000
	s_nop 0
	global_load_lds_dwordx4 v182, s[52:53]
	s_add_i32 s45, 0, 0x18000
	v_add_u32_e32 v140, s45, v212
	ds_read_b128 v[128:131], v140
	ds_read_b128 v[132:135], v140 offset:1024
	ds_read_b128 v[136:139], v140 offset:2048
	ds_read_b128 v[140:143], v140 offset:3072
	s_waitcnt vmcnt(6)
	s_setprio 1
	s_barrier
	v_mfma_f32_16x16x32_bf16 v[52:55], v[192:195], v[144:147], v[52:55]
	v_mfma_f32_16x16x32_bf16 v[48:51], v[200:203], v[144:147], v[48:51]
	v_mfma_f32_16x16x32_bf16 v[36:39], v[192:195], v[152:155], v[36:39]
	v_mfma_f32_16x16x32_bf16 v[32:35], v[200:203], v[152:155], v[32:35]
	v_mfma_f32_16x16x32_bf16 v[20:23], v[192:195], v[160:163], v[20:23]
	v_mfma_f32_16x16x32_bf16 v[16:19], v[200:203], v[160:163], v[16:19]
	v_mfma_f32_16x16x32_bf16 v[4:7], v[192:195], v[168:171], v[4:7]
	v_mfma_f32_16x16x32_bf16 v[0:3], v[200:203], v[168:171], v[0:3]
	v_mfma_f32_16x16x32_bf16 v[52:55], v[196:199], v[148:151], v[52:55]
	ds_read_b128 v[144:147], v215 offset:32768
	v_mfma_f32_16x16x32_bf16 v[48:51], v[204:207], v[148:151], v[48:51]
	ds_read_b128 v[152:155], v215 offset:34816
	v_mfma_f32_16x16x32_bf16 v[36:39], v[196:199], v[156:159], v[36:39]
	ds_read_b128 v[160:163], v215 offset:36864
	v_mfma_f32_16x16x32_bf16 v[32:35], v[204:207], v[156:159], v[32:35]
	ds_read_b128 v[168:171], v215 offset:38912
	v_mfma_f32_16x16x32_bf16 v[20:23], v[196:199], v[164:167], v[20:23]
	v_mfma_f32_16x16x32_bf16 v[16:19], v[204:207], v[164:167], v[16:19]
	v_mfma_f32_16x16x32_bf16 v[4:7], v[196:199], v[172:175], v[4:7]
	v_mfma_f32_16x16x32_bf16 v[0:3], v[204:207], v[172:175], v[0:3]
	s_barrier
	s_setprio 0
	s_add_u32 s22, s22, 0x160000
	s_addc_u32 s23, s23, 0
	s_mov_b32 m0, s34
	ds_read_b128 v[148:151], v215 offset:33792
	ds_read_b128 v[156:159], v215 offset:35840
	ds_read_b128 v[164:167], v215 offset:37888
	ds_read_b128 v[172:175], v215 offset:39936
	global_load_lds_dwordx4 v176, s[22:23]
	s_mov_b32 m0, s35
	s_nop 0
	global_load_lds_dwordx4 v180, s[22:23]
	s_waitcnt lgkmcnt(0)
	s_waitcnt vmcnt(8)
	s_setprio 1
	s_barrier
; #define PG8_STAGE(bufoff, gbase, voff) do { _Pragma("unroll") for (int _i = 0; _i < 2; ++_i) \
;     __builtin_amdgcn_global_load_lds((const unsigned*)((const char*)(gbase) + (voff)[_i]), (LAS unsigned*)(lds + (bufoff) + ldsw + _i * 8192), 16, 0, 0); } while (0)
; #define PG8_LDA(dst, b, h) do { _Pragma("unroll") for (int m = 0; m < 4; ++m) _Pragma("unroll") for (int k = 0; k < 2; ++k) dst[m][k] = *(const LAS bf16x8*)(lds + PG8_SA(b, h) + aoff + m * 2048 + k * 1024); } while (0)
; #define PG8_MMA(ai, bj, At, Bt) do { __builtin_amdgcn_s_setprio(1); _Pragma("unroll") for (int m = 0; m < 4; ++m) _Pragma("unroll") for (int n = 0; n < 2; ++n) _Pragma("unroll") for (int k = 0; k < 2; ++k) \
;     acc[ai][bj][m][n] = __builtin_amdgcn_mfma_f32_16x16x32_bf16(Bt[n][k], At[m][k], acc[ai][bj][m][n], 0, 0, 0); __builtin_amdgcn_s_setprio(0); } while (0)
; #define PG8_WAIT_V(n) asm volatile("s_waitcnt vmcnt(" #n ")" ::: "memory")
; #define PG8_WAIT_L(n) asm volatile("s_waitcnt lgkmcnt(" #n ")" ::: "memory")
; #define PG8_BAR __builtin_amdgcn_s_barrier()
; #define PG8_SCHED __builtin_amdgcn_sched_barrier(0)
; template <class Epi, class Sched = StaticOrder>
; DI void gemm_phase(LAS unsigned char* lds, const Gemm g, const Sched& S, const Epi& E) {
;     ...
;       PG8_BAR; PG8_WAIT_L(0); PG8_MMA(0, 1, At, B1); PG8_BAR;
;       PG8_LDA(At, 1, 1); PG8_STAGE(PG8_SA(1, 0), a3, voffA);
;       PG8_BAR; PG8_WAIT_L(0); PG8_MMA(1, 0, At, B0); PG8_BAR; PG8_SCHED;
;       PG8_STAGE(PG8_SB(1, 1), b3 + hstep, voffB);
;       PG8_WAIT_V(6); PG8_BAR; PG8_MMA(1, 1, At, B1); PG8_BAR;
	v_mfma_f32_16x16x32_bf16 v[124:127], v[128:131], v[144:147], v[124:127]
	v_mfma_f32_16x16x32_bf16 v[120:123], v[136:139], v[144:147], v[120:123]
	v_mfma_f32_16x16x32_bf16 v[108:111], v[128:131], v[152:155], v[108:111]
	v_mfma_f32_16x16x32_bf16 v[104:107], v[136:139], v[152:155], v[104:107]
	v_mfma_f32_16x16x32_bf16 v[92:95], v[128:131], v[160:163], v[92:95]
	v_mfma_f32_16x16x32_bf16 v[88:91], v[136:139], v[160:163], v[88:91]
	v_mfma_f32_16x16x32_bf16 v[76:79], v[128:131], v[168:171], v[76:79]
	v_mfma_f32_16x16x32_bf16 v[72:75], v[136:139], v[168:171], v[72:75]
	v_mfma_f32_16x16x32_bf16 v[124:127], v[132:135], v[148:151], v[124:127]
	v_mfma_f32_16x16x32_bf16 v[120:123], v[140:143], v[148:151], v[120:123]
	v_mfma_f32_16x16x32_bf16 v[108:111], v[132:135], v[156:159], v[108:111]
	v_mfma_f32_16x16x32_bf16 v[104:107], v[140:143], v[156:159], v[104:107]
	v_mfma_f32_16x16x32_bf16 v[92:95], v[132:135], v[164:167], v[92:95]
	v_mfma_f32_16x16x32_bf16 v[88:91], v[140:143], v[164:167], v[88:91]
	v_mfma_f32_16x16x32_bf16 v[76:79], v[132:135], v[172:175], v[76:79]
	v_mfma_f32_16x16x32_bf16 v[72:75], v[140:143], v[172:175], v[72:75]
	s_barrier
	s_setprio 0
	s_add_i32 s22, 0, 0x1c000
	s_add_i32 s23, s45, s30
	v_add_u32_e32 v204, s22, v212
	s_mov_b32 m0, s23
	ds_read_b128 v[192:195], v204
	ds_read_b128 v[196:199], v204 offset:1024
	ds_read_b128 v[200:203], v204 offset:2048
	ds_read_b128 v[204:207], v204 offset:3072
	global_load_lds_dwordx4 v178, s[98:99]
	s_add_i32 m0, s23, 0x2000
	s_nop 0
	global_load_lds_dwordx4 v182, s[98:99]
	s_waitcnt lgkmcnt(0)
	s_setprio 1
	s_barrier
	v_mfma_f32_16x16x32_bf16 v[116:119], v[192:195], v[144:147], v[116:119]
	v_mfma_f32_16x16x32_bf16 v[112:115], v[200:203], v[144:147], v[112:115]
	v_mfma_f32_16x16x32_bf16 v[100:103], v[192:195], v[152:155], v[100:103]
	v_mfma_f32_16x16x32_bf16 v[96:99], v[200:203], v[152:155], v[96:99]
	v_mfma_f32_16x16x32_bf16 v[84:87], v[192:195], v[160:163], v[84:87]
	v_mfma_f32_16x16x32_bf16 v[80:83], v[200:203], v[160:163], v[80:83]
	v_mfma_f32_16x16x32_bf16 v[68:71], v[192:195], v[168:171], v[68:71]
	v_mfma_f32_16x16x32_bf16 v[64:67], v[200:203], v[168:171], v[64:67]
	v_mfma_f32_16x16x32_bf16 v[116:119], v[196:199], v[148:151], v[116:119]
	ds_read_b128 v[144:147], v215 offset:49152
	v_mfma_f32_16x16x32_bf16 v[112:115], v[204:207], v[148:151], v[112:115]
	ds_read_b128 v[152:155], v215 offset:51200
	v_mfma_f32_16x16x32_bf16 v[100:103], v[196:199], v[156:159], v[100:103]
	ds_read_b128 v[160:163], v215 offset:53248
	v_mfma_f32_16x16x32_bf16 v[96:99], v[204:207], v[156:159], v[96:99]
	ds_read_b128 v[168:171], v215 offset:55296
	v_mfma_f32_16x16x32_bf16 v[84:87], v[196:199], v[164:167], v[84:87]
	v_mfma_f32_16x16x32_bf16 v[80:83], v[204:207], v[164:167], v[80:83]
	v_mfma_f32_16x16x32_bf16 v[68:71], v[196:199], v[172:175], v[68:71]
	v_mfma_f32_16x16x32_bf16 v[64:67], v[204:207], v[172:175], v[64:67]
	s_barrier
	s_setprio 0
	s_mov_b32 m0, s37
	ds_read_b128 v[148:151], v215 offset:50176
	ds_read_b128 v[156:159], v215 offset:52224
	ds_read_b128 v[164:167], v215 offset:54272
	ds_read_b128 v[172:175], v215 offset:56320
	global_load_lds_dwordx4 v176, s[100:101]
	s_mov_b32 m0, s38
	s_nop 0
	global_load_lds_dwordx4 v180, s[100:101]
	s_waitcnt vmcnt(8)
	s_waitcnt lgkmcnt(0)
	s_setprio 1
	s_barrier
	v_mfma_f32_16x16x32_bf16 v[60:63], v[128:131], v[144:147], v[60:63]
	v_mfma_f32_16x16x32_bf16 v[56:59], v[136:139], v[144:147], v[56:59]
	v_mfma_f32_16x16x32_bf16 v[44:47], v[128:131], v[152:155], v[44:47]
	v_mfma_f32_16x16x32_bf16 v[40:43], v[136:139], v[152:155], v[40:43]
	v_mfma_f32_16x16x32_bf16 v[28:31], v[128:131], v[160:163], v[28:31]
	v_mfma_f32_16x16x32_bf16 v[24:27], v[136:139], v[160:163], v[24:27]
	v_mfma_f32_16x16x32_bf16 v[12:15], v[128:131], v[168:171], v[12:15]
	v_mfma_f32_16x16x32_bf16 v[8:11], v[136:139], v[168:171], v[8:11]
	v_mfma_f32_16x16x32_bf16 v[60:63], v[132:135], v[148:151], v[60:63]
	v_mfma_f32_16x16x32_bf16 v[56:59], v[140:143], v[148:151], v[56:59]
	v_mfma_f32_16x16x32_bf16 v[44:47], v[132:135], v[156:159], v[44:47]
	v_mfma_f32_16x16x32_bf16 v[40:43], v[140:143], v[156:159], v[40:43]
	v_mfma_f32_16x16x32_bf16 v[28:31], v[132:135], v[164:167], v[28:31]
	v_mfma_f32_16x16x32_bf16 v[24:27], v[140:143], v[164:167], v[24:27]
	v_mfma_f32_16x16x32_bf16 v[12:15], v[132:135], v[172:175], v[12:15]
	v_mfma_f32_16x16x32_bf16 v[8:11], v[140:143], v[172:175], v[8:11]
	s_barrier
	s_setprio 0
	s_add_u32 s20, s20, 0x160080
	s_addc_u32 s21, s21, 0
	s_add_i32 s22, s22, s30
	s_mov_b32 m0, s22
	s_nop 0
	global_load_lds_dwordx4 v178, s[20:21]
	s_add_i32 m0, s22, 0x2000
	s_nop 0
	global_load_lds_dwordx4 v182, s[20:21]
	ds_read_b128 v[128:131], v214
	ds_read_b128 v[132:135], v214 offset:1024
	ds_read_b128 v[136:139], v214 offset:2048
	ds_read_b128 v[140:143], v214 offset:3072
	s_waitcnt vmcnt(6)
	s_add_i32 s44, s44, 2
	s_add_u32 s18, s18, 0x100
	s_addc_u32 s19, s19, 0
	s_add_u32 s42, s42, 0x100
	s_addc_u32 s43, s43, 0
	s_cmpk_gt_u32 s44, 0x55
	s_setprio 1
	s_barrier
; DI unsigned pack2(float lo, float hi) { f32x2 v = {lo, hi}; bf16v2 r = __builtin_convertvector(v, bf16v2); return __builtin_bit_cast(unsigned, r); }
; #define PG8_MMA(ai, bj, At, Bt) do { __builtin_amdgcn_s_setprio(1); _Pragma("unroll") for (int m = 0; m < 4; ++m) _Pragma("unroll") for (int n = 0; n < 2; ++n) _Pragma("unroll") for (int k = 0; k < 2; ++k) \
;     acc[ai][bj][m][n] = __builtin_amdgcn_mfma_f32_16x16x32_bf16(Bt[n][k], At[m][k], acc[ai][bj][m][n], 0, 0, 0); __builtin_amdgcn_s_setprio(0); } while (0)
; #define PG8_BAR __builtin_amdgcn_s_barrier()
;   DI void operator()(const f32x4 (&acc)[2][2][4][2], const Unit& u, int wr, int wc, int fr, int fq) const {
;     const int row0 = u.pm * BM + wr * 64 + fr, col0 = u.pn * BM + wc * 32 + 8 * fq;
; #pragma unroll
;     for (int ai = 0; ai < 2; ++ai) {
;       f32x4 bv[4][2][2];
; #pragma unroll
;       for (int m = 0; m < 4; ++m)
; #pragma unroll
;         for (int bj = 0; bj < 2; ++bj) {
;           const float* bp = base + (size_t)(row0 + ai * HALF + m * 16) * 2048 + col0 + bj * HALF;
;           bv[m][bj][0] = *(const f32x4*)bp; bv[m][bj][1] = *(const f32x4*)(bp + 4);
;         }
; #pragma unroll
;       for (int m = 0; m < 4; ++m) {
;         const int row = row0 + ai * HALF + m * 16;
;         const size_t off = (size_t)row * 2048 + col0;
;         float ss = 0.f;
; #pragma unroll
;         for (int bj = 0; bj < 2; ++bj) {
;           const f32x4 v0 = acc[ai][bj][m][0] + bv[m][bj][0], v1 = acc[ai][bj][m][1] + bv[m][bj][1];
;           *(f32x4*)(C + off + bj * HALF) = v0; *(f32x4*)(C + off + bj * HALF + 4) = v1;
;           if (xb) {
;             u32x4 w; w.x = pack2(v0[0], v0[1]); w.y = pack2(v0[2], v0[3]); w.z = pack2(v1[0], v1[1]); w.w = pack2(v1[2], v1[3]);
;             *(u32x4*)(xb + off + bj * HALF) = w;
;             ss += v0[0] * v0[0] + v0[1] * v0[1] + v0[2] * v0[2] + v0[3] * v0[3] + v1[0] * v1[0] + v1[1] * v1[1] + v1[2] * v1[2] + v1[3] * v1[3];
;           }
;         }
;         if (xb) {
;           ss += __shfl_xor(ss, 16); ss += __shfl_xor(ss, 32);
;           if (fq == 0) ssq[(size_t)row * 32 + u.pn * 4 + wc] = ss;
;         }
; template <class Epi, class Sched = StaticOrder>
; DI void gemm_phase(LAS unsigned char* lds, const Gemm g, const Sched& S, const Epi& E) {
;     ...
;       PG8_WAIT_V(6); PG8_BAR; PG8_MMA(1, 1, At, B1); PG8_BAR;
;     }
;     E(acc, cur, wr, wc, fr, fq);
	v_mfma_f32_16x16x32_bf16 v[52:55], v[192:195], v[144:147], v[52:55]
	v_mfma_f32_16x16x32_bf16 v[48:51], v[200:203], v[144:147], v[48:51]
	v_mfma_f32_16x16x32_bf16 v[36:39], v[192:195], v[152:155], v[36:39]
	v_mfma_f32_16x16x32_bf16 v[32:35], v[200:203], v[152:155], v[32:35]
	v_mfma_f32_16x16x32_bf16 v[20:23], v[192:195], v[160:163], v[20:23]
	v_mfma_f32_16x16x32_bf16 v[16:19], v[200:203], v[160:163], v[16:19]
	v_mfma_f32_16x16x32_bf16 v[4:7], v[192:195], v[168:171], v[4:7]
	v_mfma_f32_16x16x32_bf16 v[0:3], v[200:203], v[168:171], v[0:3]
	v_mfma_f32_16x16x32_bf16 v[52:55], v[196:199], v[148:151], v[52:55]
	ds_read_b128 v[144:147], v215
	v_mfma_f32_16x16x32_bf16 v[48:51], v[204:207], v[148:151], v[48:51]
	ds_read_b128 v[152:155], v215 offset:2048
	v_mfma_f32_16x16x32_bf16 v[36:39], v[196:199], v[156:159], v[36:39]
	ds_read_b128 v[160:163], v215 offset:4096
	v_mfma_f32_16x16x32_bf16 v[32:35], v[204:207], v[156:159], v[32:35]
	ds_read_b128 v[168:171], v215 offset:6144
	v_mfma_f32_16x16x32_bf16 v[20:23], v[196:199], v[164:167], v[20:23]
	v_mfma_f32_16x16x32_bf16 v[16:19], v[204:207], v[164:167], v[16:19]
	v_mfma_f32_16x16x32_bf16 v[4:7], v[196:199], v[172:175], v[4:7]
	v_mfma_f32_16x16x32_bf16 v[0:3], v[204:207], v[172:175], v[0:3]
	s_barrier
	s_setprio 0
	s_cbranch_scc0 .LBB0_961
	s_waitcnt lgkmcnt(0)
	v_lshl_add_u32 v194, s51, 8, v211
	v_lshl_or_b32 v192, s2, 8, v213
	v_readlane_b32 s52, v243, 3
	v_ashrrev_i32_e32 v193, 31, v192
	v_readlane_b32 s66, v243, 17
	v_readlane_b32 s67, v243, 18
	v_ashrrev_i32_e32 v195, 31, v194
	v_lshlrev_b64 v[128:129], 13, v[194:195]
	v_lshl_add_u64 v[196:197], v[192:193], 2, s[66:67]
	v_lshl_add_u64 v[236:237], v[196:197], 0, v[128:129]
	global_load_dwordx4 v[220:223], v[236:237], off
	global_load_dwordx4 v[224:227], v[236:237], off offset:16
	global_load_dwordx4 v[228:231], v[236:237], off offset:512
	global_load_dwordx4 v[232:235], v[236:237], off offset:528
	v_or_b32_e32 v206, 16, v194
	v_or_b32_e32 v202, 32, v194
	v_or_b32_e32 v198, 48, v194
	v_ashrrev_i32_e32 v207, 31, v206
	v_ashrrev_i32_e32 v203, 31, v202
	v_ashrrev_i32_e32 v199, 31, v198
	v_lshlrev_b64 v[128:129], 13, v[206:207]
	v_lshlrev_b64 v[130:131], 13, v[202:203]
	v_lshlrev_b64 v[132:133], 13, v[198:199]
	v_lshl_add_u64 v[208:209], v[196:197], 0, v[128:129]
	v_lshl_add_u64 v[204:205], v[196:197], 0, v[130:131]
	v_lshl_add_u64 v[200:201], v[196:197], 0, v[132:133]
	global_load_dwordx4 v[168:171], v[208:209], off offset:16
	global_load_dwordx4 v[172:175], v[208:209], off
	global_load_dwordx4 v[160:163], v[208:209], off offset:528
	global_load_dwordx4 v[164:167], v[208:209], off offset:512
	global_load_dwordx4 v[152:155], v[204:205], off offset:16
	global_load_dwordx4 v[156:159], v[204:205], off
	global_load_dwordx4 v[144:147], v[204:205], off offset:528
	global_load_dwordx4 v[148:151], v[204:205], off offset:512
	global_load_dwordx4 v[136:139], v[200:201], off offset:16
	global_load_dwordx4 v[140:143], v[200:201], off
	global_load_dwordx4 v[128:131], v[200:201], off offset:528
	global_load_dwordx4 v[132:135], v[200:201], off offset:512
	v_and_b32_e32 v218, 64, v217
	v_xor_b32_e32 v238, 16, v217
	v_add_u32_e32 v240, 64, v218
	v_xor_b32_e32 v239, 32, v217
	v_cmp_lt_i32_e32 vcc, v238, v240
	v_lshlrev_b64 v[218:219], 11, v[194:195]
	s_lshl_b32 s18, s2, 2
	v_cndmask_b32_e32 v241, v217, v238, vcc
	v_cmp_lt_i32_e32 vcc, v239, v240
	s_ashr_i32 s19, s18, 31
	v_readlane_b32 s53, v243, 4
	v_cndmask_b32_e32 v240, v217, v239, vcc
	v_lshl_add_u64 v[238:239], v[218:219], 0, v[192:193]
	v_lshlrev_b32_e32 v218, 2, v241
	v_lshl_add_u64 v[238:239], v[238:239], 1, s[12:13]
	v_readlane_b32 s54, v243, 5
	v_readlane_b32 s55, v243, 6
	v_readlane_b32 s56, v243, 7
	v_readlane_b32 s57, v243, 8
	v_readlane_b32 s58, v243, 9
	v_readlane_b32 s59, v243, 10
	v_readlane_b32 s60, v243, 11
	v_readlane_b32 s61, v243, 12
	v_readlane_b32 s62, v243, 13
	v_readlane_b32 s63, v243, 14
	v_readlane_b32 s64, v243, 15
	v_readlane_b32 s65, v243, 16
	s_waitcnt vmcnt(0)
	v_pk_add_f32 v[126:127], v[126:127], v[222:223]
	v_pk_add_f32 v[124:125], v[124:125], v[220:221]
	v_pk_add_f32 v[116:117], v[116:117], v[228:229]
	v_pk_add_f32 v[122:123], v[122:123], v[226:227]
	v_pk_add_f32 v[120:121], v[120:121], v[224:225]
	v_pk_add_f32 v[220:221], v[112:113], v[232:233]
	global_store_dwordx4 v[236:237], v[124:127], off
	global_store_dwordx4 v[236:237], v[120:123], off offset:16
	v_cvt_pk_bf16_f32 v112, v124, v125
	v_mul_f32_e32 v125, v125, v125
	v_mul_f32_e32 v219, v117, v117
	v_pk_add_f32 v[118:119], v[118:119], v[230:231]
	v_fmac_f32_e32 v125, v124, v124
	v_fmac_f32_e32 v219, v116, v116
	v_fmac_f32_e32 v125, v126, v126
	v_fmac_f32_e32 v219, v118, v118
	v_fmac_f32_e32 v125, v127, v127
	v_fmac_f32_e32 v219, v119, v119
	v_fmac_f32_e32 v125, v120, v120
	v_fmac_f32_e32 v219, v220, v220
	v_pk_add_f32 v[222:223], v[114:115], v[234:235]
	v_fmac_f32_e32 v125, v121, v121
	v_fmac_f32_e32 v219, v221, v221
	v_fmac_f32_e32 v125, v122, v122
	v_fmac_f32_e32 v219, v222, v222
	v_fmac_f32_e32 v125, v123, v123
	v_fmac_f32_e32 v219, v223, v223
	v_cvt_pk_bf16_f32 v114, v120, v121
	v_add_f32_e32 v121, v125, v219
	v_cvt_pk_bf16_f32 v115, v122, v123
	ds_bpermute_b32 v122, v218, v121
	v_cvt_pk_bf16_f32 v113, v126, v127
	global_store_dwordx4 v[238:239], v[112:115], off
	global_store_dwordx4 v[236:237], v[116:119], off offset:512
	global_store_dwordx4 v[236:237], v[220:223], off offset:528
	v_lshlrev_b32_e32 v126, 2, v240
	v_cvt_pk_bf16_f32 v120, v116, v117
	s_waitcnt lgkmcnt(0)
	v_add_f32_e32 v112, v121, v122
	ds_bpermute_b32 v113, v126, v112
	v_cvt_pk_bf16_f32 v121, v118, v119
	v_cvt_pk_bf16_f32 v122, v220, v221
	v_cvt_pk_bf16_f32 v123, v222, v223
	global_store_dwordx4 v[238:239], v[120:123], off offset:256
	s_and_saveexec_b64 s[20:21], s[0:1]
	s_cbranch_execz .LBB0_964
	s_waitcnt lgkmcnt(0)
	v_add_f32_e32 v114, v112, v113
	v_lshlrev_b64 v[112:113], 7, v[194:195]
	v_lshl_add_u64 v[112:113], s[14:15], 0, v[112:113]
	v_lshl_add_u64 v[112:113], s[18:19], 2, v[112:113]
	s_lshl_b32 s2, s36, 2
	v_lshl_add_u64 v[112:113], v[112:113], 0, s[2:3]
	global_store_dword v[112:113], v114, off

; #define PG8_STAGE(bufoff, gbase, voff) do { _Pragma("unroll") for (int _i = 0; _i < 2; ++_i) \
;     __builtin_amdgcn_global_load_lds((const unsigned*)((const char*)(gbase) + (voff)[_i]), (LAS unsigned*)(lds + (bufoff) + ldsw + _i * 8192), 16, 0, 0); } while (0)
; #define PG8_LDA(dst, b, h) do { _Pragma("unroll") for (int m = 0; m < 4; ++m) _Pragma("unroll") for (int k = 0; k < 2; ++k) dst[m][k] = *(const LAS bf16x8*)(lds + PG8_SA(b, h) + aoff + m * 2048 + k * 1024); } while (0)
; #define PG8_LDB(dst, b, h) do { _Pragma("unroll") for (int n = 0; n < 2; ++n) _Pragma("unroll") for (int k = 0; k < 2; ++k) dst[n][k] = *(const LAS bf16x8*)(lds + PG8_SB(b, h) + boff + n * 2048 + k * 1024); } while (0)
; #define PG8_MMA(ai, bj, At, Bt) do { __builtin_amdgcn_s_setprio(1); _Pragma("unroll") for (int m = 0; m < 4; ++m) _Pragma("unroll") for (int n = 0; n < 2; ++n) _Pragma("unroll") for (int k = 0; k < 2; ++k) \
;     acc[ai][bj][m][n] = __builtin_amdgcn_mfma_f32_16x16x32_bf16(Bt[n][k], At[m][k], acc[ai][bj][m][n], 0, 0, 0); __builtin_amdgcn_s_setprio(0); } while (0)
; #define PG8_WAIT_L(n) asm volatile("s_waitcnt lgkmcnt(" #n ")" ::: "memory")
; #define PG8_BAR __builtin_amdgcn_s_barrier()
; #define PG8_SCHED __builtin_amdgcn_sched_barrier(0)
; template <class Epi, class Sched = StaticOrder>
; DI void gemm_phase(LAS unsigned char* lds, const Gemm g, const Sched& S, const Epi& E) {
;     ...
;     const bool has_next = S.next(ui + 1, nxt);
;     const char* nA = has_next ? (const char*)g.A + (size_t)nxt.pm * tstep : cA; const char* nB = has_next ? (const char*)g.Bt + (size_t)nxt.pn * tstep : cB;
;     for (int t = 0; t < nt; t += 2) {
;       const bool last = (t == nt - 2);
;       const char* a1 = cA + (size_t)(t + 1) * kstep;
;       const char* a2 = last ? nA : cA + (size_t)(t + 2) * kstep; const char* b2 = last ? nB : cB + (size_t)(t + 2) * kstep;
;       const char* a3 = a2 + kstep; const char* b3 = b2 + kstep;
;       PG8_LDB(B0, 0, 0); PG8_SCHED; PG8_LDA(At, 0, 0); PG8_STAGE(PG8_SA(1, 1), a1 + hstep, voffA);
;       PG8_WAIT_L(8); PG8_BAR; PG8_WAIT_L(0); PG8_MMA(0, 0, At, B0); PG8_BAR; PG8_SCHED;
.LBB0_1051:
	s_ashr_i32 s41, s40, 31
	s_lshl_b64 s[42:43], s[40:41], 20
	s_add_u32 s88, s66, s42
	s_addc_u32 s89, s67, s43
	s_and_b64 s[42:43], s[64:65], exec
	s_cselect_b32 s41, s89, s11
	s_cselect_b32 s42, s88, s10
	s_ashr_i32 s87, s86, 31
	s_lshl_b64 s[44:45], s[86:87], 20
	s_add_u32 s90, s68, s44
	s_addc_u32 s91, s69, s45
	s_and_b64 s[44:45], s[64:65], exec
	s_cselect_b32 s43, s91, s13
	s_cselect_b32 s44, s90, s12
	s_add_u32 s10, s10, 0x80080
	s_addc_u32 s11, s11, 0
	s_add_u32 s45, s12, 0x100
	v_mov_b32_e32 v0, 0
	s_addc_u32 s49, s13, 0
	s_mov_b32 s52, -2
	v_mov_b32_e32 v1, v0
	v_mov_b32_e32 v2, v0
	v_mov_b32_e32 v3, v0
	v_mov_b32_e32 v4, v0
	v_mov_b32_e32 v5, v0
	v_mov_b32_e32 v6, v0
	v_mov_b32_e32 v7, v0
	v_mov_b32_e32 v16, v0
	v_mov_b32_e32 v17, v0
	v_mov_b32_e32 v18, v0
	v_mov_b32_e32 v19, v0
	v_mov_b32_e32 v20, v0
	v_mov_b32_e32 v21, v0
	v_mov_b32_e32 v22, v0
	v_mov_b32_e32 v23, v0
	v_mov_b32_e32 v32, v0
	v_mov_b32_e32 v33, v0
	v_mov_b32_e32 v34, v0
	v_mov_b32_e32 v35, v0
	v_mov_b32_e32 v36, v0
	v_mov_b32_e32 v37, v0
	v_mov_b32_e32 v38, v0
	v_mov_b32_e32 v39, v0
	v_mov_b32_e32 v44, v0
	v_mov_b32_e32 v45, v0
	v_mov_b32_e32 v46, v0
	v_mov_b32_e32 v47, v0
	v_mov_b32_e32 v52, v0
	v_mov_b32_e32 v53, v0
	v_mov_b32_e32 v54, v0
	v_mov_b32_e32 v55, v0
	v_mov_b32_e32 v8, v0
	v_mov_b32_e32 v9, v0
	v_mov_b32_e32 v10, v0
	v_mov_b32_e32 v11, v0
	v_mov_b32_e32 v12, v0
	v_mov_b32_e32 v13, v0
	v_mov_b32_e32 v14, v0
	v_mov_b32_e32 v15, v0
	v_mov_b32_e32 v24, v0
	v_mov_b32_e32 v25, v0
	v_mov_b32_e32 v26, v0
	v_mov_b32_e32 v27, v0
	v_mov_b32_e32 v28, v0
	v_mov_b32_e32 v29, v0
	v_mov_b32_e32 v30, v0
	v_mov_b32_e32 v31, v0
	v_mov_b32_e32 v40, v0
	v_mov_b32_e32 v41, v0
	v_mov_b32_e32 v42, v0
	v_mov_b32_e32 v43, v0
	v_mov_b32_e32 v48, v0
	v_mov_b32_e32 v49, v0
	v_mov_b32_e32 v50, v0
	v_mov_b32_e32 v51, v0
	v_mov_b32_e32 v56, v0
	v_mov_b32_e32 v57, v0
	v_mov_b32_e32 v58, v0
	v_mov_b32_e32 v59, v0
	v_mov_b32_e32 v60, v0
	v_mov_b32_e32 v61, v0
	v_mov_b32_e32 v62, v0
	v_mov_b32_e32 v63, v0
	v_mov_b32_e32 v64, v0
	v_mov_b32_e32 v65, v0
	v_mov_b32_e32 v66, v0
	v_mov_b32_e32 v67, v0
	v_mov_b32_e32 v68, v0
	v_mov_b32_e32 v69, v0
	v_mov_b32_e32 v70, v0
	v_mov_b32_e32 v71, v0
	v_mov_b32_e32 v76, v0
	v_mov_b32_e32 v77, v0
	v_mov_b32_e32 v78, v0
	v_mov_b32_e32 v79, v0
	v_mov_b32_e32 v80, v0
	v_mov_b32_e32 v81, v0
	v_mov_b32_e32 v82, v0
	v_mov_b32_e32 v83, v0
	v_mov_b32_e32 v96, v0
	v_mov_b32_e32 v97, v0
	v_mov_b32_e32 v98, v0
	v_mov_b32_e32 v99, v0
	v_mov_b32_e32 v100, v0
	v_mov_b32_e32 v101, v0
	v_mov_b32_e32 v102, v0
	v_mov_b32_e32 v103, v0
	v_mov_b32_e32 v108, v0
	v_mov_b32_e32 v109, v0
	v_mov_b32_e32 v110, v0
	v_mov_b32_e32 v111, v0
	v_mov_b32_e32 v112, v0
	v_mov_b32_e32 v113, v0
	v_mov_b32_e32 v114, v0
	v_mov_b32_e32 v115, v0
	v_mov_b32_e32 v72, v0
	v_mov_b32_e32 v73, v0
	v_mov_b32_e32 v74, v0
	v_mov_b32_e32 v75, v0
	v_mov_b32_e32 v84, v0
	v_mov_b32_e32 v85, v0
	v_mov_b32_e32 v86, v0
	v_mov_b32_e32 v87, v0
	v_mov_b32_e32 v88, v0
	v_mov_b32_e32 v89, v0
	v_mov_b32_e32 v90, v0
	v_mov_b32_e32 v91, v0
	v_mov_b32_e32 v92, v0
	v_mov_b32_e32 v93, v0
	v_mov_b32_e32 v94, v0
	v_mov_b32_e32 v95, v0
	v_mov_b32_e32 v104, v0
	v_mov_b32_e32 v105, v0
	v_mov_b32_e32 v106, v0
	v_mov_b32_e32 v107, v0
	v_mov_b32_e32 v116, v0
	v_mov_b32_e32 v117, v0
	v_mov_b32_e32 v118, v0
	v_mov_b32_e32 v119, v0
	v_mov_b32_e32 v120, v0
	v_mov_b32_e32 v121, v0
	v_mov_b32_e32 v122, v0
	v_mov_b32_e32 v123, v0
	v_mov_b32_e32 v124, v0
	v_mov_b32_e32 v125, v0
	v_mov_b32_e32 v126, v0
	v_mov_b32_e32 v127, v0
	ds_read_b128 v[128:131], v203
	ds_read_b128 v[132:135], v203 offset:1024
	ds_read_b128 v[136:139], v203 offset:2048
	ds_read_b128 v[140:143], v203 offset:3072
	ds_read_b128 v[144:147], v204
	ds_read_b128 v[152:155], v204 offset:2048
	ds_read_b128 v[178:181], v204 offset:4096
	ds_read_b128 v[186:189], v204 offset:6144
.LBB0_1052:
	s_add_u32 s12, s10, 0xfff80080
	s_addc_u32 s13, s11, -1
	s_cmp_eq_u32 s52, 28
	s_cselect_b32 s65, s41, s13
	s_cselect_b32 s64, s42, s12
	s_cselect_b32 s13, s43, s49
	s_cselect_b32 s12, s44, s45
	s_add_i32 m0, s61, 0xc000
	ds_read_b128 v[148:151], v204 offset:1024
	ds_read_b128 v[156:159], v204 offset:3072
	ds_read_b128 v[182:185], v204 offset:5120
	ds_read_b128 v[190:193], v204 offset:7168
	global_load_lds_dwordx4 v172, s[10:11]
	s_add_i32 m0, s61, 0xe000
	s_nop 0
	global_load_lds_dwordx4 v174, s[10:11]
	s_waitcnt lgkmcnt(0)
	s_waitcnt vmcnt(8)
	s_setprio 1
	s_barrier
	v_mfma_f32_16x16x32_bf16 v[124:127], v[128:131], v[144:147], v[124:127]
	v_mfma_f32_16x16x32_bf16 v[120:123], v[136:139], v[144:147], v[120:123]
	v_mfma_f32_16x16x32_bf16 v[116:119], v[128:131], v[152:155], v[116:119]
	v_mfma_f32_16x16x32_bf16 v[104:107], v[136:139], v[152:155], v[104:107]
	v_mfma_f32_16x16x32_bf16 v[92:95], v[128:131], v[178:181], v[92:95]
	v_mfma_f32_16x16x32_bf16 v[88:91], v[136:139], v[178:181], v[88:91]
	v_mfma_f32_16x16x32_bf16 v[84:87], v[128:131], v[186:189], v[84:87]
	v_mfma_f32_16x16x32_bf16 v[72:75], v[136:139], v[186:189], v[72:75]
	v_mfma_f32_16x16x32_bf16 v[124:127], v[132:135], v[148:151], v[124:127]
	v_mfma_f32_16x16x32_bf16 v[120:123], v[140:143], v[148:151], v[120:123]
	v_mfma_f32_16x16x32_bf16 v[116:119], v[132:135], v[156:159], v[116:119]
	v_mfma_f32_16x16x32_bf16 v[104:107], v[140:143], v[156:159], v[104:107]
	v_mfma_f32_16x16x32_bf16 v[92:95], v[132:135], v[182:185], v[92:95]
	v_mfma_f32_16x16x32_bf16 v[88:91], v[140:143], v[182:185], v[88:91]
	v_mfma_f32_16x16x32_bf16 v[84:87], v[132:135], v[190:193], v[84:87]
	v_mfma_f32_16x16x32_bf16 v[72:75], v[140:143], v[190:193], v[72:75]
	s_barrier
; #define PG8_STAGE(bufoff, gbase, voff) do { _Pragma("unroll") for (int _i = 0; _i < 2; ++_i) \
;     __builtin_amdgcn_global_load_lds((const unsigned*)((const char*)(gbase) + (voff)[_i]), (LAS unsigned*)(lds + (bufoff) + ldsw + _i * 8192), 16, 0, 0); } while (0)
; #define PG8_LDA(dst, b, h) do { _Pragma("unroll") for (int m = 0; m < 4; ++m) _Pragma("unroll") for (int k = 0; k < 2; ++k) dst[m][k] = *(const LAS bf16x8*)(lds + PG8_SA(b, h) + aoff + m * 2048 + k * 1024); } while (0)
; #define PG8_LDB(dst, b, h) do { _Pragma("unroll") for (int n = 0; n < 2; ++n) _Pragma("unroll") for (int k = 0; k < 2; ++k) dst[n][k] = *(const LAS bf16x8*)(lds + PG8_SB(b, h) + boff + n * 2048 + k * 1024); } while (0)
; #define PG8_MMA(ai, bj, At, Bt) do { __builtin_amdgcn_s_setprio(1); _Pragma("unroll") for (int m = 0; m < 4; ++m) _Pragma("unroll") for (int n = 0; n < 2; ++n) _Pragma("unroll") for (int k = 0; k < 2; ++k) \
;     acc[ai][bj][m][n] = __builtin_amdgcn_mfma_f32_16x16x32_bf16(Bt[n][k], At[m][k], acc[ai][bj][m][n], 0, 0, 0); __builtin_amdgcn_s_setprio(0); } while (0)
; #define PG8_WAIT_V(n) asm volatile("s_waitcnt vmcnt(" #n ")" ::: "memory")
; #define PG8_WAIT_L(n) asm volatile("s_waitcnt lgkmcnt(" #n ")" ::: "memory")
; #define PG8_BAR __builtin_amdgcn_s_barrier()
; #define PG8_SCHED __builtin_amdgcn_sched_barrier(0)
; template <class Epi, class Sched = StaticOrder>
; DI void gemm_phase(LAS unsigned char* lds, const Gemm g, const Sched& S, const Epi& E) {
;     ...
;       PG8_WAIT_L(8); PG8_BAR; PG8_WAIT_L(0); PG8_MMA(0, 0, At, B0); PG8_BAR; PG8_SCHED;
;       PG8_LDB(B1, 0, 1); PG8_STAGE(PG8_SB(0, 0), b2, voffB);
;       PG8_BAR; PG8_WAIT_L(0); PG8_MMA(0, 1, At, B1); PG8_BAR;
;       PG8_LDA(At, 0, 1); PG8_STAGE(PG8_SA(0, 0), a2, voffA);
;       PG8_BAR; PG8_WAIT_L(0); PG8_MMA(1, 0, At, B0); PG8_BAR; PG8_SCHED;
;       PG8_STAGE(PG8_SB(0, 1), b2 + hstep, voffB);
;       PG8_WAIT_V(6); PG8_BAR; PG8_MMA(1, 1, At, B1); PG8_BAR;
;       PG8_LDB(B0, 1, 0); PG8_SCHED; PG8_LDA(At, 1, 0); PG8_STAGE(PG8_SA(0, 1), a2 + hstep, voffA);
;       PG8_WAIT_L(8); PG8_BAR; PG8_WAIT_L(0); PG8_MMA(0, 0, At, B0); PG8_BAR; PG8_SCHED;
	s_setprio 0
	s_add_i32 s53, s80, s70
	s_add_u32 s98, s12, 0x80
	s_addc_u32 s99, s13, 0
	s_mov_b32 m0, s53
	ds_read_b128 v[194:197], v205
	ds_read_b128 v[212:215], v205 offset:1024
	ds_read_b128 v[216:219], v205 offset:2048
	ds_read_b128 v[220:223], v205 offset:3072
	global_load_lds_dwordx4 v162, s[12:13]
	s_add_i32 m0, s53, 0x2000
	s_nop 0
	global_load_lds_dwordx4 v166, s[12:13]
	s_waitcnt lgkmcnt(0)
	s_setprio 1
	s_barrier
	v_mfma_f32_16x16x32_bf16 v[112:115], v[194:197], v[144:147], v[112:115]
	v_mfma_f32_16x16x32_bf16 v[108:111], v[216:219], v[144:147], v[108:111]
	v_mfma_f32_16x16x32_bf16 v[100:103], v[194:197], v[152:155], v[100:103]
	v_mfma_f32_16x16x32_bf16 v[96:99], v[216:219], v[152:155], v[96:99]
	v_mfma_f32_16x16x32_bf16 v[80:83], v[194:197], v[178:181], v[80:83]
	v_mfma_f32_16x16x32_bf16 v[76:79], v[216:219], v[178:181], v[76:79]
	v_mfma_f32_16x16x32_bf16 v[68:71], v[194:197], v[186:189], v[68:71]
	v_mfma_f32_16x16x32_bf16 v[64:67], v[216:219], v[186:189], v[64:67]
	v_mfma_f32_16x16x32_bf16 v[112:115], v[212:215], v[148:151], v[112:115]
	ds_read_b128 v[144:147], v204 offset:16384
	v_mfma_f32_16x16x32_bf16 v[108:111], v[220:223], v[148:151], v[108:111]
	ds_read_b128 v[152:155], v204 offset:18432
	v_mfma_f32_16x16x32_bf16 v[100:103], v[212:215], v[156:159], v[100:103]
	ds_read_b128 v[178:181], v204 offset:20480
	v_mfma_f32_16x16x32_bf16 v[96:99], v[220:223], v[156:159], v[96:99]
	ds_read_b128 v[186:189], v204 offset:22528
	v_mfma_f32_16x16x32_bf16 v[80:83], v[212:215], v[182:185], v[80:83]
	v_mfma_f32_16x16x32_bf16 v[76:79], v[220:223], v[182:185], v[76:79]
	v_mfma_f32_16x16x32_bf16 v[68:71], v[212:215], v[190:193], v[68:71]
	v_mfma_f32_16x16x32_bf16 v[64:67], v[220:223], v[190:193], v[64:67]
	s_barrier
	s_setprio 0
	s_mov_b32 m0, s61
	s_add_u32 s100, s64, 0x80
	s_addc_u32 s101, s65, 0
	ds_read_b128 v[148:151], v204 offset:17408
	ds_read_b128 v[156:159], v204 offset:19456
	ds_read_b128 v[182:185], v204 offset:21504
	ds_read_b128 v[190:193], v204 offset:23552
	global_load_lds_dwordx4 v160, s[64:65]
	s_mov_b32 m0, s63
	s_nop 0
	global_load_lds_dwordx4 v164, s[64:65]
	s_waitcnt vmcnt(8)
	s_waitcnt lgkmcnt(0)
	s_setprio 1
	s_barrier
	v_mfma_f32_16x16x32_bf16 v[60:63], v[128:131], v[144:147], v[60:63]
	v_mfma_f32_16x16x32_bf16 v[56:59], v[136:139], v[144:147], v[56:59]
	v_mfma_f32_16x16x32_bf16 v[48:51], v[128:131], v[152:155], v[48:51]
	v_mfma_f32_16x16x32_bf16 v[40:43], v[136:139], v[152:155], v[40:43]
	v_mfma_f32_16x16x32_bf16 v[28:31], v[128:131], v[178:181], v[28:31]
	v_mfma_f32_16x16x32_bf16 v[24:27], v[136:139], v[178:181], v[24:27]
	v_mfma_f32_16x16x32_bf16 v[12:15], v[128:131], v[186:189], v[12:15]
	v_mfma_f32_16x16x32_bf16 v[8:11], v[136:139], v[186:189], v[8:11]
	v_mfma_f32_16x16x32_bf16 v[60:63], v[132:135], v[148:151], v[60:63]
	v_mfma_f32_16x16x32_bf16 v[56:59], v[140:143], v[148:151], v[56:59]
	v_mfma_f32_16x16x32_bf16 v[48:51], v[132:135], v[156:159], v[48:51]
	v_mfma_f32_16x16x32_bf16 v[40:43], v[140:143], v[156:159], v[40:43]
	v_mfma_f32_16x16x32_bf16 v[28:31], v[132:135], v[182:185], v[28:31]
	v_mfma_f32_16x16x32_bf16 v[24:27], v[140:143], v[182:185], v[24:27]
	v_mfma_f32_16x16x32_bf16 v[12:15], v[132:135], v[190:193], v[12:15]
	v_mfma_f32_16x16x32_bf16 v[8:11], v[140:143], v[190:193], v[8:11]
	s_barrier
	s_setprio 0
	s_add_u32 s54, s12, 0x80000
	s_addc_u32 s55, s13, 0
	s_add_i32 s53, s81, s70
	s_mov_b32 m0, s53
	s_nop 0
	global_load_lds_dwordx4 v162, s[54:55]
	s_add_i32 m0, s53, 0x2000
	s_nop 0
	global_load_lds_dwordx4 v166, s[54:55]
	s_add_i32 s53, 0, 0x18000
	v_add_u32_e32 v140, s53, v199
	ds_read_b128 v[128:131], v140
	ds_read_b128 v[132:135], v140 offset:1024
	ds_read_b128 v[136:139], v140 offset:2048
	ds_read_b128 v[140:143], v140 offset:3072
	s_waitcnt vmcnt(6)
	s_setprio 1
	s_barrier
	v_mfma_f32_16x16x32_bf16 v[52:55], v[194:197], v[144:147], v[52:55]
	v_mfma_f32_16x16x32_bf16 v[44:47], v[216:219], v[144:147], v[44:47]
	v_mfma_f32_16x16x32_bf16 v[36:39], v[194:197], v[152:155], v[36:39]
	v_mfma_f32_16x16x32_bf16 v[32:35], v[216:219], v[152:155], v[32:35]
	v_mfma_f32_16x16x32_bf16 v[20:23], v[194:197], v[178:181], v[20:23]
	v_mfma_f32_16x16x32_bf16 v[16:19], v[216:219], v[178:181], v[16:19]
	v_mfma_f32_16x16x32_bf16 v[4:7], v[194:197], v[186:189], v[4:7]
	v_mfma_f32_16x16x32_bf16 v[0:3], v[216:219], v[186:189], v[0:3]
	v_mfma_f32_16x16x32_bf16 v[52:55], v[212:215], v[148:151], v[52:55]
	ds_read_b128 v[144:147], v204 offset:32768
	v_mfma_f32_16x16x32_bf16 v[44:47], v[220:223], v[148:151], v[44:47]
	ds_read_b128 v[152:155], v204 offset:34816
	v_mfma_f32_16x16x32_bf16 v[36:39], v[212:215], v[156:159], v[36:39]
	ds_read_b128 v[178:181], v204 offset:36864
	v_mfma_f32_16x16x32_bf16 v[32:35], v[220:223], v[156:159], v[32:35]
	ds_read_b128 v[186:189], v204 offset:38912
	v_mfma_f32_16x16x32_bf16 v[20:23], v[212:215], v[182:185], v[20:23]
	v_mfma_f32_16x16x32_bf16 v[16:19], v[220:223], v[182:185], v[16:19]
	v_mfma_f32_16x16x32_bf16 v[4:7], v[212:215], v[190:193], v[4:7]
	v_mfma_f32_16x16x32_bf16 v[0:3], v[220:223], v[190:193], v[0:3]
	s_barrier
	s_setprio 0
	s_add_u32 s54, s64, 0x80000
	s_addc_u32 s55, s65, 0
	s_mov_b32 m0, s71
	ds_read_b128 v[148:151], v204 offset:33792
	ds_read_b128 v[156:159], v204 offset:35840
	ds_read_b128 v[182:185], v204 offset:37888
	ds_read_b128 v[190:193], v204 offset:39936
	global_load_lds_dwordx4 v160, s[54:55]
	s_mov_b32 m0, s72
	s_nop 0
	global_load_lds_dwordx4 v164, s[54:55]
	s_waitcnt lgkmcnt(0)
	s_waitcnt vmcnt(8)
	s_setprio 1
	s_barrier
; #define PG8_STAGE(bufoff, gbase, voff) do { _Pragma("unroll") for (int _i = 0; _i < 2; ++_i) \
;     __builtin_amdgcn_global_load_lds((const unsigned*)((const char*)(gbase) + (voff)[_i]), (LAS unsigned*)(lds + (bufoff) + ldsw + _i * 8192), 16, 0, 0); } while (0)
; #define PG8_LDA(dst, b, h) do { _Pragma("unroll") for (int m = 0; m < 4; ++m) _Pragma("unroll") for (int k = 0; k < 2; ++k) dst[m][k] = *(const LAS bf16x8*)(lds + PG8_SA(b, h) + aoff + m * 2048 + k * 1024); } while (0)
; #define PG8_LDB(dst, b, h) do { _Pragma("unroll") for (int n = 0; n < 2; ++n) _Pragma("unroll") for (int k = 0; k < 2; ++k) dst[n][k] = *(const LAS bf16x8*)(lds + PG8_SB(b, h) + boff + n * 2048 + k * 1024); } while (0)
; #define PG8_MMA(ai, bj, At, Bt) do { __builtin_amdgcn_s_setprio(1); _Pragma("unroll") for (int m = 0; m < 4; ++m) _Pragma("unroll") for (int n = 0; n < 2; ++n) _Pragma("unroll") for (int k = 0; k < 2; ++k) \
;     acc[ai][bj][m][n] = __builtin_amdgcn_mfma_f32_16x16x32_bf16(Bt[n][k], At[m][k], acc[ai][bj][m][n], 0, 0, 0); __builtin_amdgcn_s_setprio(0); } while (0)
; #define PG8_WAIT_V(n) asm volatile("s_waitcnt vmcnt(" #n ")" ::: "memory")
; #define PG8_WAIT_L(n) asm volatile("s_waitcnt lgkmcnt(" #n ")" ::: "memory")
; #define PG8_BAR __builtin_amdgcn_s_barrier()
; #define PG8_SCHED __builtin_amdgcn_sched_barrier(0)
; template <class Epi, class Sched = StaticOrder>
; DI void gemm_phase(LAS unsigned char* lds, const Gemm g, const Sched& S, const Epi& E) {
;     ...
;       PG8_WAIT_L(8); PG8_BAR; PG8_WAIT_L(0); PG8_MMA(0, 0, At, B0); PG8_BAR; PG8_SCHED;
;       PG8_LDB(B1, 1, 1); PG8_STAGE(PG8_SB(1, 0), b3, voffB);
;       PG8_BAR; PG8_WAIT_L(0); PG8_MMA(0, 1, At, B1); PG8_BAR;
;       PG8_LDA(At, 1, 1); PG8_STAGE(PG8_SA(1, 0), a3, voffA);
;       PG8_BAR; PG8_WAIT_L(0); PG8_MMA(1, 0, At, B0); PG8_BAR; PG8_SCHED;
;       PG8_STAGE(PG8_SB(1, 1), b3 + hstep, voffB);
;       PG8_WAIT_V(6); PG8_BAR; PG8_MMA(1, 1, At, B1); PG8_BAR;
	v_mfma_f32_16x16x32_bf16 v[124:127], v[128:131], v[144:147], v[124:127]
	v_mfma_f32_16x16x32_bf16 v[120:123], v[136:139], v[144:147], v[120:123]
	v_mfma_f32_16x16x32_bf16 v[116:119], v[128:131], v[152:155], v[116:119]
	v_mfma_f32_16x16x32_bf16 v[104:107], v[136:139], v[152:155], v[104:107]
	v_mfma_f32_16x16x32_bf16 v[92:95], v[128:131], v[178:181], v[92:95]
	v_mfma_f32_16x16x32_bf16 v[88:91], v[136:139], v[178:181], v[88:91]
	v_mfma_f32_16x16x32_bf16 v[84:87], v[128:131], v[186:189], v[84:87]
	v_mfma_f32_16x16x32_bf16 v[72:75], v[136:139], v[186:189], v[72:75]
	v_mfma_f32_16x16x32_bf16 v[124:127], v[132:135], v[148:151], v[124:127]
	v_mfma_f32_16x16x32_bf16 v[120:123], v[140:143], v[148:151], v[120:123]
	v_mfma_f32_16x16x32_bf16 v[116:119], v[132:135], v[156:159], v[116:119]
	v_mfma_f32_16x16x32_bf16 v[104:107], v[140:143], v[156:159], v[104:107]
	v_mfma_f32_16x16x32_bf16 v[92:95], v[132:135], v[182:185], v[92:95]
	v_mfma_f32_16x16x32_bf16 v[88:91], v[140:143], v[182:185], v[88:91]
	v_mfma_f32_16x16x32_bf16 v[84:87], v[132:135], v[190:193], v[84:87]
	v_mfma_f32_16x16x32_bf16 v[72:75], v[140:143], v[190:193], v[72:75]
	s_barrier
	s_setprio 0
	s_add_i32 s54, 0, 0x1c000
	s_add_i32 s53, s53, s70
	v_add_u32_e32 v168, s54, v199
	s_mov_b32 m0, s53
	ds_read_b128 v[194:197], v168
	ds_read_b128 v[212:215], v168 offset:1024
	ds_read_b128 v[216:219], v168 offset:2048
	ds_read_b128 v[220:223], v168 offset:3072
	global_load_lds_dwordx4 v162, s[98:99]
	s_add_i32 m0, s53, 0x2000
	s_nop 0
	global_load_lds_dwordx4 v166, s[98:99]
	s_waitcnt lgkmcnt(0)
	s_setprio 1
	s_barrier
	v_mfma_f32_16x16x32_bf16 v[112:115], v[194:197], v[144:147], v[112:115]
	v_mfma_f32_16x16x32_bf16 v[108:111], v[216:219], v[144:147], v[108:111]
	v_mfma_f32_16x16x32_bf16 v[100:103], v[194:197], v[152:155], v[100:103]
	v_mfma_f32_16x16x32_bf16 v[96:99], v[216:219], v[152:155], v[96:99]
	v_mfma_f32_16x16x32_bf16 v[80:83], v[194:197], v[178:181], v[80:83]
	v_mfma_f32_16x16x32_bf16 v[76:79], v[216:219], v[178:181], v[76:79]
	v_mfma_f32_16x16x32_bf16 v[68:71], v[194:197], v[186:189], v[68:71]
	v_mfma_f32_16x16x32_bf16 v[64:67], v[216:219], v[186:189], v[64:67]
	v_mfma_f32_16x16x32_bf16 v[112:115], v[212:215], v[148:151], v[112:115]
	ds_read_b128 v[144:147], v204 offset:49152
	v_mfma_f32_16x16x32_bf16 v[108:111], v[220:223], v[148:151], v[108:111]
	ds_read_b128 v[152:155], v204 offset:51200
	v_mfma_f32_16x16x32_bf16 v[100:103], v[212:215], v[156:159], v[100:103]
	ds_read_b128 v[178:181], v204 offset:53248
	v_mfma_f32_16x16x32_bf16 v[96:99], v[220:223], v[156:159], v[96:99]
	ds_read_b128 v[186:189], v204 offset:55296
	v_mfma_f32_16x16x32_bf16 v[80:83], v[212:215], v[182:185], v[80:83]
	v_mfma_f32_16x16x32_bf16 v[76:79], v[220:223], v[182:185], v[76:79]
	v_mfma_f32_16x16x32_bf16 v[68:71], v[212:215], v[190:193], v[68:71]
	v_mfma_f32_16x16x32_bf16 v[64:67], v[220:223], v[190:193], v[64:67]
	s_barrier
	s_setprio 0
	s_mov_b32 m0, s76
	ds_read_b128 v[148:151], v204 offset:50176
	ds_read_b128 v[156:159], v204 offset:52224
	ds_read_b128 v[182:185], v204 offset:54272
	ds_read_b128 v[190:193], v204 offset:56320
	global_load_lds_dwordx4 v160, s[100:101]
	s_mov_b32 m0, s77
	s_nop 0
	global_load_lds_dwordx4 v164, s[100:101]
	s_waitcnt vmcnt(8)
	s_waitcnt lgkmcnt(0)
	s_setprio 1
	s_barrier
	v_mfma_f32_16x16x32_bf16 v[60:63], v[128:131], v[144:147], v[60:63]
	v_mfma_f32_16x16x32_bf16 v[56:59], v[136:139], v[144:147], v[56:59]
	v_mfma_f32_16x16x32_bf16 v[48:51], v[128:131], v[152:155], v[48:51]
	v_mfma_f32_16x16x32_bf16 v[40:43], v[136:139], v[152:155], v[40:43]
	v_mfma_f32_16x16x32_bf16 v[28:31], v[128:131], v[178:181], v[28:31]
	v_mfma_f32_16x16x32_bf16 v[24:27], v[136:139], v[178:181], v[24:27]
	v_mfma_f32_16x16x32_bf16 v[12:15], v[128:131], v[186:189], v[12:15]
	v_mfma_f32_16x16x32_bf16 v[8:11], v[136:139], v[186:189], v[8:11]
	v_mfma_f32_16x16x32_bf16 v[60:63], v[132:135], v[148:151], v[60:63]
	v_mfma_f32_16x16x32_bf16 v[56:59], v[140:143], v[148:151], v[56:59]
	v_mfma_f32_16x16x32_bf16 v[48:51], v[132:135], v[156:159], v[48:51]
	v_mfma_f32_16x16x32_bf16 v[40:43], v[140:143], v[156:159], v[40:43]
	v_mfma_f32_16x16x32_bf16 v[28:31], v[132:135], v[182:185], v[28:31]
	v_mfma_f32_16x16x32_bf16 v[24:27], v[140:143], v[182:185], v[24:27]
	v_mfma_f32_16x16x32_bf16 v[12:15], v[132:135], v[190:193], v[12:15]
	v_mfma_f32_16x16x32_bf16 v[8:11], v[140:143], v[190:193], v[8:11]
	s_barrier
	s_setprio 0
	s_add_u32 s12, s12, 0x80080
	s_addc_u32 s13, s13, 0
	s_add_i32 s53, s54, s70
	s_mov_b32 m0, s53
	s_nop 0
	global_load_lds_dwordx4 v162, s[12:13]
	s_add_i32 m0, s53, 0x2000
	s_nop 0
	global_load_lds_dwordx4 v166, s[12:13]
	ds_read_b128 v[128:131], v203
	ds_read_b128 v[132:135], v203 offset:1024
	ds_read_b128 v[136:139], v203 offset:2048
	ds_read_b128 v[140:143], v203 offset:3072
	s_waitcnt vmcnt(6)
	s_add_i32 s52, s52, 2
	s_add_u32 s10, s10, 0x100
	s_addc_u32 s11, s11, 0
	s_add_u32 s45, s45, 0x100
	s_addc_u32 s49, s49, 0
	s_cmp_gt_u32 s52, 29
	s_setprio 1
	s_barrier
	v_mfma_f32_16x16x32_bf16 v[52:55], v[194:197], v[144:147], v[52:55]
	v_mfma_f32_16x16x32_bf16 v[44:47], v[216:219], v[144:147], v[44:47]
	v_mfma_f32_16x16x32_bf16 v[36:39], v[194:197], v[152:155], v[36:39]
	v_mfma_f32_16x16x32_bf16 v[32:35], v[216:219], v[152:155], v[32:35]
	v_mfma_f32_16x16x32_bf16 v[20:23], v[194:197], v[178:181], v[20:23]
	v_mfma_f32_16x16x32_bf16 v[16:19], v[216:219], v[178:181], v[16:19]
	v_mfma_f32_16x16x32_bf16 v[4:7], v[194:197], v[186:189], v[4:7]
	v_mfma_f32_16x16x32_bf16 v[0:3], v[216:219], v[186:189], v[0:3]
	v_mfma_f32_16x16x32_bf16 v[52:55], v[212:215], v[148:151], v[52:55]
	ds_read_b128 v[144:147], v204
	v_mfma_f32_16x16x32_bf16 v[44:47], v[220:223], v[148:151], v[44:47]
	ds_read_b128 v[152:155], v204 offset:2048
	v_mfma_f32_16x16x32_bf16 v[36:39], v[212:215], v[156:159], v[36:39]
	ds_read_b128 v[178:181], v204 offset:4096
	v_mfma_f32_16x16x32_bf16 v[32:35], v[220:223], v[156:159], v[32:35]
	ds_read_b128 v[186:189], v204 offset:6144
	v_mfma_f32_16x16x32_bf16 v[20:23], v[212:215], v[182:185], v[20:23]
	v_mfma_f32_16x16x32_bf16 v[16:19], v[220:223], v[182:185], v[16:19]
	v_mfma_f32_16x16x32_bf16 v[4:7], v[212:215], v[190:193], v[4:7]
	v_mfma_f32_16x16x32_bf16 v[0:3], v[220:223], v[190:193], v[0:3]
	s_barrier
;   DI void operator()(const f32x4 (&acc)[2][2][4][2], const Unit& u, int wr, int wc, int fr, int fq) const {
;     if (u.pn >= 16) {
;       const int row0 = u.pm * BM + wr * 64 + fr, col0 = (u.pn - 16) * BM + wc * 32 + 8 * fq;
;     ...
;     const int col = u.pn * 128 + wc * 32 + 8 * fq;
;     float w0[8], w1[8], w2[8];
; #pragma unroll
;     for (int e = 0; e < 8; ++e) { w0[e] = cw[col + e]; w1[e] = cw[2048 + col + e]; w2[e] = cw[4096 + col + e]; }
; #pragma unroll
;     for (int ai = 0; ai < 2; ++ai) {
;       const int row0 = u.pm * BM + ai * HALF + wr * 64, span = row0 >> 6;
;       float rsv[4];
; #pragma unroll
;       for (int m = 0; m < 4; ++m) rsv[m] = row_rstd(ssq, row0 + 16 * m + fr, fq);
	s_setprio 0
	s_cbranch_scc0 .LBB0_1052
	s_waitcnt lgkmcnt(0)
	s_cmp_lt_i32 s62, 16
	s_mov_b64 s[10:11], -1
	s_cbranch_scc0 .LBB0_1067
	s_lshl_b32 s41, s60, 8
	s_add_i32 s41, s41, s75
	v_or_b32_e32 v186, s41, v177
	v_ashrrev_i32_e32 v187, 31, v186
	v_lshlrev_b64 v[128:129], 7, v[186:187]
	v_or_b32_e32 v180, 16, v186
	v_lshl_add_u64 v[128:129], v[170:171], 0, v[128:129]
	v_ashrrev_i32_e32 v181, 31, v180
	global_load_dwordx4 v[152:155], v[128:129], off
	global_load_dwordx4 v[156:159], v[128:129], off offset:16
	v_lshlrev_b64 v[128:129], 7, v[180:181]
	v_lshl_add_u64 v[128:129], v[170:171], 0, v[128:129]
	global_load_dwordx4 v[188:191], v[128:129], off
	global_load_dwordx4 v[192:195], v[128:129], off offset:16
	v_or_b32_e32 v184, 32, v186
	v_ashrrev_i32_e32 v185, 31, v184
	v_lshlrev_b64 v[128:129], 7, v[184:185]
	v_or_b32_e32 v182, 48, v186
	v_lshl_add_u64 v[128:129], v[170:171], 0, v[128:129]
	v_ashrrev_i32_e32 v183, 31, v182
	global_load_dwordx4 v[212:215], v[128:129], off
	global_load_dwordx4 v[216:219], v[128:129], off offset:16
	v_lshlrev_b64 v[128:129], 7, v[182:183]
	v_lshl_add_u64 v[128:129], v[170:171], 0, v[128:129]
	global_load_dwordx4 v[220:223], v[128:129], off
	global_load_dwordx4 v[224:227], v[128:129], off offset:16
	v_and_b32_e32 v129, 64, v206
	v_lshl_or_b32 v178, s62, 7, v200
	v_xor_b32_e32 v128, 16, v206
	v_add_u32_e32 v129, 64, v129
	v_readlane_b32 s44, v243, 3
	v_xor_b32_e32 v130, 32, v206
	v_ashrrev_i32_e32 v179, 31, v178
	v_readlane_b32 s45, v243, 4
	v_cmp_lt_i32_e32 vcc, v128, v129
	s_movk_i32 s10, 0x2000
	v_lshl_add_u64 v[144:145], v[178:179], 2, s[44:45]
	v_cndmask_b32_e32 v134, v206, v128, vcc
	v_cmp_lt_i32_e32 vcc, v130, v129
	v_lshl_add_u64 v[132:133], v[144:145], 0, s[26:27]
	v_lshl_add_u64 v[136:137], v[144:145], 0, s[28:29]
	v_cndmask_b32_e32 v135, v206, v130, vcc
	v_add_co_u32_e32 v146, vcc, s10, v144
	global_load_dwordx4 v[128:131], v[144:145], off offset:16
	global_load_dwordx4 v[140:143], v[144:145], off
	v_addc_co_u32_e32 v147, vcc, 0, v145, vcc
	v_add_co_u32_e32 v148, vcc, s74, v144
	v_lshlrev_b32_e32 v196, 2, v134
	s_nop 0
	v_addc_co_u32_e32 v149, vcc, 0, v145, vcc
	v_lshlrev_b32_e32 v207, 2, v135
	global_load_dwordx4 v[132:135], v[132:133], off offset:16
	s_nop 0
	global_load_dwordx4 v[136:139], v[136:137], off offset:16
	s_nop 0
	global_load_dwordx4 v[144:147], v[146:147], off
	s_nop 0
	global_load_dwordx4 v[148:151], v[148:149], off
	v_mov_b32_e32 v197, 0
	v_mov_b32_e32 v211, 0
	v_readlane_b32 s46, v243, 5
	v_readlane_b32 s47, v243, 6
	v_readlane_b32 s48, v243, 7
	v_readlane_b32 s49, v243, 8
	v_readlane_b32 s50, v243, 9
	v_readlane_b32 s51, v243, 10
	v_readlane_b32 s52, v243, 11
	v_readlane_b32 s53, v243, 12
	v_readlane_b32 s54, v243, 13
	v_readlane_b32 s55, v243, 14
	v_readlane_b32 s56, v243, 15
	v_readlane_b32 s57, v243, 16
	v_readlane_b32 s58, v243, 17
	v_readlane_b32 s59, v243, 18
	s_waitcnt vmcnt(0)
	v_mov_b32_e32 v208, v152
	v_mov_b32_e32 v209, v156
	v_mov_b32_e32 v156, v153
	v_mov_b32_e32 v152, v154
	v_mov_b32_e32 v153, v158
	v_mov_b32_e32 v158, v155
	v_pk_add_f32 v[154:155], v[208:209], v[156:157]
	v_pk_add_f32 v[152:153], v[152:153], v[158:159]
	v_mov_b32_e32 v156, v188
	v_mov_b32_e32 v157, v192
	v_mov_b32_e32 v192, v189
	v_mov_b32_e32 v158, v190
	v_mov_b32_e32 v159, v194
	v_mov_b32_e32 v194, v191
	v_pk_add_f32 v[152:153], v[154:155], v[152:153]
	v_pk_add_f32 v[154:155], v[156:157], v[192:193]
	v_pk_add_f32 v[156:157], v[158:159], v[194:195]
	v_mov_b32_e32 v188, v212
	v_pk_add_f32 v[154:155], v[154:155], v[156:157]
	v_mov_b32_e32 v157, v152
	v_mov_b32_e32 v156, v154
	v_mov_b32_e32 v152, v155
	v_pk_add_f32 v[152:153], v[156:157], v[152:153]
	ds_bpermute_b32 v155, v196, v153
	ds_bpermute_b32 v154, v196, v152
	v_mov_b32_e32 v189, v216
	v_mov_b32_e32 v216, v213
	v_mov_b32_e32 v190, v214
	v_mov_b32_e32 v191, v218
	s_waitcnt lgkmcnt(0)
	v_pk_add_f32 v[152:153], v[152:153], v[154:155]
	ds_bpermute_b32 v155, v207, v153
	ds_bpermute_b32 v154, v207, v152
	v_mov_b32_e32 v218, v215
	v_mov_b32_e32 v208, v220
	v_mov_b32_e32 v209, v224
	v_mov_b32_e32 v224, v221
	v_mov_b32_e32 v212, v222
	v_mov_b32_e32 v213, v226
	v_mov_b32_e32 v226, v223
	v_pk_add_f32 v[156:157], v[188:189], v[216:217]
	v_pk_add_f32 v[158:159], v[190:191], v[218:219]
	v_pk_add_f32 v[188:189], v[208:209], v[224:225]
	v_pk_add_f32 v[190:191], v[212:213], v[226:227]
	s_waitcnt lgkmcnt(0)
; DI unsigned pack2(float lo, float hi) { f32x2 v = {lo, hi}; bf16v2 r = __builtin_convertvector(v, bf16v2); return __builtin_bit_cast(unsigned, r); }
; DI float dpp_ror1(float v) { return __int_as_float(__builtin_amdgcn_update_dpp(0, __float_as_int(v), 0x121, 0xf, 0xf, false)); }
; DI float dpp_ror2(float v) { return __int_as_float(__builtin_amdgcn_update_dpp(0, __float_as_int(v), 0x122, 0xf, 0xf, false)); }
;   DI void operator()(const f32x4 (&acc)[2][2][4][2], const Unit& u, int wr, int wc, int fr, int fq) const {
;     ...
;       for (int m = 0; m < 4; ++m) {
;         float g[8], a[8];
;         const float rs1 = rsv[m], rs2 = rs1 * rs1;
; #pragma unroll
;         for (int e = 0; e < 4; ++e) { g[e] = acc[ai][0][m][0][e] * acc[ai][1][m][0][e] * rs2; g[4 + e] = acc[ai][0][m][1][e] * acc[ai][1][m][1][e] * rs2; }
; #pragma unroll
;         for (int e = 0; e < 8; ++e) {
;           const float x1 = dpp_ror1(g[e]), x2 = dpp_ror2(g[e]);
;           const float pr1 = (fr == 0) ? p1[e] : x1, pr2 = (fr < 2) ? p2[e] : x2;
;           a[e] = w2[e] * g[e] + w1[e] * pr1 + w0[e] * pr2;
;           p1[e] = x1; p2[e] = x2;
;         }
;         if (m == 0 && fr < 2) {
;           float* hc = headC + (size_t)(span * 2 + fr) * 2048 + col;
;           *(f32x4*)hc = (f32x4){a[0], a[1], a[2], a[3]}; *(f32x4*)(hc + 4) = (f32x4){a[4], a[5], a[6], a[7]};
;         } else {
;           u32x4 w; w.x = pack2(a[0] * rs1, a[1] * rs1); w.y = pack2(a[2] * rs1, a[3] * rs1); w.z = pack2(a[4] * rs1, a[5] * rs1); w.w = pack2(a[6] * rs1, a[7] * rs1);
;           *(u32x4*)(C + (size_t)(row0 + 16 * m + fr) * 2048 + col) = w;
;         }
	v_pk_add_f32 v[152:153], v[152:153], v[154:155]
	v_pk_add_f32 v[156:157], v[156:157], v[158:159]
	v_pk_add_f32 v[158:159], v[188:189], v[190:191]
	v_pk_fma_f32 v[188:189], v[152:153], s[30:31], v[176:177] op_sel_hi:[1,0,0]
	v_mov_b32_e32 v153, v156
	v_mul_f32_e32 v152, 0x4b800000, v189
	v_cmp_gt_f32_e64 s[10:11], s84, v189
	v_mov_b32_e32 v156, v159
	v_mov_b32_e32 v194, v123
	v_cndmask_b32_e64 v152, v189, v152, s[10:11]
	v_rsq_f32_e32 v168, v152
	v_mov_b32_e32 v152, v158
	v_pk_add_f32 v[152:153], v[152:153], v[156:157]
	ds_bpermute_b32 v155, v196, v153
	ds_bpermute_b32 v154, v196, v152
	v_mul_f32_e32 v156, 0x45800000, v168
	v_cndmask_b32_e64 v195, v168, v156, s[10:11]
	v_mov_b32_e32 v217, 0
	v_mul_f32_e32 v156, v125, v113
	s_waitcnt lgkmcnt(0)
	v_pk_add_f32 v[190:191], v[152:153], v[154:155]
	v_mov_b32_e32 v152, v111
	v_mov_b32_e32 v153, v195
	v_mul_f32_e32 v154, v124, v112
	v_pk_mul_f32 v[152:153], v[194:195], v[152:153]
	v_mul_f32_e32 v155, v120, v108
	v_mul_f32_e32 v154, v154, v153
	v_pk_mul_f32 v[222:223], v[152:153], v[152:153] op_sel:[0,1] op_sel_hi:[1,0]
	v_mov_b32_e32 v213, 0
	v_mov_b32_dpp v217, v154 row_ror:1 row_mask:0xf bank_mask:0xf
	v_cndmask_b32_e64 v152, v217, 0, s[0:1]
	v_mul_f32_e32 v157, v121, v109
	v_mul_f32_e32 v158, v126, v114
	v_mul_f32_e32 v159, v122, v110
	v_mul_f32_e32 v168, v127, v115
	v_mul_f32_e32 v194, v155, v153
	v_mul_f32_e32 v155, v156, v153
	v_mov_b32_dpp v213, v154 row_ror:2 row_mask:0xf bank_mask:0xf
	v_mov_b32_e32 v221, 0
	v_mul_f32_e32 v152, v144, v152
	v_mul_f32_e32 v208, v157, v153
	v_mul_f32_e32 v156, v158, v153
	v_mul_f32_e32 v159, v159, v153
	v_mul_f32_e32 v157, v168, v153
	v_mov_b32_dpp v221, v155 row_ror:1 row_mask:0xf bank_mask:0xf
	v_cndmask_b32_e64 v153, v213, 0, s[8:9]
	v_fmac_f32_e32 v152, v148, v154
	v_mov_b32_e32 v219, 0
	v_fmac_f32_e32 v152, v140, v153
	v_cndmask_b32_e64 v153, v221, 0, s[0:1]
	v_mov_b32_dpp v219, v155 row_ror:2 row_mask:0xf bank_mask:0xf
	v_mul_f32_e32 v153, v145, v153
	v_mov_b32_e32 v216, 0
	v_cndmask_b32_e64 v154, v219, 0, s[8:9]
	v_fmac_f32_e32 v153, v149, v155
	v_mov_b32_dpp v216, v156 row_ror:1 row_mask:0xf bank_mask:0xf
	v_fmac_f32_e32 v153, v141, v154
	v_mov_b32_e32 v212, 0
	v_cndmask_b32_e64 v154, v216, 0, s[0:1]
	v_mov_b32_e32 v220, 0
	v_mov_b32_dpp v212, v156 row_ror:2 row_mask:0xf bank_mask:0xf
	v_mul_f32_e32 v154, v146, v154
	v_mov_b32_dpp v220, v157 row_ror:1 row_mask:0xf bank_mask:0xf
	v_cndmask_b32_e64 v155, v212, 0, s[8:9]
	v_fmac_f32_e32 v154, v150, v156
	v_mov_b32_e32 v218, 0
	v_fmac_f32_e32 v154, v142, v155
	v_cndmask_b32_e64 v155, v220, 0, s[0:1]
	v_mov_b32_dpp v218, v157 row_ror:2 row_mask:0xf bank_mask:0xf
	v_mul_f32_e32 v155, v147, v155
	v_cndmask_b32_e64 v156, v218, 0, s[8:9]
	v_fmac_f32_e32 v155, v151, v157
	v_mov_b32_dpp v197, v194 row_ror:1 row_mask:0xf bank_mask:0xf
	v_fmac_f32_e32 v155, v143, v156
	v_mov_b32_e32 v189, 0
	v_cndmask_b32_e64 v156, v197, 0, s[0:1]
	v_mov_b32_e32 v214, 0
	v_mov_b32_dpp v189, v194 row_ror:2 row_mask:0xf bank_mask:0xf
	v_mul_f32_e32 v156, v132, v156
	v_mov_b32_dpp v214, v208 row_ror:1 row_mask:0xf bank_mask:0xf
	v_cndmask_b32_e64 v157, v189, 0, s[8:9]
	v_fmac_f32_e32 v156, v136, v194
	v_fmac_f32_e32 v156, v128, v157
	v_cndmask_b32_e64 v157, v214, 0, s[0:1]
	v_mov_b32_e32 v209, 0
	v_mul_f32_e32 v157, v133, v157
	v_fmac_f32_e32 v157, v137, v208
	v_mov_b32_dpp v209, v208 row_ror:2 row_mask:0xf bank_mask:0xf
	v_mov_b32_e32 v208, 0
	v_cndmask_b32_e64 v158, v209, 0, s[8:9]
	v_fmac_f32_e32 v157, v129, v158
	v_mov_b32_dpp v208, v159 row_ror:1 row_mask:0xf bank_mask:0xf
	v_mov_b32_e32 v194, 0
	v_cndmask_b32_e64 v158, v208, 0, s[0:1]
	ds_bpermute_b32 v193, v207, v191
	ds_bpermute_b32 v192, v207, v190
	v_mov_b32_dpp v194, v159 row_ror:2 row_mask:0xf bank_mask:0xf
	v_mov_b32_e32 v215, 0
	v_mul_f32_e32 v158, v134, v158
	v_cndmask_b32_e64 v168, v194, 0, s[8:9]
	v_mov_b32_dpp v215, v222 row_ror:1 row_mask:0xf bank_mask:0xf
	v_fmac_f32_e32 v158, v138, v159
	v_mov_b32_dpp v211, v222 row_ror:2 row_mask:0xf bank_mask:0xf
	v_fmac_f32_e32 v158, v130, v168
	v_cndmask_b32_e64 v168, v215, 0, s[0:1]
	v_mul_f32_e32 v159, v139, v222
	v_cndmask_b32_e64 v223, v211, 0, s[8:9]
	v_fmac_f32_e32 v159, v135, v168
	v_cmp_gt_f32_e32 vcc, s84, v188
	v_fmac_f32_e32 v159, v131, v223
	s_and_saveexec_b64 s[10:11], s[4:5]
	s_xor_b64 s[10:11], exec, s[10:11]
	s_cbranch_execz .LBB0_1056
	v_mul_f32_e32 v152, v195, v152
	v_mul_f32_e32 v153, v195, v153
	v_cvt_pk_bf16_f32 v152, v152, v153
	v_mul_f32_e32 v153, v195, v154
	v_mul_f32_e32 v154, v195, v155
	v_cvt_pk_bf16_f32 v153, v153, v154
	v_mul_f32_e32 v154, v195, v156
	v_mul_f32_e32 v155, v195, v157
	v_cvt_pk_bf16_f32 v154, v154, v155
	v_mul_f32_e32 v155, v195, v158
	v_mul_f32_e32 v156, v195, v159
	v_cvt_pk_bf16_f32 v155, v155, v156
	v_lshlrev_b64 v[156:157], 12, v[186:187]
	v_lshl_add_u64 v[156:157], s[18:19], 0, v[156:157]
	v_lshl_add_u64 v[156:157], v[178:179], 1, v[156:157]
	global_store_dwordx4 v[156:157], v[152:155], off

; #define PG8_STAGE(bufoff, gbase, voff) do { _Pragma("unroll") for (int _i = 0; _i < 2; ++_i) \
;     __builtin_amdgcn_global_load_lds((const unsigned*)((const char*)(gbase) + (voff)[_i]), (LAS unsigned*)(lds + (bufoff) + ldsw + _i * 8192), 16, 0, 0); } while (0)
; #define PG8_LDA(dst, b, h) do { _Pragma("unroll") for (int m = 0; m < 4; ++m) _Pragma("unroll") for (int k = 0; k < 2; ++k) dst[m][k] = *(const LAS bf16x8*)(lds + PG8_SA(b, h) + aoff + m * 2048 + k * 1024); } while (0)
; #define PG8_LDB(dst, b, h) do { _Pragma("unroll") for (int n = 0; n < 2; ++n) _Pragma("unroll") for (int k = 0; k < 2; ++k) dst[n][k] = *(const LAS bf16x8*)(lds + PG8_SB(b, h) + boff + n * 2048 + k * 1024); } while (0)
; #define PG8_MMA(ai, bj, At, Bt) do { __builtin_amdgcn_s_setprio(1); _Pragma("unroll") for (int m = 0; m < 4; ++m) _Pragma("unroll") for (int n = 0; n < 2; ++n) _Pragma("unroll") for (int k = 0; k < 2; ++k) \
;     acc[ai][bj][m][n] = __builtin_amdgcn_mfma_f32_16x16x32_bf16(Bt[n][k], At[m][k], acc[ai][bj][m][n], 0, 0, 0); __builtin_amdgcn_s_setprio(0); } while (0)
; #define PG8_WAIT_L(n) asm volatile("s_waitcnt lgkmcnt(" #n ")" ::: "memory")
; #define PG8_BAR __builtin_amdgcn_s_barrier()
; #define PG8_SCHED __builtin_amdgcn_sched_barrier(0)
; template <class Epi, class Sched = StaticOrder>
; DI void gemm_phase(LAS unsigned char* lds, const Gemm g, const Sched& S, const Epi& E) {
;     ...
;     const bool has_next = S.next(ui + 1, nxt);
;     const char* nA = has_next ? (const char*)g.A + (size_t)nxt.pm * tstep : cA; const char* nB = has_next ? (const char*)g.Bt + (size_t)nxt.pn * tstep : cB;
;     for (int t = 0; t < nt; t += 2) {
;       const bool last = (t == nt - 2);
;       const char* a1 = cA + (size_t)(t + 1) * kstep;
;       const char* a2 = last ? nA : cA + (size_t)(t + 2) * kstep; const char* b2 = last ? nB : cB + (size_t)(t + 2) * kstep;
;       const char* a3 = a2 + kstep; const char* b3 = b2 + kstep;
;       PG8_LDB(B0, 0, 0); PG8_SCHED; PG8_LDA(At, 0, 0); PG8_STAGE(PG8_SA(1, 1), a1 + hstep, voffA);
;       PG8_WAIT_L(8); PG8_BAR; PG8_WAIT_L(0); PG8_MMA(0, 0, At, B0); PG8_BAR; PG8_SCHED;
.LBB0_1193:
	s_ashr_i32 s17, s16, 31
	v_cmp_lt_i64_e32 vcc, s[18:19], v[188:189]
	s_lshl_b64 s[18:19], s[16:17], 20
	s_add_u32 s18, s30, s18
	s_addc_u32 s19, s31, s19
	s_and_b64 s[20:21], vcc, exec
	s_cselect_b32 s17, s19, s23
	s_cselect_b32 s43, s18, s22
	s_ashr_i32 s15, s14, 31
	s_lshl_b64 s[20:21], s[14:15], 20
	s_add_u32 s20, s33, s20
	s_addc_u32 s21, s34, s21
	s_and_b64 s[26:27], vcc, exec
	s_cselect_b32 s15, s21, s25
	s_cselect_b32 s51, s20, s24
	s_add_u32 s22, s22, 0x80080
	s_addc_u32 s23, s23, 0
	s_add_u32 s52, s24, 0x100
	v_mov_b32_e32 v0, 0
	s_addc_u32 s53, s25, 0
	s_mov_b32 s54, -2
	s_waitcnt lgkmcnt(0)
	v_mov_b32_e32 v1, v0
	v_mov_b32_e32 v2, v0
	v_mov_b32_e32 v3, v0
	v_mov_b32_e32 v4, v0
	v_mov_b32_e32 v5, v0
	v_mov_b32_e32 v6, v0
	v_mov_b32_e32 v7, v0
	v_mov_b32_e32 v16, v0
	v_mov_b32_e32 v17, v0
	v_mov_b32_e32 v18, v0
	v_mov_b32_e32 v19, v0
	v_mov_b32_e32 v20, v0
	v_mov_b32_e32 v21, v0
	v_mov_b32_e32 v22, v0
	v_mov_b32_e32 v23, v0
	v_mov_b32_e32 v32, v0
	v_mov_b32_e32 v33, v0
	v_mov_b32_e32 v34, v0
	v_mov_b32_e32 v35, v0
	v_mov_b32_e32 v36, v0
	v_mov_b32_e32 v37, v0
	v_mov_b32_e32 v38, v0
	v_mov_b32_e32 v39, v0
	v_mov_b32_e32 v48, v0
	v_mov_b32_e32 v49, v0
	v_mov_b32_e32 v50, v0
	v_mov_b32_e32 v51, v0
	v_mov_b32_e32 v52, v0
	v_mov_b32_e32 v53, v0
	v_mov_b32_e32 v54, v0
	v_mov_b32_e32 v55, v0
	v_mov_b32_e32 v8, v0
	v_mov_b32_e32 v9, v0
	v_mov_b32_e32 v10, v0
	v_mov_b32_e32 v11, v0
	v_mov_b32_e32 v12, v0
	v_mov_b32_e32 v13, v0
	v_mov_b32_e32 v14, v0
	v_mov_b32_e32 v15, v0
	v_mov_b32_e32 v24, v0
	v_mov_b32_e32 v25, v0
	v_mov_b32_e32 v26, v0
	v_mov_b32_e32 v27, v0
	v_mov_b32_e32 v28, v0
	v_mov_b32_e32 v29, v0
	v_mov_b32_e32 v30, v0
	v_mov_b32_e32 v31, v0
	v_mov_b32_e32 v40, v0
	v_mov_b32_e32 v41, v0
	v_mov_b32_e32 v42, v0
	v_mov_b32_e32 v43, v0
	v_mov_b32_e32 v44, v0
	v_mov_b32_e32 v45, v0
	v_mov_b32_e32 v46, v0
	v_mov_b32_e32 v47, v0
	v_mov_b32_e32 v56, v0
	v_mov_b32_e32 v57, v0
	v_mov_b32_e32 v58, v0
	v_mov_b32_e32 v59, v0
	v_mov_b32_e32 v60, v0
	v_mov_b32_e32 v61, v0
	v_mov_b32_e32 v62, v0
	v_mov_b32_e32 v63, v0
	v_mov_b32_e32 v64, v0
	v_mov_b32_e32 v65, v0
	v_mov_b32_e32 v66, v0
	v_mov_b32_e32 v67, v0
	v_mov_b32_e32 v68, v0
	v_mov_b32_e32 v69, v0
	v_mov_b32_e32 v70, v0
	v_mov_b32_e32 v71, v0
	v_mov_b32_e32 v80, v0
	v_mov_b32_e32 v81, v0
	v_mov_b32_e32 v82, v0
	v_mov_b32_e32 v83, v0
	v_mov_b32_e32 v84, v0
	v_mov_b32_e32 v85, v0
	v_mov_b32_e32 v86, v0
	v_mov_b32_e32 v87, v0
	v_mov_b32_e32 v96, v0
	v_mov_b32_e32 v97, v0
	v_mov_b32_e32 v98, v0
	v_mov_b32_e32 v99, v0
	v_mov_b32_e32 v100, v0
	v_mov_b32_e32 v101, v0
	v_mov_b32_e32 v102, v0
	v_mov_b32_e32 v103, v0
	v_mov_b32_e32 v112, v0
	v_mov_b32_e32 v113, v0
	v_mov_b32_e32 v114, v0
	v_mov_b32_e32 v115, v0
	v_mov_b32_e32 v116, v0
	v_mov_b32_e32 v117, v0
	v_mov_b32_e32 v118, v0
	v_mov_b32_e32 v119, v0
	v_mov_b32_e32 v72, v0
	v_mov_b32_e32 v73, v0
	v_mov_b32_e32 v74, v0
	v_mov_b32_e32 v75, v0
	v_mov_b32_e32 v76, v0
	v_mov_b32_e32 v77, v0
	v_mov_b32_e32 v78, v0
	v_mov_b32_e32 v79, v0
	v_mov_b32_e32 v88, v0
	v_mov_b32_e32 v89, v0
	v_mov_b32_e32 v90, v0
	v_mov_b32_e32 v91, v0
	v_mov_b32_e32 v92, v0
	v_mov_b32_e32 v93, v0
	v_mov_b32_e32 v94, v0
	v_mov_b32_e32 v95, v0
	v_mov_b32_e32 v104, v0
	v_mov_b32_e32 v105, v0
	v_mov_b32_e32 v106, v0
	v_mov_b32_e32 v107, v0
	v_mov_b32_e32 v108, v0
	v_mov_b32_e32 v109, v0
	v_mov_b32_e32 v110, v0
	v_mov_b32_e32 v111, v0
	v_mov_b32_e32 v120, v0
	v_mov_b32_e32 v121, v0
	v_mov_b32_e32 v122, v0
	v_mov_b32_e32 v123, v0
	v_mov_b32_e32 v124, v0
	v_mov_b32_e32 v125, v0
	v_mov_b32_e32 v126, v0
	v_mov_b32_e32 v127, v0
	ds_read_b128 v[128:131], v214
	ds_read_b128 v[132:135], v214 offset:1024
	ds_read_b128 v[136:139], v214 offset:2048
	ds_read_b128 v[140:143], v214 offset:3072
	ds_read_b128 v[144:147], v215
	ds_read_b128 v[152:155], v215 offset:2048
	ds_read_b128 v[160:163], v215 offset:4096
	ds_read_b128 v[168:171], v215 offset:6144
.LBB0_1194:
	s_add_u32 s24, s22, 0xfff80080
	s_addc_u32 s25, s23, -1
	s_cmp_eq_u32 s54, 28
	s_cselect_b32 s27, s17, s25
	s_cselect_b32 s26, s43, s24
	s_cselect_b32 s25, s15, s53
	s_cselect_b32 s24, s51, s52
	s_add_i32 m0, s37, 0xc000
	ds_read_b128 v[148:151], v215 offset:1024
	ds_read_b128 v[156:159], v215 offset:3072
	ds_read_b128 v[164:167], v215 offset:5120
	ds_read_b128 v[172:175], v215 offset:7168
	global_load_lds_dwordx4 v184, s[22:23]
	s_add_i32 m0, s37, 0xe000
	s_nop 0
	global_load_lds_dwordx4 v186, s[22:23]
	s_waitcnt lgkmcnt(0)
	s_waitcnt vmcnt(8)
	s_setprio 1
	s_barrier
	v_mfma_f32_16x16x32_bf16 v[124:127], v[128:131], v[144:147], v[124:127]
	v_mfma_f32_16x16x32_bf16 v[120:123], v[136:139], v[144:147], v[120:123]
	v_mfma_f32_16x16x32_bf16 v[108:111], v[128:131], v[152:155], v[108:111]
	v_mfma_f32_16x16x32_bf16 v[104:107], v[136:139], v[152:155], v[104:107]
	v_mfma_f32_16x16x32_bf16 v[92:95], v[128:131], v[160:163], v[92:95]
	v_mfma_f32_16x16x32_bf16 v[88:91], v[136:139], v[160:163], v[88:91]
	v_mfma_f32_16x16x32_bf16 v[76:79], v[128:131], v[168:171], v[76:79]
	v_mfma_f32_16x16x32_bf16 v[72:75], v[136:139], v[168:171], v[72:75]
	v_mfma_f32_16x16x32_bf16 v[124:127], v[132:135], v[148:151], v[124:127]
	v_mfma_f32_16x16x32_bf16 v[120:123], v[140:143], v[148:151], v[120:123]
	v_mfma_f32_16x16x32_bf16 v[108:111], v[132:135], v[156:159], v[108:111]
	v_mfma_f32_16x16x32_bf16 v[104:107], v[140:143], v[156:159], v[104:107]
	v_mfma_f32_16x16x32_bf16 v[92:95], v[132:135], v[164:167], v[92:95]
	v_mfma_f32_16x16x32_bf16 v[88:91], v[140:143], v[164:167], v[88:91]
	v_mfma_f32_16x16x32_bf16 v[76:79], v[132:135], v[172:175], v[76:79]
	v_mfma_f32_16x16x32_bf16 v[72:75], v[140:143], v[172:175], v[72:75]
	s_barrier
; #define PG8_STAGE(bufoff, gbase, voff) do { _Pragma("unroll") for (int _i = 0; _i < 2; ++_i) \
;     __builtin_amdgcn_global_load_lds((const unsigned*)((const char*)(gbase) + (voff)[_i]), (LAS unsigned*)(lds + (bufoff) + ldsw + _i * 8192), 16, 0, 0); } while (0)
; #define PG8_LDA(dst, b, h) do { _Pragma("unroll") for (int m = 0; m < 4; ++m) _Pragma("unroll") for (int k = 0; k < 2; ++k) dst[m][k] = *(const LAS bf16x8*)(lds + PG8_SA(b, h) + aoff + m * 2048 + k * 1024); } while (0)
; #define PG8_LDB(dst, b, h) do { _Pragma("unroll") for (int n = 0; n < 2; ++n) _Pragma("unroll") for (int k = 0; k < 2; ++k) dst[n][k] = *(const LAS bf16x8*)(lds + PG8_SB(b, h) + boff + n * 2048 + k * 1024); } while (0)
; #define PG8_MMA(ai, bj, At, Bt) do { __builtin_amdgcn_s_setprio(1); _Pragma("unroll") for (int m = 0; m < 4; ++m) _Pragma("unroll") for (int n = 0; n < 2; ++n) _Pragma("unroll") for (int k = 0; k < 2; ++k) \
;     acc[ai][bj][m][n] = __builtin_amdgcn_mfma_f32_16x16x32_bf16(Bt[n][k], At[m][k], acc[ai][bj][m][n], 0, 0, 0); __builtin_amdgcn_s_setprio(0); } while (0)
; #define PG8_WAIT_V(n) asm volatile("s_waitcnt vmcnt(" #n ")" ::: "memory")
; #define PG8_WAIT_L(n) asm volatile("s_waitcnt lgkmcnt(" #n ")" ::: "memory")
; #define PG8_BAR __builtin_amdgcn_s_barrier()
; #define PG8_SCHED __builtin_amdgcn_sched_barrier(0)
; template <class Epi, class Sched = StaticOrder>
; DI void gemm_phase(LAS unsigned char* lds, const Gemm g, const Sched& S, const Epi& E) {
;     ...
;       PG8_WAIT_L(8); PG8_BAR; PG8_WAIT_L(0); PG8_MMA(0, 0, At, B0); PG8_BAR; PG8_SCHED;
;       PG8_LDB(B1, 0, 1); PG8_STAGE(PG8_SB(0, 0), b2, voffB);
;       PG8_BAR; PG8_WAIT_L(0); PG8_MMA(0, 1, At, B1); PG8_BAR;
;       PG8_LDA(At, 0, 1); PG8_STAGE(PG8_SA(0, 0), a2, voffA);
;       PG8_BAR; PG8_WAIT_L(0); PG8_MMA(1, 0, At, B0); PG8_BAR; PG8_SCHED;
;       PG8_STAGE(PG8_SB(0, 1), b2 + hstep, voffB);
;       PG8_WAIT_V(6); PG8_BAR; PG8_MMA(1, 1, At, B1); PG8_BAR;
;       PG8_LDB(B0, 1, 0); PG8_SCHED; PG8_LDA(At, 1, 0); PG8_STAGE(PG8_SA(0, 1), a2 + hstep, voffA);
;       PG8_WAIT_L(8); PG8_BAR; PG8_WAIT_L(0); PG8_MMA(0, 0, At, B0); PG8_BAR; PG8_SCHED;
	s_setprio 0
	s_add_i32 s55, s48, s35
	s_add_u32 s98, s24, 0x80
	s_addc_u32 s99, s25, 0
	s_mov_b32 m0, s55
	ds_read_b128 v[192:195], v216
	ds_read_b128 v[196:199], v216 offset:1024
	ds_read_b128 v[200:203], v216 offset:2048
	ds_read_b128 v[204:207], v216 offset:3072
	global_load_lds_dwordx4 v180, s[24:25]
	s_add_i32 m0, s55, 0x2000
	s_nop 0
	global_load_lds_dwordx4 v176, s[24:25]
	s_waitcnt lgkmcnt(0)
	s_setprio 1
	s_barrier
	v_mfma_f32_16x16x32_bf16 v[116:119], v[192:195], v[144:147], v[116:119]
	v_mfma_f32_16x16x32_bf16 v[112:115], v[200:203], v[144:147], v[112:115]
	v_mfma_f32_16x16x32_bf16 v[100:103], v[192:195], v[152:155], v[100:103]
	v_mfma_f32_16x16x32_bf16 v[96:99], v[200:203], v[152:155], v[96:99]
	v_mfma_f32_16x16x32_bf16 v[84:87], v[192:195], v[160:163], v[84:87]
	v_mfma_f32_16x16x32_bf16 v[80:83], v[200:203], v[160:163], v[80:83]
	v_mfma_f32_16x16x32_bf16 v[68:71], v[192:195], v[168:171], v[68:71]
	v_mfma_f32_16x16x32_bf16 v[64:67], v[200:203], v[168:171], v[64:67]
	v_mfma_f32_16x16x32_bf16 v[116:119], v[196:199], v[148:151], v[116:119]
	ds_read_b128 v[144:147], v215 offset:16384
	v_mfma_f32_16x16x32_bf16 v[112:115], v[204:207], v[148:151], v[112:115]
	ds_read_b128 v[152:155], v215 offset:18432
	v_mfma_f32_16x16x32_bf16 v[100:103], v[196:199], v[156:159], v[100:103]
	ds_read_b128 v[160:163], v215 offset:20480
	v_mfma_f32_16x16x32_bf16 v[96:99], v[204:207], v[156:159], v[96:99]
	ds_read_b128 v[168:171], v215 offset:22528
	v_mfma_f32_16x16x32_bf16 v[84:87], v[196:199], v[164:167], v[84:87]
	v_mfma_f32_16x16x32_bf16 v[80:83], v[204:207], v[164:167], v[80:83]
	v_mfma_f32_16x16x32_bf16 v[68:71], v[196:199], v[172:175], v[68:71]
	v_mfma_f32_16x16x32_bf16 v[64:67], v[204:207], v[172:175], v[64:67]
	s_barrier
	s_setprio 0
	s_mov_b32 m0, s37
	s_add_u32 s100, s26, 0x80
	s_addc_u32 s101, s27, 0
	ds_read_b128 v[148:151], v215 offset:17408
	ds_read_b128 v[156:159], v215 offset:19456
	ds_read_b128 v[164:167], v215 offset:21504
	ds_read_b128 v[172:175], v215 offset:23552
	global_load_lds_dwordx4 v182, s[26:27]
	s_mov_b32 m0, s38
	s_nop 0
	global_load_lds_dwordx4 v178, s[26:27]
	s_waitcnt vmcnt(8)
	s_waitcnt lgkmcnt(0)
	s_setprio 1
	s_barrier
	v_mfma_f32_16x16x32_bf16 v[60:63], v[128:131], v[144:147], v[60:63]
	v_mfma_f32_16x16x32_bf16 v[56:59], v[136:139], v[144:147], v[56:59]
	v_mfma_f32_16x16x32_bf16 v[44:47], v[128:131], v[152:155], v[44:47]
	v_mfma_f32_16x16x32_bf16 v[40:43], v[136:139], v[152:155], v[40:43]
	v_mfma_f32_16x16x32_bf16 v[28:31], v[128:131], v[160:163], v[28:31]
	v_mfma_f32_16x16x32_bf16 v[24:27], v[136:139], v[160:163], v[24:27]
	v_mfma_f32_16x16x32_bf16 v[12:15], v[128:131], v[168:171], v[12:15]
	v_mfma_f32_16x16x32_bf16 v[8:11], v[136:139], v[168:171], v[8:11]
	v_mfma_f32_16x16x32_bf16 v[60:63], v[132:135], v[148:151], v[60:63]
	v_mfma_f32_16x16x32_bf16 v[56:59], v[140:143], v[148:151], v[56:59]
	v_mfma_f32_16x16x32_bf16 v[44:47], v[132:135], v[156:159], v[44:47]
	v_mfma_f32_16x16x32_bf16 v[40:43], v[140:143], v[156:159], v[40:43]
	v_mfma_f32_16x16x32_bf16 v[28:31], v[132:135], v[164:167], v[28:31]
	v_mfma_f32_16x16x32_bf16 v[24:27], v[140:143], v[164:167], v[24:27]
	v_mfma_f32_16x16x32_bf16 v[12:15], v[132:135], v[172:175], v[12:15]
	v_mfma_f32_16x16x32_bf16 v[8:11], v[140:143], v[172:175], v[8:11]
	s_barrier
	s_setprio 0
	s_add_u32 s56, s24, 0x80000
	s_addc_u32 s57, s25, 0
	s_add_i32 s55, s49, s35
	s_mov_b32 m0, s55
	s_nop 0
	global_load_lds_dwordx4 v180, s[56:57]
	s_add_i32 m0, s55, 0x2000
	s_nop 0
	global_load_lds_dwordx4 v176, s[56:57]
	s_add_i32 s55, 0, 0x18000
	v_add_u32_e32 v140, s55, v212
	ds_read_b128 v[128:131], v140
	ds_read_b128 v[132:135], v140 offset:1024
	ds_read_b128 v[136:139], v140 offset:2048
	ds_read_b128 v[140:143], v140 offset:3072
	s_waitcnt vmcnt(6)
	s_setprio 1
	s_barrier
	v_mfma_f32_16x16x32_bf16 v[52:55], v[192:195], v[144:147], v[52:55]
	v_mfma_f32_16x16x32_bf16 v[48:51], v[200:203], v[144:147], v[48:51]
	v_mfma_f32_16x16x32_bf16 v[36:39], v[192:195], v[152:155], v[36:39]
	v_mfma_f32_16x16x32_bf16 v[32:35], v[200:203], v[152:155], v[32:35]
	v_mfma_f32_16x16x32_bf16 v[20:23], v[192:195], v[160:163], v[20:23]
	v_mfma_f32_16x16x32_bf16 v[16:19], v[200:203], v[160:163], v[16:19]
	v_mfma_f32_16x16x32_bf16 v[4:7], v[192:195], v[168:171], v[4:7]
	v_mfma_f32_16x16x32_bf16 v[0:3], v[200:203], v[168:171], v[0:3]
	v_mfma_f32_16x16x32_bf16 v[52:55], v[196:199], v[148:151], v[52:55]
	ds_read_b128 v[144:147], v215 offset:32768
	v_mfma_f32_16x16x32_bf16 v[48:51], v[204:207], v[148:151], v[48:51]
	ds_read_b128 v[152:155], v215 offset:34816
	v_mfma_f32_16x16x32_bf16 v[36:39], v[196:199], v[156:159], v[36:39]
	ds_read_b128 v[160:163], v215 offset:36864
	v_mfma_f32_16x16x32_bf16 v[32:35], v[204:207], v[156:159], v[32:35]
	ds_read_b128 v[168:171], v215 offset:38912
	v_mfma_f32_16x16x32_bf16 v[20:23], v[196:199], v[164:167], v[20:23]
	v_mfma_f32_16x16x32_bf16 v[16:19], v[204:207], v[164:167], v[16:19]
	v_mfma_f32_16x16x32_bf16 v[4:7], v[196:199], v[172:175], v[4:7]
	v_mfma_f32_16x16x32_bf16 v[0:3], v[204:207], v[172:175], v[0:3]
	s_barrier
	s_setprio 0
	s_add_u32 s26, s26, 0x80000
	s_addc_u32 s27, s27, 0
	s_mov_b32 m0, s39
	ds_read_b128 v[148:151], v215 offset:33792
	ds_read_b128 v[156:159], v215 offset:35840
	ds_read_b128 v[164:167], v215 offset:37888
	ds_read_b128 v[172:175], v215 offset:39936
	global_load_lds_dwordx4 v182, s[26:27]
	s_mov_b32 m0, s40
	s_nop 0
	global_load_lds_dwordx4 v178, s[26:27]
	s_waitcnt lgkmcnt(0)
	s_waitcnt vmcnt(8)
	s_setprio 1
	s_barrier
; #define PG8_STAGE(bufoff, gbase, voff) do { _Pragma("unroll") for (int _i = 0; _i < 2; ++_i) \
;     __builtin_amdgcn_global_load_lds((const unsigned*)((const char*)(gbase) + (voff)[_i]), (LAS unsigned*)(lds + (bufoff) + ldsw + _i * 8192), 16, 0, 0); } while (0)
; #define PG8_LDA(dst, b, h) do { _Pragma("unroll") for (int m = 0; m < 4; ++m) _Pragma("unroll") for (int k = 0; k < 2; ++k) dst[m][k] = *(const LAS bf16x8*)(lds + PG8_SA(b, h) + aoff + m * 2048 + k * 1024); } while (0)
; #define PG8_LDB(dst, b, h) do { _Pragma("unroll") for (int n = 0; n < 2; ++n) _Pragma("unroll") for (int k = 0; k < 2; ++k) dst[n][k] = *(const LAS bf16x8*)(lds + PG8_SB(b, h) + boff + n * 2048 + k * 1024); } while (0)
; #define PG8_MMA(ai, bj, At, Bt) do { __builtin_amdgcn_s_setprio(1); _Pragma("unroll") for (int m = 0; m < 4; ++m) _Pragma("unroll") for (int n = 0; n < 2; ++n) _Pragma("unroll") for (int k = 0; k < 2; ++k) \
;     acc[ai][bj][m][n] = __builtin_amdgcn_mfma_f32_16x16x32_bf16(Bt[n][k], At[m][k], acc[ai][bj][m][n], 0, 0, 0); __builtin_amdgcn_s_setprio(0); } while (0)
; #define PG8_WAIT_V(n) asm volatile("s_waitcnt vmcnt(" #n ")" ::: "memory")
; #define PG8_WAIT_L(n) asm volatile("s_waitcnt lgkmcnt(" #n ")" ::: "memory")
; #define PG8_BAR __builtin_amdgcn_s_barrier()
; #define PG8_SCHED __builtin_amdgcn_sched_barrier(0)
; template <class Epi, class Sched = StaticOrder>
; DI void gemm_phase(LAS unsigned char* lds, const Gemm g, const Sched& S, const Epi& E) {
;     ...
;       PG8_WAIT_L(8); PG8_BAR; PG8_WAIT_L(0); PG8_MMA(0, 0, At, B0); PG8_BAR; PG8_SCHED;
;       PG8_LDB(B1, 1, 1); PG8_STAGE(PG8_SB(1, 0), b3, voffB);
;       PG8_BAR; PG8_WAIT_L(0); PG8_MMA(0, 1, At, B1); PG8_BAR;
;       PG8_LDA(At, 1, 1); PG8_STAGE(PG8_SA(1, 0), a3, voffA);
;       PG8_BAR; PG8_WAIT_L(0); PG8_MMA(1, 0, At, B0); PG8_BAR; PG8_SCHED;
;       PG8_STAGE(PG8_SB(1, 1), b3 + hstep, voffB);
;       PG8_WAIT_V(6); PG8_BAR; PG8_MMA(1, 1, At, B1); PG8_BAR;
	v_mfma_f32_16x16x32_bf16 v[124:127], v[128:131], v[144:147], v[124:127]
	v_mfma_f32_16x16x32_bf16 v[120:123], v[136:139], v[144:147], v[120:123]
	v_mfma_f32_16x16x32_bf16 v[108:111], v[128:131], v[152:155], v[108:111]
	v_mfma_f32_16x16x32_bf16 v[104:107], v[136:139], v[152:155], v[104:107]
	v_mfma_f32_16x16x32_bf16 v[92:95], v[128:131], v[160:163], v[92:95]
	v_mfma_f32_16x16x32_bf16 v[88:91], v[136:139], v[160:163], v[88:91]
	v_mfma_f32_16x16x32_bf16 v[76:79], v[128:131], v[168:171], v[76:79]
	v_mfma_f32_16x16x32_bf16 v[72:75], v[136:139], v[168:171], v[72:75]
	v_mfma_f32_16x16x32_bf16 v[124:127], v[132:135], v[148:151], v[124:127]
	v_mfma_f32_16x16x32_bf16 v[120:123], v[140:143], v[148:151], v[120:123]
	v_mfma_f32_16x16x32_bf16 v[108:111], v[132:135], v[156:159], v[108:111]
	v_mfma_f32_16x16x32_bf16 v[104:107], v[140:143], v[156:159], v[104:107]
	v_mfma_f32_16x16x32_bf16 v[92:95], v[132:135], v[164:167], v[92:95]
	v_mfma_f32_16x16x32_bf16 v[88:91], v[140:143], v[164:167], v[88:91]
	v_mfma_f32_16x16x32_bf16 v[76:79], v[132:135], v[172:175], v[76:79]
	v_mfma_f32_16x16x32_bf16 v[72:75], v[140:143], v[172:175], v[72:75]
	s_barrier
	s_setprio 0
	s_add_i32 s26, 0, 0x1c000
	s_add_i32 s27, s55, s35
	v_add_u32_e32 v204, s26, v212
	s_mov_b32 m0, s27
	ds_read_b128 v[192:195], v204
	ds_read_b128 v[196:199], v204 offset:1024
	ds_read_b128 v[200:203], v204 offset:2048
	ds_read_b128 v[204:207], v204 offset:3072
	global_load_lds_dwordx4 v180, s[98:99]
	s_add_i32 m0, s27, 0x2000
	s_nop 0
	global_load_lds_dwordx4 v176, s[98:99]
	s_waitcnt lgkmcnt(0)
	s_setprio 1
	s_barrier
	v_mfma_f32_16x16x32_bf16 v[116:119], v[192:195], v[144:147], v[116:119]
	v_mfma_f32_16x16x32_bf16 v[112:115], v[200:203], v[144:147], v[112:115]
	v_mfma_f32_16x16x32_bf16 v[100:103], v[192:195], v[152:155], v[100:103]
	v_mfma_f32_16x16x32_bf16 v[96:99], v[200:203], v[152:155], v[96:99]
	v_mfma_f32_16x16x32_bf16 v[84:87], v[192:195], v[160:163], v[84:87]
	v_mfma_f32_16x16x32_bf16 v[80:83], v[200:203], v[160:163], v[80:83]
	v_mfma_f32_16x16x32_bf16 v[68:71], v[192:195], v[168:171], v[68:71]
	v_mfma_f32_16x16x32_bf16 v[64:67], v[200:203], v[168:171], v[64:67]
	v_mfma_f32_16x16x32_bf16 v[116:119], v[196:199], v[148:151], v[116:119]
	ds_read_b128 v[144:147], v215 offset:49152
	v_mfma_f32_16x16x32_bf16 v[112:115], v[204:207], v[148:151], v[112:115]
	ds_read_b128 v[152:155], v215 offset:51200
	v_mfma_f32_16x16x32_bf16 v[100:103], v[196:199], v[156:159], v[100:103]
	ds_read_b128 v[160:163], v215 offset:53248
	v_mfma_f32_16x16x32_bf16 v[96:99], v[204:207], v[156:159], v[96:99]
	ds_read_b128 v[168:171], v215 offset:55296
	v_mfma_f32_16x16x32_bf16 v[84:87], v[196:199], v[164:167], v[84:87]
	v_mfma_f32_16x16x32_bf16 v[80:83], v[204:207], v[164:167], v[80:83]
	v_mfma_f32_16x16x32_bf16 v[68:71], v[196:199], v[172:175], v[68:71]
	v_mfma_f32_16x16x32_bf16 v[64:67], v[204:207], v[172:175], v[64:67]
	s_barrier
	s_setprio 0
	s_mov_b32 m0, s44
	ds_read_b128 v[148:151], v215 offset:50176
	ds_read_b128 v[156:159], v215 offset:52224
	ds_read_b128 v[164:167], v215 offset:54272
	ds_read_b128 v[172:175], v215 offset:56320
	global_load_lds_dwordx4 v182, s[100:101]
	s_mov_b32 m0, s45
	s_nop 0
	global_load_lds_dwordx4 v178, s[100:101]
	s_waitcnt vmcnt(8)
	s_waitcnt lgkmcnt(0)
	s_setprio 1
	s_barrier
	v_mfma_f32_16x16x32_bf16 v[60:63], v[128:131], v[144:147], v[60:63]
	v_mfma_f32_16x16x32_bf16 v[56:59], v[136:139], v[144:147], v[56:59]
	v_mfma_f32_16x16x32_bf16 v[44:47], v[128:131], v[152:155], v[44:47]
	v_mfma_f32_16x16x32_bf16 v[40:43], v[136:139], v[152:155], v[40:43]
	v_mfma_f32_16x16x32_bf16 v[28:31], v[128:131], v[160:163], v[28:31]
	v_mfma_f32_16x16x32_bf16 v[24:27], v[136:139], v[160:163], v[24:27]
	v_mfma_f32_16x16x32_bf16 v[12:15], v[128:131], v[168:171], v[12:15]
	v_mfma_f32_16x16x32_bf16 v[8:11], v[136:139], v[168:171], v[8:11]
	v_mfma_f32_16x16x32_bf16 v[60:63], v[132:135], v[148:151], v[60:63]
	v_mfma_f32_16x16x32_bf16 v[56:59], v[140:143], v[148:151], v[56:59]
	v_mfma_f32_16x16x32_bf16 v[44:47], v[132:135], v[156:159], v[44:47]
	v_mfma_f32_16x16x32_bf16 v[40:43], v[140:143], v[156:159], v[40:43]
	v_mfma_f32_16x16x32_bf16 v[28:31], v[132:135], v[164:167], v[28:31]
	v_mfma_f32_16x16x32_bf16 v[24:27], v[140:143], v[164:167], v[24:27]
	v_mfma_f32_16x16x32_bf16 v[12:15], v[132:135], v[172:175], v[12:15]
	v_mfma_f32_16x16x32_bf16 v[8:11], v[140:143], v[172:175], v[8:11]
	s_barrier
	s_setprio 0
	s_add_u32 s24, s24, 0x80080
	s_addc_u32 s25, s25, 0
	s_add_i32 s26, s26, s35
	s_mov_b32 m0, s26
	s_nop 0
	global_load_lds_dwordx4 v180, s[24:25]
	s_add_i32 m0, s26, 0x2000
	s_nop 0
	global_load_lds_dwordx4 v176, s[24:25]
	ds_read_b128 v[128:131], v214
	ds_read_b128 v[132:135], v214 offset:1024
	ds_read_b128 v[136:139], v214 offset:2048
	ds_read_b128 v[140:143], v214 offset:3072
	s_waitcnt vmcnt(6)
	s_add_i32 s54, s54, 2
	s_add_u32 s22, s22, 0x100
	s_addc_u32 s23, s23, 0
	s_add_u32 s52, s52, 0x100
	s_addc_u32 s53, s53, 0
	s_cmp_gt_u32 s54, 29
	s_setprio 1
	s_barrier
; DI unsigned pack2(float lo, float hi) { f32x2 v = {lo, hi}; bf16v2 r = __builtin_convertvector(v, bf16v2); return __builtin_bit_cast(unsigned, r); }
; #define PG8_MMA(ai, bj, At, Bt) do { __builtin_amdgcn_s_setprio(1); _Pragma("unroll") for (int m = 0; m < 4; ++m) _Pragma("unroll") for (int n = 0; n < 2; ++n) _Pragma("unroll") for (int k = 0; k < 2; ++k) \
;     acc[ai][bj][m][n] = __builtin_amdgcn_mfma_f32_16x16x32_bf16(Bt[n][k], At[m][k], acc[ai][bj][m][n], 0, 0, 0); __builtin_amdgcn_s_setprio(0); } while (0)
; #define PG8_BAR __builtin_amdgcn_s_barrier()
;   DI void operator()(const f32x4 (&acc)[2][2][4][2], const Unit& u, int wr, int wc, int fr, int fq) const {
;     const int row0 = u.pm * BM + wr * 64 + fr, col0 = u.pn * BM + wc * 32 + 8 * fq;
; #pragma unroll
;     for (int ai = 0; ai < 2; ++ai) {
;       f32x4 bv[4][2][2];
; #pragma unroll
;       for (int m = 0; m < 4; ++m)
; #pragma unroll
;         for (int bj = 0; bj < 2; ++bj) {
;           const float* bp = base + (size_t)(row0 + ai * HALF + m * 16) * 2048 + col0 + bj * HALF;
;           bv[m][bj][0] = *(const f32x4*)bp; bv[m][bj][1] = *(const f32x4*)(bp + 4);
;         }
; #pragma unroll
;       for (int m = 0; m < 4; ++m) {
;         const int row = row0 + ai * HALF + m * 16;
;         const size_t off = (size_t)row * 2048 + col0;
;         float ss = 0.f;
; #pragma unroll
;         for (int bj = 0; bj < 2; ++bj) {
;           const f32x4 v0 = acc[ai][bj][m][0] + bv[m][bj][0], v1 = acc[ai][bj][m][1] + bv[m][bj][1];
;           *(f32x4*)(C + off + bj * HALF) = v0; *(f32x4*)(C + off + bj * HALF + 4) = v1;
;           if (xb) {
;             u32x4 w; w.x = pack2(v0[0], v0[1]); w.y = pack2(v0[2], v0[3]); w.z = pack2(v1[0], v1[1]); w.w = pack2(v1[2], v1[3]);
;             *(u32x4*)(xb + off + bj * HALF) = w;
;             ss += v0[0] * v0[0] + v0[1] * v0[1] + v0[2] * v0[2] + v0[3] * v0[3] + v1[0] * v1[0] + v1[1] * v1[1] + v1[2] * v1[2] + v1[3] * v1[3];
;           }
;         }
;         if (xb) {
;           ss += __shfl_xor(ss, 16); ss += __shfl_xor(ss, 32);
;           if (fq == 0) ssq[(size_t)row * 32 + u.pn * 4 + wc] = ss;
; template <class Epi, class Sched = StaticOrder>
; DI void gemm_phase(LAS unsigned char* lds, const Gemm g, const Sched& S, const Epi& E) {
;     ...
;       PG8_WAIT_V(6); PG8_BAR; PG8_MMA(1, 1, At, B1); PG8_BAR;
;     }
;     E(acc, cur, wr, wc, fr, fq);
	v_mfma_f32_16x16x32_bf16 v[52:55], v[192:195], v[144:147], v[52:55]
	v_mfma_f32_16x16x32_bf16 v[48:51], v[200:203], v[144:147], v[48:51]
	v_mfma_f32_16x16x32_bf16 v[36:39], v[192:195], v[152:155], v[36:39]
	v_mfma_f32_16x16x32_bf16 v[32:35], v[200:203], v[152:155], v[32:35]
	v_mfma_f32_16x16x32_bf16 v[20:23], v[192:195], v[160:163], v[20:23]
	v_mfma_f32_16x16x32_bf16 v[16:19], v[200:203], v[160:163], v[16:19]
	v_mfma_f32_16x16x32_bf16 v[4:7], v[192:195], v[168:171], v[4:7]
	v_mfma_f32_16x16x32_bf16 v[0:3], v[200:203], v[168:171], v[0:3]
	v_mfma_f32_16x16x32_bf16 v[52:55], v[196:199], v[148:151], v[52:55]
	ds_read_b128 v[144:147], v215
	v_mfma_f32_16x16x32_bf16 v[48:51], v[204:207], v[148:151], v[48:51]
	ds_read_b128 v[152:155], v215 offset:2048
	v_mfma_f32_16x16x32_bf16 v[36:39], v[196:199], v[156:159], v[36:39]
	ds_read_b128 v[160:163], v215 offset:4096
	v_mfma_f32_16x16x32_bf16 v[32:35], v[204:207], v[156:159], v[32:35]
	ds_read_b128 v[168:171], v215 offset:6144
	v_mfma_f32_16x16x32_bf16 v[20:23], v[196:199], v[164:167], v[20:23]
	v_mfma_f32_16x16x32_bf16 v[16:19], v[204:207], v[164:167], v[16:19]
	v_mfma_f32_16x16x32_bf16 v[4:7], v[196:199], v[172:175], v[4:7]
	v_mfma_f32_16x16x32_bf16 v[0:3], v[204:207], v[172:175], v[0:3]
	s_barrier
	s_setprio 0
	s_cbranch_scc0 .LBB0_1194
	s_waitcnt lgkmcnt(0)
	v_lshl_add_u32 v194, s12, 8, v211
	v_lshl_or_b32 v192, s42, 8, v213
	v_readlane_b32 s52, v243, 3
	v_ashrrev_i32_e32 v193, 31, v192
	v_readlane_b32 s66, v243, 17
	v_readlane_b32 s67, v243, 18
	v_ashrrev_i32_e32 v195, 31, v194
	v_lshlrev_b64 v[128:129], 13, v[194:195]
	v_lshl_add_u64 v[196:197], v[192:193], 2, s[66:67]
	v_lshl_add_u64 v[236:237], v[196:197], 0, v[128:129]
	global_load_dwordx4 v[220:223], v[236:237], off
	global_load_dwordx4 v[224:227], v[236:237], off offset:16
	global_load_dwordx4 v[228:231], v[236:237], off offset:512
	global_load_dwordx4 v[232:235], v[236:237], off offset:528
	v_or_b32_e32 v206, 16, v194
	v_or_b32_e32 v202, 32, v194
	v_or_b32_e32 v198, 48, v194
	v_ashrrev_i32_e32 v207, 31, v206
	v_ashrrev_i32_e32 v203, 31, v202
	v_ashrrev_i32_e32 v199, 31, v198
	v_lshlrev_b64 v[128:129], 13, v[206:207]
	v_lshlrev_b64 v[130:131], 13, v[202:203]
	v_lshlrev_b64 v[132:133], 13, v[198:199]
	v_lshl_add_u64 v[208:209], v[196:197], 0, v[128:129]
	v_lshl_add_u64 v[204:205], v[196:197], 0, v[130:131]
	v_lshl_add_u64 v[200:201], v[196:197], 0, v[132:133]
	global_load_dwordx4 v[168:171], v[208:209], off offset:16
	global_load_dwordx4 v[172:175], v[208:209], off
	global_load_dwordx4 v[160:163], v[208:209], off offset:528
	global_load_dwordx4 v[164:167], v[208:209], off offset:512
	global_load_dwordx4 v[152:155], v[204:205], off offset:16
	global_load_dwordx4 v[156:159], v[204:205], off
	global_load_dwordx4 v[144:147], v[204:205], off offset:528
	global_load_dwordx4 v[148:151], v[204:205], off offset:512
	global_load_dwordx4 v[136:139], v[200:201], off offset:16
	global_load_dwordx4 v[140:143], v[200:201], off
	global_load_dwordx4 v[128:131], v[200:201], off offset:528
	global_load_dwordx4 v[132:135], v[200:201], off offset:512
	v_and_b32_e32 v218, 64, v217
	v_xor_b32_e32 v238, 16, v217
	v_add_u32_e32 v240, 64, v218
	v_xor_b32_e32 v239, 32, v217
	v_cmp_lt_i32_e32 vcc, v238, v240
	v_lshlrev_b64 v[218:219], 11, v[194:195]
	s_lshl_b32 s22, s42, 2
	v_cndmask_b32_e32 v241, v217, v238, vcc
	v_cmp_lt_i32_e32 vcc, v239, v240
	s_ashr_i32 s23, s22, 31
	v_readlane_b32 s53, v243, 4
	v_cndmask_b32_e32 v240, v217, v239, vcc
	v_lshl_add_u64 v[238:239], v[218:219], 0, v[192:193]
	v_lshlrev_b32_e32 v218, 2, v241
	v_lshl_add_u64 v[238:239], v[238:239], 1, s[2:3]
	v_readlane_b32 s54, v243, 5
	v_readlane_b32 s55, v243, 6
	v_readlane_b32 s56, v243, 7
	v_readlane_b32 s57, v243, 8
	v_readlane_b32 s58, v243, 9
	v_readlane_b32 s59, v243, 10
	v_readlane_b32 s60, v243, 11
	v_readlane_b32 s61, v243, 12
	v_readlane_b32 s62, v243, 13
	v_readlane_b32 s63, v243, 14
	v_readlane_b32 s64, v243, 15
	v_readlane_b32 s65, v243, 16
	s_waitcnt vmcnt(0)
	v_pk_add_f32 v[126:127], v[126:127], v[222:223]
	v_pk_add_f32 v[124:125], v[124:125], v[220:221]
	v_pk_add_f32 v[116:117], v[116:117], v[228:229]
	v_pk_add_f32 v[122:123], v[122:123], v[226:227]
	v_pk_add_f32 v[120:121], v[120:121], v[224:225]
	v_pk_add_f32 v[220:221], v[112:113], v[232:233]
	global_store_dwordx4 v[236:237], v[124:127], off
	global_store_dwordx4 v[236:237], v[120:123], off offset:16
	v_cvt_pk_bf16_f32 v112, v124, v125
	v_mul_f32_e32 v125, v125, v125
	v_mul_f32_e32 v219, v117, v117
	v_pk_add_f32 v[118:119], v[118:119], v[230:231]
	v_fmac_f32_e32 v125, v124, v124
	v_fmac_f32_e32 v219, v116, v116
	v_fmac_f32_e32 v125, v126, v126
	v_fmac_f32_e32 v219, v118, v118
	v_fmac_f32_e32 v125, v127, v127
	v_fmac_f32_e32 v219, v119, v119
	v_fmac_f32_e32 v125, v120, v120
	v_fmac_f32_e32 v219, v220, v220
	v_pk_add_f32 v[222:223], v[114:115], v[234:235]
	v_fmac_f32_e32 v125, v121, v121
	v_fmac_f32_e32 v219, v221, v221
	v_fmac_f32_e32 v125, v122, v122
	v_fmac_f32_e32 v219, v222, v222
	v_fmac_f32_e32 v125, v123, v123
	v_fmac_f32_e32 v219, v223, v223
	v_cvt_pk_bf16_f32 v114, v120, v121
	v_add_f32_e32 v121, v125, v219
	v_cvt_pk_bf16_f32 v115, v122, v123
	ds_bpermute_b32 v122, v218, v121
	v_cvt_pk_bf16_f32 v113, v126, v127
	global_store_dwordx4 v[238:239], v[112:115], off
	global_store_dwordx4 v[236:237], v[116:119], off offset:512
	global_store_dwordx4 v[236:237], v[220:223], off offset:528
	v_lshlrev_b32_e32 v126, 2, v240
	v_cvt_pk_bf16_f32 v120, v116, v117
	s_waitcnt lgkmcnt(0)
	v_add_f32_e32 v112, v121, v122
	ds_bpermute_b32 v113, v126, v112
	v_cvt_pk_bf16_f32 v121, v118, v119
	v_cvt_pk_bf16_f32 v122, v220, v221
	v_cvt_pk_bf16_f32 v123, v222, v223
	global_store_dwordx4 v[238:239], v[120:123], off offset:256
	s_and_saveexec_b64 s[24:25], s[0:1]
	s_cbranch_execz .LBB0_1197
	s_waitcnt lgkmcnt(0)
	v_add_f32_e32 v114, v112, v113
	v_lshlrev_b64 v[112:113], 7, v[194:195]
	v_lshl_add_u64 v[112:113], s[8:9], 0, v[112:113]
	v_lshl_add_u64 v[112:113], s[22:23], 2, v[112:113]
	s_lshl_b32 s12, s41, 2
	v_lshl_add_u64 v[112:113], v[112:113], 0, s[12:13]
	global_store_dword v[112:113], v114, off

; #define PG8_STAGE(bufoff, gbase, voff) do { _Pragma("unroll") for (int _i = 0; _i < 2; ++_i) \
;     __builtin_amdgcn_global_load_lds((const unsigned*)((const char*)(gbase) + (voff)[_i]), (LAS unsigned*)(lds + (bufoff) + ldsw + _i * 8192), 16, 0, 0); } while (0)
; #define PG8_LDA(dst, b, h) do { _Pragma("unroll") for (int m = 0; m < 4; ++m) _Pragma("unroll") for (int k = 0; k < 2; ++k) dst[m][k] = *(const LAS bf16x8*)(lds + PG8_SA(b, h) + aoff + m * 2048 + k * 1024); } while (0)
; #define PG8_LDB(dst, b, h) do { _Pragma("unroll") for (int n = 0; n < 2; ++n) _Pragma("unroll") for (int k = 0; k < 2; ++k) dst[n][k] = *(const LAS bf16x8*)(lds + PG8_SB(b, h) + boff + n * 2048 + k * 1024); } while (0)
; #define PG8_MMA(ai, bj, At, Bt) do { __builtin_amdgcn_s_setprio(1); _Pragma("unroll") for (int m = 0; m < 4; ++m) _Pragma("unroll") for (int n = 0; n < 2; ++n) _Pragma("unroll") for (int k = 0; k < 2; ++k) \
;     acc[ai][bj][m][n] = __builtin_amdgcn_mfma_f32_16x16x32_bf16(Bt[n][k], At[m][k], acc[ai][bj][m][n], 0, 0, 0); __builtin_amdgcn_s_setprio(0); } while (0)
; #define PG8_WAIT_L(n) asm volatile("s_waitcnt lgkmcnt(" #n ")" ::: "memory")
; #define PG8_BAR __builtin_amdgcn_s_barrier()
; #define PG8_SCHED __builtin_amdgcn_sched_barrier(0)
; template <class Epi, class Sched = StaticOrder>
; DI void gemm_phase(LAS unsigned char* lds, const Gemm g, const Sched& S, const Epi& E) {
;     ...
;     for (int t = 0; t < nt; t += 2) {
;       const bool last = (t == nt - 2);
;       const char* a1 = cA + (size_t)(t + 1) * kstep;
;       const char* a2 = last ? nA : cA + (size_t)(t + 2) * kstep; const char* b2 = last ? nB : cB + (size_t)(t + 2) * kstep;
;       const char* a3 = a2 + kstep; const char* b3 = b2 + kstep;
;       PG8_LDB(B0, 0, 0); PG8_SCHED; PG8_LDA(At, 0, 0); PG8_STAGE(PG8_SA(1, 1), a1 + hstep, voffA);
;       PG8_WAIT_L(8); PG8_BAR; PG8_WAIT_L(0); PG8_MMA(0, 0, At, B0); PG8_BAR; PG8_SCHED;
;     ...
; #pragma unroll
;     for (int a = 0; a < 2; ++a)
; #pragma unroll
;       for (int b = 0; b < 2; ++b)
; #pragma unroll
;         for (int m = 0; m < 4; ++m)
; #pragma unroll
;           for (int n = 0; n < 2; ++n) acc[a][b][m][n] = (f32x4){0.f, 0.f, 0.f, 0.f};
;     cur = nxt; cA = nA; cB = nB; ++ui;
.LBB0_1276:
	s_ashr_i32 s41, s40, 31
	s_lshl_b64 s[42:43], s[40:41], 20
	v_cmp_lt_i64_e32 vcc, s[44:45], v[174:175]
	s_add_u32 s44, s56, s42
	s_addc_u32 s45, s57, s43
	s_and_b64 s[42:43], vcc, exec
	s_cselect_b32 s41, s45, s15
	s_cselect_b32 s42, s44, s14
	s_ashr_i32 s39, s38, 31
	s_lshl_b64 s[46:47], s[38:39], 20
	s_add_u32 s46, s60, s46
	s_addc_u32 s47, s61, s47
	s_and_b64 s[50:51], vcc, exec
	s_cselect_b32 s39, s47, s49
	s_cselect_b32 s43, s46, s48
	s_add_u32 s14, s14, 0x80080
	s_addc_u32 s15, s15, 0
	s_add_u32 s52, s48, 0x100
	v_mov_b32_e32 v0, 0
	s_addc_u32 s53, s49, 0
	s_mov_b32 s58, -2
	v_mov_b32_e32 v1, v0
	v_mov_b32_e32 v2, v0
	v_mov_b32_e32 v3, v0
	v_mov_b32_e32 v4, v0
	v_mov_b32_e32 v5, v0
	v_mov_b32_e32 v6, v0
	v_mov_b32_e32 v7, v0
	v_mov_b32_e32 v8, v0
	v_mov_b32_e32 v9, v0
	v_mov_b32_e32 v10, v0
	v_mov_b32_e32 v11, v0
	v_mov_b32_e32 v24, v0
	v_mov_b32_e32 v25, v0
	v_mov_b32_e32 v26, v0
	v_mov_b32_e32 v27, v0
	v_mov_b32_e32 v32, v0
	v_mov_b32_e32 v33, v0
	v_mov_b32_e32 v34, v0
	v_mov_b32_e32 v35, v0
	v_mov_b32_e32 v40, v0
	v_mov_b32_e32 v41, v0
	v_mov_b32_e32 v42, v0
	v_mov_b32_e32 v43, v0
	v_mov_b32_e32 v52, v0
	v_mov_b32_e32 v53, v0
	v_mov_b32_e32 v54, v0
	v_mov_b32_e32 v55, v0
	v_mov_b32_e32 v56, v0
	v_mov_b32_e32 v57, v0
	v_mov_b32_e32 v58, v0
	v_mov_b32_e32 v59, v0
	v_mov_b32_e32 v12, v0
	v_mov_b32_e32 v13, v0
	v_mov_b32_e32 v14, v0
	v_mov_b32_e32 v15, v0
	v_mov_b32_e32 v16, v0
	v_mov_b32_e32 v17, v0
	v_mov_b32_e32 v18, v0
	v_mov_b32_e32 v19, v0
	v_mov_b32_e32 v20, v0
	v_mov_b32_e32 v21, v0
	v_mov_b32_e32 v22, v0
	v_mov_b32_e32 v23, v0
	v_mov_b32_e32 v28, v0
	v_mov_b32_e32 v29, v0
	v_mov_b32_e32 v30, v0
	v_mov_b32_e32 v31, v0
	v_mov_b32_e32 v36, v0
	v_mov_b32_e32 v37, v0
	v_mov_b32_e32 v38, v0
	v_mov_b32_e32 v39, v0
	v_mov_b32_e32 v44, v0
	v_mov_b32_e32 v45, v0
	v_mov_b32_e32 v46, v0
	v_mov_b32_e32 v47, v0
	v_mov_b32_e32 v48, v0
	v_mov_b32_e32 v49, v0
	v_mov_b32_e32 v50, v0
	v_mov_b32_e32 v51, v0
	v_mov_b32_e32 v60, v0
	v_mov_b32_e32 v61, v0
	v_mov_b32_e32 v62, v0
	v_mov_b32_e32 v63, v0
	v_mov_b32_e32 v96, v0
	v_mov_b32_e32 v97, v0
	v_mov_b32_e32 v98, v0
	v_mov_b32_e32 v99, v0
	v_mov_b32_e32 v100, v0
	v_mov_b32_e32 v101, v0
	v_mov_b32_e32 v102, v0
	v_mov_b32_e32 v103, v0
	v_mov_b32_e32 v104, v0
	v_mov_b32_e32 v105, v0
	v_mov_b32_e32 v106, v0
	v_mov_b32_e32 v107, v0
	v_mov_b32_e32 v120, v0
	v_mov_b32_e32 v121, v0
	v_mov_b32_e32 v122, v0
	v_mov_b32_e32 v123, v0
	v_mov_b32_e32 v128, v0
	v_mov_b32_e32 v129, v0
	v_mov_b32_e32 v130, v0
	v_mov_b32_e32 v131, v0
	v_mov_b32_e32 v136, v0
	v_mov_b32_e32 v137, v0
	v_mov_b32_e32 v138, v0
	v_mov_b32_e32 v139, v0
	v_mov_b32_e32 v148, v0
	v_mov_b32_e32 v149, v0
	v_mov_b32_e32 v150, v0
	v_mov_b32_e32 v151, v0
	v_mov_b32_e32 v152, v0
	v_mov_b32_e32 v153, v0
	v_mov_b32_e32 v154, v0
	v_mov_b32_e32 v155, v0
	v_mov_b32_e32 v108, v0
	v_mov_b32_e32 v109, v0
	v_mov_b32_e32 v110, v0
	v_mov_b32_e32 v111, v0
	v_mov_b32_e32 v112, v0
	v_mov_b32_e32 v113, v0
	v_mov_b32_e32 v114, v0
	v_mov_b32_e32 v115, v0
	v_mov_b32_e32 v116, v0
	v_mov_b32_e32 v117, v0
	v_mov_b32_e32 v118, v0
	v_mov_b32_e32 v119, v0
	v_mov_b32_e32 v124, v0
	v_mov_b32_e32 v125, v0
	v_mov_b32_e32 v126, v0
	v_mov_b32_e32 v127, v0
	v_mov_b32_e32 v132, v0
	v_mov_b32_e32 v133, v0
	v_mov_b32_e32 v134, v0
	v_mov_b32_e32 v135, v0
	v_mov_b32_e32 v140, v0
	v_mov_b32_e32 v141, v0
	v_mov_b32_e32 v142, v0
	v_mov_b32_e32 v143, v0
	v_mov_b32_e32 v144, v0
	v_mov_b32_e32 v145, v0
	v_mov_b32_e32 v146, v0
	v_mov_b32_e32 v147, v0
	v_mov_b32_e32 v156, v0
	v_mov_b32_e32 v157, v0
	v_mov_b32_e32 v158, v0
	v_mov_b32_e32 v159, v0
	ds_read_b128 v[64:67], v201
	ds_read_b128 v[68:71], v201 offset:1024
	ds_read_b128 v[72:75], v201 offset:2048
	ds_read_b128 v[76:79], v201 offset:3072
	ds_read_b128 v[80:83], v202
	ds_read_b128 v[88:91], v202 offset:2048
	ds_read_b128 v[180:183], v202 offset:4096
	ds_read_b128 v[188:191], v202 offset:6144
.LBB0_1277:
	s_add_u32 s48, s14, 0xfff80080
	s_addc_u32 s49, s15, -1
	s_cmp_eq_u32 s58, 28
	s_cselect_b32 s51, s41, s49
	s_cselect_b32 s50, s42, s48
	s_cselect_b32 s49, s39, s53
	s_cselect_b32 s48, s43, s52
	s_add_i32 m0, s64, 0xc000
	ds_read_b128 v[84:87], v202 offset:1024
	ds_read_b128 v[92:95], v202 offset:3072
	ds_read_b128 v[184:187], v202 offset:5120
	ds_read_b128 v[192:195], v202 offset:7168
	global_load_lds_dwordx4 v170, s[14:15]
	s_add_i32 m0, s64, 0xe000
	s_nop 0
	global_load_lds_dwordx4 v172, s[14:15]
	s_waitcnt lgkmcnt(0)
	s_waitcnt vmcnt(8)
	s_setprio 1
	s_barrier
	v_mfma_f32_16x16x32_bf16 v[156:159], v[64:67], v[80:83], v[156:159]
	v_mfma_f32_16x16x32_bf16 v[144:147], v[72:75], v[80:83], v[144:147]
	v_mfma_f32_16x16x32_bf16 v[140:143], v[64:67], v[88:91], v[140:143]
	v_mfma_f32_16x16x32_bf16 v[132:135], v[72:75], v[88:91], v[132:135]
	v_mfma_f32_16x16x32_bf16 v[124:127], v[64:67], v[180:183], v[124:127]
	v_mfma_f32_16x16x32_bf16 v[116:119], v[72:75], v[180:183], v[116:119]
	v_mfma_f32_16x16x32_bf16 v[112:115], v[64:67], v[188:191], v[112:115]
	v_mfma_f32_16x16x32_bf16 v[108:111], v[72:75], v[188:191], v[108:111]
	v_mfma_f32_16x16x32_bf16 v[156:159], v[68:71], v[84:87], v[156:159]
	v_mfma_f32_16x16x32_bf16 v[144:147], v[76:79], v[84:87], v[144:147]
	v_mfma_f32_16x16x32_bf16 v[140:143], v[68:71], v[92:95], v[140:143]
	v_mfma_f32_16x16x32_bf16 v[132:135], v[76:79], v[92:95], v[132:135]
	v_mfma_f32_16x16x32_bf16 v[124:127], v[68:71], v[184:187], v[124:127]
	v_mfma_f32_16x16x32_bf16 v[116:119], v[76:79], v[184:187], v[116:119]
	v_mfma_f32_16x16x32_bf16 v[112:115], v[68:71], v[192:195], v[112:115]
	v_mfma_f32_16x16x32_bf16 v[108:111], v[76:79], v[192:195], v[108:111]
	s_barrier
; #define PG8_STAGE(bufoff, gbase, voff) do { _Pragma("unroll") for (int _i = 0; _i < 2; ++_i) \
;     __builtin_amdgcn_global_load_lds((const unsigned*)((const char*)(gbase) + (voff)[_i]), (LAS unsigned*)(lds + (bufoff) + ldsw + _i * 8192), 16, 0, 0); } while (0)
; #define PG8_LDA(dst, b, h) do { _Pragma("unroll") for (int m = 0; m < 4; ++m) _Pragma("unroll") for (int k = 0; k < 2; ++k) dst[m][k] = *(const LAS bf16x8*)(lds + PG8_SA(b, h) + aoff + m * 2048 + k * 1024); } while (0)
; #define PG8_LDB(dst, b, h) do { _Pragma("unroll") for (int n = 0; n < 2; ++n) _Pragma("unroll") for (int k = 0; k < 2; ++k) dst[n][k] = *(const LAS bf16x8*)(lds + PG8_SB(b, h) + boff + n * 2048 + k * 1024); } while (0)
; #define PG8_MMA(ai, bj, At, Bt) do { __builtin_amdgcn_s_setprio(1); _Pragma("unroll") for (int m = 0; m < 4; ++m) _Pragma("unroll") for (int n = 0; n < 2; ++n) _Pragma("unroll") for (int k = 0; k < 2; ++k) \
;     acc[ai][bj][m][n] = __builtin_amdgcn_mfma_f32_16x16x32_bf16(Bt[n][k], At[m][k], acc[ai][bj][m][n], 0, 0, 0); __builtin_amdgcn_s_setprio(0); } while (0)
; #define PG8_WAIT_V(n) asm volatile("s_waitcnt vmcnt(" #n ")" ::: "memory")
; #define PG8_WAIT_L(n) asm volatile("s_waitcnt lgkmcnt(" #n ")" ::: "memory")
; #define PG8_BAR __builtin_amdgcn_s_barrier()
; #define PG8_SCHED __builtin_amdgcn_sched_barrier(0)
; template <class Epi, class Sched = StaticOrder>
; DI void gemm_phase(LAS unsigned char* lds, const Gemm g, const Sched& S, const Epi& E) {
;     ...
;       PG8_LDB(B1, 0, 1); PG8_STAGE(PG8_SB(0, 0), b2, voffB);
;       PG8_BAR; PG8_WAIT_L(0); PG8_MMA(0, 1, At, B1); PG8_BAR;
;       PG8_LDA(At, 0, 1); PG8_STAGE(PG8_SA(0, 0), a2, voffA);
;       PG8_BAR; PG8_WAIT_L(0); PG8_MMA(1, 0, At, B0); PG8_BAR; PG8_SCHED;
;       PG8_STAGE(PG8_SB(0, 1), b2 + hstep, voffB);
;       PG8_WAIT_V(6); PG8_BAR; PG8_MMA(1, 1, At, B1); PG8_BAR;
;       PG8_LDB(B0, 1, 0); PG8_SCHED; PG8_LDA(At, 1, 0); PG8_STAGE(PG8_SA(0, 1), a2 + hstep, voffA);
;       PG8_WAIT_L(8); PG8_BAR; PG8_WAIT_L(0); PG8_MMA(0, 0, At, B0); PG8_BAR; PG8_SCHED;
	s_setprio 0
	s_add_i32 s59, s72, s62
	s_add_u32 s98, s48, 0x80
	s_addc_u32 s99, s49, 0
	s_mov_b32 m0, s59
	ds_read_b128 v[206:209], v203
	ds_read_b128 v[212:215], v203 offset:1024
	ds_read_b128 v[216:219], v203 offset:2048
	ds_read_b128 v[220:223], v203 offset:3072
	global_load_lds_dwordx4 v164, s[48:49]
	s_add_i32 m0, s59, 0x2000
	s_nop 0
	global_load_lds_dwordx4 v160, s[48:49]
	s_waitcnt lgkmcnt(0)
	s_setprio 1
	s_barrier
	v_mfma_f32_16x16x32_bf16 v[152:155], v[206:209], v[80:83], v[152:155]
	v_mfma_f32_16x16x32_bf16 v[80:83], v[216:219], v[80:83], v[148:151]
	v_mfma_f32_16x16x32_bf16 v[152:155], v[212:215], v[84:87], v[152:155]
	v_mfma_f32_16x16x32_bf16 v[80:83], v[220:223], v[84:87], v[80:83]
	v_mfma_f32_16x16x32_bf16 v[84:87], v[206:209], v[88:91], v[136:139]
	v_mfma_f32_16x16x32_bf16 v[88:91], v[216:219], v[88:91], v[128:131]
	v_mfma_f32_16x16x32_bf16 v[104:107], v[216:219], v[180:183], v[104:107]
	v_mfma_f32_16x16x32_bf16 v[100:103], v[206:209], v[188:191], v[100:103]
	v_mfma_f32_16x16x32_bf16 v[96:99], v[216:219], v[188:191], v[96:99]
	ds_read_b128 v[128:131], v202 offset:17408
	v_mfma_f32_16x16x32_bf16 v[84:87], v[212:215], v[92:95], v[84:87]
	ds_read_b128 v[136:139], v202 offset:18432
	v_mfma_f32_16x16x32_bf16 v[88:91], v[220:223], v[92:95], v[88:91]
	ds_read_b128 v[148:151], v202 offset:19456
	v_mfma_f32_16x16x32_bf16 v[92:95], v[206:209], v[180:183], v[120:123]
	v_mfma_f32_16x16x32_bf16 v[104:107], v[220:223], v[184:187], v[104:107]
	v_mfma_f32_16x16x32_bf16 v[100:103], v[212:215], v[192:195], v[100:103]
	v_mfma_f32_16x16x32_bf16 v[96:99], v[220:223], v[192:195], v[96:99]
	v_mfma_f32_16x16x32_bf16 v[92:95], v[212:215], v[184:187], v[92:95]
	s_barrier
	s_setprio 0
	s_mov_b32 m0, s64
	s_add_u32 s100, s50, 0x80
	s_addc_u32 s101, s51, 0
	ds_read_b128 v[120:123], v202 offset:16384
	ds_read_b128 v[180:183], v202 offset:20480
	ds_read_b128 v[184:187], v202 offset:21504
	ds_read_b128 v[188:191], v202 offset:22528
	ds_read_b128 v[192:195], v202 offset:23552
	global_load_lds_dwordx4 v166, s[50:51]
	s_mov_b32 m0, s65
	s_nop 0
	global_load_lds_dwordx4 v162, s[50:51]
	s_waitcnt vmcnt(8)
	s_waitcnt lgkmcnt(0)
	s_setprio 1
	s_barrier
	v_mfma_f32_16x16x32_bf16 v[60:63], v[64:67], v[120:123], v[60:63]
	v_mfma_f32_16x16x32_bf16 v[48:51], v[72:75], v[120:123], v[48:51]
	v_mfma_f32_16x16x32_bf16 v[44:47], v[64:67], v[136:139], v[44:47]
	v_mfma_f32_16x16x32_bf16 v[36:39], v[72:75], v[136:139], v[36:39]
	v_mfma_f32_16x16x32_bf16 v[28:31], v[64:67], v[180:183], v[28:31]
	v_mfma_f32_16x16x32_bf16 v[20:23], v[72:75], v[180:183], v[20:23]
	v_mfma_f32_16x16x32_bf16 v[16:19], v[64:67], v[188:191], v[16:19]
	v_mfma_f32_16x16x32_bf16 v[12:15], v[72:75], v[188:191], v[12:15]
	v_mfma_f32_16x16x32_bf16 v[60:63], v[68:71], v[128:131], v[60:63]
	v_mfma_f32_16x16x32_bf16 v[48:51], v[76:79], v[128:131], v[48:51]
	v_mfma_f32_16x16x32_bf16 v[44:47], v[68:71], v[148:151], v[44:47]
	v_mfma_f32_16x16x32_bf16 v[36:39], v[76:79], v[148:151], v[36:39]
	v_mfma_f32_16x16x32_bf16 v[28:31], v[68:71], v[184:187], v[28:31]
	v_mfma_f32_16x16x32_bf16 v[20:23], v[76:79], v[184:187], v[20:23]
	v_mfma_f32_16x16x32_bf16 v[16:19], v[68:71], v[192:195], v[16:19]
	v_mfma_f32_16x16x32_bf16 v[12:15], v[76:79], v[192:195], v[12:15]
	s_barrier
	s_setprio 0
	s_add_u32 s78, s48, 0x80000
	s_addc_u32 s79, s49, 0
	s_add_i32 s59, s73, s62
	s_mov_b32 m0, s59
	s_nop 0
	global_load_lds_dwordx4 v164, s[78:79]
	s_add_i32 m0, s59, 0x2000
	s_nop 0
	global_load_lds_dwordx4 v160, s[78:79]
	s_add_i32 s59, 0, 0x18000
	v_add_u32_e32 v76, s59, v198
	ds_read_b128 v[64:67], v76
	ds_read_b128 v[68:71], v76 offset:1024
	ds_read_b128 v[72:75], v76 offset:2048
	ds_read_b128 v[76:79], v76 offset:3072
	s_waitcnt vmcnt(6)
	s_setprio 1
	s_barrier
	v_mfma_f32_16x16x32_bf16 v[56:59], v[206:209], v[120:123], v[56:59]
	v_mfma_f32_16x16x32_bf16 v[52:55], v[216:219], v[120:123], v[52:55]
	v_mfma_f32_16x16x32_bf16 v[40:43], v[206:209], v[136:139], v[40:43]
	v_mfma_f32_16x16x32_bf16 v[32:35], v[216:219], v[136:139], v[32:35]
	v_mfma_f32_16x16x32_bf16 v[24:27], v[206:209], v[180:183], v[24:27]
	v_mfma_f32_16x16x32_bf16 v[8:11], v[216:219], v[180:183], v[8:11]
	v_mfma_f32_16x16x32_bf16 v[4:7], v[206:209], v[188:191], v[4:7]
	v_mfma_f32_16x16x32_bf16 v[0:3], v[216:219], v[188:191], v[0:3]
	v_mfma_f32_16x16x32_bf16 v[56:59], v[212:215], v[128:131], v[56:59]
	ds_read_b128 v[120:123], v202 offset:32768
	v_mfma_f32_16x16x32_bf16 v[52:55], v[220:223], v[128:131], v[52:55]
	ds_read_b128 v[180:183], v202 offset:34816
	v_mfma_f32_16x16x32_bf16 v[40:43], v[212:215], v[148:151], v[40:43]
	ds_read_b128 v[188:191], v202 offset:36864
	v_mfma_f32_16x16x32_bf16 v[32:35], v[220:223], v[148:151], v[32:35]
	ds_read_b128 v[206:209], v202 offset:38912
	v_mfma_f32_16x16x32_bf16 v[24:27], v[212:215], v[184:187], v[24:27]
	v_mfma_f32_16x16x32_bf16 v[8:11], v[220:223], v[184:187], v[8:11]
	v_mfma_f32_16x16x32_bf16 v[4:7], v[212:215], v[192:195], v[4:7]
	v_mfma_f32_16x16x32_bf16 v[0:3], v[220:223], v[192:195], v[0:3]
	s_barrier
	s_setprio 0
	s_add_u32 s50, s50, 0x80000
	s_addc_u32 s51, s51, 0
	s_mov_b32 m0, s66
	ds_read_b128 v[128:131], v202 offset:33792
	ds_read_b128 v[184:187], v202 offset:35840
	ds_read_b128 v[192:195], v202 offset:37888
	ds_read_b128 v[212:215], v202 offset:39936
	global_load_lds_dwordx4 v166, s[50:51]
	s_mov_b32 m0, s67
	s_nop 0
	global_load_lds_dwordx4 v162, s[50:51]
	s_waitcnt lgkmcnt(0)
	s_waitcnt vmcnt(8)
	s_setprio 1
	s_barrier
; #define PG8_STAGE(bufoff, gbase, voff) do { _Pragma("unroll") for (int _i = 0; _i < 2; ++_i) \
;     __builtin_amdgcn_global_load_lds((const unsigned*)((const char*)(gbase) + (voff)[_i]), (LAS unsigned*)(lds + (bufoff) + ldsw + _i * 8192), 16, 0, 0); } while (0)
; #define PG8_LDA(dst, b, h) do { _Pragma("unroll") for (int m = 0; m < 4; ++m) _Pragma("unroll") for (int k = 0; k < 2; ++k) dst[m][k] = *(const LAS bf16x8*)(lds + PG8_SA(b, h) + aoff + m * 2048 + k * 1024); } while (0)
; #define PG8_LDB(dst, b, h) do { _Pragma("unroll") for (int n = 0; n < 2; ++n) _Pragma("unroll") for (int k = 0; k < 2; ++k) dst[n][k] = *(const LAS bf16x8*)(lds + PG8_SB(b, h) + boff + n * 2048 + k * 1024); } while (0)
; #define PG8_MMA(ai, bj, At, Bt) do { __builtin_amdgcn_s_setprio(1); _Pragma("unroll") for (int m = 0; m < 4; ++m) _Pragma("unroll") for (int n = 0; n < 2; ++n) _Pragma("unroll") for (int k = 0; k < 2; ++k) \
;     acc[ai][bj][m][n] = __builtin_amdgcn_mfma_f32_16x16x32_bf16(Bt[n][k], At[m][k], acc[ai][bj][m][n], 0, 0, 0); __builtin_amdgcn_s_setprio(0); } while (0)
; #define PG8_WAIT_V(n) asm volatile("s_waitcnt vmcnt(" #n ")" ::: "memory")
; #define PG8_WAIT_L(n) asm volatile("s_waitcnt lgkmcnt(" #n ")" ::: "memory")
; #define PG8_BAR __builtin_amdgcn_s_barrier()
; #define PG8_SCHED __builtin_amdgcn_sched_barrier(0)
; template <class Epi, class Sched = StaticOrder>
; DI void gemm_phase(LAS unsigned char* lds, const Gemm g, const Sched& S, const Epi& E) {
;     ...
;       PG8_LDB(B1, 1, 1); PG8_STAGE(PG8_SB(1, 0), b3, voffB);
;       PG8_BAR; PG8_WAIT_L(0); PG8_MMA(0, 1, At, B1); PG8_BAR;
;       PG8_LDA(At, 1, 1); PG8_STAGE(PG8_SA(1, 0), a3, voffA);
;       PG8_BAR; PG8_WAIT_L(0); PG8_MMA(1, 0, At, B0); PG8_BAR; PG8_SCHED;
;       PG8_STAGE(PG8_SB(1, 1), b3 + hstep, voffB);
;       PG8_WAIT_V(6); PG8_BAR; PG8_MMA(1, 1, At, B1); PG8_BAR;
	v_mfma_f32_16x16x32_bf16 v[136:139], v[64:67], v[120:123], v[156:159]
	v_mfma_f32_16x16x32_bf16 v[156:159], v[68:71], v[128:131], v[136:139]
	v_mfma_f32_16x16x32_bf16 v[136:139], v[72:75], v[120:123], v[144:147]
	v_mfma_f32_16x16x32_bf16 v[144:147], v[76:79], v[128:131], v[136:139]
	v_mfma_f32_16x16x32_bf16 v[136:139], v[64:67], v[180:183], v[140:143]
	v_mfma_f32_16x16x32_bf16 v[132:135], v[72:75], v[180:183], v[132:135]
	v_mfma_f32_16x16x32_bf16 v[124:127], v[64:67], v[188:191], v[124:127]
	v_mfma_f32_16x16x32_bf16 v[116:119], v[72:75], v[188:191], v[116:119]
	v_mfma_f32_16x16x32_bf16 v[112:115], v[64:67], v[206:209], v[112:115]
	v_mfma_f32_16x16x32_bf16 v[108:111], v[72:75], v[206:209], v[108:111]
	v_mfma_f32_16x16x32_bf16 v[140:143], v[68:71], v[184:187], v[136:139]
	v_mfma_f32_16x16x32_bf16 v[132:135], v[76:79], v[184:187], v[132:135]
	v_mfma_f32_16x16x32_bf16 v[124:127], v[68:71], v[192:195], v[124:127]
	v_mfma_f32_16x16x32_bf16 v[116:119], v[76:79], v[192:195], v[116:119]
	v_mfma_f32_16x16x32_bf16 v[112:115], v[68:71], v[212:215], v[112:115]
	v_mfma_f32_16x16x32_bf16 v[108:111], v[76:79], v[212:215], v[108:111]
	s_barrier
	s_setprio 0
	s_add_i32 s50, 0, 0x1c000
	v_add_u32_e32 v136, s50, v198
	s_add_i32 s51, s59, s62
	ds_read_b128 v[216:219], v136
	ds_read_b128 v[220:223], v136 offset:1024
	ds_read_b128 v[224:227], v136 offset:2048
	ds_read_b128 v[228:231], v136 offset:3072
	s_mov_b32 m0, s51
	s_nop 0
	global_load_lds_dwordx4 v164, s[98:99]
	s_add_i32 m0, s51, 0x2000
	s_nop 0
	global_load_lds_dwordx4 v160, s[98:99]
	s_waitcnt lgkmcnt(0)
	s_setprio 1
	s_barrier
	v_mfma_f32_16x16x32_bf16 v[80:83], v[224:227], v[120:123], v[80:83]
	v_mfma_f32_16x16x32_bf16 v[136:139], v[216:219], v[120:123], v[152:155]
	v_mfma_f32_16x16x32_bf16 v[148:151], v[228:231], v[128:131], v[80:83]
	v_mfma_f32_16x16x32_bf16 v[80:83], v[216:219], v[180:183], v[84:87]
	v_mfma_f32_16x16x32_bf16 v[152:155], v[220:223], v[128:131], v[136:139]
	v_mfma_f32_16x16x32_bf16 v[136:139], v[220:223], v[184:187], v[80:83]
	v_mfma_f32_16x16x32_bf16 v[80:83], v[224:227], v[180:183], v[88:91]
	v_mfma_f32_16x16x32_bf16 v[128:131], v[228:231], v[184:187], v[80:83]
	v_mfma_f32_16x16x32_bf16 v[80:83], v[216:219], v[188:191], v[92:95]
	ds_read_b128 v[84:87], v202 offset:50176
	v_mfma_f32_16x16x32_bf16 v[120:123], v[220:223], v[192:195], v[80:83]
	ds_read_b128 v[88:91], v202 offset:51200
	v_mfma_f32_16x16x32_bf16 v[80:83], v[224:227], v[188:191], v[104:107]
	ds_read_b128 v[180:183], v202 offset:53248
	v_mfma_f32_16x16x32_bf16 v[104:107], v[228:231], v[192:195], v[80:83]
	ds_read_b128 v[184:187], v202 offset:54272
	v_mfma_f32_16x16x32_bf16 v[80:83], v[216:219], v[206:209], v[100:103]
	v_mfma_f32_16x16x32_bf16 v[100:103], v[220:223], v[212:215], v[80:83]
	v_mfma_f32_16x16x32_bf16 v[80:83], v[224:227], v[206:209], v[96:99]
	v_mfma_f32_16x16x32_bf16 v[96:99], v[228:231], v[212:215], v[80:83]
	s_barrier
	s_setprio 0
	s_mov_b32 m0, s55
	s_nop 2
	ds_read_b128 v[80:83], v202 offset:49152
	ds_read_b128 v[92:95], v202 offset:52224
	ds_read_b128 v[188:191], v202 offset:55296
	ds_read_b128 v[192:195], v202 offset:56320
	global_load_lds_dwordx4 v166, s[100:101]
	s_mov_b32 m0, s68
	s_nop 0
	global_load_lds_dwordx4 v162, s[100:101]
	s_waitcnt vmcnt(8)
	s_waitcnt lgkmcnt(0)
	s_setprio 1
	s_barrier
	v_mfma_f32_16x16x32_bf16 v[60:63], v[64:67], v[80:83], v[60:63]
	v_mfma_f32_16x16x32_bf16 v[48:51], v[72:75], v[80:83], v[48:51]
	v_mfma_f32_16x16x32_bf16 v[44:47], v[64:67], v[88:91], v[44:47]
	v_mfma_f32_16x16x32_bf16 v[36:39], v[72:75], v[88:91], v[36:39]
	v_mfma_f32_16x16x32_bf16 v[28:31], v[64:67], v[180:183], v[28:31]
	v_mfma_f32_16x16x32_bf16 v[20:23], v[72:75], v[180:183], v[20:23]
	v_mfma_f32_16x16x32_bf16 v[16:19], v[64:67], v[188:191], v[16:19]
	v_mfma_f32_16x16x32_bf16 v[12:15], v[72:75], v[188:191], v[12:15]
	v_mfma_f32_16x16x32_bf16 v[60:63], v[68:71], v[84:87], v[60:63]
	v_mfma_f32_16x16x32_bf16 v[48:51], v[76:79], v[84:87], v[48:51]
	v_mfma_f32_16x16x32_bf16 v[44:47], v[68:71], v[92:95], v[44:47]
	v_mfma_f32_16x16x32_bf16 v[36:39], v[76:79], v[92:95], v[36:39]
	v_mfma_f32_16x16x32_bf16 v[28:31], v[68:71], v[184:187], v[28:31]
	v_mfma_f32_16x16x32_bf16 v[20:23], v[76:79], v[184:187], v[20:23]
	v_mfma_f32_16x16x32_bf16 v[16:19], v[68:71], v[192:195], v[16:19]
	v_mfma_f32_16x16x32_bf16 v[12:15], v[76:79], v[192:195], v[12:15]
	s_barrier
	s_setprio 0
	s_add_u32 s48, s48, 0x80080
	s_addc_u32 s49, s49, 0
	s_add_i32 s50, s50, s62
	s_mov_b32 m0, s50
	s_nop 0
	global_load_lds_dwordx4 v164, s[48:49]
	s_add_i32 m0, s50, 0x2000
	s_nop 0
	global_load_lds_dwordx4 v160, s[48:49]
	ds_read_b128 v[64:67], v201
	ds_read_b128 v[68:71], v201 offset:1024
	ds_read_b128 v[72:75], v201 offset:2048
	ds_read_b128 v[76:79], v201 offset:3072
	s_waitcnt vmcnt(6)
	s_add_i32 s58, s58, 2
	s_add_u32 s14, s14, 0x100
	s_addc_u32 s15, s15, 0
	s_add_u32 s52, s52, 0x100
	s_addc_u32 s53, s53, 0
	s_cmp_gt_u32 s58, 29
	s_setprio 1
	s_barrier
	v_mfma_f32_16x16x32_bf16 v[56:59], v[216:219], v[80:83], v[56:59]
	v_mfma_f32_16x16x32_bf16 v[52:55], v[224:227], v[80:83], v[52:55]
	v_mfma_f32_16x16x32_bf16 v[40:43], v[216:219], v[88:91], v[40:43]
	v_mfma_f32_16x16x32_bf16 v[32:35], v[224:227], v[88:91], v[32:35]
	v_mfma_f32_16x16x32_bf16 v[24:27], v[216:219], v[180:183], v[24:27]
	v_mfma_f32_16x16x32_bf16 v[8:11], v[224:227], v[180:183], v[8:11]
	v_mfma_f32_16x16x32_bf16 v[4:7], v[216:219], v[188:191], v[4:7]
	v_mfma_f32_16x16x32_bf16 v[0:3], v[224:227], v[188:191], v[0:3]
	v_mfma_f32_16x16x32_bf16 v[56:59], v[220:223], v[84:87], v[56:59]
	ds_read_b128 v[80:83], v202
	v_mfma_f32_16x16x32_bf16 v[52:55], v[228:231], v[84:87], v[52:55]
	ds_read_b128 v[88:91], v202 offset:2048
	v_mfma_f32_16x16x32_bf16 v[40:43], v[220:223], v[92:95], v[40:43]
	ds_read_b128 v[180:183], v202 offset:4096
	v_mfma_f32_16x16x32_bf16 v[32:35], v[228:231], v[92:95], v[32:35]
	ds_read_b128 v[188:191], v202 offset:6144
	v_mfma_f32_16x16x32_bf16 v[24:27], v[220:223], v[184:187], v[24:27]
	v_mfma_f32_16x16x32_bf16 v[8:11], v[228:231], v[184:187], v[8:11]
	v_mfma_f32_16x16x32_bf16 v[4:7], v[220:223], v[192:195], v[4:7]
	v_mfma_f32_16x16x32_bf16 v[0:3], v[228:231], v[192:195], v[0:3]
	s_barrier
; DI float dpp_ror1(float v) { return __int_as_float(__builtin_amdgcn_update_dpp(0, __float_as_int(v), 0x121, 0xf, 0xf, false)); }
; DI float dpp_ror2(float v) { return __int_as_float(__builtin_amdgcn_update_dpp(0, __float_as_int(v), 0x122, 0xf, 0xf, false)); }
; DI float row_rstd(const float* ssq, int row, int fq) {
;   const f32x4 a = *(const f32x4*)(ssq + (size_t)row * 32 + fq * 8), b = *(const f32x4*)(ssq + (size_t)row * 32 + fq * 8 + 4);
;   float sm = ((a[0] + a[1]) + (a[2] + a[3])) + ((b[0] + b[1]) + (b[2] + b[3]));
;   sm += __shfl_xor(sm, 16); sm += __shfl_xor(sm, 32);
;   return rsqrtf(sm * (1.0f / 2048.f) + 1e-6f);
;   DI void operator()(const f32x4 (&acc)[2][2][4][2], const Unit& u, int wr, int wc, int fr, int fq) const {
;     const int col = u.pn * 128 + wc * 32 + 8 * fq;
;     float w0[8], w1[8], w2[8], bb[8];
; #pragma unroll
;     for (int e = 0; e < 8; ++e) { w0[e] = cw[col + e]; w1[e] = cw[5632 + col + e]; w2[e] = cw[2 * 5632 + col + e]; bb[e] = cb[col + e]; }
; #pragma unroll
;     for (int ai = 0; ai < 2; ++ai) {
;       const int row0 = u.pm * BM + ai * HALF + wr * 64, span = row0 >> 6;
;       float rsv[4];
; #pragma unroll
;       for (int m = 0; m < 4; ++m) rsv[m] = row_rstd(ssq, row0 + 16 * m + fr, fq);
;       float p1[8], p2[8];
; #pragma unroll
;       for (int e = 0; e < 8; ++e) { p1[e] = 0.f; p2[e] = 0.f; }
; #pragma unroll
;       for (int m = 0; m < 4; ++m) {
;         float g[8], uu[8], a[8];
;         const float rs = rsv[m];
; #pragma unroll
;         for (int e = 0; e < 4; ++e) { g[e] = acc[ai][0][m][0][e] * rs; g[4 + e] = acc[ai][0][m][1][e] * rs; uu[e] = acc[ai][1][m][0][e] * rs; uu[4 + e] = acc[ai][1][m][1][e] * rs; }
; #pragma unroll
;         for (int e = 0; e < 8; ++e) {
;           const float x1 = dpp_ror1(g[e]), x2 = dpp_ror2(g[e]);
;           const float pr1 = (fr == 0) ? p1[e] : x1, pr2 = (fr < 2) ? p2[e] : x2;
;           a[e] = w2[e] * g[e] + w1[e] * pr1 + w0[e] * pr2 + bb[e];
;           p1[e] = x1; p2[e] = x2;
;         }
	s_setprio 0
	s_cbranch_scc0 .LBB0_1277
	s_waitcnt lgkmcnt(0)
	s_lshl_b32 s39, s12, 8
	s_add_i32 s39, s39, s54
	v_or_b32_e32 v190, s39, v179
	v_ashrrev_i32_e32 v191, 31, v190
	v_lshlrev_b64 v[64:65], 7, v[190:191]
	v_or_b32_e32 v188, 16, v190
	v_lshl_add_u64 v[64:65], v[168:169], 0, v[64:65]
	v_ashrrev_i32_e32 v189, 31, v188
	global_load_dwordx4 v[192:195], v[64:65], off
	global_load_dwordx4 v[206:209], v[64:65], off offset:16
	v_lshlrev_b64 v[64:65], 7, v[188:189]
	v_lshl_add_u64 v[64:65], v[168:169], 0, v[64:65]
	global_load_dwordx4 v[212:215], v[64:65], off
	global_load_dwordx4 v[216:219], v[64:65], off offset:16
	v_or_b32_e32 v186, 32, v190
	v_ashrrev_i32_e32 v187, 31, v186
	v_lshlrev_b64 v[64:65], 7, v[186:187]
	v_or_b32_e32 v184, 48, v190
	v_lshl_add_u64 v[64:65], v[168:169], 0, v[64:65]
	v_ashrrev_i32_e32 v185, 31, v184
	global_load_dwordx4 v[220:223], v[64:65], off
	global_load_dwordx4 v[224:227], v[64:65], off offset:16
	v_lshlrev_b64 v[64:65], 7, v[184:185]
	v_lshl_add_u64 v[64:65], v[168:169], 0, v[64:65]
	global_load_dwordx4 v[228:231], v[64:65], off
	global_load_dwordx4 v[232:235], v[64:65], off offset:16
	v_lshl_or_b32 v180, s13, 7, v200
	v_and_b32_e32 v65, 64, v204
	v_xor_b32_e32 v64, 16, v204
	v_ashrrev_i32_e32 v181, 31, v180
	v_add_u32_e32 v65, 64, v65
	v_xor_b32_e32 v66, 32, v204
	v_lshlrev_b64 v[182:183], 2, v[180:181]
	v_cmp_lt_i32_e32 vcc, v64, v65
	v_lshl_add_u64 v[88:89], s[16:17], 0, v[182:183]
	v_lshl_add_u64 v[72:73], s[18:19], 0, v[182:183]
	v_cndmask_b32_e32 v64, v204, v64, vcc
	v_cmp_lt_i32_e32 vcc, v66, v65
	v_lshl_add_u64 v[74:75], v[88:89], 0, s[30:31]
	v_lshl_add_u64 v[76:77], v[88:89], 0, s[34:35]
	v_cndmask_b32_e32 v65, v204, v66, vcc
	v_add_co_u32_e32 v90, vcc, 0x5000, v88
	v_lshlrev_b32_e32 v187, 2, v64
	s_nop 0
	v_addc_co_u32_e32 v91, vcc, 0, v89, vcc
	v_add_co_u32_e32 v92, vcc, 0xb000, v88
	v_lshlrev_b32_e32 v185, 2, v65
	s_nop 0
	v_addc_co_u32_e32 v93, vcc, 0, v89, vcc
	global_load_dwordx4 v[64:67], v[88:89], off offset:16
	global_load_dwordx4 v[80:83], v[88:89], off
	global_load_dwordx4 v[68:71], v[72:73], off offset:16
	global_load_dwordx4 v[84:87], v[72:73], off
	s_nop 0
	global_load_dwordx4 v[72:75], v[74:75], off offset:16
	s_nop 0
	global_load_dwordx4 v[76:79], v[76:77], off offset:16
	s_nop 0
	global_load_dwordx4 v[88:91], v[90:91], off offset:2048
	s_nop 0
	global_load_dwordx4 v[92:95], v[92:93], off
	v_mov_b32_e32 v211, 0
	v_mov_b32_e32 v205, 0
	s_waitcnt vmcnt(0)
	v_mov_b32_e32 v196, v192
	v_mov_b32_e32 v197, v206
	v_mov_b32_e32 v206, v193
	v_mov_b32_e32 v192, v194
	v_mov_b32_e32 v193, v208
	v_mov_b32_e32 v208, v195
	v_pk_add_f32 v[194:195], v[196:197], v[206:207]
	v_pk_add_f32 v[192:193], v[192:193], v[208:209]
	v_mov_b32_e32 v196, v212
	v_mov_b32_e32 v197, v216
	v_mov_b32_e32 v216, v213
	v_mov_b32_e32 v206, v214
	v_mov_b32_e32 v207, v218
	v_mov_b32_e32 v218, v215
	v_pk_add_f32 v[192:193], v[194:195], v[192:193]
	v_pk_add_f32 v[194:195], v[196:197], v[216:217]
	v_pk_add_f32 v[196:197], v[206:207], v[218:219]
	v_mov_b32_e32 v208, v220
	v_pk_add_f32 v[194:195], v[194:195], v[196:197]
	v_mov_b32_e32 v197, v192
	v_mov_b32_e32 v196, v194
	v_mov_b32_e32 v192, v195
	v_pk_add_f32 v[192:193], v[196:197], v[192:193]
	ds_bpermute_b32 v195, v187, v193
	ds_bpermute_b32 v194, v187, v192
	v_mov_b32_e32 v209, v224
	v_mov_b32_e32 v224, v221
	v_mov_b32_e32 v212, v222
	v_mov_b32_e32 v213, v226
	s_waitcnt lgkmcnt(0)
	v_pk_add_f32 v[192:193], v[192:193], v[194:195]
	ds_bpermute_b32 v195, v185, v193
	ds_bpermute_b32 v194, v185, v192
	v_mov_b32_e32 v226, v223
	v_mov_b32_e32 v196, v228
	v_mov_b32_e32 v197, v232
	v_mov_b32_e32 v232, v229
	s_waitcnt lgkmcnt(0)
	v_pk_add_f32 v[192:193], v[192:193], v[194:195]
	v_mov_b32_e32 v206, v230
	v_pk_fma_f32 v[192:193], v[192:193], s[36:37], v[178:179] op_sel_hi:[1,0,0]
	v_mov_b32_e32 v207, v234
	v_mul_f32_e32 v189, 0x4b800000, v193
	v_cmp_gt_f32_e64 s[12:13], s74, v193
	v_mov_b32_e32 v234, v231
	v_pk_add_f32 v[208:209], v[208:209], v[224:225]
	v_cndmask_b32_e64 v189, v193, v189, s[12:13]
	v_rsq_f32_e32 v189, v189
	v_pk_add_f32 v[212:213], v[212:213], v[226:227]
	v_pk_add_f32 v[196:197], v[196:197], v[232:233]
	v_pk_add_f32 v[194:195], v[206:207], v[234:235]
	v_mul_f32_e32 v191, 0x45800000, v189
	v_cndmask_b32_e64 v220, v189, v191, s[12:13]
	v_pk_add_f32 v[208:209], v[208:209], v[212:213]
	v_pk_add_f32 v[194:195], v[196:197], v[194:195]
	v_pk_mul_f32 v[156:157], v[156:157], v[220:221] op_sel_hi:[1,0]
	v_mov_b32_e32 v216, 0
	v_mov_b32_e32 v218, 0
	v_mov_b32_e32 v196, v194
	v_mov_b32_e32 v197, v208
	v_mov_b32_e32 v208, v195
	v_mov_b32_dpp v216, v156 row_ror:1 row_mask:0xf bank_mask:0xf
	v_mov_b32_dpp v218, v157 row_ror:1 row_mask:0xf bank_mask:0xf
	v_pk_add_f32 v[194:195], v[196:197], v[208:209]
	v_cndmask_b32_e64 v207, v218, 0, s[0:1]
	v_cndmask_b32_e64 v206, v216, 0, s[0:1]
	v_pk_mul_f32 v[158:159], v[158:159], v[220:221] op_sel_hi:[1,0]
	v_mov_b32_e32 v212, 0
	v_mov_b32_e32 v214, 0
	ds_bpermute_b32 v197, v187, v195
	ds_bpermute_b32 v196, v187, v194
	v_mov_b32_e32 v215, 0
	v_mov_b32_e32 v217, 0
	v_pk_mul_f32 v[206:207], v[88:89], v[206:207]
	v_mov_b32_dpp v212, v158 row_ror:1 row_mask:0xf bank_mask:0xf
	v_mov_b32_dpp v214, v159 row_ror:1 row_mask:0xf bank_mask:0xf
	v_mov_b32_dpp v215, v156 row_ror:2 row_mask:0xf bank_mask:0xf
	v_mov_b32_dpp v217, v157 row_ror:2 row_mask:0xf bank_mask:0xf
	v_pk_fma_f32 v[156:157], v[92:93], v[156:157], v[206:207]
	v_mov_b32_e32 v213, 0
	v_cndmask_b32_e64 v207, v214, 0, s[0:1]
	v_cndmask_b32_e64 v206, v212, 0, s[0:1]
	v_cndmask_b32_e64 v209, v217, 0, s[4:5]
	v_cndmask_b32_e64 v208, v215, 0, s[4:5]
	v_mov_b32_dpp v211, v158 row_ror:2 row_mask:0xf bank_mask:0xf
	v_mov_b32_dpp v213, v159 row_ror:2 row_mask:0xf bank_mask:0xf
	v_pk_mul_f32 v[206:207], v[90:91], v[206:207]
	v_pk_fma_f32 v[156:157], v[80:81], v[208:209], v[156:157]
	v_cndmask_b32_e64 v209, v213, 0, s[4:5]
	v_cndmask_b32_e64 v208, v211, 0, s[4:5]
	v_pk_fma_f32 v[158:159], v[94:95], v[158:159], v[206:207]
	v_pk_mul_f32 v[144:145], v[144:145], v[220:221] op_sel_hi:[1,0]
	v_pk_fma_f32 v[158:159], v[82:83], v[208:209], v[158:159]
	v_mov_b32_e32 v207, 0
	v_mov_b32_e32 v209, 0
	v_pk_mul_f32 v[146:147], v[146:147], v[220:221] op_sel_hi:[1,0]
	v_mov_b32_e32 v191, 0
	s_waitcnt lgkmcnt(0)
; DI unsigned pack2(float lo, float hi) { f32x2 v = {lo, hi}; bf16v2 r = __builtin_convertvector(v, bf16v2); return __builtin_bit_cast(unsigned, r); }
; DI float silu_f(float x) { return x * sigmoid_f(x); }
; DI float dpp_ror1(float v) { return __int_as_float(__builtin_amdgcn_update_dpp(0, __float_as_int(v), 0x121, 0xf, 0xf, false)); }
; DI float dpp_ror2(float v) { return __int_as_float(__builtin_amdgcn_update_dpp(0, __float_as_int(v), 0x122, 0xf, 0xf, false)); }
;   DI void operator()(const f32x4 (&acc)[2][2][4][2], const Unit& u, int wr, int wc, int fr, int fq) const {
;     ...
;         for (int e = 0; e < 4; ++e) { g[e] = acc[ai][0][m][0][e] * rs; g[4 + e] = acc[ai][0][m][1][e] * rs; uu[e] = acc[ai][1][m][0][e] * rs; uu[4 + e] = acc[ai][1][m][1][e] * rs; }
; #pragma unroll
;         for (int e = 0; e < 8; ++e) {
;           const float x1 = dpp_ror1(g[e]), x2 = dpp_ror2(g[e]);
;           const float pr1 = (fr == 0) ? p1[e] : x1, pr2 = (fr < 2) ? p2[e] : x2;
;           a[e] = w2[e] * g[e] + w1[e] * pr1 + w0[e] * pr2 + bb[e];
;           p1[e] = x1; p2[e] = x2;
;         }
;         if (m == 0 && fr < 2) {
;           float* ha = headA + (size_t)(span * 2 + fr) * 5632 + col; float* hu = headU + (size_t)(span * 2 + fr) * 5632 + col;
;           *(f32x4*)ha = (f32x4){a[0], a[1], a[2], a[3]}; *(f32x4*)(ha + 4) = (f32x4){a[4], a[5], a[6], a[7]};
;           *(f32x4*)hu = (f32x4){uu[0], uu[1], uu[2], uu[3]}; *(f32x4*)(hu + 4) = (f32x4){uu[4], uu[5], uu[6], uu[7]};
;         } else {
;           u32x4 w;
;           w.x = pack2(silu_f(a[0]) * uu[0], silu_f(a[1]) * uu[1]);
;           w.y = pack2(silu_f(a[2]) * uu[2], silu_f(a[3]) * uu[3]);
;           w.z = pack2(silu_f(a[4]) * uu[4], silu_f(a[5]) * uu[5]);
;           w.w = pack2(silu_f(a[6]) * uu[6], silu_f(a[7]) * uu[7]);
;           *(u32x4*)(H + (size_t)(row0 + 16 * m + fr) * 5632 + col) = w;
	v_pk_add_f32 v[194:195], v[194:195], v[196:197]
	v_mov_b32_dpp v207, v144 row_ror:1 row_mask:0xf bank_mask:0xf
	v_mov_b32_dpp v209, v145 row_ror:1 row_mask:0xf bank_mask:0xf
	v_mov_b32_dpp v191, v146 row_ror:1 row_mask:0xf bank_mask:0xf
	v_mov_b32_dpp v205, v147 row_ror:1 row_mask:0xf bank_mask:0xf
	ds_bpermute_b32 v197, v185, v195
	ds_bpermute_b32 v196, v185, v194
	v_pk_mul_f32 v[152:153], v[152:153], v[220:221] op_sel_hi:[1,0]
	v_pk_mul_f32 v[148:149], v[148:149], v[220:221] op_sel_hi:[1,0]
	v_pk_mul_f32 v[154:155], v[154:155], v[220:221] op_sel_hi:[1,0]
	v_pk_mul_f32 v[150:151], v[150:151], v[220:221] op_sel_hi:[1,0]
	v_mov_b32_e32 v206, 0
	v_mov_b32_e32 v208, 0
	v_cndmask_b32_e64 v223, v209, 0, s[0:1]
	v_cndmask_b32_e64 v222, v207, 0, s[0:1]
	v_mov_b32_e32 v189, 0
	v_mov_b32_e32 v193, 0
	v_cndmask_b32_e64 v221, v205, 0, s[0:1]
	v_cndmask_b32_e64 v220, v191, 0, s[0:1]
	v_mov_b32_dpp v206, v144 row_ror:2 row_mask:0xf bank_mask:0xf
	v_mov_b32_dpp v208, v145 row_ror:2 row_mask:0xf bank_mask:0xf
	v_pk_mul_f32 v[222:223], v[72:73], v[222:223]
	v_mov_b32_dpp v189, v146 row_ror:2 row_mask:0xf bank_mask:0xf
	v_mov_b32_dpp v193, v147 row_ror:2 row_mask:0xf bank_mask:0xf
	v_pk_mul_f32 v[220:221], v[74:75], v[220:221]
	v_cndmask_b32_e64 v225, v208, 0, s[4:5]
	v_cndmask_b32_e64 v224, v206, 0, s[4:5]
	v_pk_fma_f32 v[144:145], v[76:77], v[144:145], v[222:223]
	v_cndmask_b32_e64 v223, v193, 0, s[4:5]
	v_cndmask_b32_e64 v222, v189, 0, s[4:5]
	v_pk_fma_f32 v[146:147], v[78:79], v[146:147], v[220:221]
	v_pk_fma_f32 v[144:145], v[64:65], v[224:225], v[144:145]
	v_pk_fma_f32 v[146:147], v[66:67], v[222:223], v[146:147]
	v_cmp_gt_f32_e32 vcc, s74, v192
	v_pk_add_f32 v[156:157], v[84:85], v[156:157]
	v_pk_add_f32 v[158:159], v[86:87], v[158:159]
	v_pk_add_f32 v[144:145], v[68:69], v[144:145]
	v_pk_add_f32 v[146:147], v[70:71], v[146:147]
	s_and_saveexec_b64 s[12:13], s[10:11]
	s_xor_b64 s[12:13], exec, s[12:13]
	s_cbranch_execz .LBB0_1280
	v_mul_f32_e32 v219, 0xbfb8aa3b, v156
	v_exp_f32_e32 v219, v219
	v_mul_f32_e32 v220, 0xbfb8aa3b, v157
	v_exp_f32_e32 v220, v220
	v_mul_f32_e32 v222, 0xbfb8aa3b, v159
	v_add_f32_e32 v219, 1.0, v219
	v_exp_f32_e32 v223, v222
	v_add_f32_e32 v221, 1.0, v220
	v_rcp_f32_e32 v220, v219
	v_mul_f32_e32 v219, 0xbfb8aa3b, v158
	v_exp_f32_e32 v219, v219
	v_rcp_f32_e32 v221, v221
	v_add_f32_e32 v219, 1.0, v219
	v_rcp_f32_e32 v222, v219
	v_add_f32_e32 v219, 1.0, v223
	v_rcp_f32_e32 v223, v219
	v_pk_mul_f32 v[156:157], v[156:157], v[220:221]
	s_nop 0
	v_pk_mul_f32 v[152:153], v[152:153], v[156:157]
	v_pk_mul_f32 v[156:157], v[158:159], v[222:223]
	v_cvt_pk_bf16_f32 v152, v152, v153
	v_mul_f32_e32 v153, 0xbfb8aa3b, v144
	v_pk_mul_f32 v[154:155], v[154:155], v[156:157]
	v_exp_f32_e32 v156, v153
	v_mul_f32_e32 v153, 0xbfb8aa3b, v145
	v_exp_f32_e32 v157, v153
	v_cvt_pk_bf16_f32 v153, v154, v155
	v_add_f32_e32 v154, 1.0, v156
	v_mul_f32_e32 v156, 0xbfb8aa3b, v146
	v_add_f32_e32 v155, 1.0, v157
	v_mul_f32_e32 v157, 0xbfb8aa3b, v147
	v_exp_f32_e32 v156, v156
	v_exp_f32_e32 v157, v157
	v_rcp_f32_e32 v154, v154
	v_rcp_f32_e32 v155, v155
	v_add_f32_e32 v156, 1.0, v156
	v_add_f32_e32 v157, 1.0, v157
	v_rcp_f32_e32 v156, v156
	v_rcp_f32_e32 v157, v157
	v_pk_mul_f32 v[144:145], v[144:145], v[154:155]
	s_nop 0
	v_pk_mul_f32 v[144:145], v[148:149], v[144:145]
	s_nop 0
	v_cvt_pk_bf16_f32 v154, v144, v145
	v_pk_mul_f32 v[144:145], v[146:147], v[156:157]
	s_nop 0
	v_pk_mul_f32 v[144:145], v[150:151], v[144:145]
	s_nop 0
	v_cvt_pk_bf16_f32 v155, v144, v145
	v_mov_b64_e32 v[144:145], s[20:21]
	v_mad_i64_i32 v[144:145], s[14:15], v190, s75, v[144:145]
	v_lshl_add_u64 v[144:145], v[180:181], 1, v[144:145]
	global_store_dwordx4 v[144:145], v[152:155], off

; #define PG8_STAGE(bufoff, gbase, voff) do { _Pragma("unroll") for (int _i = 0; _i < 2; ++_i) \
;     __builtin_amdgcn_global_load_lds((const unsigned*)((const char*)(gbase) + (voff)[_i]), (LAS unsigned*)(lds + (bufoff) + ldsw + _i * 8192), 16, 0, 0); } while (0)
; #define PG8_LDA(dst, b, h) do { _Pragma("unroll") for (int m = 0; m < 4; ++m) _Pragma("unroll") for (int k = 0; k < 2; ++k) dst[m][k] = *(const LAS bf16x8*)(lds + PG8_SA(b, h) + aoff + m * 2048 + k * 1024); } while (0)
; #define PG8_LDB(dst, b, h) do { _Pragma("unroll") for (int n = 0; n < 2; ++n) _Pragma("unroll") for (int k = 0; k < 2; ++k) dst[n][k] = *(const LAS bf16x8*)(lds + PG8_SB(b, h) + boff + n * 2048 + k * 1024); } while (0)
; #define PG8_MMA(ai, bj, At, Bt) do { __builtin_amdgcn_s_setprio(1); _Pragma("unroll") for (int m = 0; m < 4; ++m) _Pragma("unroll") for (int n = 0; n < 2; ++n) _Pragma("unroll") for (int k = 0; k < 2; ++k) \
;     acc[ai][bj][m][n] = __builtin_amdgcn_mfma_f32_16x16x32_bf16(Bt[n][k], At[m][k], acc[ai][bj][m][n], 0, 0, 0); __builtin_amdgcn_s_setprio(0); } while (0)
; #define PG8_WAIT_L(n) asm volatile("s_waitcnt lgkmcnt(" #n ")" ::: "memory")
; #define PG8_BAR __builtin_amdgcn_s_barrier()
; #define PG8_SCHED __builtin_amdgcn_sched_barrier(0)
; template <class Epi, class Sched = StaticOrder>
; DI void gemm_phase(LAS unsigned char* lds, const Gemm g, const Sched& S, const Epi& E) {
;     ...
;     for (int t = 0; t < nt; t += 2) {
;       const bool last = (t == nt - 2);
;       const char* a1 = cA + (size_t)(t + 1) * kstep;
;       const char* a2 = last ? nA : cA + (size_t)(t + 2) * kstep; const char* b2 = last ? nB : cB + (size_t)(t + 2) * kstep;
;       const char* a3 = a2 + kstep; const char* b3 = b2 + kstep;
;       PG8_LDB(B0, 0, 0); PG8_SCHED; PG8_LDA(At, 0, 0); PG8_STAGE(PG8_SA(1, 1), a1 + hstep, voffA);
;       PG8_WAIT_L(8); PG8_BAR; PG8_WAIT_L(0); PG8_MMA(0, 0, At, B0); PG8_BAR; PG8_SCHED;
;     ...
; #pragma unroll
;     for (int a = 0; a < 2; ++a)
; #pragma unroll
;       for (int b = 0; b < 2; ++b)
; #pragma unroll
;         for (int m = 0; m < 4; ++m)
; #pragma unroll
;           for (int n = 0; n < 2; ++n) acc[a][b][m][n] = (f32x4){0.f, 0.f, 0.f, 0.f};
;     cur = nxt; cA = nA; cB = nB; ++ui;
.LBB0_1423:
	s_add_u32 s16, s16, 0x160080
	s_addc_u32 s17, s17, 0
	s_add_u32 s45, s18, 0x100
	v_mov_b32_e32 v0, 0
	s_addc_u32 s46, s19, 0
	s_mov_b32 s47, -2
	v_mov_b32_e32 v1, v0
	v_mov_b32_e32 v2, v0
	v_mov_b32_e32 v3, v0
	v_mov_b32_e32 v4, v0
	v_mov_b32_e32 v5, v0
	v_mov_b32_e32 v6, v0
	v_mov_b32_e32 v7, v0
	v_mov_b32_e32 v8, v0
	v_mov_b32_e32 v9, v0
	v_mov_b32_e32 v10, v0
	v_mov_b32_e32 v11, v0
	v_mov_b32_e32 v16, v0
	v_mov_b32_e32 v17, v0
	v_mov_b32_e32 v18, v0
	v_mov_b32_e32 v19, v0
	v_mov_b32_e32 v24, v0
	v_mov_b32_e32 v25, v0
	v_mov_b32_e32 v26, v0
	v_mov_b32_e32 v27, v0
	v_mov_b32_e32 v32, v0
	v_mov_b32_e32 v33, v0
	v_mov_b32_e32 v34, v0
	v_mov_b32_e32 v35, v0
	v_mov_b32_e32 v40, v0
	v_mov_b32_e32 v41, v0
	v_mov_b32_e32 v42, v0
	v_mov_b32_e32 v43, v0
	v_mov_b32_e32 v48, v0
	v_mov_b32_e32 v49, v0
	v_mov_b32_e32 v50, v0
	v_mov_b32_e32 v51, v0
	v_mov_b32_e32 v12, v0
	v_mov_b32_e32 v13, v0
	v_mov_b32_e32 v14, v0
	v_mov_b32_e32 v15, v0
	v_mov_b32_e32 v20, v0
	v_mov_b32_e32 v21, v0
	v_mov_b32_e32 v22, v0
	v_mov_b32_e32 v23, v0
	v_mov_b32_e32 v28, v0
	v_mov_b32_e32 v29, v0
	v_mov_b32_e32 v30, v0
	v_mov_b32_e32 v31, v0
	v_mov_b32_e32 v36, v0
	v_mov_b32_e32 v37, v0
	v_mov_b32_e32 v38, v0
	v_mov_b32_e32 v39, v0
	v_mov_b32_e32 v44, v0
	v_mov_b32_e32 v45, v0
	v_mov_b32_e32 v46, v0
	v_mov_b32_e32 v47, v0
	v_mov_b32_e32 v52, v0
	v_mov_b32_e32 v53, v0
	v_mov_b32_e32 v54, v0
	v_mov_b32_e32 v55, v0
	v_mov_b32_e32 v56, v0
	v_mov_b32_e32 v57, v0
	v_mov_b32_e32 v58, v0
	v_mov_b32_e32 v59, v0
	v_mov_b32_e32 v60, v0
	v_mov_b32_e32 v61, v0
	v_mov_b32_e32 v62, v0
	v_mov_b32_e32 v63, v0
	v_mov_b32_e32 v64, v0
	v_mov_b32_e32 v65, v0
	v_mov_b32_e32 v66, v0
	v_mov_b32_e32 v67, v0
	v_mov_b32_e32 v68, v0
	v_mov_b32_e32 v69, v0
	v_mov_b32_e32 v70, v0
	v_mov_b32_e32 v71, v0
	v_mov_b32_e32 v72, v0
	v_mov_b32_e32 v73, v0
	v_mov_b32_e32 v74, v0
	v_mov_b32_e32 v75, v0
	v_mov_b32_e32 v76, v0
	v_mov_b32_e32 v77, v0
	v_mov_b32_e32 v78, v0
	v_mov_b32_e32 v79, v0
	v_mov_b32_e32 v84, v0
	v_mov_b32_e32 v85, v0
	v_mov_b32_e32 v86, v0
	v_mov_b32_e32 v87, v0
	v_mov_b32_e32 v92, v0
	v_mov_b32_e32 v93, v0
	v_mov_b32_e32 v94, v0
	v_mov_b32_e32 v95, v0
	v_mov_b32_e32 v100, v0
	v_mov_b32_e32 v101, v0
	v_mov_b32_e32 v102, v0
	v_mov_b32_e32 v103, v0
	v_mov_b32_e32 v108, v0
	v_mov_b32_e32 v109, v0
	v_mov_b32_e32 v110, v0
	v_mov_b32_e32 v111, v0
	v_mov_b32_e32 v80, v0
	v_mov_b32_e32 v81, v0
	v_mov_b32_e32 v82, v0
	v_mov_b32_e32 v83, v0
	v_mov_b32_e32 v88, v0
	v_mov_b32_e32 v89, v0
	v_mov_b32_e32 v90, v0
	v_mov_b32_e32 v91, v0
	v_mov_b32_e32 v96, v0
	v_mov_b32_e32 v97, v0
	v_mov_b32_e32 v98, v0
	v_mov_b32_e32 v99, v0
	v_mov_b32_e32 v104, v0
	v_mov_b32_e32 v105, v0
	v_mov_b32_e32 v106, v0
	v_mov_b32_e32 v107, v0
	v_mov_b32_e32 v112, v0
	v_mov_b32_e32 v113, v0
	v_mov_b32_e32 v114, v0
	v_mov_b32_e32 v115, v0
	v_mov_b32_e32 v116, v0
	v_mov_b32_e32 v117, v0
	v_mov_b32_e32 v118, v0
	v_mov_b32_e32 v119, v0
	v_mov_b32_e32 v120, v0
	v_mov_b32_e32 v121, v0
	v_mov_b32_e32 v122, v0
	v_mov_b32_e32 v123, v0
	v_mov_b32_e32 v124, v0
	v_mov_b32_e32 v125, v0
	v_mov_b32_e32 v126, v0
	v_mov_b32_e32 v127, v0
	ds_read_b128 v[144:147], v159
	ds_read_b128 v[148:151], v159 offset:1024
	ds_read_b128 v[152:155], v159 offset:2048
	ds_read_b128 v[162:165], v159 offset:3072
	ds_read_b128 v[166:169], v160
	ds_read_b128 v[174:177], v160 offset:2048
	ds_read_b128 v[182:185], v160 offset:4096
	ds_read_b128 v[190:193], v160 offset:6144
.LBB0_1424:
	s_add_u32 s18, s16, 0xffea0080
	s_addc_u32 s19, s17, -1
	s_cmpk_eq_i32 s47, 0x54
	s_cselect_b32 s21, s3, s19
	s_cselect_b32 s20, s2, s18
	s_cselect_b32 s19, s5, s46
	s_cselect_b32 s18, s4, s45
	s_add_i32 m0, s30, 0xc000
	ds_read_b128 v[170:173], v160 offset:1024
	ds_read_b128 v[178:181], v160 offset:3072
	ds_read_b128 v[186:189], v160 offset:5120
	ds_read_b128 v[194:197], v160 offset:7168
	global_load_lds_dwordx4 v136, s[16:17]
	s_add_i32 m0, s30, 0xe000
	s_nop 0
	global_load_lds_dwordx4 v138, s[16:17]
	s_waitcnt lgkmcnt(0)
	s_waitcnt vmcnt(8)
	s_setprio 1
	s_barrier
	v_mfma_f32_16x16x32_bf16 v[124:127], v[144:147], v[166:169], v[124:127]
	v_mfma_f32_16x16x32_bf16 v[120:123], v[152:155], v[166:169], v[120:123]
	v_mfma_f32_16x16x32_bf16 v[116:119], v[144:147], v[174:177], v[116:119]
	v_mfma_f32_16x16x32_bf16 v[112:115], v[152:155], v[174:177], v[112:115]
	v_mfma_f32_16x16x32_bf16 v[104:107], v[144:147], v[182:185], v[104:107]
	v_mfma_f32_16x16x32_bf16 v[96:99], v[152:155], v[182:185], v[96:99]
	v_mfma_f32_16x16x32_bf16 v[88:91], v[144:147], v[190:193], v[88:91]
	v_mfma_f32_16x16x32_bf16 v[80:83], v[152:155], v[190:193], v[80:83]
	v_mfma_f32_16x16x32_bf16 v[124:127], v[148:151], v[170:173], v[124:127]
	v_mfma_f32_16x16x32_bf16 v[120:123], v[162:165], v[170:173], v[120:123]
	v_mfma_f32_16x16x32_bf16 v[116:119], v[148:151], v[178:181], v[116:119]
	v_mfma_f32_16x16x32_bf16 v[112:115], v[162:165], v[178:181], v[112:115]
	v_mfma_f32_16x16x32_bf16 v[104:107], v[148:151], v[186:189], v[104:107]
	v_mfma_f32_16x16x32_bf16 v[96:99], v[162:165], v[186:189], v[96:99]
	v_mfma_f32_16x16x32_bf16 v[88:91], v[148:151], v[194:197], v[88:91]
	v_mfma_f32_16x16x32_bf16 v[80:83], v[162:165], v[194:197], v[80:83]
	s_barrier
	s_setprio 0
	s_add_i32 s48, s39, s28
	s_add_u32 s98, s18, 0x80
	s_addc_u32 s99, s19, 0
	s_mov_b32 m0, s48
	ds_read_b128 v[198:201], v161
	ds_read_b128 v[202:205], v161 offset:1024
	ds_read_b128 v[206:209], v161 offset:2048
	ds_read_b128 v[210:213], v161 offset:3072
	global_load_lds_dwordx4 v132, s[18:19]
	s_add_i32 m0, s48, 0x2000
	s_nop 0
	global_load_lds_dwordx4 v128, s[18:19]
	s_waitcnt lgkmcnt(0)
	s_setprio 1
	s_barrier
; #define PG8_STAGE(bufoff, gbase, voff) do { _Pragma("unroll") for (int _i = 0; _i < 2; ++_i) \
;     __builtin_amdgcn_global_load_lds((const unsigned*)((const char*)(gbase) + (voff)[_i]), (LAS unsigned*)(lds + (bufoff) + ldsw + _i * 8192), 16, 0, 0); } while (0)
; #define PG8_LDA(dst, b, h) do { _Pragma("unroll") for (int m = 0; m < 4; ++m) _Pragma("unroll") for (int k = 0; k < 2; ++k) dst[m][k] = *(const LAS bf16x8*)(lds + PG8_SA(b, h) + aoff + m * 2048 + k * 1024); } while (0)
; #define PG8_LDB(dst, b, h) do { _Pragma("unroll") for (int n = 0; n < 2; ++n) _Pragma("unroll") for (int k = 0; k < 2; ++k) dst[n][k] = *(const LAS bf16x8*)(lds + PG8_SB(b, h) + boff + n * 2048 + k * 1024); } while (0)
; #define PG8_MMA(ai, bj, At, Bt) do { __builtin_amdgcn_s_setprio(1); _Pragma("unroll") for (int m = 0; m < 4; ++m) _Pragma("unroll") for (int n = 0; n < 2; ++n) _Pragma("unroll") for (int k = 0; k < 2; ++k) \
;     acc[ai][bj][m][n] = __builtin_amdgcn_mfma_f32_16x16x32_bf16(Bt[n][k], At[m][k], acc[ai][bj][m][n], 0, 0, 0); __builtin_amdgcn_s_setprio(0); } while (0)
; #define PG8_WAIT_V(n) asm volatile("s_waitcnt vmcnt(" #n ")" ::: "memory")
; #define PG8_WAIT_L(n) asm volatile("s_waitcnt lgkmcnt(" #n ")" ::: "memory")
; #define PG8_BAR __builtin_amdgcn_s_barrier()
; #define PG8_SCHED __builtin_amdgcn_sched_barrier(0)
; template <class Epi, class Sched = StaticOrder>
; DI void gemm_phase(LAS unsigned char* lds, const Gemm g, const Sched& S, const Epi& E) {
;     ...
;       PG8_LDB(B1, 0, 1); PG8_STAGE(PG8_SB(0, 0), b2, voffB);
;       PG8_BAR; PG8_WAIT_L(0); PG8_MMA(0, 1, At, B1); PG8_BAR;
;       PG8_LDA(At, 0, 1); PG8_STAGE(PG8_SA(0, 0), a2, voffA);
;       PG8_BAR; PG8_WAIT_L(0); PG8_MMA(1, 0, At, B0); PG8_BAR; PG8_SCHED;
;       PG8_STAGE(PG8_SB(0, 1), b2 + hstep, voffB);
;       PG8_WAIT_V(6); PG8_BAR; PG8_MMA(1, 1, At, B1); PG8_BAR;
;       PG8_LDB(B0, 1, 0); PG8_SCHED; PG8_LDA(At, 1, 0); PG8_STAGE(PG8_SA(0, 1), a2 + hstep, voffA);
;       PG8_WAIT_L(8); PG8_BAR; PG8_WAIT_L(0); PG8_MMA(0, 0, At, B0); PG8_BAR; PG8_SCHED;
	v_mfma_f32_16x16x32_bf16 v[108:111], v[198:201], v[166:169], v[108:111]
	v_mfma_f32_16x16x32_bf16 v[100:103], v[206:209], v[166:169], v[100:103]
	v_mfma_f32_16x16x32_bf16 v[92:95], v[198:201], v[174:177], v[92:95]
	v_mfma_f32_16x16x32_bf16 v[84:87], v[206:209], v[174:177], v[84:87]
	v_mfma_f32_16x16x32_bf16 v[76:79], v[198:201], v[182:185], v[76:79]
	v_mfma_f32_16x16x32_bf16 v[72:75], v[206:209], v[182:185], v[72:75]
	v_mfma_f32_16x16x32_bf16 v[68:71], v[198:201], v[190:193], v[68:71]
	v_mfma_f32_16x16x32_bf16 v[64:67], v[206:209], v[190:193], v[64:67]
	v_mfma_f32_16x16x32_bf16 v[108:111], v[202:205], v[170:173], v[108:111]
	ds_read_b128 v[166:169], v160 offset:16384
	v_mfma_f32_16x16x32_bf16 v[100:103], v[210:213], v[170:173], v[100:103]
	ds_read_b128 v[174:177], v160 offset:18432
	v_mfma_f32_16x16x32_bf16 v[92:95], v[202:205], v[178:181], v[92:95]
	ds_read_b128 v[182:185], v160 offset:20480
	v_mfma_f32_16x16x32_bf16 v[84:87], v[210:213], v[178:181], v[84:87]
	ds_read_b128 v[190:193], v160 offset:22528
	v_mfma_f32_16x16x32_bf16 v[76:79], v[202:205], v[186:189], v[76:79]
	v_mfma_f32_16x16x32_bf16 v[72:75], v[210:213], v[186:189], v[72:75]
	v_mfma_f32_16x16x32_bf16 v[68:71], v[202:205], v[194:197], v[68:71]
	v_mfma_f32_16x16x32_bf16 v[64:67], v[210:213], v[194:197], v[64:67]
	s_barrier
	s_setprio 0
	s_mov_b32 m0, s30
	s_add_u32 s100, s20, 0x80
	s_addc_u32 s101, s21, 0
	ds_read_b128 v[170:173], v160 offset:17408
	ds_read_b128 v[178:181], v160 offset:19456
	ds_read_b128 v[186:189], v160 offset:21504
	ds_read_b128 v[194:197], v160 offset:23552
	global_load_lds_dwordx4 v134, s[20:21]
	s_mov_b32 m0, s31
	s_nop 0
	global_load_lds_dwordx4 v130, s[20:21]
	s_waitcnt vmcnt(8)
	s_waitcnt lgkmcnt(0)
	s_setprio 1
	s_barrier
	v_mfma_f32_16x16x32_bf16 v[60:63], v[144:147], v[166:169], v[60:63]
	v_mfma_f32_16x16x32_bf16 v[56:59], v[152:155], v[166:169], v[56:59]
	v_mfma_f32_16x16x32_bf16 v[52:55], v[144:147], v[174:177], v[52:55]
	v_mfma_f32_16x16x32_bf16 v[44:47], v[152:155], v[174:177], v[44:47]
	v_mfma_f32_16x16x32_bf16 v[36:39], v[144:147], v[182:185], v[36:39]
	v_mfma_f32_16x16x32_bf16 v[28:31], v[152:155], v[182:185], v[28:31]
	v_mfma_f32_16x16x32_bf16 v[20:23], v[144:147], v[190:193], v[20:23]
	v_mfma_f32_16x16x32_bf16 v[12:15], v[152:155], v[190:193], v[12:15]
	v_mfma_f32_16x16x32_bf16 v[60:63], v[148:151], v[170:173], v[60:63]
	v_mfma_f32_16x16x32_bf16 v[56:59], v[162:165], v[170:173], v[56:59]
	v_mfma_f32_16x16x32_bf16 v[52:55], v[148:151], v[178:181], v[52:55]
	v_mfma_f32_16x16x32_bf16 v[44:47], v[162:165], v[178:181], v[44:47]
	v_mfma_f32_16x16x32_bf16 v[36:39], v[148:151], v[186:189], v[36:39]
	v_mfma_f32_16x16x32_bf16 v[28:31], v[162:165], v[186:189], v[28:31]
	v_mfma_f32_16x16x32_bf16 v[20:23], v[148:151], v[194:197], v[20:23]
	v_mfma_f32_16x16x32_bf16 v[12:15], v[162:165], v[194:197], v[12:15]
	s_barrier
	s_setprio 0
	s_add_u32 s48, s18, 0x160000
	s_addc_u32 s49, s19, 0
	s_add_i32 s50, s40, s28
	s_mov_b32 m0, s50
	s_nop 0
	global_load_lds_dwordx4 v132, s[48:49]
	s_add_i32 m0, s50, 0x2000
	s_nop 0
	global_load_lds_dwordx4 v128, s[48:49]
	s_add_i32 s48, 0, 0x18000
	v_add_u32_e32 v162, s48, v157
	ds_read_b128 v[144:147], v162
	ds_read_b128 v[148:151], v162 offset:1024
	ds_read_b128 v[152:155], v162 offset:2048
	ds_read_b128 v[162:165], v162 offset:3072
	s_waitcnt vmcnt(6)
	s_setprio 1
	s_barrier
	v_mfma_f32_16x16x32_bf16 v[48:51], v[198:201], v[166:169], v[48:51]
	v_mfma_f32_16x16x32_bf16 v[40:43], v[206:209], v[166:169], v[40:43]
	v_mfma_f32_16x16x32_bf16 v[32:35], v[198:201], v[174:177], v[32:35]
	v_mfma_f32_16x16x32_bf16 v[24:27], v[206:209], v[174:177], v[24:27]
	v_mfma_f32_16x16x32_bf16 v[16:19], v[198:201], v[182:185], v[16:19]
	v_mfma_f32_16x16x32_bf16 v[8:11], v[206:209], v[182:185], v[8:11]
	v_mfma_f32_16x16x32_bf16 v[4:7], v[198:201], v[190:193], v[4:7]
	v_mfma_f32_16x16x32_bf16 v[0:3], v[206:209], v[190:193], v[0:3]
	v_mfma_f32_16x16x32_bf16 v[48:51], v[202:205], v[170:173], v[48:51]
	ds_read_b128 v[166:169], v160 offset:32768
	v_mfma_f32_16x16x32_bf16 v[40:43], v[210:213], v[170:173], v[40:43]
	ds_read_b128 v[174:177], v160 offset:34816
	v_mfma_f32_16x16x32_bf16 v[32:35], v[202:205], v[178:181], v[32:35]
	ds_read_b128 v[182:185], v160 offset:36864
	v_mfma_f32_16x16x32_bf16 v[24:27], v[210:213], v[178:181], v[24:27]
	ds_read_b128 v[190:193], v160 offset:38912
	v_mfma_f32_16x16x32_bf16 v[16:19], v[202:205], v[186:189], v[16:19]
	v_mfma_f32_16x16x32_bf16 v[8:11], v[210:213], v[186:189], v[8:11]
	v_mfma_f32_16x16x32_bf16 v[4:7], v[202:205], v[194:197], v[4:7]
	v_mfma_f32_16x16x32_bf16 v[0:3], v[210:213], v[194:197], v[0:3]
	s_barrier
	s_setprio 0
	s_add_u32 s20, s20, 0x160000
	s_addc_u32 s21, s21, 0
	s_mov_b32 m0, s33
	ds_read_b128 v[170:173], v160 offset:33792
	ds_read_b128 v[178:181], v160 offset:35840
	ds_read_b128 v[186:189], v160 offset:37888
	ds_read_b128 v[194:197], v160 offset:39936
	global_load_lds_dwordx4 v134, s[20:21]
	s_mov_b32 m0, s34
	s_nop 0
	global_load_lds_dwordx4 v130, s[20:21]
	s_waitcnt lgkmcnt(0)
	s_waitcnt vmcnt(8)
	s_setprio 1
	s_barrier
	v_mfma_f32_16x16x32_bf16 v[124:127], v[144:147], v[166:169], v[124:127]
	v_mfma_f32_16x16x32_bf16 v[120:123], v[152:155], v[166:169], v[120:123]
	v_mfma_f32_16x16x32_bf16 v[116:119], v[144:147], v[174:177], v[116:119]
	v_mfma_f32_16x16x32_bf16 v[112:115], v[152:155], v[174:177], v[112:115]
	v_mfma_f32_16x16x32_bf16 v[104:107], v[144:147], v[182:185], v[104:107]
	v_mfma_f32_16x16x32_bf16 v[96:99], v[152:155], v[182:185], v[96:99]
	v_mfma_f32_16x16x32_bf16 v[88:91], v[144:147], v[190:193], v[88:91]
	v_mfma_f32_16x16x32_bf16 v[80:83], v[152:155], v[190:193], v[80:83]
	v_mfma_f32_16x16x32_bf16 v[124:127], v[148:151], v[170:173], v[124:127]
	v_mfma_f32_16x16x32_bf16 v[120:123], v[162:165], v[170:173], v[120:123]
	v_mfma_f32_16x16x32_bf16 v[116:119], v[148:151], v[178:181], v[116:119]
	v_mfma_f32_16x16x32_bf16 v[112:115], v[162:165], v[178:181], v[112:115]
	v_mfma_f32_16x16x32_bf16 v[104:107], v[148:151], v[186:189], v[104:107]
	v_mfma_f32_16x16x32_bf16 v[96:99], v[162:165], v[186:189], v[96:99]
	v_mfma_f32_16x16x32_bf16 v[88:91], v[148:151], v[194:197], v[88:91]
	v_mfma_f32_16x16x32_bf16 v[80:83], v[162:165], v[194:197], v[80:83]
	s_barrier
; #define PG8_STAGE(bufoff, gbase, voff) do { _Pragma("unroll") for (int _i = 0; _i < 2; ++_i) \
;     __builtin_amdgcn_global_load_lds((const unsigned*)((const char*)(gbase) + (voff)[_i]), (LAS unsigned*)(lds + (bufoff) + ldsw + _i * 8192), 16, 0, 0); } while (0)
; #define PG8_LDA(dst, b, h) do { _Pragma("unroll") for (int m = 0; m < 4; ++m) _Pragma("unroll") for (int k = 0; k < 2; ++k) dst[m][k] = *(const LAS bf16x8*)(lds + PG8_SA(b, h) + aoff + m * 2048 + k * 1024); } while (0)
; #define PG8_LDB(dst, b, h) do { _Pragma("unroll") for (int n = 0; n < 2; ++n) _Pragma("unroll") for (int k = 0; k < 2; ++k) dst[n][k] = *(const LAS bf16x8*)(lds + PG8_SB(b, h) + boff + n * 2048 + k * 1024); } while (0)
; #define PG8_MMA(ai, bj, At, Bt) do { __builtin_amdgcn_s_setprio(1); _Pragma("unroll") for (int m = 0; m < 4; ++m) _Pragma("unroll") for (int n = 0; n < 2; ++n) _Pragma("unroll") for (int k = 0; k < 2; ++k) \
;     acc[ai][bj][m][n] = __builtin_amdgcn_mfma_f32_16x16x32_bf16(Bt[n][k], At[m][k], acc[ai][bj][m][n], 0, 0, 0); __builtin_amdgcn_s_setprio(0); } while (0)
; #define PG8_WAIT_V(n) asm volatile("s_waitcnt vmcnt(" #n ")" ::: "memory")
; #define PG8_WAIT_L(n) asm volatile("s_waitcnt lgkmcnt(" #n ")" ::: "memory")
; #define PG8_BAR __builtin_amdgcn_s_barrier()
; #define PG8_SCHED __builtin_amdgcn_sched_barrier(0)
; template <class Epi, class Sched = StaticOrder>
; DI void gemm_phase(LAS unsigned char* lds, const Gemm g, const Sched& S, const Epi& E) {
;     ...
;       PG8_LDB(B1, 1, 1); PG8_STAGE(PG8_SB(1, 0), b3, voffB);
;       PG8_BAR; PG8_WAIT_L(0); PG8_MMA(0, 1, At, B1); PG8_BAR;
;       PG8_LDA(At, 1, 1); PG8_STAGE(PG8_SA(1, 0), a3, voffA);
;       PG8_BAR; PG8_WAIT_L(0); PG8_MMA(1, 0, At, B0); PG8_BAR; PG8_SCHED;
;       PG8_STAGE(PG8_SB(1, 1), b3 + hstep, voffB);
;       PG8_WAIT_V(6); PG8_BAR; PG8_MMA(1, 1, At, B1); PG8_BAR;
	s_setprio 0
	s_add_i32 s20, 0, 0x1c000
	s_add_i32 s21, s48, s28
	v_add_u32_e32 v210, s20, v157
	s_mov_b32 m0, s21
	ds_read_b128 v[198:201], v210
	ds_read_b128 v[202:205], v210 offset:1024
	ds_read_b128 v[206:209], v210 offset:2048
	ds_read_b128 v[210:213], v210 offset:3072
	global_load_lds_dwordx4 v132, s[98:99]
	s_add_i32 m0, s21, 0x2000
	s_nop 0
	global_load_lds_dwordx4 v128, s[98:99]
	s_waitcnt lgkmcnt(0)
	s_setprio 1
	s_barrier
	v_mfma_f32_16x16x32_bf16 v[108:111], v[198:201], v[166:169], v[108:111]
	v_mfma_f32_16x16x32_bf16 v[100:103], v[206:209], v[166:169], v[100:103]
	v_mfma_f32_16x16x32_bf16 v[92:95], v[198:201], v[174:177], v[92:95]
	v_mfma_f32_16x16x32_bf16 v[84:87], v[206:209], v[174:177], v[84:87]
	v_mfma_f32_16x16x32_bf16 v[76:79], v[198:201], v[182:185], v[76:79]
	v_mfma_f32_16x16x32_bf16 v[72:75], v[206:209], v[182:185], v[72:75]
	v_mfma_f32_16x16x32_bf16 v[68:71], v[198:201], v[190:193], v[68:71]
	v_mfma_f32_16x16x32_bf16 v[64:67], v[206:209], v[190:193], v[64:67]
	v_mfma_f32_16x16x32_bf16 v[108:111], v[202:205], v[170:173], v[108:111]
	ds_read_b128 v[166:169], v160 offset:49152
	v_mfma_f32_16x16x32_bf16 v[100:103], v[210:213], v[170:173], v[100:103]
	ds_read_b128 v[174:177], v160 offset:51200
	v_mfma_f32_16x16x32_bf16 v[92:95], v[202:205], v[178:181], v[92:95]
	ds_read_b128 v[182:185], v160 offset:53248
	v_mfma_f32_16x16x32_bf16 v[84:87], v[210:213], v[178:181], v[84:87]
	ds_read_b128 v[190:193], v160 offset:55296
	v_mfma_f32_16x16x32_bf16 v[76:79], v[202:205], v[186:189], v[76:79]
	v_mfma_f32_16x16x32_bf16 v[72:75], v[210:213], v[186:189], v[72:75]
	v_mfma_f32_16x16x32_bf16 v[68:71], v[202:205], v[194:197], v[68:71]
	v_mfma_f32_16x16x32_bf16 v[64:67], v[210:213], v[194:197], v[64:67]
	s_barrier
	s_setprio 0
	s_mov_b32 m0, s35
	ds_read_b128 v[170:173], v160 offset:50176
	ds_read_b128 v[178:181], v160 offset:52224
	ds_read_b128 v[186:189], v160 offset:54272
	ds_read_b128 v[194:197], v160 offset:56320
	global_load_lds_dwordx4 v134, s[100:101]
	s_mov_b32 m0, s36
	s_nop 0
	global_load_lds_dwordx4 v130, s[100:101]
	s_waitcnt vmcnt(8)
	s_waitcnt lgkmcnt(0)
	s_setprio 1
	s_barrier
	v_mfma_f32_16x16x32_bf16 v[60:63], v[144:147], v[166:169], v[60:63]
	v_mfma_f32_16x16x32_bf16 v[56:59], v[152:155], v[166:169], v[56:59]
	v_mfma_f32_16x16x32_bf16 v[52:55], v[144:147], v[174:177], v[52:55]
	v_mfma_f32_16x16x32_bf16 v[44:47], v[152:155], v[174:177], v[44:47]
	v_mfma_f32_16x16x32_bf16 v[36:39], v[144:147], v[182:185], v[36:39]
	v_mfma_f32_16x16x32_bf16 v[28:31], v[152:155], v[182:185], v[28:31]
	v_mfma_f32_16x16x32_bf16 v[20:23], v[144:147], v[190:193], v[20:23]
	v_mfma_f32_16x16x32_bf16 v[12:15], v[152:155], v[190:193], v[12:15]
	v_mfma_f32_16x16x32_bf16 v[60:63], v[148:151], v[170:173], v[60:63]
	v_mfma_f32_16x16x32_bf16 v[56:59], v[162:165], v[170:173], v[56:59]
	v_mfma_f32_16x16x32_bf16 v[52:55], v[148:151], v[178:181], v[52:55]
	v_mfma_f32_16x16x32_bf16 v[44:47], v[162:165], v[178:181], v[44:47]
	v_mfma_f32_16x16x32_bf16 v[36:39], v[148:151], v[186:189], v[36:39]
	v_mfma_f32_16x16x32_bf16 v[28:31], v[162:165], v[186:189], v[28:31]
	v_mfma_f32_16x16x32_bf16 v[20:23], v[148:151], v[194:197], v[20:23]
	v_mfma_f32_16x16x32_bf16 v[12:15], v[162:165], v[194:197], v[12:15]
	s_barrier
	s_setprio 0
	s_add_u32 s18, s18, 0x160080
	s_addc_u32 s19, s19, 0
	s_add_i32 s20, s20, s28
	s_mov_b32 m0, s20
	s_nop 0
	global_load_lds_dwordx4 v132, s[18:19]
	s_add_i32 m0, s20, 0x2000
	s_nop 0
	global_load_lds_dwordx4 v128, s[18:19]
	ds_read_b128 v[144:147], v159
	ds_read_b128 v[148:151], v159 offset:1024
	ds_read_b128 v[152:155], v159 offset:2048
	ds_read_b128 v[162:165], v159 offset:3072
	s_waitcnt vmcnt(6)
	s_add_i32 s47, s47, 2
	s_add_u32 s16, s16, 0x100
	s_addc_u32 s17, s17, 0
	s_add_u32 s45, s45, 0x100
	s_addc_u32 s46, s46, 0
	s_cmpk_gt_u32 s47, 0x55
	s_setprio 1
	s_barrier
	v_mfma_f32_16x16x32_bf16 v[48:51], v[198:201], v[166:169], v[48:51]
	v_mfma_f32_16x16x32_bf16 v[40:43], v[206:209], v[166:169], v[40:43]
	v_mfma_f32_16x16x32_bf16 v[32:35], v[198:201], v[174:177], v[32:35]
	v_mfma_f32_16x16x32_bf16 v[24:27], v[206:209], v[174:177], v[24:27]
	v_mfma_f32_16x16x32_bf16 v[16:19], v[198:201], v[182:185], v[16:19]
	v_mfma_f32_16x16x32_bf16 v[8:11], v[206:209], v[182:185], v[8:11]
	v_mfma_f32_16x16x32_bf16 v[4:7], v[198:201], v[190:193], v[4:7]
	v_mfma_f32_16x16x32_bf16 v[0:3], v[206:209], v[190:193], v[0:3]
	v_mfma_f32_16x16x32_bf16 v[48:51], v[202:205], v[170:173], v[48:51]
	ds_read_b128 v[166:169], v160
	v_mfma_f32_16x16x32_bf16 v[40:43], v[210:213], v[170:173], v[40:43]
	ds_read_b128 v[174:177], v160 offset:2048
	v_mfma_f32_16x16x32_bf16 v[32:35], v[202:205], v[178:181], v[32:35]
	ds_read_b128 v[182:185], v160 offset:4096
	v_mfma_f32_16x16x32_bf16 v[24:27], v[210:213], v[178:181], v[24:27]
	ds_read_b128 v[190:193], v160 offset:6144
	v_mfma_f32_16x16x32_bf16 v[16:19], v[202:205], v[186:189], v[16:19]
	v_mfma_f32_16x16x32_bf16 v[8:11], v[210:213], v[186:189], v[8:11]
	v_mfma_f32_16x16x32_bf16 v[4:7], v[202:205], v[194:197], v[4:7]
	v_mfma_f32_16x16x32_bf16 v[0:3], v[210:213], v[194:197], v[0:3]
	s_barrier
	s_setprio 0
	s_cbranch_scc0 .LBB0_1424
;   DI void operator()(const f32x4 (&acc)[2][2][4][2], const Unit& u, int wr, int wc, int fr, int fq) const {
;     const int row0 = u.pm * BM + wr * 64 + fr, col0 = u.pn * BM + wc * 32 + 8 * fq;
; #pragma unroll
;     for (int ai = 0; ai < 2; ++ai) {
;       f32x4 bv[4][2][2];
; #pragma unroll
;       for (int m = 0; m < 4; ++m)
; #pragma unroll
;         for (int bj = 0; bj < 2; ++bj) {
;           const float* bp = base + (size_t)(row0 + ai * HALF + m * 16) * 2048 + col0 + bj * HALF;
;           bv[m][bj][0] = *(const f32x4*)bp; bv[m][bj][1] = *(const f32x4*)(bp + 4);
;         }
; #pragma unroll
;       for (int m = 0; m < 4; ++m) {
;         const int row = row0 + ai * HALF + m * 16;
;         const size_t off = (size_t)row * 2048 + col0;
;         float ss = 0.f;
; #pragma unroll
;         for (int bj = 0; bj < 2; ++bj) {
;           const f32x4 v0 = acc[ai][bj][m][0] + bv[m][bj][0], v1 = acc[ai][bj][m][1] + bv[m][bj][1];
;           *(f32x4*)(C + off + bj * HALF) = v0; *(f32x4*)(C + off + bj * HALF + 4) = v1;
	s_waitcnt lgkmcnt(0)
	v_lshl_or_b32 v144, s44, 8, v158
	v_lshl_add_u32 v154, s43, 8, v156
	v_ashrrev_i32_e32 v145, 31, v144
	v_lshlrev_b64 v[144:145], 2, v[144:145]
	v_ashrrev_i32_e32 v155, 31, v154
	v_lshl_add_u64 v[146:147], s[54:55], 0, v[144:145]
	v_lshlrev_b64 v[148:149], 13, v[154:155]
	v_or_b32_e32 v174, 16, v154
	v_lshl_add_u64 v[170:171], v[146:147], 0, v[148:149]
	v_ashrrev_i32_e32 v175, 31, v174
	global_load_dwordx4 v[150:153], v[170:171], off offset:16
	global_load_dwordx4 v[162:165], v[170:171], off
	global_load_dwordx4 v[166:169], v[170:171], off offset:528
	s_nop 0
	global_load_dwordx4 v[170:173], v[170:171], off offset:512
	v_lshlrev_b64 v[222:223], 13, v[174:175]
	v_or_b32_e32 v190, 32, v154
	v_lshl_add_u64 v[186:187], v[146:147], 0, v[222:223]
	v_ashrrev_i32_e32 v191, 31, v190
	global_load_dwordx4 v[174:177], v[186:187], off offset:16
	global_load_dwordx4 v[178:181], v[186:187], off
	global_load_dwordx4 v[182:185], v[186:187], off offset:528
	s_nop 0
	global_load_dwordx4 v[186:189], v[186:187], off offset:512
	v_lshlrev_b64 v[224:225], 13, v[190:191]
	v_or_b32_e32 v154, 48, v154
	v_lshl_add_u64 v[202:203], v[146:147], 0, v[224:225]
	v_ashrrev_i32_e32 v155, 31, v154
	global_load_dwordx4 v[190:193], v[202:203], off offset:16
	global_load_dwordx4 v[194:197], v[202:203], off
	global_load_dwordx4 v[198:201], v[202:203], off offset:528
	s_nop 0
	global_load_dwordx4 v[202:205], v[202:203], off offset:512
	v_lshlrev_b64 v[154:155], 13, v[154:155]
	v_lshl_add_u64 v[218:219], v[146:147], 0, v[154:155]
	global_load_dwordx4 v[206:209], v[218:219], off offset:16
	global_load_dwordx4 v[210:213], v[218:219], off
	global_load_dwordx4 v[214:217], v[218:219], off offset:528
	s_nop 0
	global_load_dwordx4 v[218:221], v[218:219], off offset:512
	s_and_b64 vcc, exec, s[0:1]
	s_mov_b32 s44, s41
	s_mov_b32 s43, s42
	s_mov_b64 s[18:19], s[4:5]
	s_mov_b64 s[16:17], s[2:3]
	s_waitcnt vmcnt(0)
	v_pk_add_f32 v[120:121], v[120:121], v[150:151]
	v_lshl_add_u64 v[150:151], s[54:55], 0, v[148:149]
	v_pk_add_f32 v[126:127], v[126:127], v[164:165]
	v_pk_add_f32 v[124:125], v[124:125], v[162:163]
	v_lshl_add_u64 v[150:151], v[150:151], 0, v[144:145]
	v_pk_add_f32 v[110:111], v[110:111], v[172:173]
	v_pk_add_f32 v[108:109], v[108:109], v[170:171]
	v_pk_add_f32 v[122:123], v[122:123], v[152:153]
	global_store_dwordx4 v[150:151], v[124:127], off
	global_store_dwordx4 v[150:151], v[120:123], off offset:16
	v_pk_add_f32 v[102:103], v[102:103], v[168:169]
	v_pk_add_f32 v[100:101], v[100:101], v[166:167]
	global_store_dwordx4 v[150:151], v[108:111], off offset:512
	global_store_dwordx4 v[150:151], v[100:103], off offset:528
	v_pk_add_f32 v[94:95], v[94:95], v[188:189]
	v_pk_add_f32 v[108:109], v[112:113], v[174:175]
	v_lshl_add_u64 v[112:113], s[54:55], 0, v[222:223]
	v_pk_add_f32 v[102:103], v[118:119], v[180:181]
	v_pk_add_f32 v[100:101], v[116:117], v[178:179]
	v_lshl_add_u64 v[112:113], v[112:113], 0, v[144:145]
	v_pk_add_f32 v[92:93], v[92:93], v[186:187]
	v_pk_add_f32 v[110:111], v[114:115], v[176:177]
	global_store_dwordx4 v[112:113], v[100:103], off
	global_store_dwordx4 v[112:113], v[108:111], off offset:16
	v_pk_add_f32 v[86:87], v[86:87], v[184:185]
	v_pk_add_f32 v[84:85], v[84:85], v[182:183]
	global_store_dwordx4 v[112:113], v[92:95], off offset:512
	global_store_dwordx4 v[112:113], v[84:87], off offset:528
	v_pk_add_f32 v[78:79], v[78:79], v[204:205]
	v_pk_add_f32 v[92:93], v[96:97], v[190:191]
	v_lshl_add_u64 v[96:97], s[54:55], 0, v[224:225]
	v_pk_add_f32 v[86:87], v[106:107], v[196:197]
	v_pk_add_f32 v[84:85], v[104:105], v[194:195]
	v_lshl_add_u64 v[96:97], v[96:97], 0, v[144:145]
	v_pk_add_f32 v[76:77], v[76:77], v[202:203]
	v_pk_add_f32 v[94:95], v[98:99], v[192:193]
	global_store_dwordx4 v[96:97], v[84:87], off
	global_store_dwordx4 v[96:97], v[92:95], off offset:16
	v_pk_add_f32 v[74:75], v[74:75], v[200:201]
	v_pk_add_f32 v[72:73], v[72:73], v[198:199]
	global_store_dwordx4 v[96:97], v[76:79], off offset:512
	global_store_dwordx4 v[96:97], v[72:75], off offset:528
	v_pk_add_f32 v[70:71], v[70:71], v[220:221]
	v_pk_add_f32 v[76:77], v[80:81], v[206:207]
	v_lshl_add_u64 v[80:81], s[54:55], 0, v[154:155]
	v_pk_add_f32 v[74:75], v[90:91], v[212:213]
	v_pk_add_f32 v[72:73], v[88:89], v[210:211]
	v_lshl_add_u64 v[80:81], v[80:81], 0, v[144:145]
	v_pk_add_f32 v[68:69], v[68:69], v[218:219]
	v_pk_add_f32 v[64:65], v[64:65], v[214:215]
	v_lshl_add_u64 v[154:155], v[148:149], 0, s[10:11]
	v_pk_add_f32 v[78:79], v[82:83], v[208:209]
	global_store_dwordx4 v[80:81], v[72:75], off
	global_store_dwordx4 v[80:81], v[76:79], off offset:16
	v_pk_add_f32 v[66:67], v[66:67], v[216:217]
	global_store_dwordx4 v[80:81], v[68:71], off offset:512
	global_store_dwordx4 v[80:81], v[64:67], off offset:528
	v_lshl_add_u64 v[152:153], v[148:149], 0, s[12:13]
	v_lshl_add_u64 v[150:151], v[148:149], 0, s[14:15]
	v_lshl_add_u64 v[64:65], v[146:147], 0, v[154:155]
	global_load_dwordx4 v[108:111], v[64:65], off offset:16
	global_load_dwordx4 v[120:123], v[64:65], off
	global_load_dwordx4 v[92:95], v[64:65], off offset:528
	global_load_dwordx4 v[100:103], v[64:65], off offset:512
	v_lshl_add_u64 v[64:65], v[146:147], 0, v[152:153]
	global_load_dwordx4 v[88:91], v[64:65], off offset:16
	global_load_dwordx4 v[96:99], v[64:65], off
	global_load_dwordx4 v[76:79], v[64:65], off offset:528
	global_load_dwordx4 v[84:87], v[64:65], off offset:512
	v_lshl_add_u64 v[68:69], v[146:147], 0, v[150:151]
	global_load_dwordx4 v[72:75], v[68:69], off offset:16
	global_load_dwordx4 v[80:83], v[68:69], off
	global_load_dwordx4 v[64:67], v[68:69], off offset:528
	s_nop 0
	global_load_dwordx4 v[68:71], v[68:69], off offset:512
	v_lshl_add_u64 v[148:149], v[148:149], 0, s[6:7]
	v_lshl_add_u64 v[112:113], v[146:147], 0, v[148:149]
	global_load_dwordx4 v[116:119], v[112:113], off offset:16
	global_load_dwordx4 v[124:127], v[112:113], off
	global_load_dwordx4 v[104:107], v[112:113], off offset:528
	s_nop 0
	global_load_dwordx4 v[112:115], v[112:113], off offset:512
	s_waitcnt vmcnt(0)
; #define PG8_WAIT_V(n) asm volatile("s_waitcnt vmcnt(" #n ")" ::: "memory")
; #define PG8_BAR __builtin_amdgcn_s_barrier()
;   DI void operator()(const f32x4 (&acc)[2][2][4][2], const Unit& u, int wr, int wc, int fr, int fq) const {
;     ...
;         for (int bj = 0; bj < 2; ++bj) {
;           const f32x4 v0 = acc[ai][bj][m][0] + bv[m][bj][0], v1 = acc[ai][bj][m][1] + bv[m][bj][1];
;           *(f32x4*)(C + off + bj * HALF) = v0; *(f32x4*)(C + off + bj * HALF + 4) = v1;
; template <class Epi, class Sched = StaticOrder>
; DI void gemm_phase(LAS unsigned char* lds, const Gemm g, const Sched& S, const Epi& E) {
;     ...
;     if (!has_next) break;
; #pragma unroll
;     for (int a = 0; a < 2; ++a)
; #pragma unroll
;       for (int b = 0; b < 2; ++b)
; #pragma unroll
;         for (int m = 0; m < 4; ++m)
; #pragma unroll
;           for (int n = 0; n < 2; ++n) acc[a][b][m][n] = (f32x4){0.f, 0.f, 0.f, 0.f};
;     cur = nxt; cA = nA; cB = nB; ++ui;
;   }
;   PG8_WAIT_V(0);
;   if (wr == 0) PG8_BAR;
;   PG8_BAR;
	v_pk_add_f32 v[56:57], v[56:57], v[108:109]
	v_lshl_add_u64 v[108:109], s[54:55], 0, v[154:155]
	v_pk_add_f32 v[62:63], v[62:63], v[122:123]
	v_pk_add_f32 v[60:61], v[60:61], v[120:121]
	v_lshl_add_u64 v[108:109], v[108:109], 0, v[144:145]
	v_pk_add_f32 v[50:51], v[50:51], v[102:103]
	v_pk_add_f32 v[48:49], v[48:49], v[100:101]
	v_pk_add_f32 v[58:59], v[58:59], v[110:111]
	global_store_dwordx4 v[108:109], v[60:63], off
	global_store_dwordx4 v[108:109], v[56:59], off offset:16
	v_pk_add_f32 v[42:43], v[42:43], v[94:95]
	v_pk_add_f32 v[40:41], v[40:41], v[92:93]
	global_store_dwordx4 v[108:109], v[48:51], off offset:512
	global_store_dwordx4 v[108:109], v[40:43], off offset:528
	v_pk_add_f32 v[34:35], v[34:35], v[86:87]
	v_lshl_add_u64 v[48:49], s[54:55], 0, v[152:153]
	v_pk_add_f32 v[42:43], v[54:55], v[98:99]
	v_pk_add_f32 v[40:41], v[52:53], v[96:97]
	v_lshl_add_u64 v[48:49], v[48:49], 0, v[144:145]
	v_pk_add_f32 v[32:33], v[32:33], v[84:85]
	v_pk_add_f32 v[46:47], v[46:47], v[90:91]
	v_pk_add_f32 v[44:45], v[44:45], v[88:89]
	global_store_dwordx4 v[48:49], v[40:43], off
	global_store_dwordx4 v[48:49], v[44:47], off offset:16
	v_pk_add_f32 v[26:27], v[26:27], v[78:79]
	v_pk_add_f32 v[24:25], v[24:25], v[76:77]
	global_store_dwordx4 v[48:49], v[32:35], off offset:512
	global_store_dwordx4 v[48:49], v[24:27], off offset:528
	v_pk_add_f32 v[18:19], v[18:19], v[70:71]
	v_lshl_add_u64 v[32:33], s[54:55], 0, v[150:151]
	v_pk_add_f32 v[26:27], v[38:39], v[82:83]
	v_pk_add_f32 v[24:25], v[36:37], v[80:81]
	v_lshl_add_u64 v[32:33], v[32:33], 0, v[144:145]
	v_pk_add_f32 v[16:17], v[16:17], v[68:69]
	v_pk_add_f32 v[30:31], v[30:31], v[74:75]
	v_pk_add_f32 v[28:29], v[28:29], v[72:73]
	global_store_dwordx4 v[32:33], v[24:27], off
	global_store_dwordx4 v[32:33], v[28:31], off offset:16
	v_pk_add_f32 v[10:11], v[10:11], v[66:67]
	v_pk_add_f32 v[8:9], v[8:9], v[64:65]
	global_store_dwordx4 v[32:33], v[16:19], off offset:512
	global_store_dwordx4 v[32:33], v[8:11], off offset:528
	v_pk_add_f32 v[6:7], v[6:7], v[114:115]
	v_lshl_add_u64 v[16:17], s[54:55], 0, v[148:149]
	v_pk_add_f32 v[10:11], v[22:23], v[126:127]
	v_pk_add_f32 v[8:9], v[20:21], v[124:125]
	v_lshl_add_u64 v[16:17], v[16:17], 0, v[144:145]
	v_pk_add_f32 v[4:5], v[4:5], v[112:113]
	v_pk_add_f32 v[14:15], v[14:15], v[118:119]
	v_pk_add_f32 v[12:13], v[12:13], v[116:117]
	global_store_dwordx4 v[16:17], v[8:11], off
	global_store_dwordx4 v[16:17], v[12:15], off offset:16
	v_pk_add_f32 v[2:3], v[2:3], v[106:107]
	v_pk_add_f32 v[0:1], v[0:1], v[104:105]
	global_store_dwordx4 v[16:17], v[4:7], off offset:512
	global_store_dwordx4 v[16:17], v[0:3], off offset:528
	s_cbranch_vccz .LBB0_1417
	s_waitcnt vmcnt(0)
	s_cmpk_gt_u32 s23, 0xff
	s_cbranch_scc1 .LBB0_1428
	s_barrier
